# prologue x->bf16 row loop and final norm loop: row loads issued together (counted waits); GLA g1 epilogue rewritten (DPP pair exchange, batched exec-masked stores); every __shfl_xor(.,1) LDS round tri
# speedup vs baseline: 1.0136x; 1.0136x over previous
.LBB0_460:
	s_add_i32 s0, 0, 0x22100
	v_mov_b32_e32 v1, s0
	s_waitcnt vmcnt(62)
	ds_read_b128 v[6:9], v1
	v_add_u32_e32 v0, s25, v5
	v_ashrrev_i32_e32 v0, 6, v0
	v_readlane_b32 s0, v253, 2
	s_waitcnt vmcnt(43)
	v_and_b32_e32 v28, 63, v5
	s_lshl_b32 s4, s24, 3
	v_lshl_add_u32 v0, s0, 3, v0
	s_movk_i32 s0, 0x2200
	s_waitcnt lgkmcnt(0)
	v_readfirstlane_b32 s3, v7
	v_readfirstlane_b32 s2, v6
	v_readfirstlane_b32 s7, v9
	v_readfirstlane_b32 s6, v8
	v_cmp_gt_i32_e32 vcc, s0, v0
	v_lshlrev_b32_e32 v8, 2, v28
	s_and_saveexec_b64 s[8:9], vcc
	s_cbranch_execz .LBB0_467
	v_mov_b32_e32 v3, 0
	v_mov_b32_e32 v9, v3
	v_lshlrev_b32_e32 v2, 3, v28
	v_ashrrev_i32_e32 v1, 31, v0
	v_lshl_add_u64 v[4:5], s[12:13], 0, v[8:9]
	s_mov_b64 s[0:1], 0x437a6000
	v_or_b32_e32 v14, 0x400, v8
	v_or_b32_e32 v16, 0x500, v8
	v_or_b32_e32 v18, 0x600, v8
	v_or_b32_e32 v20, 0x700, v8
	v_lshl_add_u64 v[6:7], s[12:13], 0, v[2:3]
	s_mov_b64 s[10:11], 0x1ca00000
	s_ashr_i32 s5, s4, 31
	v_lshlrev_b64 v[10:11], 13, v[0:1]
	v_cmp_gt_u32_e32 vcc, 32, v28
	v_lshl_add_u64 v[4:5], v[4:5], 0, s[0:1]
	v_cmp_eq_u32_e64 s[0:1], 0, v28
	v_lshl_add_u64 v[6:7], v[6:7], 0, s[10:11]
	v_lshl_add_u64 v[10:11], s[2:3], 0, v[10:11]
	s_lshl_b64 s[10:11], s[4:5], 13
	s_mov_b64 s[14:15], 0
	s_movk_i32 s18, 0x1fff
	v_lshlrev_b32_e32 v12, 2, v8
	v_mov_b32_e32 v13, v3
	v_lshlrev_b32_e32 v14, 2, v14
	v_mov_b32_e32 v15, v3
	v_lshlrev_b32_e32 v16, 2, v16
	v_mov_b32_e32 v17, v3
	v_lshlrev_b32_e32 v18, 2, v18
	v_mov_b32_e32 v19, v3
	v_lshlrev_b32_e32 v20, 2, v20
	v_mov_b32_e32 v21, v3
	s_movk_i32 s19, 0x21ff
	v_mov_b64_e32 v[22:23], v[0:1]
	s_waitcnt vmcnt(0)
	s_branch .LBB0_463

.LBB0_463:
	v_cmp_lt_i32_e64 s[2:3], s18, v22
	v_mov_b64_e32 v[24:25], v[22:23]
	v_mov_b64_e32 v[26:27], v[10:11]
	s_and_saveexec_b64 s[16:17], s[2:3]
	v_add_u32_e32 v2, 0xffffe000, v22
	v_lshlrev_b64 v[24:25], 13, v[2:3]
	v_mov_b32_e32 v2, v22
	v_lshl_add_u64 v[26:27], s[6:7], 0, v[24:25]
	v_mov_b64_e32 v[24:25], v[2:3]
	s_or_b64 exec, exec, s[16:17]
	v_lshl_add_u64 v[42:43], v[26:27], 0, v[12:13]
	v_lshlrev_b64 v[34:35], 12, v[24:25]
	v_lshl_add_u64 v[46:47], v[26:27], 0, v[14:15]
	v_lshl_add_u64 v[50:51], v[26:27], 0, v[16:17]
	v_lshl_add_u64 v[54:55], v[26:27], 0, v[18:19]
	v_lshl_add_u64 v[26:27], v[26:27], 0, v[20:21]
	v_lshl_add_u64 v[62:63], v[6:7], 0, v[34:35]
	global_load_dwordx4 v[30:33], v[42:43], off
	global_load_dwordx4 v[34:37], v[42:43], off offset:1024
	global_load_dwordx4 v[38:41], v[42:43], off offset:2048
	global_load_dwordx4 v[42:45], v[42:43], off offset:3072
	global_load_dwordx4 v[46:49], v[46:47], off
	global_load_dwordx4 v[50:53], v[50:51], off
	global_load_dwordx4 v[54:57], v[54:55], off
	global_load_dwordx4 v[58:61], v[26:27], off
	s_waitcnt vmcnt(7)
	v_cvt_pk_bf16_f32 v194, v30, v31
	v_cvt_pk_bf16_f32 v195, v32, v33
	global_store_dwordx2 v[62:63], v[194:195], off
	s_waitcnt vmcnt(7)
	v_cvt_pk_bf16_f32 v196, v34, v35
	v_cvt_pk_bf16_f32 v197, v36, v37
	global_store_dwordx2 v[62:63], v[196:197], off offset:512
	s_waitcnt vmcnt(7)
	v_cvt_pk_bf16_f32 v194, v38, v39
	v_cvt_pk_bf16_f32 v195, v40, v41
	global_store_dwordx2 v[62:63], v[194:195], off offset:1024
	s_waitcnt vmcnt(7)
	v_cvt_pk_bf16_f32 v196, v42, v43
	v_cvt_pk_bf16_f32 v197, v44, v45
	global_store_dwordx2 v[62:63], v[196:197], off offset:1536
	s_waitcnt vmcnt(7)
	v_cvt_pk_bf16_f32 v194, v46, v47
	v_cvt_pk_bf16_f32 v195, v48, v49
	global_store_dwordx2 v[62:63], v[194:195], off offset:2048
	s_waitcnt vmcnt(7)
	v_cvt_pk_bf16_f32 v196, v50, v51
	v_cvt_pk_bf16_f32 v197, v52, v53
	global_store_dwordx2 v[62:63], v[196:197], off offset:2560
	s_waitcnt vmcnt(7)
	v_cvt_pk_bf16_f32 v194, v54, v55
	v_cvt_pk_bf16_f32 v195, v56, v57
	global_store_dwordx2 v[62:63], v[194:195], off offset:3072
	s_waitcnt vmcnt(7)
	v_cvt_pk_bf16_f32 v196, v58, v59
	v_cvt_pk_bf16_f32 v197, v60, v61
	global_store_dwordx2 v[62:63], v[196:197], off offset:3584
	v_mul_f32_e32 v1, v31, v31
	v_mul_f32_e32 v2, v33, v33
	v_fmac_f32_e32 v1, v30, v30
	v_fmac_f32_e32 v2, v32, v32
	v_add_f32_e32 v1, v1, v2
	v_mul_f32_e32 v2, v35, v35
	v_mul_f32_e32 v9, v37, v37
	v_fmac_f32_e32 v2, v34, v34
	v_fmac_f32_e32 v9, v36, v36
	v_add_f32_e32 v2, v2, v9
	v_add_f32_e32 v1, v1, v2
	v_mul_f32_e32 v2, v39, v39
	v_mul_f32_e32 v9, v41, v41
	v_fmac_f32_e32 v2, v38, v38
	v_fmac_f32_e32 v9, v40, v40
	v_add_f32_e32 v2, v2, v9
	v_add_f32_e32 v1, v1, v2
	v_mul_f32_e32 v2, v43, v43
	v_mul_f32_e32 v9, v45, v45
	v_fmac_f32_e32 v2, v42, v42
	v_fmac_f32_e32 v9, v44, v44
	v_add_f32_e32 v2, v2, v9
	v_add_f32_e32 v1, v1, v2
	v_mul_f32_e32 v2, v47, v47
	v_mul_f32_e32 v9, v49, v49
	v_fmac_f32_e32 v2, v46, v46
	v_fmac_f32_e32 v9, v48, v48
	v_add_f32_e32 v2, v2, v9
	v_add_f32_e32 v1, v1, v2
	v_mul_f32_e32 v2, v51, v51
	v_mul_f32_e32 v9, v53, v53
	v_fmac_f32_e32 v2, v50, v50
	v_fmac_f32_e32 v9, v52, v52
	v_add_f32_e32 v2, v2, v9
	v_add_f32_e32 v1, v1, v2
	v_mul_f32_e32 v2, v55, v55
	v_mul_f32_e32 v9, v57, v57
	v_fmac_f32_e32 v2, v54, v54
	v_fmac_f32_e32 v9, v56, v56
	v_add_f32_e32 v2, v2, v9
	v_add_f32_e32 v1, v1, v2
	v_mul_f32_e32 v2, v59, v59
	v_mul_f32_e32 v9, v61, v61
	v_fmac_f32_e32 v2, v58, v58
	v_fmac_f32_e32 v9, v60, v60
	v_add_f32_e32 v2, v2, v9
	v_add_f32_e32 v1, v1, v2
	ds_swizzle_b32 v2, v1 offset:swizzle(SWAP,1)
	s_waitcnt lgkmcnt(0)
	v_add_f32_e32 v1, v1, v2
	ds_swizzle_b32 v2, v1 offset:swizzle(SWAP,2)
	s_waitcnt lgkmcnt(0)
	v_add_f32_e32 v1, v1, v2
	ds_swizzle_b32 v2, v1 offset:swizzle(SWAP,4)
	s_waitcnt lgkmcnt(0)
	v_add_f32_e32 v1, v1, v2
	ds_swizzle_b32 v2, v1 offset:swizzle(SWAP,8)
	s_waitcnt lgkmcnt(0)
	v_add_f32_e32 v1, v1, v2
	ds_swizzle_b32 v2, v1 offset:swizzle(SWAP,16)
	s_waitcnt lgkmcnt(0)
	v_add_f32_e32 v1, v1, v2
	v_mov_b32_e32 v2, v1
	s_nop 1
	v_permlane32_swap_b32_e32 v1, v2
	s_and_saveexec_b64 s[2:3], vcc
	s_cbranch_execz .LBB0_462
	v_lshlrev_b64 v[24:25], 7, v[24:25]
	v_add_f32_e32 v1, v1, v2
	v_lshl_add_u64 v[24:25], v[4:5], 0, v[24:25]
	v_cndmask_b32_e64 v1, 0, v1, s[0:1]
	global_store_dword v[24:25], v1, off
	s_branch .LBB0_462

.LBB0_539:
	s_mov_b64 s[20:21], 0x80
	s_add_i32 m0, s17, 0x18000
	v_lshl_add_u64 v[26:27], v[26:27], 0, s[20:21]
	s_waitcnt vmcnt(2)
	s_barrier
	global_load_lds_dwordx4 v[26:27], off
	v_lshl_add_u64 v[24:25], v[24:25], 0, s[20:21]
	s_add_i32 m0, s17, 0x1a000
	s_add_i32 s66, s17, 0x8000
	s_add_i32 s67, s17, 0xa000
	global_load_lds_dwordx4 v[24:25], off
	v_lshl_add_u64 v[20:21], v[20:21], 0, s[20:21]
	s_mov_b32 m0, s66
	s_add_u32 s0, s8, 0x80080
	global_load_lds_dwordx4 v[20:21], off
	v_lshl_add_u64 v[20:21], v[22:23], 0, s[20:21]
	s_mov_b32 m0, s67
	s_addc_u32 s1, s9, 0
	global_load_lds_dwordx4 v[20:21], off
	s_add_i32 m0, s17, 0x1c000
	v_lshl_add_u64 v[20:21], s[0:1], 0, v[150:151]
	global_load_lds_dwordx4 v[20:21], off
	v_lshl_add_u64 v[20:21], s[0:1], 0, v[154:155]
	s_add_i32 m0, s17, 0x1e000
	s_waitcnt vmcnt(0)
	v_pk_add_f32 v[10:11], v[14:15], v[10:11]
	global_load_lds_dwordx4 v[20:21], off
	v_pk_add_f32 v[8:9], v[12:13], v[8:9]
	v_pk_add_f32 v[0:1], v[4:5], v[0:1]
	v_pk_add_f32 v[2:3], v[6:7], v[2:3]
	v_pk_add_f32 v[0:1], v[8:9], v[0:1]
	v_pk_add_f32 v[2:3], v[10:11], v[2:3]
	v_add_f32_e32 v0, v0, v1
	v_add_f32_e32 v1, v2, v3
	v_add_f32_e32 v2, v0, v1
	v_mbcnt_lo_u32_b32 v0, -1, 0
	v_mbcnt_hi_u32_b32 v0, -1, v0
	v_and_b32_e32 v1, 64, v0
	v_xor_b32_e32 v3, 1, v0
	v_add_u32_e32 v1, 64, v1
	v_cmp_lt_i32_e32 vcc, v3, v1
	s_waitcnt vmcnt(6)
	v_writelane_b32 v253, s68, 5
	v_cmp_eq_u32_e64 s[0:1], 0, v35
	v_cndmask_b32_e32 v3, v0, v3, vcc
	v_lshlrev_b32_e32 v202, 2, v3
	s_nop 1
	v_mov_b32_dpp v3, v2 quad_perm:[1,0,3,2] row_mask:0xf bank_mask:0xf
	s_barrier
	s_and_saveexec_b64 s[4:5], s[0:1]
	s_cbranch_execz .LBB0_541
	s_waitcnt lgkmcnt(0)
	v_add_f32_e32 v2, v2, v3
	v_mov_b32_e32 v3, 0x358637bd
	v_fmac_f32_e32 v3, 0x3a000000, v2
	s_mov_b32 s26, 0x800000
	v_mul_f32_e32 v2, 0x4b800000, v3
	v_cmp_gt_f32_e32 vcc, s26, v3
	s_nop 1
	v_cndmask_b32_e32 v2, v3, v2, vcc
	v_rsq_f32_e32 v2, v2
	s_nop 0
	v_mul_f32_e32 v3, 0x45800000, v2
	v_cndmask_b32_e32 v2, v2, v3, vcc
	v_lshl_add_u32 v3, v18, 2, 0
	v_add_u32_e32 v3, 0x20000, v3
	ds_write_b32 v3, v2

.LBB0_973:
	s_and_b64 vcc, exec, s[28:29]
	s_cbranch_vccz .LBB0_771
	v_cmp_gt_u32_e32 vcc, 32, v226
	s_and_saveexec_b64 s[0:1], vcc
	v_lshl_add_u32 v0, v224, 2, s5
	ds_write_b32 v0, v80
	s_or_b64 exec, exec, s[0:1]
	s_waitcnt lgkmcnt(0)
	ds_read_b32 v2, v222
	v_and_b32_e32 v3, 64, v204
	v_xor_b32_e32 v0, 1, v204
	v_add_u32_e32 v3, 64, v3
	v_cmp_lt_i32_e32 vcc, v0, v3
	s_waitcnt lgkmcnt(0)
	v_rcp_f32_e32 v7, v2
	s_ashr_i32 s5, s4, 31
	v_cndmask_b32_e32 v0, v204, v0, vcc
	v_lshlrev_b32_e32 v6, 2, v0
	v_mul_f32_e32 v8, v64, v7
	s_lshl_b64 s[0:1], s[4:5], 12
	s_nop 1
	v_mov_b32_dpp v9, v8 quad_perm:[1,0,3,2] row_mask:0xf bank_mask:0xf
	s_add_u32 s0, s10, s0
	v_and_b32_e32 v0, 1, v225
	s_addc_u32 s1, s11, s1
	v_cmp_eq_u32_e32 vcc, 0, v0
	v_lshlrev_b32_e32 v0, 1, v224
	v_lshl_add_u64 v[2:3], s[0:1], 0, v[0:1]
	v_lshlrev_b32_e32 v0, 14, v223
	v_lshl_add_u64 v[4:5], v[2:3], 0, v[0:1]
	s_and_saveexec_b64 s[0:1], vcc
	s_cbranch_execz .LBB0_978
	s_waitcnt lgkmcnt(0)
	v_cvt_pk_bf16_f32 v0, v8, v9
	global_store_dword v[4:5], v0, off
.LBB0_978:
	s_or_b64 exec, exec, s[0:1]
	v_mul_f32_e32 v0, v48, v7
	s_nop 1
	v_mov_b32_dpp v8, v0 quad_perm:[1,0,3,2] row_mask:0xf bank_mask:0xf
	s_and_saveexec_b64 s[0:1], vcc
	s_cbranch_execz .LBB0_980
	s_waitcnt lgkmcnt(0)
	v_cvt_pk_bf16_f32 v0, v0, v8
	global_store_dword v[4:5], v0, off offset:64
.LBB0_980:
	s_or_b64 exec, exec, s[0:1]
	v_mul_f32_e32 v0, v32, v7
	s_waitcnt lgkmcnt(0)
	s_nop 1
	v_mov_b32_dpp v8, v0 quad_perm:[1,0,3,2] row_mask:0xf bank_mask:0xf
	s_and_saveexec_b64 s[0:1], vcc
	s_cbranch_execz .LBB0_982
	s_waitcnt lgkmcnt(0)
	v_cvt_pk_bf16_f32 v0, v0, v8
	global_store_dword v[4:5], v0, off offset:128
.LBB0_982:
	s_or_b64 exec, exec, s[0:1]
	v_mul_f32_e32 v0, v16, v7
	s_nop 1
	v_mov_b32_dpp v7, v0 quad_perm:[1,0,3,2] row_mask:0xf bank_mask:0xf
	s_and_saveexec_b64 s[0:1], vcc
	s_cbranch_execz .LBB0_984
	s_waitcnt lgkmcnt(0)
	v_cvt_pk_bf16_f32 v0, v0, v7
	global_store_dword v[4:5], v0, off offset:192
.LBB0_984:
	s_or_b64 exec, exec, s[0:1]
	ds_read_b32 v0, v222 offset:4
	s_waitcnt lgkmcnt(0)
	v_rcp_f32_e32 v7, v0
	v_lshl_or_b32 v0, v221, 12, v206
	v_lshl_add_u64 v[4:5], v[2:3], 0, v[0:1]
	v_mul_f32_e32 v8, v65, v7
	s_nop 1
	v_mov_b32_dpp v9, v8 quad_perm:[1,0,3,2] row_mask:0xf bank_mask:0xf
	s_and_saveexec_b64 s[0:1], vcc
	s_cbranch_execz .LBB0_986
	s_waitcnt lgkmcnt(0)
	v_cvt_pk_bf16_f32 v0, v8, v9
	global_store_dword v[4:5], v0, off
.LBB0_986:
	s_or_b64 exec, exec, s[0:1]
	v_mul_f32_e32 v0, v49, v7
	s_nop 1
	v_mov_b32_dpp v8, v0 quad_perm:[1,0,3,2] row_mask:0xf bank_mask:0xf
	s_and_saveexec_b64 s[0:1], vcc
	s_cbranch_execz .LBB0_988
	s_waitcnt lgkmcnt(0)
	v_cvt_pk_bf16_f32 v0, v0, v8
	global_store_dword v[4:5], v0, off offset:64
.LBB0_988:
	s_or_b64 exec, exec, s[0:1]
	v_mul_f32_e32 v0, v33, v7
	s_waitcnt lgkmcnt(0)
	s_nop 1
	v_mov_b32_dpp v8, v0 quad_perm:[1,0,3,2] row_mask:0xf bank_mask:0xf
	s_and_saveexec_b64 s[0:1], vcc
	s_cbranch_execz .LBB0_990
	s_waitcnt lgkmcnt(0)
	v_cvt_pk_bf16_f32 v0, v0, v8
	global_store_dword v[4:5], v0, off offset:128
.LBB0_990:
	s_or_b64 exec, exec, s[0:1]
	v_mul_f32_e32 v0, v17, v7
	s_nop 1
	v_mov_b32_dpp v7, v0 quad_perm:[1,0,3,2] row_mask:0xf bank_mask:0xf
	s_and_saveexec_b64 s[0:1], vcc
	s_cbranch_execz .LBB0_992
	s_waitcnt lgkmcnt(0)
	v_cvt_pk_bf16_f32 v0, v0, v7
	global_store_dword v[4:5], v0, off offset:192
.LBB0_992:
	s_or_b64 exec, exec, s[0:1]
	ds_read_b32 v0, v222 offset:8
	s_waitcnt lgkmcnt(0)
	v_rcp_f32_e32 v7, v0
	v_lshl_or_b32 v0, v221, 12, v207
	v_lshl_add_u64 v[4:5], v[2:3], 0, v[0:1]
	v_mul_f32_e32 v8, v66, v7
	s_nop 1
	v_mov_b32_dpp v9, v8 quad_perm:[1,0,3,2] row_mask:0xf bank_mask:0xf
	s_and_saveexec_b64 s[0:1], vcc
	s_cbranch_execz .LBB0_994
	s_waitcnt lgkmcnt(0)
	v_cvt_pk_bf16_f32 v0, v8, v9
	global_store_dword v[4:5], v0, off
.LBB0_994:
	s_or_b64 exec, exec, s[0:1]
	v_mul_f32_e32 v0, v50, v7
	s_nop 1
	v_mov_b32_dpp v8, v0 quad_perm:[1,0,3,2] row_mask:0xf bank_mask:0xf
	s_and_saveexec_b64 s[0:1], vcc
	s_cbranch_execz .LBB0_996
	s_waitcnt lgkmcnt(0)
	v_cvt_pk_bf16_f32 v0, v0, v8
	global_store_dword v[4:5], v0, off offset:64
.LBB0_996:
	s_or_b64 exec, exec, s[0:1]
	v_mul_f32_e32 v0, v34, v7
	s_waitcnt lgkmcnt(0)
	s_nop 1
	v_mov_b32_dpp v8, v0 quad_perm:[1,0,3,2] row_mask:0xf bank_mask:0xf
	s_and_saveexec_b64 s[0:1], vcc
	s_cbranch_execz .LBB0_998
	s_waitcnt lgkmcnt(0)
	v_cvt_pk_bf16_f32 v0, v0, v8
	global_store_dword v[4:5], v0, off offset:128
.LBB0_998:
	s_or_b64 exec, exec, s[0:1]
	v_mul_f32_e32 v0, v18, v7
	s_nop 1
	v_mov_b32_dpp v7, v0 quad_perm:[1,0,3,2] row_mask:0xf bank_mask:0xf
	s_and_saveexec_b64 s[0:1], vcc
	s_cbranch_execz .LBB0_1000
	s_waitcnt lgkmcnt(0)
	v_cvt_pk_bf16_f32 v0, v0, v7
	global_store_dword v[4:5], v0, off offset:192
.LBB0_1000:
	s_or_b64 exec, exec, s[0:1]
	ds_read_b32 v0, v222 offset:12
	s_waitcnt lgkmcnt(0)
	v_rcp_f32_e32 v7, v0
	v_lshl_or_b32 v0, v221, 12, v208
	v_lshl_add_u64 v[4:5], v[2:3], 0, v[0:1]
	v_mul_f32_e32 v8, v67, v7
	s_nop 1
	v_mov_b32_dpp v9, v8 quad_perm:[1,0,3,2] row_mask:0xf bank_mask:0xf
	s_and_saveexec_b64 s[0:1], vcc
	s_cbranch_execz .LBB0_1002
	s_waitcnt lgkmcnt(0)
	v_cvt_pk_bf16_f32 v0, v8, v9
	global_store_dword v[4:5], v0, off
.LBB0_1002:
	s_or_b64 exec, exec, s[0:1]
	v_mul_f32_e32 v0, v51, v7
	s_nop 1
	v_mov_b32_dpp v8, v0 quad_perm:[1,0,3,2] row_mask:0xf bank_mask:0xf
	s_and_saveexec_b64 s[0:1], vcc
	s_cbranch_execz .LBB0_1004
	s_waitcnt lgkmcnt(0)
	v_cvt_pk_bf16_f32 v0, v0, v8
	global_store_dword v[4:5], v0, off offset:64
.LBB0_1004:
	s_or_b64 exec, exec, s[0:1]
	v_mul_f32_e32 v0, v35, v7
	s_waitcnt lgkmcnt(0)
	s_nop 1
	v_mov_b32_dpp v8, v0 quad_perm:[1,0,3,2] row_mask:0xf bank_mask:0xf
	s_and_saveexec_b64 s[0:1], vcc
	s_cbranch_execz .LBB0_1006
	s_waitcnt lgkmcnt(0)
	v_cvt_pk_bf16_f32 v0, v0, v8
	global_store_dword v[4:5], v0, off offset:128
.LBB0_1006:
	s_or_b64 exec, exec, s[0:1]
	v_mul_f32_e32 v0, v19, v7
	s_nop 1
	v_mov_b32_dpp v7, v0 quad_perm:[1,0,3,2] row_mask:0xf bank_mask:0xf
	s_and_saveexec_b64 s[0:1], vcc
	s_cbranch_execz .LBB0_1008
	s_waitcnt lgkmcnt(0)
	v_cvt_pk_bf16_f32 v0, v0, v7
	global_store_dword v[4:5], v0, off offset:192
.LBB0_1008:
	s_or_b64 exec, exec, s[0:1]
	ds_read_b32 v0, v222 offset:32
	s_waitcnt lgkmcnt(0)
	v_rcp_f32_e32 v7, v0
	v_lshl_or_b32 v0, v221, 12, v209
	v_lshl_add_u64 v[4:5], v[2:3], 0, v[0:1]
	v_mul_f32_e32 v8, v68, v7
	s_nop 1
	v_mov_b32_dpp v9, v8 quad_perm:[1,0,3,2] row_mask:0xf bank_mask:0xf
	s_and_saveexec_b64 s[0:1], vcc
	s_cbranch_execz .LBB0_1010
	s_waitcnt lgkmcnt(0)
	v_cvt_pk_bf16_f32 v0, v8, v9
	global_store_dword v[4:5], v0, off
.LBB0_1010:
	s_or_b64 exec, exec, s[0:1]
	v_mul_f32_e32 v0, v52, v7
	s_nop 1
	v_mov_b32_dpp v8, v0 quad_perm:[1,0,3,2] row_mask:0xf bank_mask:0xf
	s_and_saveexec_b64 s[0:1], vcc
	s_cbranch_execz .LBB0_1012
	s_waitcnt lgkmcnt(0)
	v_cvt_pk_bf16_f32 v0, v0, v8
	global_store_dword v[4:5], v0, off offset:64
.LBB0_1012:
	s_or_b64 exec, exec, s[0:1]
	v_mul_f32_e32 v0, v36, v7
	s_waitcnt lgkmcnt(0)
	s_nop 1
	v_mov_b32_dpp v8, v0 quad_perm:[1,0,3,2] row_mask:0xf bank_mask:0xf
	s_and_saveexec_b64 s[0:1], vcc
	s_cbranch_execz .LBB0_1014
	s_waitcnt lgkmcnt(0)
	v_cvt_pk_bf16_f32 v0, v0, v8
	global_store_dword v[4:5], v0, off offset:128
.LBB0_1014:
	s_or_b64 exec, exec, s[0:1]
	v_mul_f32_e32 v0, v20, v7
	s_nop 1
	v_mov_b32_dpp v7, v0 quad_perm:[1,0,3,2] row_mask:0xf bank_mask:0xf
	s_and_saveexec_b64 s[0:1], vcc
	s_cbranch_execz .LBB0_1016
	s_waitcnt lgkmcnt(0)
	v_cvt_pk_bf16_f32 v0, v0, v7
	global_store_dword v[4:5], v0, off offset:192
.LBB0_1016:
	s_or_b64 exec, exec, s[0:1]
	ds_read_b32 v0, v222 offset:36
	s_waitcnt lgkmcnt(0)
	v_rcp_f32_e32 v7, v0
	v_lshl_or_b32 v0, v221, 12, v210
	v_lshl_add_u64 v[4:5], v[2:3], 0, v[0:1]
	v_mul_f32_e32 v8, v69, v7
	s_nop 1
	v_mov_b32_dpp v9, v8 quad_perm:[1,0,3,2] row_mask:0xf bank_mask:0xf
	s_and_saveexec_b64 s[0:1], vcc
	s_cbranch_execz .LBB0_1018
	s_waitcnt lgkmcnt(0)
	v_cvt_pk_bf16_f32 v0, v8, v9
	global_store_dword v[4:5], v0, off
.LBB0_1018:
	s_or_b64 exec, exec, s[0:1]
	v_mul_f32_e32 v0, v53, v7
	s_nop 1
	v_mov_b32_dpp v8, v0 quad_perm:[1,0,3,2] row_mask:0xf bank_mask:0xf
	s_and_saveexec_b64 s[0:1], vcc
	s_cbranch_execz .LBB0_1020
	s_waitcnt lgkmcnt(0)
	v_cvt_pk_bf16_f32 v0, v0, v8
	global_store_dword v[4:5], v0, off offset:64
.LBB0_1020:
	s_or_b64 exec, exec, s[0:1]
	v_mul_f32_e32 v0, v37, v7
	s_waitcnt lgkmcnt(0)
	s_nop 1
	v_mov_b32_dpp v8, v0 quad_perm:[1,0,3,2] row_mask:0xf bank_mask:0xf
	s_and_saveexec_b64 s[0:1], vcc
	s_cbranch_execz .LBB0_1022
	s_waitcnt lgkmcnt(0)
	v_cvt_pk_bf16_f32 v0, v0, v8
	global_store_dword v[4:5], v0, off offset:128
.LBB0_1022:
	s_or_b64 exec, exec, s[0:1]
	v_mul_f32_e32 v0, v21, v7
	s_nop 1
	v_mov_b32_dpp v7, v0 quad_perm:[1,0,3,2] row_mask:0xf bank_mask:0xf
	s_and_saveexec_b64 s[0:1], vcc
	s_cbranch_execz .LBB0_1024
	s_waitcnt lgkmcnt(0)
	v_cvt_pk_bf16_f32 v0, v0, v7
	global_store_dword v[4:5], v0, off offset:192
.LBB0_1024:
	s_or_b64 exec, exec, s[0:1]
	ds_read_b32 v0, v222 offset:40
	s_waitcnt lgkmcnt(0)
	v_rcp_f32_e32 v7, v0
	v_lshl_or_b32 v0, v221, 12, v211
	v_lshl_add_u64 v[4:5], v[2:3], 0, v[0:1]
	v_mul_f32_e32 v8, v70, v7
	s_nop 1
	v_mov_b32_dpp v9, v8 quad_perm:[1,0,3,2] row_mask:0xf bank_mask:0xf
	s_and_saveexec_b64 s[0:1], vcc
	s_cbranch_execz .LBB0_1026
	s_waitcnt lgkmcnt(0)
	v_cvt_pk_bf16_f32 v0, v8, v9
	global_store_dword v[4:5], v0, off
.LBB0_1026:
	s_or_b64 exec, exec, s[0:1]
	v_mul_f32_e32 v0, v54, v7
	s_nop 1
	v_mov_b32_dpp v8, v0 quad_perm:[1,0,3,2] row_mask:0xf bank_mask:0xf
	s_and_saveexec_b64 s[0:1], vcc
	s_cbranch_execz .LBB0_1028
	s_waitcnt lgkmcnt(0)
	v_cvt_pk_bf16_f32 v0, v0, v8
	global_store_dword v[4:5], v0, off offset:64
.LBB0_1028:
	s_or_b64 exec, exec, s[0:1]
	v_mul_f32_e32 v0, v38, v7
	s_waitcnt lgkmcnt(0)
	s_nop 1
	v_mov_b32_dpp v8, v0 quad_perm:[1,0,3,2] row_mask:0xf bank_mask:0xf
	s_and_saveexec_b64 s[0:1], vcc
	s_cbranch_execz .LBB0_1030
	s_waitcnt lgkmcnt(0)
	v_cvt_pk_bf16_f32 v0, v0, v8
	global_store_dword v[4:5], v0, off offset:128
.LBB0_1030:
	s_or_b64 exec, exec, s[0:1]
	v_mul_f32_e32 v0, v22, v7
	s_nop 1
	v_mov_b32_dpp v7, v0 quad_perm:[1,0,3,2] row_mask:0xf bank_mask:0xf
	s_and_saveexec_b64 s[0:1], vcc
	s_cbranch_execz .LBB0_1032
	s_waitcnt lgkmcnt(0)
	v_cvt_pk_bf16_f32 v0, v0, v7
	global_store_dword v[4:5], v0, off offset:192
.LBB0_1032:
	s_or_b64 exec, exec, s[0:1]
	ds_read_b32 v0, v222 offset:44
	s_waitcnt lgkmcnt(0)
	v_rcp_f32_e32 v7, v0
	v_lshl_or_b32 v0, v221, 12, v212
	v_lshl_add_u64 v[4:5], v[2:3], 0, v[0:1]
	v_mul_f32_e32 v8, v71, v7
	s_nop 1
	v_mov_b32_dpp v9, v8 quad_perm:[1,0,3,2] row_mask:0xf bank_mask:0xf
	s_and_saveexec_b64 s[0:1], vcc
	s_cbranch_execz .LBB0_1034
	s_waitcnt lgkmcnt(0)
	v_cvt_pk_bf16_f32 v0, v8, v9
	global_store_dword v[4:5], v0, off
.LBB0_1034:
	s_or_b64 exec, exec, s[0:1]
	v_mul_f32_e32 v0, v55, v7
	s_nop 1
	v_mov_b32_dpp v8, v0 quad_perm:[1,0,3,2] row_mask:0xf bank_mask:0xf
	s_and_saveexec_b64 s[0:1], vcc
	s_cbranch_execz .LBB0_1036
	s_waitcnt lgkmcnt(0)
	v_cvt_pk_bf16_f32 v0, v0, v8
	global_store_dword v[4:5], v0, off offset:64
.LBB0_1036:
	s_or_b64 exec, exec, s[0:1]
	v_mul_f32_e32 v0, v39, v7
	s_waitcnt lgkmcnt(0)
	s_nop 1
	v_mov_b32_dpp v8, v0 quad_perm:[1,0,3,2] row_mask:0xf bank_mask:0xf
	s_and_saveexec_b64 s[0:1], vcc
	s_cbranch_execz .LBB0_1038
	s_waitcnt lgkmcnt(0)
	v_cvt_pk_bf16_f32 v0, v0, v8
	global_store_dword v[4:5], v0, off offset:128
.LBB0_1038:
	s_or_b64 exec, exec, s[0:1]
	v_mul_f32_e32 v0, v23, v7
	s_nop 1
	v_mov_b32_dpp v7, v0 quad_perm:[1,0,3,2] row_mask:0xf bank_mask:0xf
	s_and_saveexec_b64 s[0:1], vcc
	s_cbranch_execz .LBB0_1040
	s_waitcnt lgkmcnt(0)
	v_cvt_pk_bf16_f32 v0, v0, v7
	global_store_dword v[4:5], v0, off offset:192
.LBB0_1040:
	s_or_b64 exec, exec, s[0:1]
	ds_read_b32 v0, v222 offset:64
	s_waitcnt lgkmcnt(0)
	v_rcp_f32_e32 v7, v0
	v_lshl_or_b32 v0, v221, 12, v213
	v_lshl_add_u64 v[4:5], v[2:3], 0, v[0:1]
	v_mul_f32_e32 v8, v72, v7
	s_nop 1
	v_mov_b32_dpp v9, v8 quad_perm:[1,0,3,2] row_mask:0xf bank_mask:0xf
	s_and_saveexec_b64 s[0:1], vcc
	s_cbranch_execz .LBB0_1042
	s_waitcnt lgkmcnt(0)
	v_cvt_pk_bf16_f32 v0, v8, v9
	global_store_dword v[4:5], v0, off
.LBB0_1042:
	s_or_b64 exec, exec, s[0:1]
	v_mul_f32_e32 v0, v56, v7
	s_nop 1
	v_mov_b32_dpp v8, v0 quad_perm:[1,0,3,2] row_mask:0xf bank_mask:0xf
	s_and_saveexec_b64 s[0:1], vcc
	s_cbranch_execz .LBB0_1044
	s_waitcnt lgkmcnt(0)
	v_cvt_pk_bf16_f32 v0, v0, v8
	global_store_dword v[4:5], v0, off offset:64
.LBB0_1044:
	s_or_b64 exec, exec, s[0:1]
	v_mul_f32_e32 v0, v40, v7
	s_waitcnt lgkmcnt(0)
	s_nop 1
	v_mov_b32_dpp v8, v0 quad_perm:[1,0,3,2] row_mask:0xf bank_mask:0xf
	s_and_saveexec_b64 s[0:1], vcc
	s_cbranch_execz .LBB0_1046
	s_waitcnt lgkmcnt(0)
	v_cvt_pk_bf16_f32 v0, v0, v8
	global_store_dword v[4:5], v0, off offset:128
.LBB0_1046:
	s_or_b64 exec, exec, s[0:1]
	v_mul_f32_e32 v0, v24, v7
	s_nop 1
	v_mov_b32_dpp v7, v0 quad_perm:[1,0,3,2] row_mask:0xf bank_mask:0xf
	s_and_saveexec_b64 s[0:1], vcc
	s_cbranch_execz .LBB0_1048
	s_waitcnt lgkmcnt(0)
	v_cvt_pk_bf16_f32 v0, v0, v7
	global_store_dword v[4:5], v0, off offset:192
.LBB0_1048:
	s_or_b64 exec, exec, s[0:1]
	ds_read_b32 v0, v222 offset:68
	s_waitcnt lgkmcnt(0)
	v_rcp_f32_e32 v7, v0
	v_lshl_or_b32 v0, v221, 12, v214
	v_lshl_add_u64 v[4:5], v[2:3], 0, v[0:1]
	v_mul_f32_e32 v8, v73, v7
	s_nop 1
	v_mov_b32_dpp v9, v8 quad_perm:[1,0,3,2] row_mask:0xf bank_mask:0xf
	s_and_saveexec_b64 s[0:1], vcc
	s_cbranch_execz .LBB0_1050
	s_waitcnt lgkmcnt(0)
	v_cvt_pk_bf16_f32 v0, v8, v9
	global_store_dword v[4:5], v0, off
.LBB0_1050:
	s_or_b64 exec, exec, s[0:1]
	v_mul_f32_e32 v0, v57, v7
	s_nop 1
	v_mov_b32_dpp v8, v0 quad_perm:[1,0,3,2] row_mask:0xf bank_mask:0xf
	s_and_saveexec_b64 s[0:1], vcc
	s_cbranch_execz .LBB0_1052
	s_waitcnt lgkmcnt(0)
	v_cvt_pk_bf16_f32 v0, v0, v8
	global_store_dword v[4:5], v0, off offset:64
.LBB0_1052:
	s_or_b64 exec, exec, s[0:1]
	v_mul_f32_e32 v0, v41, v7
	s_waitcnt lgkmcnt(0)
	s_nop 1
	v_mov_b32_dpp v8, v0 quad_perm:[1,0,3,2] row_mask:0xf bank_mask:0xf
	s_and_saveexec_b64 s[0:1], vcc
	s_cbranch_execz .LBB0_1054
	s_waitcnt lgkmcnt(0)
	v_cvt_pk_bf16_f32 v0, v0, v8
	global_store_dword v[4:5], v0, off offset:128
.LBB0_1054:
	s_or_b64 exec, exec, s[0:1]
	v_mul_f32_e32 v0, v25, v7
	s_nop 1
	v_mov_b32_dpp v7, v0 quad_perm:[1,0,3,2] row_mask:0xf bank_mask:0xf
	s_and_saveexec_b64 s[0:1], vcc
	s_cbranch_execz .LBB0_1056
	s_waitcnt lgkmcnt(0)
	v_cvt_pk_bf16_f32 v0, v0, v7
	global_store_dword v[4:5], v0, off offset:192
.LBB0_1056:
	s_or_b64 exec, exec, s[0:1]
	ds_read_b32 v0, v222 offset:72
	s_waitcnt lgkmcnt(0)
	v_rcp_f32_e32 v7, v0
	v_lshl_or_b32 v0, v221, 12, v215
	v_lshl_add_u64 v[4:5], v[2:3], 0, v[0:1]
	v_mul_f32_e32 v8, v74, v7
	s_nop 1
	v_mov_b32_dpp v9, v8 quad_perm:[1,0,3,2] row_mask:0xf bank_mask:0xf
	s_and_saveexec_b64 s[0:1], vcc
	s_cbranch_execz .LBB0_1058
	s_waitcnt lgkmcnt(0)
	v_cvt_pk_bf16_f32 v0, v8, v9
	global_store_dword v[4:5], v0, off
.LBB0_1058:
	s_or_b64 exec, exec, s[0:1]
	v_mul_f32_e32 v0, v58, v7
	s_nop 1
	v_mov_b32_dpp v8, v0 quad_perm:[1,0,3,2] row_mask:0xf bank_mask:0xf
	s_and_saveexec_b64 s[0:1], vcc
	s_cbranch_execz .LBB0_1060
	s_waitcnt lgkmcnt(0)
	v_cvt_pk_bf16_f32 v0, v0, v8
	global_store_dword v[4:5], v0, off offset:64
.LBB0_1060:
	s_or_b64 exec, exec, s[0:1]
	v_mul_f32_e32 v0, v42, v7
	s_waitcnt lgkmcnt(0)
	s_nop 1
	v_mov_b32_dpp v8, v0 quad_perm:[1,0,3,2] row_mask:0xf bank_mask:0xf
	s_and_saveexec_b64 s[0:1], vcc
	s_cbranch_execz .LBB0_1062
	s_waitcnt lgkmcnt(0)
	v_cvt_pk_bf16_f32 v0, v0, v8
	global_store_dword v[4:5], v0, off offset:128
.LBB0_1062:
	s_or_b64 exec, exec, s[0:1]
	v_mul_f32_e32 v0, v26, v7
	s_nop 1
	v_mov_b32_dpp v7, v0 quad_perm:[1,0,3,2] row_mask:0xf bank_mask:0xf
	s_and_saveexec_b64 s[0:1], vcc
	s_cbranch_execz .LBB0_1064
	s_waitcnt lgkmcnt(0)
	v_cvt_pk_bf16_f32 v0, v0, v7
	global_store_dword v[4:5], v0, off offset:192
.LBB0_1064:
	s_or_b64 exec, exec, s[0:1]
	ds_read_b32 v0, v222 offset:76
	s_waitcnt lgkmcnt(0)
	v_rcp_f32_e32 v7, v0
	v_lshl_or_b32 v0, v221, 12, v216
	v_lshl_add_u64 v[4:5], v[2:3], 0, v[0:1]
	v_mul_f32_e32 v8, v75, v7
	s_nop 1
	v_mov_b32_dpp v9, v8 quad_perm:[1,0,3,2] row_mask:0xf bank_mask:0xf
	s_and_saveexec_b64 s[0:1], vcc
	s_cbranch_execz .LBB0_1066
	s_waitcnt lgkmcnt(0)
	v_cvt_pk_bf16_f32 v0, v8, v9
	global_store_dword v[4:5], v0, off
.LBB0_1066:
	s_or_b64 exec, exec, s[0:1]
	v_mul_f32_e32 v0, v59, v7
	s_nop 1
	v_mov_b32_dpp v8, v0 quad_perm:[1,0,3,2] row_mask:0xf bank_mask:0xf
	s_and_saveexec_b64 s[0:1], vcc
	s_cbranch_execz .LBB0_1068
	s_waitcnt lgkmcnt(0)
	v_cvt_pk_bf16_f32 v0, v0, v8
	global_store_dword v[4:5], v0, off offset:64
.LBB0_1068:
	s_or_b64 exec, exec, s[0:1]
	v_mul_f32_e32 v0, v43, v7
	s_waitcnt lgkmcnt(0)
	s_nop 1
	v_mov_b32_dpp v8, v0 quad_perm:[1,0,3,2] row_mask:0xf bank_mask:0xf
	s_and_saveexec_b64 s[0:1], vcc
	s_cbranch_execz .LBB0_1070
	s_waitcnt lgkmcnt(0)
	v_cvt_pk_bf16_f32 v0, v0, v8
	global_store_dword v[4:5], v0, off offset:128
.LBB0_1070:
	s_or_b64 exec, exec, s[0:1]
	v_mul_f32_e32 v0, v27, v7
	s_nop 1
	v_mov_b32_dpp v7, v0 quad_perm:[1,0,3,2] row_mask:0xf bank_mask:0xf
	s_and_saveexec_b64 s[0:1], vcc
	s_cbranch_execz .LBB0_1072
	s_waitcnt lgkmcnt(0)
	v_cvt_pk_bf16_f32 v0, v0, v7
	global_store_dword v[4:5], v0, off offset:192
.LBB0_1072:
	s_or_b64 exec, exec, s[0:1]
	ds_read_b32 v0, v222 offset:96
	s_waitcnt lgkmcnt(0)
	v_rcp_f32_e32 v7, v0
	v_lshl_or_b32 v0, v221, 12, v217
	v_lshl_add_u64 v[4:5], v[2:3], 0, v[0:1]
	v_mul_f32_e32 v8, v76, v7
	s_nop 1
	v_mov_b32_dpp v9, v8 quad_perm:[1,0,3,2] row_mask:0xf bank_mask:0xf
	s_and_saveexec_b64 s[0:1], vcc
	s_cbranch_execz .LBB0_1074
	s_waitcnt lgkmcnt(0)
	v_cvt_pk_bf16_f32 v0, v8, v9
	global_store_dword v[4:5], v0, off
.LBB0_1074:
	s_or_b64 exec, exec, s[0:1]
	v_mul_f32_e32 v0, v60, v7
	s_nop 1
	v_mov_b32_dpp v8, v0 quad_perm:[1,0,3,2] row_mask:0xf bank_mask:0xf
	s_and_saveexec_b64 s[0:1], vcc
	s_cbranch_execz .LBB0_1076
	s_waitcnt lgkmcnt(0)
	v_cvt_pk_bf16_f32 v0, v0, v8
	global_store_dword v[4:5], v0, off offset:64
.LBB0_1076:
	s_or_b64 exec, exec, s[0:1]
	v_mul_f32_e32 v0, v44, v7
	s_waitcnt lgkmcnt(0)
	s_nop 1
	v_mov_b32_dpp v8, v0 quad_perm:[1,0,3,2] row_mask:0xf bank_mask:0xf
	s_and_saveexec_b64 s[0:1], vcc
	s_cbranch_execz .LBB0_1078
	s_waitcnt lgkmcnt(0)
	v_cvt_pk_bf16_f32 v0, v0, v8
	global_store_dword v[4:5], v0, off offset:128
.LBB0_1078:
	s_or_b64 exec, exec, s[0:1]
	v_mul_f32_e32 v0, v28, v7
	s_nop 1
	v_mov_b32_dpp v7, v0 quad_perm:[1,0,3,2] row_mask:0xf bank_mask:0xf
	s_and_saveexec_b64 s[0:1], vcc
	s_cbranch_execz .LBB0_1080
	s_waitcnt lgkmcnt(0)
	v_cvt_pk_bf16_f32 v0, v0, v7
	global_store_dword v[4:5], v0, off offset:192
.LBB0_1080:
	s_or_b64 exec, exec, s[0:1]
	ds_read_b32 v0, v222 offset:100
	s_waitcnt lgkmcnt(0)
	v_rcp_f32_e32 v7, v0
	v_lshl_or_b32 v0, v221, 12, v218
	v_lshl_add_u64 v[4:5], v[2:3], 0, v[0:1]
	v_mul_f32_e32 v8, v77, v7
	s_nop 1
	v_mov_b32_dpp v9, v8 quad_perm:[1,0,3,2] row_mask:0xf bank_mask:0xf
	s_and_saveexec_b64 s[0:1], vcc
	s_cbranch_execz .LBB0_1082
	s_waitcnt lgkmcnt(0)
	v_cvt_pk_bf16_f32 v0, v8, v9
	global_store_dword v[4:5], v0, off
.LBB0_1082:
	s_or_b64 exec, exec, s[0:1]
	v_mul_f32_e32 v0, v61, v7
	s_nop 1
	v_mov_b32_dpp v8, v0 quad_perm:[1,0,3,2] row_mask:0xf bank_mask:0xf
	s_and_saveexec_b64 s[0:1], vcc
	s_cbranch_execz .LBB0_1084
	s_waitcnt lgkmcnt(0)
	v_cvt_pk_bf16_f32 v0, v0, v8
	global_store_dword v[4:5], v0, off offset:64
.LBB0_1084:
	s_or_b64 exec, exec, s[0:1]
	v_mul_f32_e32 v0, v45, v7
	s_waitcnt lgkmcnt(0)
	s_nop 1
	v_mov_b32_dpp v8, v0 quad_perm:[1,0,3,2] row_mask:0xf bank_mask:0xf
	s_and_saveexec_b64 s[0:1], vcc
	s_cbranch_execz .LBB0_1086
	s_waitcnt lgkmcnt(0)
	v_cvt_pk_bf16_f32 v0, v0, v8
	global_store_dword v[4:5], v0, off offset:128
.LBB0_1086:
	s_or_b64 exec, exec, s[0:1]
	v_mul_f32_e32 v0, v29, v7
	s_nop 1
	v_mov_b32_dpp v7, v0 quad_perm:[1,0,3,2] row_mask:0xf bank_mask:0xf
	s_and_saveexec_b64 s[0:1], vcc
	s_cbranch_execz .LBB0_1088
	s_waitcnt lgkmcnt(0)
	v_cvt_pk_bf16_f32 v0, v0, v7
	global_store_dword v[4:5], v0, off offset:192
.LBB0_1088:
	s_or_b64 exec, exec, s[0:1]
	ds_read_b32 v0, v222 offset:104
	s_waitcnt lgkmcnt(0)
	v_rcp_f32_e32 v7, v0
	v_lshl_or_b32 v0, v221, 12, v219
	v_lshl_add_u64 v[4:5], v[2:3], 0, v[0:1]
	v_mul_f32_e32 v8, v78, v7
	s_nop 1
	v_mov_b32_dpp v9, v8 quad_perm:[1,0,3,2] row_mask:0xf bank_mask:0xf
	s_and_saveexec_b64 s[0:1], vcc
	s_cbranch_execz .LBB0_1090
	s_waitcnt lgkmcnt(0)
	v_cvt_pk_bf16_f32 v0, v8, v9
	global_store_dword v[4:5], v0, off
.LBB0_1090:
	s_or_b64 exec, exec, s[0:1]
	v_mul_f32_e32 v0, v62, v7
	s_nop 1
	v_mov_b32_dpp v8, v0 quad_perm:[1,0,3,2] row_mask:0xf bank_mask:0xf
	s_and_saveexec_b64 s[0:1], vcc
	s_cbranch_execz .LBB0_1092
	s_waitcnt lgkmcnt(0)
	v_cvt_pk_bf16_f32 v0, v0, v8
	global_store_dword v[4:5], v0, off offset:64
.LBB0_1092:
	s_or_b64 exec, exec, s[0:1]
	v_mul_f32_e32 v0, v46, v7
	s_waitcnt lgkmcnt(0)
	s_nop 1
	v_mov_b32_dpp v8, v0 quad_perm:[1,0,3,2] row_mask:0xf bank_mask:0xf
	s_and_saveexec_b64 s[0:1], vcc
	s_cbranch_execz .LBB0_1094
	s_waitcnt lgkmcnt(0)
	v_cvt_pk_bf16_f32 v0, v0, v8
	global_store_dword v[4:5], v0, off offset:128
.LBB0_1094:
	s_or_b64 exec, exec, s[0:1]
	v_mul_f32_e32 v0, v30, v7
	s_nop 1
	v_mov_b32_dpp v7, v0 quad_perm:[1,0,3,2] row_mask:0xf bank_mask:0xf
	s_and_saveexec_b64 s[0:1], vcc
	s_cbranch_execz .LBB0_1096
	s_waitcnt lgkmcnt(0)
	v_cvt_pk_bf16_f32 v0, v0, v7
	global_store_dword v[4:5], v0, off offset:192
.LBB0_1096:
	s_or_b64 exec, exec, s[0:1]
	ds_read_b32 v0, v222 offset:108
	s_waitcnt lgkmcnt(0)
	v_rcp_f32_e32 v4, v0
	v_lshl_or_b32 v0, v221, 12, v220
	v_lshl_add_u64 v[2:3], v[2:3], 0, v[0:1]
	v_mul_f32_e32 v5, v79, v4
	s_nop 1
	v_mov_b32_dpp v7, v5 quad_perm:[1,0,3,2] row_mask:0xf bank_mask:0xf
	s_and_saveexec_b64 s[0:1], vcc
	s_cbranch_execz .LBB0_1098
	s_waitcnt lgkmcnt(0)
	v_cvt_pk_bf16_f32 v0, v5, v7
	global_store_dword v[2:3], v0, off
.LBB0_1098:
	s_or_b64 exec, exec, s[0:1]
	v_mul_f32_e32 v0, v63, v4
	s_nop 1
	v_mov_b32_dpp v5, v0 quad_perm:[1,0,3,2] row_mask:0xf bank_mask:0xf
	s_and_saveexec_b64 s[0:1], vcc
	s_cbranch_execz .LBB0_1100
	s_waitcnt lgkmcnt(0)
	v_cvt_pk_bf16_f32 v0, v0, v5
	global_store_dword v[2:3], v0, off offset:64
.LBB0_1100:
	s_or_b64 exec, exec, s[0:1]
	v_mul_f32_e32 v0, v47, v4
	s_waitcnt lgkmcnt(0)
	s_nop 1
	v_mov_b32_dpp v5, v0 quad_perm:[1,0,3,2] row_mask:0xf bank_mask:0xf
	s_and_saveexec_b64 s[0:1], vcc
	s_cbranch_execz .LBB0_1102
	s_waitcnt lgkmcnt(0)
	v_cvt_pk_bf16_f32 v0, v0, v5
	global_store_dword v[2:3], v0, off offset:128
.LBB0_1102:
	s_or_b64 exec, exec, s[0:1]
	v_mul_f32_e32 v0, v31, v4
	s_nop 1
	v_mov_b32_dpp v4, v0 quad_perm:[1,0,3,2] row_mask:0xf bank_mask:0xf
	s_and_saveexec_b64 s[0:1], vcc
	s_cbranch_execz .LBB0_770
	s_waitcnt lgkmcnt(0)
	v_cvt_pk_bf16_f32 v0, v0, v4
	global_store_dword v[2:3], v0, off offset:192
	s_branch .LBB0_770

.LBB0_1525:
	s_waitcnt vmcnt(8)
	s_waitcnt vmcnt(9)
	ds_write_b128 v212, v[112:115] offset:32768
	s_waitcnt vmcnt(8)
	ds_write_b128 v212, v[116:119] offset:40960
	v_cmp_gt_u32_e32 vcc, 32, v213
	s_and_saveexec_b64 s[4:5], vcc
	ds_write_b32 v215, v1
	s_or_b64 exec, exec, s[4:5]
	s_waitcnt lgkmcnt(0)
	s_and_b64 vcc, exec, s[2:3]
	s_cbranch_vccnz .LBB0_1657
	ds_read2_b32 v[80:81], v214 offset1:3
	ds_read2_b32 v[82:83], v214 offset0:1 offset1:2
	ds_read_b128 v[10:13], v214 offset:32
	ds_read_b128 v[6:9], v214 offset:64
	ds_read_b128 v[2:5], v214 offset:96
	s_waitcnt lgkmcnt(4)
	v_rcp_f32_e32 v80, v80
	v_and_b32_e32 v14, 64, v207
	v_xor_b32_e32 v1, 1, v207
	v_add_u32_e32 v14, 64, v14
	v_cmp_lt_i32_e32 vcc, v1, v14
	v_mul_f32_e32 v48, v48, v80
	s_ashr_i32 s29, s28, 31
	v_cndmask_b32_e32 v1, v207, v1, vcc
	v_lshlrev_b32_e32 v1, 2, v1
	s_nop 1
	v_mov_b32_dpp v84, v48 quad_perm:[1,0,3,2] row_mask:0xf bank_mask:0xf
	s_lshl_b64 s[2:3], s[28:29], 12
	s_add_u32 s2, s68, s2
	v_and_b32_e32 v14, 1, v210
	s_addc_u32 s3, s69, s3
	v_cmp_eq_u32_e32 vcc, 0, v14
	v_lshlrev_b32_e32 v196, 12, v209
	v_lshlrev_b32_e32 v14, 1, v211
	s_and_saveexec_b64 s[4:5], vcc
	s_cbranch_execz .LBB0_1530
	v_lshl_add_u64 v[86:87], s[2:3], 0, v[196:197]
	v_mov_b32_e32 v15, v197
	v_lshl_add_u64 v[86:87], v[86:87], 0, v[14:15]
	s_waitcnt lgkmcnt(0)
	v_cvt_pk_bf16_f32 v15, v48, v84
	global_store_dword v[86:87], v15, off
.LBB0_1530:
	s_or_b64 exec, exec, s[4:5]
	v_mul_f32_e32 v48, v64, v80
	s_nop 1
	v_mov_b32_dpp v64, v48 quad_perm:[1,0,3,2] row_mask:0xf bank_mask:0xf
	s_and_saveexec_b64 s[4:5], vcc
	s_cbranch_execz .LBB0_1532
	s_waitcnt lgkmcnt(0)
	v_lshl_add_u64 v[84:85], s[2:3], 0, v[196:197]
	v_mov_b32_e32 v15, v197
	v_lshl_add_u64 v[84:85], v[84:85], 0, v[14:15]
	s_waitcnt lgkmcnt(0)
	v_cvt_pk_bf16_f32 v15, v48, v64
	global_store_dword v[84:85], v15, off offset:64
.LBB0_1532:
	s_or_b64 exec, exec, s[4:5]
	v_mul_f32_e32 v32, v32, v80
	s_nop 1
	v_mov_b32_dpp v48, v32 quad_perm:[1,0,3,2] row_mask:0xf bank_mask:0xf
	s_and_saveexec_b64 s[4:5], vcc
	s_cbranch_execz .LBB0_1534
	s_waitcnt lgkmcnt(0)
	v_lshl_add_u64 v[84:85], s[2:3], 0, v[196:197]
	v_mov_b32_e32 v15, v197
	v_lshl_add_u64 v[84:85], v[84:85], 0, v[14:15]
	s_waitcnt lgkmcnt(0)
	v_cvt_pk_bf16_f32 v15, v32, v48
	global_store_dword v[84:85], v15, off offset:128
.LBB0_1534:
	s_or_b64 exec, exec, s[4:5]
	v_mul_f32_e32 v16, v16, v80
	s_nop 1
	v_mov_b32_dpp v32, v16 quad_perm:[1,0,3,2] row_mask:0xf bank_mask:0xf
	s_and_saveexec_b64 s[4:5], vcc
	s_cbranch_execz .LBB0_1536
	s_waitcnt lgkmcnt(0)
	v_lshl_add_u64 v[84:85], s[2:3], 0, v[196:197]
	v_mov_b32_e32 v15, v197
	v_lshl_add_u64 v[84:85], v[84:85], 0, v[14:15]
	s_waitcnt lgkmcnt(0)
	v_cvt_pk_bf16_f32 v15, v16, v32
	global_store_dword v[84:85], v15, off offset:192
.LBB0_1536:
	s_or_b64 exec, exec, s[4:5]
	s_waitcnt lgkmcnt(7)
	v_rcp_f32_e32 v16, v82
	v_or_b32_e32 v15, 1, v209
	v_lshlrev_b32_e32 v196, 12, v15
	s_waitcnt lgkmcnt(0)
	v_mul_f32_e32 v32, v49, v16
	s_nop 1
	v_mov_b32_dpp v48, v32 quad_perm:[1,0,3,2] row_mask:0xf bank_mask:0xf
	s_and_saveexec_b64 s[4:5], vcc
	s_cbranch_execz .LBB0_1538
	v_lshl_add_u64 v[84:85], s[2:3], 0, v[196:197]
	v_mov_b32_e32 v15, v197
	v_lshl_add_u64 v[84:85], v[84:85], 0, v[14:15]
	s_waitcnt lgkmcnt(0)
	v_cvt_pk_bf16_f32 v15, v32, v48
	global_store_dword v[84:85], v15, off
.LBB0_1538:
	s_or_b64 exec, exec, s[4:5]
	v_mul_f32_e32 v32, v65, v16
	s_waitcnt lgkmcnt(0)
	s_nop 1
	v_mov_b32_dpp v48, v32 quad_perm:[1,0,3,2] row_mask:0xf bank_mask:0xf
	s_and_saveexec_b64 s[4:5], vcc
	s_cbranch_execz .LBB0_1540
	v_lshl_add_u64 v[64:65], s[2:3], 0, v[196:197]
	v_mov_b32_e32 v15, v197
	v_lshl_add_u64 v[64:65], v[64:65], 0, v[14:15]
	s_waitcnt lgkmcnt(0)
	v_cvt_pk_bf16_f32 v15, v32, v48
	global_store_dword v[64:65], v15, off offset:64
.LBB0_1540:
	s_or_b64 exec, exec, s[4:5]
	v_mul_f32_e32 v32, v33, v16
	s_nop 1
	v_mov_b32_dpp v33, v32 quad_perm:[1,0,3,2] row_mask:0xf bank_mask:0xf
	s_and_saveexec_b64 s[4:5], vcc
	s_cbranch_execz .LBB0_1542
	s_waitcnt lgkmcnt(0)
	v_lshl_add_u64 v[48:49], s[2:3], 0, v[196:197]
	v_mov_b32_e32 v15, v197
	v_lshl_add_u64 v[48:49], v[48:49], 0, v[14:15]
	s_waitcnt lgkmcnt(0)
	v_cvt_pk_bf16_f32 v15, v32, v33
	global_store_dword v[48:49], v15, off offset:128
.LBB0_1542:
	s_or_b64 exec, exec, s[4:5]
	v_mul_f32_e32 v16, v17, v16
	s_nop 1
	v_mov_b32_dpp v17, v16 quad_perm:[1,0,3,2] row_mask:0xf bank_mask:0xf
	s_and_saveexec_b64 s[4:5], vcc
	s_cbranch_execz .LBB0_1544
	s_waitcnt lgkmcnt(0)
	v_lshl_add_u64 v[32:33], s[2:3], 0, v[196:197]
	v_mov_b32_e32 v15, v197
	v_lshl_add_u64 v[32:33], v[32:33], 0, v[14:15]
	s_waitcnt lgkmcnt(0)
	v_cvt_pk_bf16_f32 v15, v16, v17
	global_store_dword v[32:33], v15, off offset:192
.LBB0_1544:
	s_or_b64 exec, exec, s[4:5]
	v_rcp_f32_e32 v16, v83
	v_or_b32_e32 v15, 2, v209
	v_lshlrev_b32_e32 v196, 12, v15
	s_waitcnt lgkmcnt(0)
	v_mul_f32_e32 v17, v50, v16
	s_nop 1
	v_mov_b32_dpp v32, v17 quad_perm:[1,0,3,2] row_mask:0xf bank_mask:0xf
	s_and_saveexec_b64 s[4:5], vcc
	s_cbranch_execz .LBB0_1546
	v_lshl_add_u64 v[48:49], s[2:3], 0, v[196:197]
	v_mov_b32_e32 v15, v197
	v_lshl_add_u64 v[48:49], v[48:49], 0, v[14:15]
	s_waitcnt lgkmcnt(0)
	v_cvt_pk_bf16_f32 v15, v17, v32
	global_store_dword v[48:49], v15, off
.LBB0_1546:
	s_or_b64 exec, exec, s[4:5]
	v_mul_f32_e32 v17, v66, v16
	s_waitcnt lgkmcnt(0)
	s_nop 1
	v_mov_b32_dpp v32, v17 quad_perm:[1,0,3,2] row_mask:0xf bank_mask:0xf
	s_and_saveexec_b64 s[4:5], vcc
	s_cbranch_execz .LBB0_1548
	v_lshl_add_u64 v[48:49], s[2:3], 0, v[196:197]
	v_mov_b32_e32 v15, v197
	v_lshl_add_u64 v[48:49], v[48:49], 0, v[14:15]
	s_waitcnt lgkmcnt(0)
	v_cvt_pk_bf16_f32 v15, v17, v32
	global_store_dword v[48:49], v15, off offset:64
.LBB0_1548:
	s_or_b64 exec, exec, s[4:5]
	v_mul_f32_e32 v17, v34, v16
	s_waitcnt lgkmcnt(0)
	s_nop 1
	v_mov_b32_dpp v32, v17 quad_perm:[1,0,3,2] row_mask:0xf bank_mask:0xf
	s_and_saveexec_b64 s[4:5], vcc
	s_cbranch_execz .LBB0_1550
	v_lshl_add_u64 v[48:49], s[2:3], 0, v[196:197]
	v_mov_b32_e32 v15, v197
	v_lshl_add_u64 v[48:49], v[48:49], 0, v[14:15]
	s_waitcnt lgkmcnt(0)
	v_cvt_pk_bf16_f32 v15, v17, v32
	global_store_dword v[48:49], v15, off offset:128
.LBB0_1550:
	s_or_b64 exec, exec, s[4:5]
	v_mul_f32_e32 v16, v18, v16
	s_nop 1
	v_mov_b32_dpp v17, v16 quad_perm:[1,0,3,2] row_mask:0xf bank_mask:0xf
	s_and_saveexec_b64 s[4:5], vcc
	s_cbranch_execz .LBB0_1552
	s_waitcnt lgkmcnt(0)
	v_lshl_add_u64 v[32:33], s[2:3], 0, v[196:197]
	v_mov_b32_e32 v15, v197
	v_lshl_add_u64 v[32:33], v[32:33], 0, v[14:15]
	s_waitcnt lgkmcnt(0)
	v_cvt_pk_bf16_f32 v15, v16, v17
	global_store_dword v[32:33], v15, off offset:192
.LBB0_1552:
	s_or_b64 exec, exec, s[4:5]
	v_rcp_f32_e32 v16, v81
	v_or_b32_e32 v15, 3, v209
	v_lshlrev_b32_e32 v196, 12, v15
	s_waitcnt lgkmcnt(0)
	v_mul_f32_e32 v17, v51, v16
	s_nop 1
	v_mov_b32_dpp v18, v17 quad_perm:[1,0,3,2] row_mask:0xf bank_mask:0xf
	s_and_saveexec_b64 s[4:5], vcc
	s_cbranch_execz .LBB0_1554
	v_lshl_add_u64 v[32:33], s[2:3], 0, v[196:197]
	v_mov_b32_e32 v15, v197
	v_lshl_add_u64 v[32:33], v[32:33], 0, v[14:15]
	s_waitcnt lgkmcnt(0)
	v_cvt_pk_bf16_f32 v15, v17, v18
	global_store_dword v[32:33], v15, off
.LBB0_1554:
	s_or_b64 exec, exec, s[4:5]
	v_mul_f32_e32 v17, v67, v16
	s_waitcnt lgkmcnt(0)
	s_nop 1
	v_mov_b32_dpp v18, v17 quad_perm:[1,0,3,2] row_mask:0xf bank_mask:0xf
	s_and_saveexec_b64 s[4:5], vcc
	s_cbranch_execz .LBB0_1556
	v_lshl_add_u64 v[32:33], s[2:3], 0, v[196:197]
	v_mov_b32_e32 v15, v197
	v_lshl_add_u64 v[32:33], v[32:33], 0, v[14:15]
	s_waitcnt lgkmcnt(0)
	v_cvt_pk_bf16_f32 v15, v17, v18
	global_store_dword v[32:33], v15, off offset:64
.LBB0_1556:
	s_or_b64 exec, exec, s[4:5]
	v_mul_f32_e32 v17, v35, v16
	s_waitcnt lgkmcnt(0)
	s_nop 1
	v_mov_b32_dpp v18, v17 quad_perm:[1,0,3,2] row_mask:0xf bank_mask:0xf
	s_and_saveexec_b64 s[4:5], vcc
	s_cbranch_execz .LBB0_1558
	v_lshl_add_u64 v[32:33], s[2:3], 0, v[196:197]
	v_mov_b32_e32 v15, v197
	v_lshl_add_u64 v[32:33], v[32:33], 0, v[14:15]
	s_waitcnt lgkmcnt(0)
	v_cvt_pk_bf16_f32 v15, v17, v18
	global_store_dword v[32:33], v15, off offset:128
.LBB0_1558:
	s_or_b64 exec, exec, s[4:5]
	v_mul_f32_e32 v16, v19, v16
	s_nop 1
	v_mov_b32_dpp v17, v16 quad_perm:[1,0,3,2] row_mask:0xf bank_mask:0xf
	s_and_saveexec_b64 s[4:5], vcc
	s_cbranch_execz .LBB0_1560
	s_waitcnt lgkmcnt(0)
	v_lshl_add_u64 v[18:19], s[2:3], 0, v[196:197]
	v_mov_b32_e32 v15, v197
	v_lshl_add_u64 v[18:19], v[18:19], 0, v[14:15]
	s_waitcnt lgkmcnt(0)
	v_cvt_pk_bf16_f32 v15, v16, v17
	global_store_dword v[18:19], v15, off offset:192
.LBB0_1560:
	s_or_b64 exec, exec, s[4:5]
	v_rcp_f32_e32 v10, v10
	v_or_b32_e32 v15, 8, v209
	v_lshlrev_b32_e32 v196, 12, v15
	v_mul_f32_e32 v16, v52, v10
	s_waitcnt lgkmcnt(0)
	s_nop 1
	v_mov_b32_dpp v17, v16 quad_perm:[1,0,3,2] row_mask:0xf bank_mask:0xf
	s_and_saveexec_b64 s[4:5], vcc
	s_cbranch_execz .LBB0_1562
	v_lshl_add_u64 v[18:19], s[2:3], 0, v[196:197]
	v_mov_b32_e32 v15, v197
	v_lshl_add_u64 v[18:19], v[18:19], 0, v[14:15]
	s_waitcnt lgkmcnt(0)
	v_cvt_pk_bf16_f32 v15, v16, v17
	global_store_dword v[18:19], v15, off
.LBB0_1562:
	s_or_b64 exec, exec, s[4:5]
	v_mul_f32_e32 v16, v68, v10
	s_waitcnt lgkmcnt(0)
	s_nop 1
	v_mov_b32_dpp v17, v16 quad_perm:[1,0,3,2] row_mask:0xf bank_mask:0xf
	s_and_saveexec_b64 s[4:5], vcc
	s_cbranch_execz .LBB0_1564
	v_lshl_add_u64 v[18:19], s[2:3], 0, v[196:197]
	v_mov_b32_e32 v15, v197
	v_lshl_add_u64 v[18:19], v[18:19], 0, v[14:15]
	s_waitcnt lgkmcnt(0)
	v_cvt_pk_bf16_f32 v15, v16, v17
	global_store_dword v[18:19], v15, off offset:64
.LBB0_1564:
	s_or_b64 exec, exec, s[4:5]
	v_mul_f32_e32 v16, v36, v10
	s_waitcnt lgkmcnt(0)
	s_nop 1
	v_mov_b32_dpp v17, v16 quad_perm:[1,0,3,2] row_mask:0xf bank_mask:0xf
	s_and_saveexec_b64 s[4:5], vcc
	s_cbranch_execz .LBB0_1566
	v_lshl_add_u64 v[18:19], s[2:3], 0, v[196:197]
	v_mov_b32_e32 v15, v197
	v_lshl_add_u64 v[18:19], v[18:19], 0, v[14:15]
	s_waitcnt lgkmcnt(0)
	v_cvt_pk_bf16_f32 v15, v16, v17
	global_store_dword v[18:19], v15, off offset:128
.LBB0_1566:
	s_or_b64 exec, exec, s[4:5]
	v_mul_f32_e32 v10, v20, v10
	s_nop 1
	v_mov_b32_dpp v16, v10 quad_perm:[1,0,3,2] row_mask:0xf bank_mask:0xf
	s_and_saveexec_b64 s[4:5], vcc
	s_cbranch_execz .LBB0_1568
	v_lshl_add_u64 v[18:19], s[2:3], 0, v[196:197]
	v_mov_b32_e32 v15, v197
	v_lshl_add_u64 v[18:19], v[18:19], 0, v[14:15]
	s_waitcnt lgkmcnt(0)
	v_cvt_pk_bf16_f32 v10, v10, v16
	global_store_dword v[18:19], v10, off offset:192
.LBB0_1568:
	s_or_b64 exec, exec, s[4:5]
	v_rcp_f32_e32 v10, v11
	v_or_b32_e32 v15, 9, v209
	v_lshlrev_b32_e32 v196, 12, v15
	v_mul_f32_e32 v11, v53, v10
	s_waitcnt lgkmcnt(0)
	s_nop 1
	v_mov_b32_dpp v16, v11 quad_perm:[1,0,3,2] row_mask:0xf bank_mask:0xf
	s_and_saveexec_b64 s[4:5], vcc
	s_cbranch_execz .LBB0_1570
	v_lshl_add_u64 v[18:19], s[2:3], 0, v[196:197]
	v_mov_b32_e32 v15, v197
	v_lshl_add_u64 v[18:19], v[18:19], 0, v[14:15]
	s_waitcnt lgkmcnt(0)
	v_cvt_pk_bf16_f32 v11, v11, v16
	global_store_dword v[18:19], v11, off
.LBB0_1570:
	s_or_b64 exec, exec, s[4:5]
	v_mul_f32_e32 v11, v69, v10
	s_waitcnt lgkmcnt(0)
	s_nop 1
	v_mov_b32_dpp v16, v11 quad_perm:[1,0,3,2] row_mask:0xf bank_mask:0xf
	s_and_saveexec_b64 s[4:5], vcc
	s_cbranch_execz .LBB0_1572
	v_lshl_add_u64 v[18:19], s[2:3], 0, v[196:197]
	v_mov_b32_e32 v15, v197
	v_lshl_add_u64 v[18:19], v[18:19], 0, v[14:15]
	s_waitcnt lgkmcnt(0)
	v_cvt_pk_bf16_f32 v11, v11, v16
	global_store_dword v[18:19], v11, off offset:64
.LBB0_1572:
	s_or_b64 exec, exec, s[4:5]
	v_mul_f32_e32 v11, v37, v10
	s_waitcnt lgkmcnt(0)
	s_nop 1
	v_mov_b32_dpp v16, v11 quad_perm:[1,0,3,2] row_mask:0xf bank_mask:0xf
	s_and_saveexec_b64 s[4:5], vcc
	s_cbranch_execz .LBB0_1574
	v_lshl_add_u64 v[18:19], s[2:3], 0, v[196:197]
	v_mov_b32_e32 v15, v197
	v_lshl_add_u64 v[18:19], v[18:19], 0, v[14:15]
	s_waitcnt lgkmcnt(0)
	v_cvt_pk_bf16_f32 v11, v11, v16
	global_store_dword v[18:19], v11, off offset:128
.LBB0_1574:
	s_or_b64 exec, exec, s[4:5]
	v_mul_f32_e32 v10, v21, v10
	s_nop 1
	v_mov_b32_dpp v11, v10 quad_perm:[1,0,3,2] row_mask:0xf bank_mask:0xf
	s_and_saveexec_b64 s[4:5], vcc
	s_cbranch_execz .LBB0_1576
	s_waitcnt lgkmcnt(0)
	v_lshl_add_u64 v[16:17], s[2:3], 0, v[196:197]
	v_mov_b32_e32 v15, v197
	v_lshl_add_u64 v[16:17], v[16:17], 0, v[14:15]
	s_waitcnt lgkmcnt(0)
	v_cvt_pk_bf16_f32 v10, v10, v11
	global_store_dword v[16:17], v10, off offset:192
.LBB0_1576:
	s_or_b64 exec, exec, s[4:5]
	v_rcp_f32_e32 v10, v12
	v_or_b32_e32 v15, 10, v209
	v_lshlrev_b32_e32 v196, 12, v15
	s_waitcnt lgkmcnt(0)
	v_mul_f32_e32 v11, v54, v10
	s_nop 1
	v_mov_b32_dpp v12, v11 quad_perm:[1,0,3,2] row_mask:0xf bank_mask:0xf
	s_and_saveexec_b64 s[4:5], vcc
	s_cbranch_execz .LBB0_1578
	v_lshl_add_u64 v[16:17], s[2:3], 0, v[196:197]
	v_mov_b32_e32 v15, v197
	v_lshl_add_u64 v[16:17], v[16:17], 0, v[14:15]
	s_waitcnt lgkmcnt(0)
	v_cvt_pk_bf16_f32 v11, v11, v12
	global_store_dword v[16:17], v11, off
.LBB0_1578:
	s_or_b64 exec, exec, s[4:5]
	v_mul_f32_e32 v11, v70, v10
	s_waitcnt lgkmcnt(0)
	s_nop 1
	v_mov_b32_dpp v12, v11 quad_perm:[1,0,3,2] row_mask:0xf bank_mask:0xf
	s_and_saveexec_b64 s[4:5], vcc
	s_cbranch_execz .LBB0_1580
	v_lshl_add_u64 v[16:17], s[2:3], 0, v[196:197]
	v_mov_b32_e32 v15, v197
	v_lshl_add_u64 v[16:17], v[16:17], 0, v[14:15]
	s_waitcnt lgkmcnt(0)
	v_cvt_pk_bf16_f32 v11, v11, v12
	global_store_dword v[16:17], v11, off offset:64
.LBB0_1580:
	s_or_b64 exec, exec, s[4:5]
	v_mul_f32_e32 v11, v38, v10
	s_waitcnt lgkmcnt(0)
	s_nop 1
	v_mov_b32_dpp v12, v11 quad_perm:[1,0,3,2] row_mask:0xf bank_mask:0xf
	s_and_saveexec_b64 s[4:5], vcc
	s_cbranch_execz .LBB0_1582
	v_lshl_add_u64 v[16:17], s[2:3], 0, v[196:197]
	v_mov_b32_e32 v15, v197
	v_lshl_add_u64 v[16:17], v[16:17], 0, v[14:15]
	s_waitcnt lgkmcnt(0)
	v_cvt_pk_bf16_f32 v11, v11, v12
	global_store_dword v[16:17], v11, off offset:128
.LBB0_1582:
	s_or_b64 exec, exec, s[4:5]
	v_mul_f32_e32 v10, v22, v10
	s_nop 1
	v_mov_b32_dpp v11, v10 quad_perm:[1,0,3,2] row_mask:0xf bank_mask:0xf
	s_and_saveexec_b64 s[4:5], vcc
	s_cbranch_execz .LBB0_1584
	v_lshl_add_u64 v[16:17], s[2:3], 0, v[196:197]
	v_mov_b32_e32 v15, v197
	v_lshl_add_u64 v[16:17], v[16:17], 0, v[14:15]
	s_waitcnt lgkmcnt(0)
	v_cvt_pk_bf16_f32 v10, v10, v11
	global_store_dword v[16:17], v10, off offset:192
.LBB0_1584:
	s_or_b64 exec, exec, s[4:5]
	v_rcp_f32_e32 v10, v13
	v_or_b32_e32 v13, 11, v209
	v_lshlrev_b32_e32 v196, 12, v13
	s_waitcnt lgkmcnt(0)
	v_mul_f32_e32 v11, v55, v10
	s_nop 1
	v_mov_b32_dpp v12, v11 quad_perm:[1,0,3,2] row_mask:0xf bank_mask:0xf
	s_and_saveexec_b64 s[4:5], vcc
	s_cbranch_execz .LBB0_1586
	v_lshl_add_u64 v[16:17], s[2:3], 0, v[196:197]
	v_mov_b32_e32 v15, v197
	v_lshl_add_u64 v[16:17], v[16:17], 0, v[14:15]
	s_waitcnt lgkmcnt(0)
	v_cvt_pk_bf16_f32 v11, v11, v12
	global_store_dword v[16:17], v11, off
.LBB0_1586:
	s_or_b64 exec, exec, s[4:5]
	v_mul_f32_e32 v11, v71, v10
	s_waitcnt lgkmcnt(0)
	s_nop 1
	v_mov_b32_dpp v12, v11 quad_perm:[1,0,3,2] row_mask:0xf bank_mask:0xf
	s_and_saveexec_b64 s[4:5], vcc
	s_cbranch_execz .LBB0_1588
	v_lshl_add_u64 v[16:17], s[2:3], 0, v[196:197]
	v_mov_b32_e32 v15, v197
	v_lshl_add_u64 v[16:17], v[16:17], 0, v[14:15]
	s_waitcnt lgkmcnt(0)
	v_cvt_pk_bf16_f32 v11, v11, v12
	global_store_dword v[16:17], v11, off offset:64
.LBB0_1588:
	s_or_b64 exec, exec, s[4:5]
	v_mul_f32_e32 v11, v39, v10
	s_waitcnt lgkmcnt(0)
	s_nop 1
	v_mov_b32_dpp v12, v11 quad_perm:[1,0,3,2] row_mask:0xf bank_mask:0xf
	s_and_saveexec_b64 s[4:5], vcc
	s_cbranch_execz .LBB0_1590
	v_lshl_add_u64 v[16:17], s[2:3], 0, v[196:197]
	v_mov_b32_e32 v15, v197
	v_lshl_add_u64 v[16:17], v[16:17], 0, v[14:15]
	s_waitcnt lgkmcnt(0)
	v_cvt_pk_bf16_f32 v11, v11, v12
	global_store_dword v[16:17], v11, off offset:128
.LBB0_1590:
	s_or_b64 exec, exec, s[4:5]
	v_mul_f32_e32 v10, v23, v10
	s_nop 1
	v_mov_b32_dpp v11, v10 quad_perm:[1,0,3,2] row_mask:0xf bank_mask:0xf
	s_and_saveexec_b64 s[4:5], vcc
	s_cbranch_execz .LBB0_1592
	s_waitcnt lgkmcnt(0)
	v_lshl_add_u64 v[12:13], s[2:3], 0, v[196:197]
	v_mov_b32_e32 v15, v197
	v_lshl_add_u64 v[12:13], v[12:13], 0, v[14:15]
	s_waitcnt lgkmcnt(0)
	v_cvt_pk_bf16_f32 v10, v10, v11
	global_store_dword v[12:13], v10, off offset:192
.LBB0_1592:
	s_or_b64 exec, exec, s[4:5]
	v_rcp_f32_e32 v6, v6
	s_waitcnt lgkmcnt(1)
	v_or_b32_e32 v12, 16, v209
	v_lshlrev_b32_e32 v196, 12, v12
	v_mul_f32_e32 v10, v56, v6
	s_waitcnt lgkmcnt(0)
	s_nop 1
	v_mov_b32_dpp v11, v10 quad_perm:[1,0,3,2] row_mask:0xf bank_mask:0xf
	s_and_saveexec_b64 s[4:5], vcc
	s_cbranch_execz .LBB0_1594
	v_lshl_add_u64 v[12:13], s[2:3], 0, v[196:197]
	v_mov_b32_e32 v15, v197
	v_lshl_add_u64 v[12:13], v[12:13], 0, v[14:15]
	s_waitcnt lgkmcnt(0)
	v_cvt_pk_bf16_f32 v10, v10, v11
	global_store_dword v[12:13], v10, off
.LBB0_1594:
	s_or_b64 exec, exec, s[4:5]
	v_mul_f32_e32 v10, v72, v6
	s_waitcnt lgkmcnt(0)
	s_nop 1
	v_mov_b32_dpp v11, v10 quad_perm:[1,0,3,2] row_mask:0xf bank_mask:0xf
	s_and_saveexec_b64 s[4:5], vcc
	s_cbranch_execz .LBB0_1596
	v_lshl_add_u64 v[12:13], s[2:3], 0, v[196:197]
	v_mov_b32_e32 v15, v197
	v_lshl_add_u64 v[12:13], v[12:13], 0, v[14:15]
	s_waitcnt lgkmcnt(0)
	v_cvt_pk_bf16_f32 v10, v10, v11
	global_store_dword v[12:13], v10, off offset:64
.LBB0_1596:
	s_or_b64 exec, exec, s[4:5]
	v_mul_f32_e32 v10, v40, v6
	s_waitcnt lgkmcnt(0)
	s_nop 1
	v_mov_b32_dpp v11, v10 quad_perm:[1,0,3,2] row_mask:0xf bank_mask:0xf
	s_and_saveexec_b64 s[4:5], vcc
	s_cbranch_execz .LBB0_1598
	v_lshl_add_u64 v[12:13], s[2:3], 0, v[196:197]
	v_mov_b32_e32 v15, v197
	v_lshl_add_u64 v[12:13], v[12:13], 0, v[14:15]
	s_waitcnt lgkmcnt(0)
	v_cvt_pk_bf16_f32 v10, v10, v11
	global_store_dword v[12:13], v10, off offset:128
.LBB0_1598:
	s_or_b64 exec, exec, s[4:5]
	v_mul_f32_e32 v6, v24, v6
	s_nop 1
	v_mov_b32_dpp v10, v6 quad_perm:[1,0,3,2] row_mask:0xf bank_mask:0xf
	s_and_saveexec_b64 s[4:5], vcc
	s_cbranch_execz .LBB0_1600
	v_lshl_add_u64 v[12:13], s[2:3], 0, v[196:197]
	v_mov_b32_e32 v15, v197
	v_lshl_add_u64 v[12:13], v[12:13], 0, v[14:15]
	s_waitcnt lgkmcnt(0)
	v_cvt_pk_bf16_f32 v6, v6, v10
	global_store_dword v[12:13], v6, off offset:192
.LBB0_1600:
	s_or_b64 exec, exec, s[4:5]
	v_rcp_f32_e32 v6, v7
	s_waitcnt lgkmcnt(1)
	v_or_b32_e32 v11, 17, v209
	v_lshlrev_b32_e32 v196, 12, v11
	v_mul_f32_e32 v7, v57, v6
	s_waitcnt lgkmcnt(0)
	s_nop 1
	v_mov_b32_dpp v10, v7 quad_perm:[1,0,3,2] row_mask:0xf bank_mask:0xf
	s_and_saveexec_b64 s[4:5], vcc
	s_cbranch_execz .LBB0_1602
	v_lshl_add_u64 v[12:13], s[2:3], 0, v[196:197]
	v_mov_b32_e32 v15, v197
	v_lshl_add_u64 v[12:13], v[12:13], 0, v[14:15]
	s_waitcnt lgkmcnt(0)
	v_cvt_pk_bf16_f32 v7, v7, v10
	global_store_dword v[12:13], v7, off
.LBB0_1602:
	s_or_b64 exec, exec, s[4:5]
	v_mul_f32_e32 v7, v73, v6
	s_waitcnt lgkmcnt(0)
	s_nop 1
	v_mov_b32_dpp v10, v7 quad_perm:[1,0,3,2] row_mask:0xf bank_mask:0xf
	s_and_saveexec_b64 s[4:5], vcc
	s_cbranch_execz .LBB0_1604
	v_lshl_add_u64 v[12:13], s[2:3], 0, v[196:197]
	v_mov_b32_e32 v15, v197
	v_lshl_add_u64 v[12:13], v[12:13], 0, v[14:15]
	s_waitcnt lgkmcnt(0)
	v_cvt_pk_bf16_f32 v7, v7, v10
	global_store_dword v[12:13], v7, off offset:64
.LBB0_1604:
	s_or_b64 exec, exec, s[4:5]
	v_mul_f32_e32 v7, v41, v6
	s_waitcnt lgkmcnt(0)
	s_nop 1
	v_mov_b32_dpp v10, v7 quad_perm:[1,0,3,2] row_mask:0xf bank_mask:0xf
	s_and_saveexec_b64 s[4:5], vcc
	s_cbranch_execz .LBB0_1606
	v_lshl_add_u64 v[12:13], s[2:3], 0, v[196:197]
	v_mov_b32_e32 v15, v197
	v_lshl_add_u64 v[12:13], v[12:13], 0, v[14:15]
	s_waitcnt lgkmcnt(0)
	v_cvt_pk_bf16_f32 v7, v7, v10
	global_store_dword v[12:13], v7, off offset:128
.LBB0_1606:
	s_or_b64 exec, exec, s[4:5]
	v_mul_f32_e32 v6, v25, v6
	s_nop 1
	v_mov_b32_dpp v7, v6 quad_perm:[1,0,3,2] row_mask:0xf bank_mask:0xf
	s_and_saveexec_b64 s[4:5], vcc
	s_cbranch_execz .LBB0_1608
	s_waitcnt lgkmcnt(0)
	v_lshl_add_u64 v[10:11], s[2:3], 0, v[196:197]
	v_mov_b32_e32 v15, v197
	v_lshl_add_u64 v[10:11], v[10:11], 0, v[14:15]
	s_waitcnt lgkmcnt(0)
	v_cvt_pk_bf16_f32 v6, v6, v7
	global_store_dword v[10:11], v6, off offset:192
.LBB0_1608:
	s_or_b64 exec, exec, s[4:5]
	v_rcp_f32_e32 v6, v8
	s_waitcnt lgkmcnt(1)
	v_or_b32_e32 v10, 18, v209
	v_lshlrev_b32_e32 v196, 12, v10
	s_waitcnt lgkmcnt(0)
	v_mul_f32_e32 v7, v58, v6
	s_nop 1
	v_mov_b32_dpp v8, v7 quad_perm:[1,0,3,2] row_mask:0xf bank_mask:0xf
	s_and_saveexec_b64 s[4:5], vcc
	s_cbranch_execz .LBB0_1610
	v_lshl_add_u64 v[10:11], s[2:3], 0, v[196:197]
	v_mov_b32_e32 v15, v197
	v_lshl_add_u64 v[10:11], v[10:11], 0, v[14:15]
	s_waitcnt lgkmcnt(0)
	v_cvt_pk_bf16_f32 v7, v7, v8
	global_store_dword v[10:11], v7, off
.LBB0_1610:
	s_or_b64 exec, exec, s[4:5]
	v_mul_f32_e32 v7, v74, v6
	s_waitcnt lgkmcnt(0)
	s_nop 1
	v_mov_b32_dpp v8, v7 quad_perm:[1,0,3,2] row_mask:0xf bank_mask:0xf
	s_and_saveexec_b64 s[4:5], vcc
	s_cbranch_execz .LBB0_1612
	v_lshl_add_u64 v[10:11], s[2:3], 0, v[196:197]
	v_mov_b32_e32 v15, v197
	v_lshl_add_u64 v[10:11], v[10:11], 0, v[14:15]
	s_waitcnt lgkmcnt(0)
	v_cvt_pk_bf16_f32 v7, v7, v8
	global_store_dword v[10:11], v7, off offset:64
.LBB0_1612:
	s_or_b64 exec, exec, s[4:5]
	v_mul_f32_e32 v7, v42, v6
	s_waitcnt lgkmcnt(0)
	s_nop 1
	v_mov_b32_dpp v8, v7 quad_perm:[1,0,3,2] row_mask:0xf bank_mask:0xf
	s_and_saveexec_b64 s[4:5], vcc
	s_cbranch_execz .LBB0_1614
	v_lshl_add_u64 v[10:11], s[2:3], 0, v[196:197]
	v_mov_b32_e32 v15, v197
	v_lshl_add_u64 v[10:11], v[10:11], 0, v[14:15]
	s_waitcnt lgkmcnt(0)
	v_cvt_pk_bf16_f32 v7, v7, v8
	global_store_dword v[10:11], v7, off offset:128
.LBB0_1614:
	s_or_b64 exec, exec, s[4:5]
	v_mul_f32_e32 v6, v26, v6
	s_nop 1
	v_mov_b32_dpp v7, v6 quad_perm:[1,0,3,2] row_mask:0xf bank_mask:0xf
	s_and_saveexec_b64 s[4:5], vcc
	s_cbranch_execz .LBB0_1616
	v_lshl_add_u64 v[10:11], s[2:3], 0, v[196:197]
	v_mov_b32_e32 v15, v197
	v_lshl_add_u64 v[10:11], v[10:11], 0, v[14:15]
	s_waitcnt lgkmcnt(0)
	v_cvt_pk_bf16_f32 v6, v6, v7
	global_store_dword v[10:11], v6, off offset:192
.LBB0_1616:
	s_or_b64 exec, exec, s[4:5]
	v_rcp_f32_e32 v6, v9
	v_or_b32_e32 v9, 19, v209
	v_lshlrev_b32_e32 v196, 12, v9
	s_waitcnt lgkmcnt(0)
	v_mul_f32_e32 v7, v59, v6
	s_nop 1
	v_mov_b32_dpp v8, v7 quad_perm:[1,0,3,2] row_mask:0xf bank_mask:0xf
	s_and_saveexec_b64 s[4:5], vcc
	s_cbranch_execz .LBB0_1618
	v_lshl_add_u64 v[10:11], s[2:3], 0, v[196:197]
	v_mov_b32_e32 v15, v197
	v_lshl_add_u64 v[10:11], v[10:11], 0, v[14:15]
	s_waitcnt lgkmcnt(0)
	v_cvt_pk_bf16_f32 v7, v7, v8
	global_store_dword v[10:11], v7, off
.LBB0_1618:
	s_or_b64 exec, exec, s[4:5]
	v_mul_f32_e32 v7, v75, v6
	s_waitcnt lgkmcnt(0)
	s_nop 1
	v_mov_b32_dpp v8, v7 quad_perm:[1,0,3,2] row_mask:0xf bank_mask:0xf
	s_and_saveexec_b64 s[4:5], vcc
	s_cbranch_execz .LBB0_1620
	v_lshl_add_u64 v[10:11], s[2:3], 0, v[196:197]
	v_mov_b32_e32 v15, v197
	v_lshl_add_u64 v[10:11], v[10:11], 0, v[14:15]
	s_waitcnt lgkmcnt(0)
	v_cvt_pk_bf16_f32 v7, v7, v8
	global_store_dword v[10:11], v7, off offset:64
.LBB0_1620:
	s_or_b64 exec, exec, s[4:5]
	v_mul_f32_e32 v7, v43, v6
	s_waitcnt lgkmcnt(0)
	s_nop 1
	v_mov_b32_dpp v8, v7 quad_perm:[1,0,3,2] row_mask:0xf bank_mask:0xf
	s_and_saveexec_b64 s[4:5], vcc
	s_cbranch_execz .LBB0_1622
	v_lshl_add_u64 v[10:11], s[2:3], 0, v[196:197]
	v_mov_b32_e32 v15, v197
	v_lshl_add_u64 v[10:11], v[10:11], 0, v[14:15]
	s_waitcnt lgkmcnt(0)
	v_cvt_pk_bf16_f32 v7, v7, v8
	global_store_dword v[10:11], v7, off offset:128
.LBB0_1622:
	s_or_b64 exec, exec, s[4:5]
	v_mul_f32_e32 v6, v27, v6
	s_nop 1
	v_mov_b32_dpp v7, v6 quad_perm:[1,0,3,2] row_mask:0xf bank_mask:0xf
	s_and_saveexec_b64 s[4:5], vcc
	s_cbranch_execz .LBB0_1624
	s_waitcnt lgkmcnt(0)
	v_lshl_add_u64 v[8:9], s[2:3], 0, v[196:197]
	v_mov_b32_e32 v15, v197
	v_lshl_add_u64 v[8:9], v[8:9], 0, v[14:15]
	s_waitcnt lgkmcnt(0)
	v_cvt_pk_bf16_f32 v6, v6, v7
	global_store_dword v[8:9], v6, off offset:192
.LBB0_1624:
	s_or_b64 exec, exec, s[4:5]
	v_rcp_f32_e32 v2, v2
	s_waitcnt lgkmcnt(1)
	v_or_b32_e32 v8, 24, v209
	v_lshlrev_b32_e32 v196, 12, v8
	v_mul_f32_e32 v6, v60, v2
	s_waitcnt lgkmcnt(0)
	s_nop 1
	v_mov_b32_dpp v7, v6 quad_perm:[1,0,3,2] row_mask:0xf bank_mask:0xf
	s_and_saveexec_b64 s[4:5], vcc
	s_cbranch_execz .LBB0_1626
	v_lshl_add_u64 v[8:9], s[2:3], 0, v[196:197]
	v_mov_b32_e32 v15, v197
	v_lshl_add_u64 v[8:9], v[8:9], 0, v[14:15]
	s_waitcnt lgkmcnt(0)
	v_cvt_pk_bf16_f32 v6, v6, v7
	global_store_dword v[8:9], v6, off
.LBB0_1626:
	s_or_b64 exec, exec, s[4:5]
	v_mul_f32_e32 v6, v76, v2
	s_waitcnt lgkmcnt(0)
	s_nop 1
	v_mov_b32_dpp v7, v6 quad_perm:[1,0,3,2] row_mask:0xf bank_mask:0xf
	s_and_saveexec_b64 s[4:5], vcc
	s_cbranch_execz .LBB0_1628
	v_lshl_add_u64 v[8:9], s[2:3], 0, v[196:197]
	v_mov_b32_e32 v15, v197
	v_lshl_add_u64 v[8:9], v[8:9], 0, v[14:15]
	s_waitcnt lgkmcnt(0)
	v_cvt_pk_bf16_f32 v6, v6, v7
	global_store_dword v[8:9], v6, off offset:64
.LBB0_1628:
	s_or_b64 exec, exec, s[4:5]
	v_mul_f32_e32 v6, v44, v2
	s_waitcnt lgkmcnt(0)
	s_nop 1
	v_mov_b32_dpp v7, v6 quad_perm:[1,0,3,2] row_mask:0xf bank_mask:0xf
	s_and_saveexec_b64 s[4:5], vcc
	s_cbranch_execz .LBB0_1630
	v_lshl_add_u64 v[8:9], s[2:3], 0, v[196:197]
	v_mov_b32_e32 v15, v197
	v_lshl_add_u64 v[8:9], v[8:9], 0, v[14:15]
	s_waitcnt lgkmcnt(0)
	v_cvt_pk_bf16_f32 v6, v6, v7
	global_store_dword v[8:9], v6, off offset:128
.LBB0_1630:
	s_or_b64 exec, exec, s[4:5]
	v_mul_f32_e32 v2, v28, v2
	s_nop 1
	v_mov_b32_dpp v6, v2 quad_perm:[1,0,3,2] row_mask:0xf bank_mask:0xf
	s_and_saveexec_b64 s[4:5], vcc
	s_cbranch_execz .LBB0_1632
	v_lshl_add_u64 v[8:9], s[2:3], 0, v[196:197]
	v_mov_b32_e32 v15, v197
	v_lshl_add_u64 v[8:9], v[8:9], 0, v[14:15]
	s_waitcnt lgkmcnt(0)
	v_cvt_pk_bf16_f32 v2, v2, v6
	global_store_dword v[8:9], v2, off offset:192
.LBB0_1632:
	s_or_b64 exec, exec, s[4:5]
	v_rcp_f32_e32 v2, v3
	s_waitcnt lgkmcnt(1)
	v_or_b32_e32 v7, 25, v209
	v_lshlrev_b32_e32 v196, 12, v7
	v_mul_f32_e32 v3, v61, v2
	s_waitcnt lgkmcnt(0)
	s_nop 1
	v_mov_b32_dpp v6, v3 quad_perm:[1,0,3,2] row_mask:0xf bank_mask:0xf
	s_and_saveexec_b64 s[4:5], vcc
	s_cbranch_execz .LBB0_1634
	v_lshl_add_u64 v[8:9], s[2:3], 0, v[196:197]
	v_mov_b32_e32 v15, v197
	v_lshl_add_u64 v[8:9], v[8:9], 0, v[14:15]
	s_waitcnt lgkmcnt(0)
	v_cvt_pk_bf16_f32 v3, v3, v6
	global_store_dword v[8:9], v3, off
.LBB0_1634:
	s_or_b64 exec, exec, s[4:5]
	v_mul_f32_e32 v3, v77, v2
	s_waitcnt lgkmcnt(0)
	s_nop 1
	v_mov_b32_dpp v6, v3 quad_perm:[1,0,3,2] row_mask:0xf bank_mask:0xf
	s_and_saveexec_b64 s[4:5], vcc
	s_cbranch_execz .LBB0_1636
	v_lshl_add_u64 v[8:9], s[2:3], 0, v[196:197]
	v_mov_b32_e32 v15, v197
	v_lshl_add_u64 v[8:9], v[8:9], 0, v[14:15]
	s_waitcnt lgkmcnt(0)
	v_cvt_pk_bf16_f32 v3, v3, v6
	global_store_dword v[8:9], v3, off offset:64
.LBB0_1636:
	s_or_b64 exec, exec, s[4:5]
	v_mul_f32_e32 v3, v45, v2
	s_waitcnt lgkmcnt(0)
	s_nop 1
	v_mov_b32_dpp v6, v3 quad_perm:[1,0,3,2] row_mask:0xf bank_mask:0xf
	s_and_saveexec_b64 s[4:5], vcc
	s_cbranch_execz .LBB0_1638
	v_lshl_add_u64 v[8:9], s[2:3], 0, v[196:197]
	v_mov_b32_e32 v15, v197
	v_lshl_add_u64 v[8:9], v[8:9], 0, v[14:15]
	s_waitcnt lgkmcnt(0)
	v_cvt_pk_bf16_f32 v3, v3, v6
	global_store_dword v[8:9], v3, off offset:128
.LBB0_1638:
	s_or_b64 exec, exec, s[4:5]
	v_mul_f32_e32 v2, v29, v2
	s_nop 1
	v_mov_b32_dpp v3, v2 quad_perm:[1,0,3,2] row_mask:0xf bank_mask:0xf
	s_and_saveexec_b64 s[4:5], vcc
	s_cbranch_execz .LBB0_1640
	s_waitcnt lgkmcnt(0)
	v_lshl_add_u64 v[6:7], s[2:3], 0, v[196:197]
	v_mov_b32_e32 v15, v197
	v_lshl_add_u64 v[6:7], v[6:7], 0, v[14:15]
	s_waitcnt lgkmcnt(0)
	v_cvt_pk_bf16_f32 v2, v2, v3
	global_store_dword v[6:7], v2, off offset:192
.LBB0_1640:
	s_or_b64 exec, exec, s[4:5]
	v_rcp_f32_e32 v2, v4
	s_waitcnt lgkmcnt(1)
	v_or_b32_e32 v6, 26, v209
	v_lshlrev_b32_e32 v196, 12, v6
	s_waitcnt lgkmcnt(0)
	v_mul_f32_e32 v3, v62, v2
	s_nop 1
	v_mov_b32_dpp v4, v3 quad_perm:[1,0,3,2] row_mask:0xf bank_mask:0xf
	s_and_saveexec_b64 s[4:5], vcc
	s_cbranch_execz .LBB0_1642
	v_lshl_add_u64 v[6:7], s[2:3], 0, v[196:197]
	v_mov_b32_e32 v15, v197
	v_lshl_add_u64 v[6:7], v[6:7], 0, v[14:15]
	s_waitcnt lgkmcnt(0)
	v_cvt_pk_bf16_f32 v3, v3, v4
	global_store_dword v[6:7], v3, off
.LBB0_1642:
	s_or_b64 exec, exec, s[4:5]
	v_mul_f32_e32 v3, v78, v2
	s_waitcnt lgkmcnt(0)
	s_nop 1
	v_mov_b32_dpp v4, v3 quad_perm:[1,0,3,2] row_mask:0xf bank_mask:0xf
	s_and_saveexec_b64 s[4:5], vcc
	s_cbranch_execz .LBB0_1644
	v_lshl_add_u64 v[6:7], s[2:3], 0, v[196:197]
	v_mov_b32_e32 v15, v197
	v_lshl_add_u64 v[6:7], v[6:7], 0, v[14:15]
	s_waitcnt lgkmcnt(0)
	v_cvt_pk_bf16_f32 v3, v3, v4
	global_store_dword v[6:7], v3, off offset:64
.LBB0_1644:
	s_or_b64 exec, exec, s[4:5]
	v_mul_f32_e32 v3, v46, v2
	s_waitcnt lgkmcnt(0)
	s_nop 1
	v_mov_b32_dpp v4, v3 quad_perm:[1,0,3,2] row_mask:0xf bank_mask:0xf
	s_and_saveexec_b64 s[4:5], vcc
	s_cbranch_execz .LBB0_1646
	v_lshl_add_u64 v[6:7], s[2:3], 0, v[196:197]
	v_mov_b32_e32 v15, v197
	v_lshl_add_u64 v[6:7], v[6:7], 0, v[14:15]
	s_waitcnt lgkmcnt(0)
	v_cvt_pk_bf16_f32 v3, v3, v4
	global_store_dword v[6:7], v3, off offset:128
.LBB0_1646:
	s_or_b64 exec, exec, s[4:5]
	v_mul_f32_e32 v2, v30, v2
	s_nop 1
	v_mov_b32_dpp v3, v2 quad_perm:[1,0,3,2] row_mask:0xf bank_mask:0xf
	s_and_saveexec_b64 s[4:5], vcc
	s_cbranch_execz .LBB0_1648
	v_lshl_add_u64 v[6:7], s[2:3], 0, v[196:197]
	v_mov_b32_e32 v15, v197
	v_lshl_add_u64 v[6:7], v[6:7], 0, v[14:15]
	s_waitcnt lgkmcnt(0)
	v_cvt_pk_bf16_f32 v2, v2, v3
	global_store_dword v[6:7], v2, off offset:192
.LBB0_1648:
	s_or_b64 exec, exec, s[4:5]
	v_rcp_f32_e32 v2, v5
	v_or_b32_e32 v5, 27, v209
	v_lshlrev_b32_e32 v196, 12, v5
	s_waitcnt lgkmcnt(0)
	v_mul_f32_e32 v3, v63, v2
	s_nop 1
	v_mov_b32_dpp v4, v3 quad_perm:[1,0,3,2] row_mask:0xf bank_mask:0xf
	s_and_saveexec_b64 s[4:5], vcc
	s_cbranch_execz .LBB0_1650
	v_lshl_add_u64 v[6:7], s[2:3], 0, v[196:197]
	v_mov_b32_e32 v15, v197
	v_lshl_add_u64 v[6:7], v[6:7], 0, v[14:15]
	s_waitcnt lgkmcnt(0)
	v_cvt_pk_bf16_f32 v3, v3, v4
	global_store_dword v[6:7], v3, off
.LBB0_1650:
	s_or_b64 exec, exec, s[4:5]
	v_mul_f32_e32 v3, v79, v2
	s_waitcnt lgkmcnt(0)
	s_nop 1
	v_mov_b32_dpp v4, v3 quad_perm:[1,0,3,2] row_mask:0xf bank_mask:0xf
	s_and_saveexec_b64 s[4:5], vcc
	s_cbranch_execz .LBB0_1652
	v_lshl_add_u64 v[6:7], s[2:3], 0, v[196:197]
	v_mov_b32_e32 v15, v197
	v_lshl_add_u64 v[6:7], v[6:7], 0, v[14:15]
	s_waitcnt lgkmcnt(0)
	v_cvt_pk_bf16_f32 v3, v3, v4
	global_store_dword v[6:7], v3, off offset:64
.LBB0_1652:
	s_or_b64 exec, exec, s[4:5]
	v_mul_f32_e32 v3, v47, v2
	s_waitcnt lgkmcnt(0)
	s_nop 1
	v_mov_b32_dpp v4, v3 quad_perm:[1,0,3,2] row_mask:0xf bank_mask:0xf
	s_and_saveexec_b64 s[4:5], vcc
	s_cbranch_execz .LBB0_1654
	v_lshl_add_u64 v[6:7], s[2:3], 0, v[196:197]
	v_mov_b32_e32 v15, v197
	v_lshl_add_u64 v[6:7], v[6:7], 0, v[14:15]
	s_waitcnt lgkmcnt(0)
	v_cvt_pk_bf16_f32 v3, v3, v4
	global_store_dword v[6:7], v3, off offset:128
.LBB0_1654:
	s_or_b64 exec, exec, s[4:5]
	v_mul_f32_e32 v2, v31, v2
	s_nop 1
	v_mov_b32_dpp v1, v2 quad_perm:[1,0,3,2] row_mask:0xf bank_mask:0xf
	s_and_saveexec_b64 s[4:5], vcc
	s_cbranch_execz .LBB0_1656
	s_waitcnt lgkmcnt(0)
	v_lshl_add_u64 v[4:5], s[2:3], 0, v[196:197]
	v_mov_b32_e32 v15, v197
	v_lshl_add_u64 v[4:5], v[4:5], 0, v[14:15]
	s_waitcnt lgkmcnt(0)
	v_cvt_pk_bf16_f32 v1, v2, v1
	global_store_dword v[4:5], v1, off offset:192

.LBB0_1758:
	v_lshl_add_u64 v[22:23], s[64:65], 0, v[144:145]
	v_mov_b32_e32 v157, v145
	v_lshl_add_u64 v[24:25], s[64:65], 0, v[156:157]
	v_mov_b32_e32 v153, v145
	s_add_i32 m0, s7, 0x18000
	v_lshl_add_u64 v[22:23], v[22:23], 0, s[44:45]
	v_lshl_add_u64 v[26:27], s[62:63], 0, v[152:153]
	v_mov_b32_e32 v155, v145
	s_waitcnt vmcnt(2)
	s_barrier
	global_load_lds_dwordx4 v[22:23], off
	v_lshl_add_u64 v[22:23], v[24:25], 0, s[44:45]
	s_add_i32 m0, s7, 0x1a000
	s_add_i32 s11, s7, 0x8000
	s_add_i32 s12, s7, 0xa000
	v_lshl_add_u64 v[28:29], s[62:63], 0, v[154:155]
	global_load_lds_dwordx4 v[22:23], off
	v_lshl_add_u64 v[22:23], v[26:27], 0, s[44:45]
	s_mov_b32 m0, s11
	s_add_u32 s26, s64, 0x80080
	global_load_lds_dwordx4 v[22:23], off
	v_lshl_add_u64 v[22:23], v[28:29], 0, s[44:45]
	s_mov_b32 m0, s12
	s_addc_u32 s27, s65, 0
	global_load_lds_dwordx4 v[22:23], off
	s_add_i32 m0, s7, 0x1c000
	v_lshl_add_u64 v[22:23], s[26:27], 0, v[144:145]
	global_load_lds_dwordx4 v[22:23], off
	v_lshl_add_u64 v[22:23], s[26:27], 0, v[156:157]
	s_add_i32 m0, s7, 0x1e000
	s_waitcnt vmcnt(0)
	v_pk_add_f32 v[10:11], v[14:15], v[10:11]
	global_load_lds_dwordx4 v[22:23], off
	v_pk_add_f32 v[8:9], v[12:13], v[8:9]
	v_pk_add_f32 v[0:1], v[4:5], v[0:1]
	v_pk_add_f32 v[2:3], v[6:7], v[2:3]
	v_pk_add_f32 v[0:1], v[8:9], v[0:1]
	v_pk_add_f32 v[2:3], v[10:11], v[2:3]
	v_add_f32_e32 v0, v0, v1
	v_add_f32_e32 v1, v2, v3
	v_and_b32_e32 v2, 64, v204
	v_add_f32_e32 v0, v0, v1
	v_xor_b32_e32 v1, 1, v204
	v_add_u32_e32 v2, 64, v2
	v_cmp_lt_i32_e32 vcc, v1, v2
	s_waitcnt vmcnt(6)
	v_cmp_eq_u32_e64 s[34:35], 0, v17
	s_barrier
	v_cndmask_b32_e32 v1, v204, v1, vcc
	v_lshlrev_b32_e32 v167, 2, v1
	s_nop 1
	v_mov_b32_dpp v1, v0 quad_perm:[1,0,3,2] row_mask:0xf bank_mask:0xf
	s_and_saveexec_b64 s[26:27], s[34:35]
	s_cbranch_execz .LBB0_1760
	s_waitcnt lgkmcnt(0)
	v_add_f32_e32 v0, v0, v1
	v_fmamk_f32 v0, v0, 0x3a000000, v164
	v_cmp_gt_f32_e32 vcc, s78, v0
	v_mul_f32_e32 v1, 0x4b800000, v0
	s_nop 0
	v_cndmask_b32_e32 v0, v0, v1, vcc
	v_rsq_f32_e32 v0, v0
	s_nop 0
	v_mul_f32_e32 v1, 0x45800000, v0
	v_cndmask_b32_e32 v0, v0, v1, vcc
	v_lshl_add_u32 v1, v16, 2, 0
	v_add_u32_e32 v1, 0x20000, v1
	ds_write_b32 v1, v0

.LBB0_2120:
	s_mov_b64 s[48:49], 0x80
	s_add_i32 m0, s7, 0x18000
	v_lshl_add_u64 v[26:27], v[26:27], 0, s[48:49]
	s_waitcnt vmcnt(2)
	s_barrier
	global_load_lds_dwordx4 v[26:27], off
	v_lshl_add_u64 v[24:25], v[24:25], 0, s[48:49]
	s_add_i32 m0, s7, 0x1a000
	s_add_i32 s11, s7, 0x8000
	s_add_i32 s12, s7, 0xa000
	global_load_lds_dwordx4 v[24:25], off
	v_lshl_add_u64 v[20:21], v[20:21], 0, s[48:49]
	s_mov_b32 m0, s11
	s_add_u32 s28, s40, 0x80080
	global_load_lds_dwordx4 v[20:21], off
	v_lshl_add_u64 v[20:21], v[22:23], 0, s[48:49]
	s_mov_b32 m0, s12
	s_addc_u32 s29, s41, 0
	global_load_lds_dwordx4 v[20:21], off
	s_add_i32 m0, s7, 0x1c000
	v_lshl_add_u64 v[20:21], s[28:29], 0, v[150:151]
	global_load_lds_dwordx4 v[20:21], off
	v_lshl_add_u64 v[20:21], s[28:29], 0, v[154:155]
	s_add_i32 m0, s7, 0x1e000
	s_waitcnt vmcnt(0)
	v_pk_add_f32 v[10:11], v[14:15], v[10:11]
	global_load_lds_dwordx4 v[20:21], off
	v_pk_add_f32 v[8:9], v[12:13], v[8:9]
	v_pk_add_f32 v[0:1], v[4:5], v[0:1]
	v_pk_add_f32 v[2:3], v[6:7], v[2:3]
	v_pk_add_f32 v[0:1], v[8:9], v[0:1]
	v_pk_add_f32 v[2:3], v[10:11], v[2:3]
	v_add_f32_e32 v0, v0, v1
	v_add_f32_e32 v1, v2, v3
	v_and_b32_e32 v2, 64, v204
	v_add_f32_e32 v0, v0, v1
	v_xor_b32_e32 v1, 1, v204
	v_add_u32_e32 v2, 64, v2
	v_cmp_lt_i32_e32 vcc, v1, v2
	s_waitcnt vmcnt(6)
	s_mov_b32 s51, 0
	v_cmp_eq_u32_e64 s[34:35], 0, v17
	v_cndmask_b32_e32 v1, v204, v1, vcc
	v_lshlrev_b32_e32 v194, 2, v1
	s_nop 1
	v_mov_b32_dpp v1, v0 quad_perm:[1,0,3,2] row_mask:0xf bank_mask:0xf
	s_barrier
	s_and_saveexec_b64 s[38:39], s[34:35]
	s_cbranch_execz .LBB0_2122
	s_waitcnt lgkmcnt(0)
	v_add_f32_e32 v0, v0, v1
	v_mov_b32_e32 v1, 0x358637bd
	v_fmac_f32_e32 v1, 0x3a000000, v0
	s_mov_b32 s13, 0x800000
	v_mul_f32_e32 v0, 0x4b800000, v1
	v_cmp_gt_f32_e32 vcc, s13, v1
	s_nop 1
	v_cndmask_b32_e32 v0, v1, v0, vcc
	v_rsq_f32_e32 v0, v0
	s_nop 0
	v_mul_f32_e32 v1, 0x45800000, v0
	v_cndmask_b32_e32 v0, v0, v1, vcc
	v_lshl_add_u32 v1, v16, 2, 0
	v_add_u32_e32 v1, 0x20000, v1
	ds_write_b32 v1, v0

.LBB0_2293:
	s_cmp_ge_i32 s0, s1
	s_cbranch_scc1 .LBB0_2264
	v_and_b32_e32 v65, 64, v204
	v_xor_b32_e32 v64, 1, v204
	v_add_u32_e32 v65, 64, v65
	v_cmp_lt_i32_e32 vcc, v64, v65
	s_ashr_i32 s1, s0, 31
	s_lshl_b64 s[0:1], s[0:1], 12
	v_cndmask_b32_e32 v64, v204, v64, vcc
	v_lshlrev_b32_e32 v66, 2, v64
	s_nop 1
	v_mov_b32_dpp v67, v32 quad_perm:[1,0,3,2] row_mask:0xf bank_mask:0xf
	s_add_u32 s0, s22, s0
	v_and_b32_e32 v64, 1, v188
	s_addc_u32 s1, s23, s1
	v_cmp_eq_u32_e32 vcc, 0, v64
	v_lshlrev_b32_e32 v176, 12, v187
	v_lshlrev_b32_e32 v64, 1, v189
	s_and_saveexec_b64 s[22:23], vcc
	s_cbranch_execz .LBB0_2296
	v_lshl_add_u64 v[68:69], s[0:1], 0, v[176:177]
	v_mov_b32_e32 v65, v177
	v_lshl_add_u64 v[68:69], v[68:69], 0, v[64:65]
	s_waitcnt lgkmcnt(0)
	v_cvt_pk_bf16_f32 v32, v32, v67
	global_store_dword v[68:69], v32, off
.LBB0_2296:
	s_or_b64 exec, exec, s[22:23]
	s_nop 1
	v_mov_b32_dpp v32, v48 quad_perm:[1,0,3,2] row_mask:0xf bank_mask:0xf
	s_and_saveexec_b64 s[22:23], vcc
	s_cbranch_execz .LBB0_2298
	v_lshl_add_u64 v[68:69], s[0:1], 0, v[176:177]
	v_mov_b32_e32 v65, v177
	v_lshl_add_u64 v[68:69], v[68:69], 0, v[64:65]
	s_waitcnt lgkmcnt(0)
	v_cvt_pk_bf16_f32 v32, v48, v32
	global_store_dword v[68:69], v32, off offset:64
.LBB0_2298:
	s_or_b64 exec, exec, s[22:23]
	s_waitcnt lgkmcnt(0)
	s_nop 1
	v_mov_b32_dpp v32, v16 quad_perm:[1,0,3,2] row_mask:0xf bank_mask:0xf
	s_and_saveexec_b64 s[22:23], vcc
	s_cbranch_execz .LBB0_2300
	v_lshl_add_u64 v[68:69], s[0:1], 0, v[176:177]
	v_mov_b32_e32 v65, v177
	v_lshl_add_u64 v[68:69], v[68:69], 0, v[64:65]
	s_waitcnt lgkmcnt(0)
	v_cvt_pk_bf16_f32 v16, v16, v32
	global_store_dword v[68:69], v16, off offset:128
.LBB0_2300:
	s_or_b64 exec, exec, s[22:23]
	s_nop 1
	v_mov_b32_dpp v16, v0 quad_perm:[1,0,3,2] row_mask:0xf bank_mask:0xf
	s_and_saveexec_b64 s[22:23], vcc
	s_cbranch_execz .LBB0_2302
	v_lshl_add_u64 v[68:69], s[0:1], 0, v[176:177]
	v_mov_b32_e32 v65, v177
	v_lshl_add_u64 v[68:69], v[68:69], 0, v[64:65]
	s_waitcnt lgkmcnt(0)
	v_cvt_pk_bf16_f32 v0, v0, v16
	global_store_dword v[68:69], v0, off offset:192
.LBB0_2302:
	s_or_b64 exec, exec, s[22:23]
	s_nop 1
	v_mov_b32_dpp v0, v33 quad_perm:[1,0,3,2] row_mask:0xf bank_mask:0xf
	s_waitcnt lgkmcnt(0)
	v_or_b32_e32 v16, 1, v187
	v_lshlrev_b32_e32 v176, 12, v16
	s_and_saveexec_b64 s[22:23], vcc
	s_cbranch_execz .LBB0_2304
	v_lshl_add_u64 v[68:69], s[0:1], 0, v[176:177]
	v_mov_b32_e32 v65, v177
	v_lshl_add_u64 v[68:69], v[68:69], 0, v[64:65]
	s_waitcnt lgkmcnt(0)
	v_cvt_pk_bf16_f32 v0, v33, v0
	global_store_dword v[68:69], v0, off
.LBB0_2304:
	s_or_b64 exec, exec, s[22:23]
	s_waitcnt lgkmcnt(0)
	s_nop 1
	v_mov_b32_dpp v0, v49 quad_perm:[1,0,3,2] row_mask:0xf bank_mask:0xf
	s_and_saveexec_b64 s[22:23], vcc
	s_cbranch_execz .LBB0_2306
	v_lshl_add_u64 v[32:33], s[0:1], 0, v[176:177]
	v_mov_b32_e32 v65, v177
	v_lshl_add_u64 v[32:33], v[32:33], 0, v[64:65]
	s_waitcnt lgkmcnt(0)
	v_cvt_pk_bf16_f32 v0, v49, v0
	global_store_dword v[32:33], v0, off offset:64
.LBB0_2306:
	s_or_b64 exec, exec, s[22:23]
	s_waitcnt lgkmcnt(0)
	s_nop 1
	v_mov_b32_dpp v0, v17 quad_perm:[1,0,3,2] row_mask:0xf bank_mask:0xf
	s_and_saveexec_b64 s[22:23], vcc
	s_cbranch_execz .LBB0_2308
	v_lshl_add_u64 v[32:33], s[0:1], 0, v[176:177]
	v_mov_b32_e32 v65, v177
	v_lshl_add_u64 v[32:33], v[32:33], 0, v[64:65]
	s_waitcnt lgkmcnt(0)
	v_cvt_pk_bf16_f32 v0, v17, v0
	global_store_dword v[32:33], v0, off offset:128
.LBB0_2308:
	s_or_b64 exec, exec, s[22:23]
	s_waitcnt lgkmcnt(0)
	s_nop 1
	v_mov_b32_dpp v0, v1 quad_perm:[1,0,3,2] row_mask:0xf bank_mask:0xf
	s_and_saveexec_b64 s[22:23], vcc
	s_cbranch_execz .LBB0_2310
	v_lshl_add_u64 v[16:17], s[0:1], 0, v[176:177]
	v_mov_b32_e32 v65, v177
	v_lshl_add_u64 v[16:17], v[16:17], 0, v[64:65]
	s_waitcnt lgkmcnt(0)
	v_cvt_pk_bf16_f32 v0, v1, v0
	global_store_dword v[16:17], v0, off offset:192
.LBB0_2310:
	s_or_b64 exec, exec, s[22:23]
	s_waitcnt lgkmcnt(0)
	s_nop 1
	v_mov_b32_dpp v0, v34 quad_perm:[1,0,3,2] row_mask:0xf bank_mask:0xf
	v_or_b32_e32 v1, 2, v187
	v_lshlrev_b32_e32 v176, 12, v1
	s_and_saveexec_b64 s[22:23], vcc
	s_cbranch_execz .LBB0_2312
	v_lshl_add_u64 v[16:17], s[0:1], 0, v[176:177]
	v_mov_b32_e32 v65, v177
	v_lshl_add_u64 v[16:17], v[16:17], 0, v[64:65]
	s_waitcnt lgkmcnt(0)
	v_cvt_pk_bf16_f32 v0, v34, v0
	global_store_dword v[16:17], v0, off
.LBB0_2312:
	s_or_b64 exec, exec, s[22:23]
	s_waitcnt lgkmcnt(0)
	s_nop 1
	v_mov_b32_dpp v0, v50 quad_perm:[1,0,3,2] row_mask:0xf bank_mask:0xf
	s_and_saveexec_b64 s[22:23], vcc
	s_cbranch_execz .LBB0_2314
	v_lshl_add_u64 v[16:17], s[0:1], 0, v[176:177]
	v_mov_b32_e32 v65, v177
	v_lshl_add_u64 v[16:17], v[16:17], 0, v[64:65]
	s_waitcnt lgkmcnt(0)
	v_cvt_pk_bf16_f32 v0, v50, v0
	global_store_dword v[16:17], v0, off offset:64
.LBB0_2314:
	s_or_b64 exec, exec, s[22:23]
	s_waitcnt lgkmcnt(0)
	s_nop 1
	v_mov_b32_dpp v0, v18 quad_perm:[1,0,3,2] row_mask:0xf bank_mask:0xf
	s_and_saveexec_b64 s[22:23], vcc
	s_cbranch_execz .LBB0_2316
	v_lshl_add_u64 v[16:17], s[0:1], 0, v[176:177]
	v_mov_b32_e32 v65, v177
	v_lshl_add_u64 v[16:17], v[16:17], 0, v[64:65]
	s_waitcnt lgkmcnt(0)
	v_cvt_pk_bf16_f32 v0, v18, v0
	global_store_dword v[16:17], v0, off offset:128
.LBB0_2316:
	s_or_b64 exec, exec, s[22:23]
	s_waitcnt lgkmcnt(0)
	s_nop 1
	v_mov_b32_dpp v0, v2 quad_perm:[1,0,3,2] row_mask:0xf bank_mask:0xf
	s_and_saveexec_b64 s[22:23], vcc
	s_cbranch_execz .LBB0_2318
	v_lshl_add_u64 v[16:17], s[0:1], 0, v[176:177]
	v_mov_b32_e32 v65, v177
	v_lshl_add_u64 v[16:17], v[16:17], 0, v[64:65]
	s_waitcnt lgkmcnt(0)
	v_cvt_pk_bf16_f32 v0, v2, v0
	global_store_dword v[16:17], v0, off offset:192
.LBB0_2318:
	s_or_b64 exec, exec, s[22:23]
	s_waitcnt lgkmcnt(0)
	s_nop 1
	v_mov_b32_dpp v0, v35 quad_perm:[1,0,3,2] row_mask:0xf bank_mask:0xf
	v_or_b32_e32 v1, 3, v187
	v_lshlrev_b32_e32 v176, 12, v1
	s_and_saveexec_b64 s[22:23], vcc
	s_cbranch_execz .LBB0_2320
	v_lshl_add_u64 v[16:17], s[0:1], 0, v[176:177]
	v_mov_b32_e32 v65, v177
	v_lshl_add_u64 v[16:17], v[16:17], 0, v[64:65]
	s_waitcnt lgkmcnt(0)
	v_cvt_pk_bf16_f32 v0, v35, v0
	global_store_dword v[16:17], v0, off
.LBB0_2320:
	s_or_b64 exec, exec, s[22:23]
	s_waitcnt lgkmcnt(0)
	s_nop 1
	v_mov_b32_dpp v0, v51 quad_perm:[1,0,3,2] row_mask:0xf bank_mask:0xf
	s_and_saveexec_b64 s[22:23], vcc
	s_cbranch_execz .LBB0_2322
	v_lshl_add_u64 v[16:17], s[0:1], 0, v[176:177]
	v_mov_b32_e32 v65, v177
	v_lshl_add_u64 v[16:17], v[16:17], 0, v[64:65]
	s_waitcnt lgkmcnt(0)
	v_cvt_pk_bf16_f32 v0, v51, v0
	global_store_dword v[16:17], v0, off offset:64
.LBB0_2322:
	s_or_b64 exec, exec, s[22:23]
	s_waitcnt lgkmcnt(0)
	s_nop 1
	v_mov_b32_dpp v0, v19 quad_perm:[1,0,3,2] row_mask:0xf bank_mask:0xf
	s_and_saveexec_b64 s[22:23], vcc
	s_cbranch_execz .LBB0_2324
	v_lshl_add_u64 v[16:17], s[0:1], 0, v[176:177]
	v_mov_b32_e32 v65, v177
	v_lshl_add_u64 v[16:17], v[16:17], 0, v[64:65]
	s_waitcnt lgkmcnt(0)
	v_cvt_pk_bf16_f32 v0, v19, v0
	global_store_dword v[16:17], v0, off offset:128
.LBB0_2324:
	s_or_b64 exec, exec, s[22:23]
	s_waitcnt lgkmcnt(0)
	s_nop 1
	v_mov_b32_dpp v0, v3 quad_perm:[1,0,3,2] row_mask:0xf bank_mask:0xf
	s_and_saveexec_b64 s[22:23], vcc
	s_cbranch_execz .LBB0_2326
	v_lshl_add_u64 v[16:17], s[0:1], 0, v[176:177]
	v_mov_b32_e32 v65, v177
	v_lshl_add_u64 v[16:17], v[16:17], 0, v[64:65]
	s_waitcnt lgkmcnt(0)
	v_cvt_pk_bf16_f32 v0, v3, v0
	global_store_dword v[16:17], v0, off offset:192
.LBB0_2326:
	s_or_b64 exec, exec, s[22:23]
	s_waitcnt lgkmcnt(0)
	s_nop 1
	v_mov_b32_dpp v0, v36 quad_perm:[1,0,3,2] row_mask:0xf bank_mask:0xf
	v_or_b32_e32 v1, 8, v187
	v_lshlrev_b32_e32 v176, 12, v1
	s_and_saveexec_b64 s[22:23], vcc
	s_cbranch_execz .LBB0_2328
	v_lshl_add_u64 v[2:3], s[0:1], 0, v[176:177]
	v_mov_b32_e32 v65, v177
	v_lshl_add_u64 v[2:3], v[2:3], 0, v[64:65]
	s_waitcnt lgkmcnt(0)
	v_cvt_pk_bf16_f32 v0, v36, v0
	global_store_dword v[2:3], v0, off
.LBB0_2328:
	s_or_b64 exec, exec, s[22:23]
	s_waitcnt lgkmcnt(0)
	s_nop 1
	v_mov_b32_dpp v0, v52 quad_perm:[1,0,3,2] row_mask:0xf bank_mask:0xf
	s_and_saveexec_b64 s[22:23], vcc
	s_cbranch_execz .LBB0_2330
	v_lshl_add_u64 v[2:3], s[0:1], 0, v[176:177]
	v_mov_b32_e32 v65, v177
	v_lshl_add_u64 v[2:3], v[2:3], 0, v[64:65]
	s_waitcnt lgkmcnt(0)
	v_cvt_pk_bf16_f32 v0, v52, v0
	global_store_dword v[2:3], v0, off offset:64
.LBB0_2330:
	s_or_b64 exec, exec, s[22:23]
	s_waitcnt lgkmcnt(0)
	s_nop 1
	v_mov_b32_dpp v0, v20 quad_perm:[1,0,3,2] row_mask:0xf bank_mask:0xf
	s_and_saveexec_b64 s[22:23], vcc
	s_cbranch_execz .LBB0_2332
	v_lshl_add_u64 v[2:3], s[0:1], 0, v[176:177]
	v_mov_b32_e32 v65, v177
	v_lshl_add_u64 v[2:3], v[2:3], 0, v[64:65]
	s_waitcnt lgkmcnt(0)
	v_cvt_pk_bf16_f32 v0, v20, v0
	global_store_dword v[2:3], v0, off offset:128
.LBB0_2332:
	s_or_b64 exec, exec, s[22:23]
	s_waitcnt lgkmcnt(0)
	s_nop 1
	v_mov_b32_dpp v0, v4 quad_perm:[1,0,3,2] row_mask:0xf bank_mask:0xf
	s_and_saveexec_b64 s[22:23], vcc
	s_cbranch_execz .LBB0_2334
	v_lshl_add_u64 v[2:3], s[0:1], 0, v[176:177]
	v_mov_b32_e32 v65, v177
	v_lshl_add_u64 v[2:3], v[2:3], 0, v[64:65]
	s_waitcnt lgkmcnt(0)
	v_cvt_pk_bf16_f32 v0, v4, v0
	global_store_dword v[2:3], v0, off offset:192
.LBB0_2334:
	s_or_b64 exec, exec, s[22:23]
	s_waitcnt lgkmcnt(0)
	s_nop 1
	v_mov_b32_dpp v0, v37 quad_perm:[1,0,3,2] row_mask:0xf bank_mask:0xf
	v_or_b32_e32 v1, 9, v187
	v_lshlrev_b32_e32 v176, 12, v1
	s_and_saveexec_b64 s[22:23], vcc
	s_cbranch_execz .LBB0_2336
	v_lshl_add_u64 v[2:3], s[0:1], 0, v[176:177]
	v_mov_b32_e32 v65, v177
	v_lshl_add_u64 v[2:3], v[2:3], 0, v[64:65]
	s_waitcnt lgkmcnt(0)
	v_cvt_pk_bf16_f32 v0, v37, v0
	global_store_dword v[2:3], v0, off
.LBB0_2336:
	s_or_b64 exec, exec, s[22:23]
	s_waitcnt lgkmcnt(0)
	s_nop 1
	v_mov_b32_dpp v0, v53 quad_perm:[1,0,3,2] row_mask:0xf bank_mask:0xf
	s_and_saveexec_b64 s[22:23], vcc
	s_cbranch_execz .LBB0_2338
	v_lshl_add_u64 v[2:3], s[0:1], 0, v[176:177]
	v_mov_b32_e32 v65, v177
	v_lshl_add_u64 v[2:3], v[2:3], 0, v[64:65]
	s_waitcnt lgkmcnt(0)
	v_cvt_pk_bf16_f32 v0, v53, v0
	global_store_dword v[2:3], v0, off offset:64
.LBB0_2338:
	s_or_b64 exec, exec, s[22:23]
	s_waitcnt lgkmcnt(0)
	s_nop 1
	v_mov_b32_dpp v0, v21 quad_perm:[1,0,3,2] row_mask:0xf bank_mask:0xf
	s_and_saveexec_b64 s[22:23], vcc
	s_cbranch_execz .LBB0_2340
	v_lshl_add_u64 v[2:3], s[0:1], 0, v[176:177]
	v_mov_b32_e32 v65, v177
	v_lshl_add_u64 v[2:3], v[2:3], 0, v[64:65]
	s_waitcnt lgkmcnt(0)
	v_cvt_pk_bf16_f32 v0, v21, v0
	global_store_dword v[2:3], v0, off offset:128
.LBB0_2340:
	s_or_b64 exec, exec, s[22:23]
	s_waitcnt lgkmcnt(0)
	s_nop 1
	v_mov_b32_dpp v0, v5 quad_perm:[1,0,3,2] row_mask:0xf bank_mask:0xf
	s_and_saveexec_b64 s[22:23], vcc
	s_cbranch_execz .LBB0_2342
	v_lshl_add_u64 v[2:3], s[0:1], 0, v[176:177]
	v_mov_b32_e32 v65, v177
	v_lshl_add_u64 v[2:3], v[2:3], 0, v[64:65]
	s_waitcnt lgkmcnt(0)
	v_cvt_pk_bf16_f32 v0, v5, v0
	global_store_dword v[2:3], v0, off offset:192
.LBB0_2342:
	s_or_b64 exec, exec, s[22:23]
	s_waitcnt lgkmcnt(0)
	s_nop 1
	v_mov_b32_dpp v0, v38 quad_perm:[1,0,3,2] row_mask:0xf bank_mask:0xf
	v_or_b32_e32 v1, 10, v187
	v_lshlrev_b32_e32 v176, 12, v1
	s_and_saveexec_b64 s[22:23], vcc
	s_cbranch_execz .LBB0_2344
	v_lshl_add_u64 v[2:3], s[0:1], 0, v[176:177]
	v_mov_b32_e32 v65, v177
	v_lshl_add_u64 v[2:3], v[2:3], 0, v[64:65]
	s_waitcnt lgkmcnt(0)
	v_cvt_pk_bf16_f32 v0, v38, v0
	global_store_dword v[2:3], v0, off
.LBB0_2344:
	s_or_b64 exec, exec, s[22:23]
	s_waitcnt lgkmcnt(0)
	s_nop 1
	v_mov_b32_dpp v0, v54 quad_perm:[1,0,3,2] row_mask:0xf bank_mask:0xf
	s_and_saveexec_b64 s[22:23], vcc
	s_cbranch_execz .LBB0_2346
	v_lshl_add_u64 v[2:3], s[0:1], 0, v[176:177]
	v_mov_b32_e32 v65, v177
	v_lshl_add_u64 v[2:3], v[2:3], 0, v[64:65]
	s_waitcnt lgkmcnt(0)
	v_cvt_pk_bf16_f32 v0, v54, v0
	global_store_dword v[2:3], v0, off offset:64
.LBB0_2346:
	s_or_b64 exec, exec, s[22:23]
	s_waitcnt lgkmcnt(0)
	s_nop 1
	v_mov_b32_dpp v0, v22 quad_perm:[1,0,3,2] row_mask:0xf bank_mask:0xf
	s_and_saveexec_b64 s[22:23], vcc
	s_cbranch_execz .LBB0_2348
	v_lshl_add_u64 v[2:3], s[0:1], 0, v[176:177]
	v_mov_b32_e32 v65, v177
	v_lshl_add_u64 v[2:3], v[2:3], 0, v[64:65]
	s_waitcnt lgkmcnt(0)
	v_cvt_pk_bf16_f32 v0, v22, v0
	global_store_dword v[2:3], v0, off offset:128
.LBB0_2348:
	s_or_b64 exec, exec, s[22:23]
	s_waitcnt lgkmcnt(0)
	s_nop 1
	v_mov_b32_dpp v0, v6 quad_perm:[1,0,3,2] row_mask:0xf bank_mask:0xf
	s_and_saveexec_b64 s[22:23], vcc
	s_cbranch_execz .LBB0_2350
	v_lshl_add_u64 v[2:3], s[0:1], 0, v[176:177]
	v_mov_b32_e32 v65, v177
	v_lshl_add_u64 v[2:3], v[2:3], 0, v[64:65]
	s_waitcnt lgkmcnt(0)
	v_cvt_pk_bf16_f32 v0, v6, v0
	global_store_dword v[2:3], v0, off offset:192
.LBB0_2350:
	s_or_b64 exec, exec, s[22:23]
	s_waitcnt lgkmcnt(0)
	s_nop 1
	v_mov_b32_dpp v0, v39 quad_perm:[1,0,3,2] row_mask:0xf bank_mask:0xf
	v_or_b32_e32 v1, 11, v187
	v_lshlrev_b32_e32 v176, 12, v1
	s_and_saveexec_b64 s[22:23], vcc
	s_cbranch_execz .LBB0_2352
	v_lshl_add_u64 v[2:3], s[0:1], 0, v[176:177]
	v_mov_b32_e32 v65, v177
	v_lshl_add_u64 v[2:3], v[2:3], 0, v[64:65]
	s_waitcnt lgkmcnt(0)
	v_cvt_pk_bf16_f32 v0, v39, v0
	global_store_dword v[2:3], v0, off
.LBB0_2352:
	s_or_b64 exec, exec, s[22:23]
	s_waitcnt lgkmcnt(0)
	s_nop 1
	v_mov_b32_dpp v0, v55 quad_perm:[1,0,3,2] row_mask:0xf bank_mask:0xf
	s_and_saveexec_b64 s[22:23], vcc
	s_cbranch_execz .LBB0_2354
	v_lshl_add_u64 v[2:3], s[0:1], 0, v[176:177]
	v_mov_b32_e32 v65, v177
	v_lshl_add_u64 v[2:3], v[2:3], 0, v[64:65]
	s_waitcnt lgkmcnt(0)
	v_cvt_pk_bf16_f32 v0, v55, v0
	global_store_dword v[2:3], v0, off offset:64
.LBB0_2354:
	s_or_b64 exec, exec, s[22:23]
	s_waitcnt lgkmcnt(0)
	s_nop 1
	v_mov_b32_dpp v0, v23 quad_perm:[1,0,3,2] row_mask:0xf bank_mask:0xf
	s_and_saveexec_b64 s[22:23], vcc
	s_cbranch_execz .LBB0_2356
	v_lshl_add_u64 v[2:3], s[0:1], 0, v[176:177]
	v_mov_b32_e32 v65, v177
	v_lshl_add_u64 v[2:3], v[2:3], 0, v[64:65]
	s_waitcnt lgkmcnt(0)
	v_cvt_pk_bf16_f32 v0, v23, v0
	global_store_dword v[2:3], v0, off offset:128
.LBB0_2356:
	s_or_b64 exec, exec, s[22:23]
	s_waitcnt lgkmcnt(0)
	s_nop 1
	v_mov_b32_dpp v0, v7 quad_perm:[1,0,3,2] row_mask:0xf bank_mask:0xf
	s_and_saveexec_b64 s[22:23], vcc
	s_cbranch_execz .LBB0_2358
	v_lshl_add_u64 v[2:3], s[0:1], 0, v[176:177]
	v_mov_b32_e32 v65, v177
	v_lshl_add_u64 v[2:3], v[2:3], 0, v[64:65]
	s_waitcnt lgkmcnt(0)
	v_cvt_pk_bf16_f32 v0, v7, v0
	global_store_dword v[2:3], v0, off offset:192
.LBB0_2358:
	s_or_b64 exec, exec, s[22:23]
	s_waitcnt lgkmcnt(0)
	s_nop 1
	v_mov_b32_dpp v0, v40 quad_perm:[1,0,3,2] row_mask:0xf bank_mask:0xf
	v_or_b32_e32 v1, 16, v187
	v_lshlrev_b32_e32 v176, 12, v1
	s_and_saveexec_b64 s[22:23], vcc
	s_cbranch_execz .LBB0_2360
	v_lshl_add_u64 v[2:3], s[0:1], 0, v[176:177]
	v_mov_b32_e32 v65, v177
	v_lshl_add_u64 v[2:3], v[2:3], 0, v[64:65]
	s_waitcnt lgkmcnt(0)
	v_cvt_pk_bf16_f32 v0, v40, v0
	global_store_dword v[2:3], v0, off
.LBB0_2360:
	s_or_b64 exec, exec, s[22:23]
	s_waitcnt lgkmcnt(0)
	s_nop 1
	v_mov_b32_dpp v0, v56 quad_perm:[1,0,3,2] row_mask:0xf bank_mask:0xf
	s_and_saveexec_b64 s[22:23], vcc
	s_cbranch_execz .LBB0_2362
	v_lshl_add_u64 v[2:3], s[0:1], 0, v[176:177]
	v_mov_b32_e32 v65, v177
	v_lshl_add_u64 v[2:3], v[2:3], 0, v[64:65]
	s_waitcnt lgkmcnt(0)
	v_cvt_pk_bf16_f32 v0, v56, v0
	global_store_dword v[2:3], v0, off offset:64
.LBB0_2362:
	s_or_b64 exec, exec, s[22:23]
	s_waitcnt lgkmcnt(0)
	s_nop 1
	v_mov_b32_dpp v0, v24 quad_perm:[1,0,3,2] row_mask:0xf bank_mask:0xf
	s_and_saveexec_b64 s[22:23], vcc
	s_cbranch_execz .LBB0_2364
	v_lshl_add_u64 v[2:3], s[0:1], 0, v[176:177]
	v_mov_b32_e32 v65, v177
	v_lshl_add_u64 v[2:3], v[2:3], 0, v[64:65]
	s_waitcnt lgkmcnt(0)
	v_cvt_pk_bf16_f32 v0, v24, v0
	global_store_dword v[2:3], v0, off offset:128
.LBB0_2364:
	s_or_b64 exec, exec, s[22:23]
	s_waitcnt lgkmcnt(0)
	s_nop 1
	v_mov_b32_dpp v0, v8 quad_perm:[1,0,3,2] row_mask:0xf bank_mask:0xf
	s_and_saveexec_b64 s[22:23], vcc
	s_cbranch_execz .LBB0_2366
	v_lshl_add_u64 v[2:3], s[0:1], 0, v[176:177]
	v_mov_b32_e32 v65, v177
	v_lshl_add_u64 v[2:3], v[2:3], 0, v[64:65]
	s_waitcnt lgkmcnt(0)
	v_cvt_pk_bf16_f32 v0, v8, v0
	global_store_dword v[2:3], v0, off offset:192
.LBB0_2366:
	s_or_b64 exec, exec, s[22:23]
	s_waitcnt lgkmcnt(0)
	s_nop 1
	v_mov_b32_dpp v0, v41 quad_perm:[1,0,3,2] row_mask:0xf bank_mask:0xf
	v_or_b32_e32 v1, 17, v187
	v_lshlrev_b32_e32 v176, 12, v1
	s_and_saveexec_b64 s[22:23], vcc
	s_cbranch_execz .LBB0_2368
	v_lshl_add_u64 v[2:3], s[0:1], 0, v[176:177]
	v_mov_b32_e32 v65, v177
	v_lshl_add_u64 v[2:3], v[2:3], 0, v[64:65]
	s_waitcnt lgkmcnt(0)
	v_cvt_pk_bf16_f32 v0, v41, v0
	global_store_dword v[2:3], v0, off
.LBB0_2368:
	s_or_b64 exec, exec, s[22:23]
	s_waitcnt lgkmcnt(0)
	s_nop 1
	v_mov_b32_dpp v0, v57 quad_perm:[1,0,3,2] row_mask:0xf bank_mask:0xf
	s_and_saveexec_b64 s[22:23], vcc
	s_cbranch_execz .LBB0_2370
	v_lshl_add_u64 v[2:3], s[0:1], 0, v[176:177]
	v_mov_b32_e32 v65, v177
	v_lshl_add_u64 v[2:3], v[2:3], 0, v[64:65]
	s_waitcnt lgkmcnt(0)
	v_cvt_pk_bf16_f32 v0, v57, v0
	global_store_dword v[2:3], v0, off offset:64
.LBB0_2370:
	s_or_b64 exec, exec, s[22:23]
	s_waitcnt lgkmcnt(0)
	s_nop 1
	v_mov_b32_dpp v0, v25 quad_perm:[1,0,3,2] row_mask:0xf bank_mask:0xf
	s_and_saveexec_b64 s[22:23], vcc
	s_cbranch_execz .LBB0_2372
	v_lshl_add_u64 v[2:3], s[0:1], 0, v[176:177]
	v_mov_b32_e32 v65, v177
	v_lshl_add_u64 v[2:3], v[2:3], 0, v[64:65]
	s_waitcnt lgkmcnt(0)
	v_cvt_pk_bf16_f32 v0, v25, v0
	global_store_dword v[2:3], v0, off offset:128
.LBB0_2372:
	s_or_b64 exec, exec, s[22:23]
	s_waitcnt lgkmcnt(0)
	s_nop 1
	v_mov_b32_dpp v0, v9 quad_perm:[1,0,3,2] row_mask:0xf bank_mask:0xf
	s_and_saveexec_b64 s[22:23], vcc
	s_cbranch_execz .LBB0_2374
	v_lshl_add_u64 v[2:3], s[0:1], 0, v[176:177]
	v_mov_b32_e32 v65, v177
	v_lshl_add_u64 v[2:3], v[2:3], 0, v[64:65]
	s_waitcnt lgkmcnt(0)
	v_cvt_pk_bf16_f32 v0, v9, v0
	global_store_dword v[2:3], v0, off offset:192
.LBB0_2374:
	s_or_b64 exec, exec, s[22:23]
	s_waitcnt lgkmcnt(0)
	s_nop 1
	v_mov_b32_dpp v0, v42 quad_perm:[1,0,3,2] row_mask:0xf bank_mask:0xf
	v_or_b32_e32 v1, 18, v187
	v_lshlrev_b32_e32 v176, 12, v1
	s_and_saveexec_b64 s[22:23], vcc
	s_cbranch_execz .LBB0_2376
	v_lshl_add_u64 v[2:3], s[0:1], 0, v[176:177]
	v_mov_b32_e32 v65, v177
	v_lshl_add_u64 v[2:3], v[2:3], 0, v[64:65]
	s_waitcnt lgkmcnt(0)
	v_cvt_pk_bf16_f32 v0, v42, v0
	global_store_dword v[2:3], v0, off
.LBB0_2376:
	s_or_b64 exec, exec, s[22:23]
	s_waitcnt lgkmcnt(0)
	s_nop 1
	v_mov_b32_dpp v0, v58 quad_perm:[1,0,3,2] row_mask:0xf bank_mask:0xf
	s_and_saveexec_b64 s[22:23], vcc
	s_cbranch_execz .LBB0_2378
	v_lshl_add_u64 v[2:3], s[0:1], 0, v[176:177]
	v_mov_b32_e32 v65, v177
	v_lshl_add_u64 v[2:3], v[2:3], 0, v[64:65]
	s_waitcnt lgkmcnt(0)
	v_cvt_pk_bf16_f32 v0, v58, v0
	global_store_dword v[2:3], v0, off offset:64
.LBB0_2378:
	s_or_b64 exec, exec, s[22:23]
	s_waitcnt lgkmcnt(0)
	s_nop 1
	v_mov_b32_dpp v0, v26 quad_perm:[1,0,3,2] row_mask:0xf bank_mask:0xf
	s_and_saveexec_b64 s[22:23], vcc
	s_cbranch_execz .LBB0_2380
	v_lshl_add_u64 v[2:3], s[0:1], 0, v[176:177]
	v_mov_b32_e32 v65, v177
	v_lshl_add_u64 v[2:3], v[2:3], 0, v[64:65]
	s_waitcnt lgkmcnt(0)
	v_cvt_pk_bf16_f32 v0, v26, v0
	global_store_dword v[2:3], v0, off offset:128
.LBB0_2380:
	s_or_b64 exec, exec, s[22:23]
	s_waitcnt lgkmcnt(0)
	s_nop 1
	v_mov_b32_dpp v0, v10 quad_perm:[1,0,3,2] row_mask:0xf bank_mask:0xf
	s_and_saveexec_b64 s[22:23], vcc
	s_cbranch_execz .LBB0_2382
	v_lshl_add_u64 v[2:3], s[0:1], 0, v[176:177]
	v_mov_b32_e32 v65, v177
	v_lshl_add_u64 v[2:3], v[2:3], 0, v[64:65]
	s_waitcnt lgkmcnt(0)
	v_cvt_pk_bf16_f32 v0, v10, v0
	global_store_dword v[2:3], v0, off offset:192
.LBB0_2382:
	s_or_b64 exec, exec, s[22:23]
	s_waitcnt lgkmcnt(0)
	s_nop 1
	v_mov_b32_dpp v0, v43 quad_perm:[1,0,3,2] row_mask:0xf bank_mask:0xf
	v_or_b32_e32 v1, 19, v187
	v_lshlrev_b32_e32 v176, 12, v1
	s_and_saveexec_b64 s[22:23], vcc
	s_cbranch_execz .LBB0_2384
	v_lshl_add_u64 v[2:3], s[0:1], 0, v[176:177]
	v_mov_b32_e32 v65, v177
	v_lshl_add_u64 v[2:3], v[2:3], 0, v[64:65]
	s_waitcnt lgkmcnt(0)
	v_cvt_pk_bf16_f32 v0, v43, v0
	global_store_dword v[2:3], v0, off
.LBB0_2384:
	s_or_b64 exec, exec, s[22:23]
	s_waitcnt lgkmcnt(0)
	s_nop 1
	v_mov_b32_dpp v0, v59 quad_perm:[1,0,3,2] row_mask:0xf bank_mask:0xf
	s_and_saveexec_b64 s[22:23], vcc
	s_cbranch_execz .LBB0_2386
	v_lshl_add_u64 v[2:3], s[0:1], 0, v[176:177]
	v_mov_b32_e32 v65, v177
	v_lshl_add_u64 v[2:3], v[2:3], 0, v[64:65]
	s_waitcnt lgkmcnt(0)
	v_cvt_pk_bf16_f32 v0, v59, v0
	global_store_dword v[2:3], v0, off offset:64
.LBB0_2386:
	s_or_b64 exec, exec, s[22:23]
	s_waitcnt lgkmcnt(0)
	s_nop 1
	v_mov_b32_dpp v0, v27 quad_perm:[1,0,3,2] row_mask:0xf bank_mask:0xf
	s_and_saveexec_b64 s[22:23], vcc
	s_cbranch_execz .LBB0_2388
	v_lshl_add_u64 v[2:3], s[0:1], 0, v[176:177]
	v_mov_b32_e32 v65, v177
	v_lshl_add_u64 v[2:3], v[2:3], 0, v[64:65]
	s_waitcnt lgkmcnt(0)
	v_cvt_pk_bf16_f32 v0, v27, v0
	global_store_dword v[2:3], v0, off offset:128
.LBB0_2388:
	s_or_b64 exec, exec, s[22:23]
	s_waitcnt lgkmcnt(0)
	s_nop 1
	v_mov_b32_dpp v0, v11 quad_perm:[1,0,3,2] row_mask:0xf bank_mask:0xf
	s_and_saveexec_b64 s[22:23], vcc
	s_cbranch_execz .LBB0_2390
	v_lshl_add_u64 v[2:3], s[0:1], 0, v[176:177]
	v_mov_b32_e32 v65, v177
	v_lshl_add_u64 v[2:3], v[2:3], 0, v[64:65]
	s_waitcnt lgkmcnt(0)
	v_cvt_pk_bf16_f32 v0, v11, v0
	global_store_dword v[2:3], v0, off offset:192
.LBB0_2390:
	s_or_b64 exec, exec, s[22:23]
	s_waitcnt lgkmcnt(0)
	s_nop 1
	v_mov_b32_dpp v0, v44 quad_perm:[1,0,3,2] row_mask:0xf bank_mask:0xf
	v_or_b32_e32 v1, 24, v187
	v_lshlrev_b32_e32 v176, 12, v1
	s_and_saveexec_b64 s[22:23], vcc
	s_cbranch_execz .LBB0_2392
	v_lshl_add_u64 v[2:3], s[0:1], 0, v[176:177]
	v_mov_b32_e32 v65, v177
	v_lshl_add_u64 v[2:3], v[2:3], 0, v[64:65]
	s_waitcnt lgkmcnt(0)
	v_cvt_pk_bf16_f32 v0, v44, v0
	global_store_dword v[2:3], v0, off
.LBB0_2392:
	s_or_b64 exec, exec, s[22:23]
	s_waitcnt lgkmcnt(0)
	s_nop 1
	v_mov_b32_dpp v0, v60 quad_perm:[1,0,3,2] row_mask:0xf bank_mask:0xf
	s_and_saveexec_b64 s[22:23], vcc
	s_cbranch_execz .LBB0_2394
	v_lshl_add_u64 v[2:3], s[0:1], 0, v[176:177]
	v_mov_b32_e32 v65, v177
	v_lshl_add_u64 v[2:3], v[2:3], 0, v[64:65]
	s_waitcnt lgkmcnt(0)
	v_cvt_pk_bf16_f32 v0, v60, v0
	global_store_dword v[2:3], v0, off offset:64
.LBB0_2394:
	s_or_b64 exec, exec, s[22:23]
	s_waitcnt lgkmcnt(0)
	s_nop 1
	v_mov_b32_dpp v0, v28 quad_perm:[1,0,3,2] row_mask:0xf bank_mask:0xf
	s_and_saveexec_b64 s[22:23], vcc
	s_cbranch_execz .LBB0_2396
	v_lshl_add_u64 v[2:3], s[0:1], 0, v[176:177]
	v_mov_b32_e32 v65, v177
	v_lshl_add_u64 v[2:3], v[2:3], 0, v[64:65]
	s_waitcnt lgkmcnt(0)
	v_cvt_pk_bf16_f32 v0, v28, v0
	global_store_dword v[2:3], v0, off offset:128
.LBB0_2396:
	s_or_b64 exec, exec, s[22:23]
	s_waitcnt lgkmcnt(0)
	s_nop 1
	v_mov_b32_dpp v0, v12 quad_perm:[1,0,3,2] row_mask:0xf bank_mask:0xf
	s_and_saveexec_b64 s[22:23], vcc
	s_cbranch_execz .LBB0_2398
	v_lshl_add_u64 v[2:3], s[0:1], 0, v[176:177]
	v_mov_b32_e32 v65, v177
	v_lshl_add_u64 v[2:3], v[2:3], 0, v[64:65]
	s_waitcnt lgkmcnt(0)
	v_cvt_pk_bf16_f32 v0, v12, v0
	global_store_dword v[2:3], v0, off offset:192
.LBB0_2398:
	s_or_b64 exec, exec, s[22:23]
	s_waitcnt lgkmcnt(0)
	s_nop 1
	v_mov_b32_dpp v0, v45 quad_perm:[1,0,3,2] row_mask:0xf bank_mask:0xf
	v_or_b32_e32 v1, 25, v187
	v_lshlrev_b32_e32 v176, 12, v1
	s_and_saveexec_b64 s[22:23], vcc
	s_cbranch_execz .LBB0_2400
	v_lshl_add_u64 v[2:3], s[0:1], 0, v[176:177]
	v_mov_b32_e32 v65, v177
	v_lshl_add_u64 v[2:3], v[2:3], 0, v[64:65]
	s_waitcnt lgkmcnt(0)
	v_cvt_pk_bf16_f32 v0, v45, v0
	global_store_dword v[2:3], v0, off
.LBB0_2400:
	s_or_b64 exec, exec, s[22:23]
	s_waitcnt lgkmcnt(0)
	s_nop 1
	v_mov_b32_dpp v0, v61 quad_perm:[1,0,3,2] row_mask:0xf bank_mask:0xf
	s_and_saveexec_b64 s[22:23], vcc
	s_cbranch_execz .LBB0_2402
	v_lshl_add_u64 v[2:3], s[0:1], 0, v[176:177]
	v_mov_b32_e32 v65, v177
	v_lshl_add_u64 v[2:3], v[2:3], 0, v[64:65]
	s_waitcnt lgkmcnt(0)
	v_cvt_pk_bf16_f32 v0, v61, v0
	global_store_dword v[2:3], v0, off offset:64
.LBB0_2402:
	s_or_b64 exec, exec, s[22:23]
	s_waitcnt lgkmcnt(0)
	s_nop 1
	v_mov_b32_dpp v0, v29 quad_perm:[1,0,3,2] row_mask:0xf bank_mask:0xf
	s_and_saveexec_b64 s[22:23], vcc
	s_cbranch_execz .LBB0_2404
	v_lshl_add_u64 v[2:3], s[0:1], 0, v[176:177]
	v_mov_b32_e32 v65, v177
	v_lshl_add_u64 v[2:3], v[2:3], 0, v[64:65]
	s_waitcnt lgkmcnt(0)
	v_cvt_pk_bf16_f32 v0, v29, v0
	global_store_dword v[2:3], v0, off offset:128
.LBB0_2404:
	s_or_b64 exec, exec, s[22:23]
	s_waitcnt lgkmcnt(0)
	s_nop 1
	v_mov_b32_dpp v0, v13 quad_perm:[1,0,3,2] row_mask:0xf bank_mask:0xf
	s_and_saveexec_b64 s[22:23], vcc
	s_cbranch_execz .LBB0_2406
	v_lshl_add_u64 v[2:3], s[0:1], 0, v[176:177]
	v_mov_b32_e32 v65, v177
	v_lshl_add_u64 v[2:3], v[2:3], 0, v[64:65]
	s_waitcnt lgkmcnt(0)
	v_cvt_pk_bf16_f32 v0, v13, v0
	global_store_dword v[2:3], v0, off offset:192
.LBB0_2406:
	s_or_b64 exec, exec, s[22:23]
	s_waitcnt lgkmcnt(0)
	s_nop 1
	v_mov_b32_dpp v0, v46 quad_perm:[1,0,3,2] row_mask:0xf bank_mask:0xf
	v_or_b32_e32 v1, 26, v187
	v_lshlrev_b32_e32 v176, 12, v1
	s_and_saveexec_b64 s[22:23], vcc
	s_cbranch_execz .LBB0_2408
	v_lshl_add_u64 v[2:3], s[0:1], 0, v[176:177]
	v_mov_b32_e32 v65, v177
	v_lshl_add_u64 v[2:3], v[2:3], 0, v[64:65]
	s_waitcnt lgkmcnt(0)
	v_cvt_pk_bf16_f32 v0, v46, v0
	global_store_dword v[2:3], v0, off
.LBB0_2408:
	s_or_b64 exec, exec, s[22:23]
	s_waitcnt lgkmcnt(0)
	s_nop 1
	v_mov_b32_dpp v0, v62 quad_perm:[1,0,3,2] row_mask:0xf bank_mask:0xf
	s_and_saveexec_b64 s[22:23], vcc
	s_cbranch_execz .LBB0_2410
	v_lshl_add_u64 v[2:3], s[0:1], 0, v[176:177]
	v_mov_b32_e32 v65, v177
	v_lshl_add_u64 v[2:3], v[2:3], 0, v[64:65]
	s_waitcnt lgkmcnt(0)
	v_cvt_pk_bf16_f32 v0, v62, v0
	global_store_dword v[2:3], v0, off offset:64
.LBB0_2410:
	s_or_b64 exec, exec, s[22:23]
	s_waitcnt lgkmcnt(0)
	s_nop 1
	v_mov_b32_dpp v0, v30 quad_perm:[1,0,3,2] row_mask:0xf bank_mask:0xf
	s_and_saveexec_b64 s[22:23], vcc
	s_cbranch_execz .LBB0_2412
	v_lshl_add_u64 v[2:3], s[0:1], 0, v[176:177]
	v_mov_b32_e32 v65, v177
	v_lshl_add_u64 v[2:3], v[2:3], 0, v[64:65]
	s_waitcnt lgkmcnt(0)
	v_cvt_pk_bf16_f32 v0, v30, v0
	global_store_dword v[2:3], v0, off offset:128
.LBB0_2412:
	s_or_b64 exec, exec, s[22:23]
	s_waitcnt lgkmcnt(0)
	s_nop 1
	v_mov_b32_dpp v0, v14 quad_perm:[1,0,3,2] row_mask:0xf bank_mask:0xf
	s_and_saveexec_b64 s[22:23], vcc
	s_cbranch_execz .LBB0_2414
	v_lshl_add_u64 v[2:3], s[0:1], 0, v[176:177]
	v_mov_b32_e32 v65, v177
	v_lshl_add_u64 v[2:3], v[2:3], 0, v[64:65]
	s_waitcnt lgkmcnt(0)
	v_cvt_pk_bf16_f32 v0, v14, v0
	global_store_dword v[2:3], v0, off offset:192
.LBB0_2414:
	s_or_b64 exec, exec, s[22:23]
	s_waitcnt lgkmcnt(0)
	s_nop 1
	v_mov_b32_dpp v0, v47 quad_perm:[1,0,3,2] row_mask:0xf bank_mask:0xf
	v_or_b32_e32 v1, 27, v187
	v_lshlrev_b32_e32 v176, 12, v1
	s_and_saveexec_b64 s[22:23], vcc
	s_cbranch_execz .LBB0_2416
	v_lshl_add_u64 v[2:3], s[0:1], 0, v[176:177]
	v_mov_b32_e32 v65, v177
	v_lshl_add_u64 v[2:3], v[2:3], 0, v[64:65]
	s_waitcnt lgkmcnt(0)
	v_cvt_pk_bf16_f32 v0, v47, v0
	global_store_dword v[2:3], v0, off
.LBB0_2416:
	s_or_b64 exec, exec, s[22:23]
	s_waitcnt lgkmcnt(0)
	s_nop 1
	v_mov_b32_dpp v0, v63 quad_perm:[1,0,3,2] row_mask:0xf bank_mask:0xf
	s_and_saveexec_b64 s[22:23], vcc
	s_cbranch_execz .LBB0_2418
	v_lshl_add_u64 v[2:3], s[0:1], 0, v[176:177]
	v_mov_b32_e32 v65, v177
	v_lshl_add_u64 v[2:3], v[2:3], 0, v[64:65]
	s_waitcnt lgkmcnt(0)
	v_cvt_pk_bf16_f32 v0, v63, v0
	global_store_dword v[2:3], v0, off offset:64
.LBB0_2418:
	s_or_b64 exec, exec, s[22:23]
	s_waitcnt lgkmcnt(0)
	s_nop 1
	v_mov_b32_dpp v0, v31 quad_perm:[1,0,3,2] row_mask:0xf bank_mask:0xf
	s_and_saveexec_b64 s[22:23], vcc
	s_cbranch_execz .LBB0_2420
	v_lshl_add_u64 v[2:3], s[0:1], 0, v[176:177]
	v_mov_b32_e32 v65, v177
	v_lshl_add_u64 v[2:3], v[2:3], 0, v[64:65]
	s_waitcnt lgkmcnt(0)
	v_cvt_pk_bf16_f32 v0, v31, v0
	global_store_dword v[2:3], v0, off offset:128
.LBB0_2420:
	s_or_b64 exec, exec, s[22:23]
	s_waitcnt lgkmcnt(0)
	s_nop 1
	v_mov_b32_dpp v0, v15 quad_perm:[1,0,3,2] row_mask:0xf bank_mask:0xf
	s_and_saveexec_b64 s[22:23], vcc
	s_cbranch_execz .LBB0_2263
	v_lshl_add_u64 v[2:3], s[0:1], 0, v[176:177]
	v_mov_b32_e32 v65, v177
	v_lshl_add_u64 v[2:3], v[2:3], 0, v[64:65]
	s_waitcnt lgkmcnt(0)
	v_cvt_pk_bf16_f32 v0, v15, v0
	global_store_dword v[2:3], v0, off offset:192
	s_branch .LBB0_2263

.LBB0_2532:
	s_and_b64 vcc, exec, s[22:23]
	s_cbranch_vccz .LBB0_2426
	v_cmp_gt_u32_e32 vcc, 32, v226
	s_and_saveexec_b64 s[20:21], vcc
	v_lshl_add_u32 v0, v225, 2, s1
	ds_write_b32 v0, v80
	s_or_b64 exec, exec, s[20:21]
	v_and_b32_e32 v2, 64, v204
	v_xor_b32_e32 v0, 1, v204
	v_add_u32_e32 v2, 64, v2
	s_ashr_i32 s1, s0, 31
	v_cmp_lt_i32_e32 vcc, v0, v2
	s_lshl_b64 s[0:1], s[0:1], 12
	s_add_u32 s0, s44, s0
	v_cndmask_b32_e32 v0, v204, v0, vcc
	v_lshlrev_b32_e32 v6, 2, v0
	v_and_b32_e32 v0, 1, v224
	s_waitcnt lgkmcnt(0)
	s_addc_u32 s1, s45, s1
	v_cmp_eq_u32_e32 vcc, 0, v0
	v_lshlrev_b32_e32 v0, 1, v225
	v_lshl_add_u64 v[2:3], s[0:1], 0, v[0:1]
	ds_read_b32 v0, v222
	s_waitcnt lgkmcnt(0)
	v_rcp_f32_e32 v7, v0
	v_lshlrev_b32_e32 v0, 14, v223
	v_lshl_add_u64 v[4:5], v[2:3], 0, v[0:1]
	v_mul_f32_e32 v0, v64, v7
	s_nop 1
	v_mov_b32_dpp v8, v0 quad_perm:[1,0,3,2] row_mask:0xf bank_mask:0xf
	s_and_saveexec_b64 s[0:1], vcc
	s_cbranch_execz .LBB0_2537
	s_waitcnt lgkmcnt(0)
	v_cvt_pk_bf16_f32 v0, v0, v8
	global_store_dword v[4:5], v0, off
.LBB0_2537:
	s_or_b64 exec, exec, s[0:1]
	v_mul_f32_e32 v0, v48, v7
	s_waitcnt lgkmcnt(0)
	s_nop 1
	v_mov_b32_dpp v8, v0 quad_perm:[1,0,3,2] row_mask:0xf bank_mask:0xf
	s_and_saveexec_b64 s[0:1], vcc
	s_cbranch_execz .LBB0_2539
	s_waitcnt lgkmcnt(0)
	v_cvt_pk_bf16_f32 v0, v0, v8
	global_store_dword v[4:5], v0, off offset:64

.LBB0_2543:
	s_or_b64 exec, exec, s[0:1]
	ds_read_b32 v0, v222 offset:4
	s_waitcnt lgkmcnt(0)
	v_rcp_f32_e32 v7, v0
	v_lshl_or_b32 v0, v221, 12, v206
	v_lshl_add_u64 v[4:5], v[2:3], 0, v[0:1]
	v_mul_f32_e32 v0, v65, v7
	s_nop 1
	v_mov_b32_dpp v8, v0 quad_perm:[1,0,3,2] row_mask:0xf bank_mask:0xf
	s_and_saveexec_b64 s[0:1], vcc
	s_cbranch_execz .LBB0_2545
	s_waitcnt lgkmcnt(0)
	v_cvt_pk_bf16_f32 v0, v0, v8
	global_store_dword v[4:5], v0, off
.LBB0_2545:
	s_or_b64 exec, exec, s[0:1]
	v_mul_f32_e32 v0, v49, v7
	s_waitcnt lgkmcnt(0)
	s_nop 1
	v_mov_b32_dpp v8, v0 quad_perm:[1,0,3,2] row_mask:0xf bank_mask:0xf
	s_and_saveexec_b64 s[0:1], vcc
	s_cbranch_execz .LBB0_2547
	s_waitcnt lgkmcnt(0)
	v_cvt_pk_bf16_f32 v0, v0, v8
	global_store_dword v[4:5], v0, off offset:64

.LBB0_2551:
	s_or_b64 exec, exec, s[0:1]
	ds_read_b32 v0, v222 offset:8
	s_waitcnt lgkmcnt(0)
	v_rcp_f32_e32 v7, v0
	v_lshl_or_b32 v0, v221, 12, v207
	v_lshl_add_u64 v[4:5], v[2:3], 0, v[0:1]
	v_mul_f32_e32 v0, v66, v7
	s_nop 1
	v_mov_b32_dpp v8, v0 quad_perm:[1,0,3,2] row_mask:0xf bank_mask:0xf
	s_and_saveexec_b64 s[0:1], vcc
	s_cbranch_execz .LBB0_2553
	s_waitcnt lgkmcnt(0)
	v_cvt_pk_bf16_f32 v0, v0, v8
	global_store_dword v[4:5], v0, off
.LBB0_2553:
	s_or_b64 exec, exec, s[0:1]
	v_mul_f32_e32 v0, v50, v7
	s_waitcnt lgkmcnt(0)
	s_nop 1
	v_mov_b32_dpp v8, v0 quad_perm:[1,0,3,2] row_mask:0xf bank_mask:0xf
	s_and_saveexec_b64 s[0:1], vcc
	s_cbranch_execz .LBB0_2555
	s_waitcnt lgkmcnt(0)
	v_cvt_pk_bf16_f32 v0, v0, v8
	global_store_dword v[4:5], v0, off offset:64

.LBB0_2559:
	s_or_b64 exec, exec, s[0:1]
	ds_read_b32 v0, v222 offset:12
	s_waitcnt lgkmcnt(0)
	v_rcp_f32_e32 v7, v0
	v_lshl_or_b32 v0, v221, 12, v208
	v_lshl_add_u64 v[4:5], v[2:3], 0, v[0:1]
	v_mul_f32_e32 v0, v67, v7
	s_nop 1
	v_mov_b32_dpp v8, v0 quad_perm:[1,0,3,2] row_mask:0xf bank_mask:0xf
	s_and_saveexec_b64 s[0:1], vcc
	s_cbranch_execz .LBB0_2561
	s_waitcnt lgkmcnt(0)
	v_cvt_pk_bf16_f32 v0, v0, v8
	global_store_dword v[4:5], v0, off
.LBB0_2561:
	s_or_b64 exec, exec, s[0:1]
	v_mul_f32_e32 v0, v51, v7
	s_waitcnt lgkmcnt(0)
	s_nop 1
	v_mov_b32_dpp v8, v0 quad_perm:[1,0,3,2] row_mask:0xf bank_mask:0xf
	s_and_saveexec_b64 s[0:1], vcc
	s_cbranch_execz .LBB0_2563
	s_waitcnt lgkmcnt(0)
	v_cvt_pk_bf16_f32 v0, v0, v8
	global_store_dword v[4:5], v0, off offset:64

.LBB0_2567:
	s_or_b64 exec, exec, s[0:1]
	ds_read_b32 v0, v222 offset:32
	s_waitcnt lgkmcnt(0)
	v_rcp_f32_e32 v7, v0
	v_lshl_or_b32 v0, v221, 12, v209
	v_lshl_add_u64 v[4:5], v[2:3], 0, v[0:1]
	v_mul_f32_e32 v0, v68, v7
	s_nop 1
	v_mov_b32_dpp v8, v0 quad_perm:[1,0,3,2] row_mask:0xf bank_mask:0xf
	s_and_saveexec_b64 s[0:1], vcc
	s_cbranch_execz .LBB0_2569
	s_waitcnt lgkmcnt(0)
	v_cvt_pk_bf16_f32 v0, v0, v8
	global_store_dword v[4:5], v0, off
.LBB0_2569:
	s_or_b64 exec, exec, s[0:1]
	v_mul_f32_e32 v0, v52, v7
	s_waitcnt lgkmcnt(0)
	s_nop 1
	v_mov_b32_dpp v8, v0 quad_perm:[1,0,3,2] row_mask:0xf bank_mask:0xf
	s_and_saveexec_b64 s[0:1], vcc
	s_cbranch_execz .LBB0_2571
	s_waitcnt lgkmcnt(0)
	v_cvt_pk_bf16_f32 v0, v0, v8
	global_store_dword v[4:5], v0, off offset:64

.LBB0_2575:
	s_or_b64 exec, exec, s[0:1]
	ds_read_b32 v0, v222 offset:36
	s_waitcnt lgkmcnt(0)
	v_rcp_f32_e32 v7, v0
	v_lshl_or_b32 v0, v221, 12, v210
	v_lshl_add_u64 v[4:5], v[2:3], 0, v[0:1]
	v_mul_f32_e32 v0, v69, v7
	s_nop 1
	v_mov_b32_dpp v8, v0 quad_perm:[1,0,3,2] row_mask:0xf bank_mask:0xf
	s_and_saveexec_b64 s[0:1], vcc
	s_cbranch_execz .LBB0_2577
	s_waitcnt lgkmcnt(0)
	v_cvt_pk_bf16_f32 v0, v0, v8
	global_store_dword v[4:5], v0, off
.LBB0_2577:
	s_or_b64 exec, exec, s[0:1]
	v_mul_f32_e32 v0, v53, v7
	s_waitcnt lgkmcnt(0)
	s_nop 1
	v_mov_b32_dpp v8, v0 quad_perm:[1,0,3,2] row_mask:0xf bank_mask:0xf
	s_and_saveexec_b64 s[0:1], vcc
	s_cbranch_execz .LBB0_2579
	s_waitcnt lgkmcnt(0)
	v_cvt_pk_bf16_f32 v0, v0, v8
	global_store_dword v[4:5], v0, off offset:64

.LBB0_2583:
	s_or_b64 exec, exec, s[0:1]
	ds_read_b32 v0, v222 offset:40
	s_waitcnt lgkmcnt(0)
	v_rcp_f32_e32 v7, v0
	v_lshl_or_b32 v0, v221, 12, v211
	v_lshl_add_u64 v[4:5], v[2:3], 0, v[0:1]
	v_mul_f32_e32 v0, v70, v7
	s_nop 1
	v_mov_b32_dpp v8, v0 quad_perm:[1,0,3,2] row_mask:0xf bank_mask:0xf
	s_and_saveexec_b64 s[0:1], vcc
	s_cbranch_execz .LBB0_2585
	s_waitcnt lgkmcnt(0)
	v_cvt_pk_bf16_f32 v0, v0, v8
	global_store_dword v[4:5], v0, off
.LBB0_2585:
	s_or_b64 exec, exec, s[0:1]
	v_mul_f32_e32 v0, v54, v7
	s_waitcnt lgkmcnt(0)
	s_nop 1
	v_mov_b32_dpp v8, v0 quad_perm:[1,0,3,2] row_mask:0xf bank_mask:0xf
	s_and_saveexec_b64 s[0:1], vcc
	s_cbranch_execz .LBB0_2587
	s_waitcnt lgkmcnt(0)
	v_cvt_pk_bf16_f32 v0, v0, v8
	global_store_dword v[4:5], v0, off offset:64

.LBB0_2591:
	s_or_b64 exec, exec, s[0:1]
	ds_read_b32 v0, v222 offset:44
	s_waitcnt lgkmcnt(0)
	v_rcp_f32_e32 v7, v0
	v_lshl_or_b32 v0, v221, 12, v212
	v_lshl_add_u64 v[4:5], v[2:3], 0, v[0:1]
	v_mul_f32_e32 v0, v71, v7
	s_nop 1
	v_mov_b32_dpp v8, v0 quad_perm:[1,0,3,2] row_mask:0xf bank_mask:0xf
	s_and_saveexec_b64 s[0:1], vcc
	s_cbranch_execz .LBB0_2593
	s_waitcnt lgkmcnt(0)
	v_cvt_pk_bf16_f32 v0, v0, v8
	global_store_dword v[4:5], v0, off
.LBB0_2593:
	s_or_b64 exec, exec, s[0:1]
	v_mul_f32_e32 v0, v55, v7
	s_waitcnt lgkmcnt(0)
	s_nop 1
	v_mov_b32_dpp v8, v0 quad_perm:[1,0,3,2] row_mask:0xf bank_mask:0xf
	s_and_saveexec_b64 s[0:1], vcc
	s_cbranch_execz .LBB0_2595
	s_waitcnt lgkmcnt(0)
	v_cvt_pk_bf16_f32 v0, v0, v8
	global_store_dword v[4:5], v0, off offset:64

.LBB0_2599:
	s_or_b64 exec, exec, s[0:1]
	ds_read_b32 v0, v222 offset:64
	s_waitcnt lgkmcnt(0)
	v_rcp_f32_e32 v7, v0
	v_lshl_or_b32 v0, v221, 12, v213
	v_lshl_add_u64 v[4:5], v[2:3], 0, v[0:1]
	v_mul_f32_e32 v0, v72, v7
	s_nop 1
	v_mov_b32_dpp v8, v0 quad_perm:[1,0,3,2] row_mask:0xf bank_mask:0xf
	s_and_saveexec_b64 s[0:1], vcc
	s_cbranch_execz .LBB0_2601
	s_waitcnt lgkmcnt(0)
	v_cvt_pk_bf16_f32 v0, v0, v8
	global_store_dword v[4:5], v0, off
.LBB0_2601:
	s_or_b64 exec, exec, s[0:1]
	v_mul_f32_e32 v0, v56, v7
	s_waitcnt lgkmcnt(0)
	s_nop 1
	v_mov_b32_dpp v8, v0 quad_perm:[1,0,3,2] row_mask:0xf bank_mask:0xf
	s_and_saveexec_b64 s[0:1], vcc
	s_cbranch_execz .LBB0_2603
	s_waitcnt lgkmcnt(0)
	v_cvt_pk_bf16_f32 v0, v0, v8
	global_store_dword v[4:5], v0, off offset:64

.LBB0_2607:
	s_or_b64 exec, exec, s[0:1]
	ds_read_b32 v0, v222 offset:68
	s_waitcnt lgkmcnt(0)
	v_rcp_f32_e32 v7, v0
	v_lshl_or_b32 v0, v221, 12, v214
	v_lshl_add_u64 v[4:5], v[2:3], 0, v[0:1]
	v_mul_f32_e32 v0, v73, v7
	s_nop 1
	v_mov_b32_dpp v8, v0 quad_perm:[1,0,3,2] row_mask:0xf bank_mask:0xf
	s_and_saveexec_b64 s[0:1], vcc
	s_cbranch_execz .LBB0_2609
	s_waitcnt lgkmcnt(0)
	v_cvt_pk_bf16_f32 v0, v0, v8
	global_store_dword v[4:5], v0, off
.LBB0_2609:
	s_or_b64 exec, exec, s[0:1]
	v_mul_f32_e32 v0, v57, v7
	s_waitcnt lgkmcnt(0)
	s_nop 1
	v_mov_b32_dpp v8, v0 quad_perm:[1,0,3,2] row_mask:0xf bank_mask:0xf
	s_and_saveexec_b64 s[0:1], vcc
	s_cbranch_execz .LBB0_2611
	s_waitcnt lgkmcnt(0)
	v_cvt_pk_bf16_f32 v0, v0, v8
	global_store_dword v[4:5], v0, off offset:64

.LBB0_2615:
	s_or_b64 exec, exec, s[0:1]
	ds_read_b32 v0, v222 offset:72
	s_waitcnt lgkmcnt(0)
	v_rcp_f32_e32 v7, v0
	v_lshl_or_b32 v0, v221, 12, v215
	v_lshl_add_u64 v[4:5], v[2:3], 0, v[0:1]
	v_mul_f32_e32 v0, v74, v7
	s_nop 1
	v_mov_b32_dpp v8, v0 quad_perm:[1,0,3,2] row_mask:0xf bank_mask:0xf
	s_and_saveexec_b64 s[0:1], vcc
	s_cbranch_execz .LBB0_2617
	s_waitcnt lgkmcnt(0)
	v_cvt_pk_bf16_f32 v0, v0, v8
	global_store_dword v[4:5], v0, off
.LBB0_2617:
	s_or_b64 exec, exec, s[0:1]
	v_mul_f32_e32 v0, v58, v7
	s_waitcnt lgkmcnt(0)
	s_nop 1
	v_mov_b32_dpp v8, v0 quad_perm:[1,0,3,2] row_mask:0xf bank_mask:0xf
	s_and_saveexec_b64 s[0:1], vcc
	s_cbranch_execz .LBB0_2619
	s_waitcnt lgkmcnt(0)
	v_cvt_pk_bf16_f32 v0, v0, v8
	global_store_dword v[4:5], v0, off offset:64

.LBB0_2623:
	s_or_b64 exec, exec, s[0:1]
	ds_read_b32 v0, v222 offset:76
	s_waitcnt lgkmcnt(0)
	v_rcp_f32_e32 v7, v0
	v_lshl_or_b32 v0, v221, 12, v216
	v_lshl_add_u64 v[4:5], v[2:3], 0, v[0:1]
	v_mul_f32_e32 v0, v75, v7
	s_nop 1
	v_mov_b32_dpp v8, v0 quad_perm:[1,0,3,2] row_mask:0xf bank_mask:0xf
	s_and_saveexec_b64 s[0:1], vcc
	s_cbranch_execz .LBB0_2625
	s_waitcnt lgkmcnt(0)
	v_cvt_pk_bf16_f32 v0, v0, v8
	global_store_dword v[4:5], v0, off
.LBB0_2625:
	s_or_b64 exec, exec, s[0:1]
	v_mul_f32_e32 v0, v59, v7
	s_waitcnt lgkmcnt(0)
	s_nop 1
	v_mov_b32_dpp v8, v0 quad_perm:[1,0,3,2] row_mask:0xf bank_mask:0xf
	s_and_saveexec_b64 s[0:1], vcc
	s_cbranch_execz .LBB0_2627
	s_waitcnt lgkmcnt(0)
	v_cvt_pk_bf16_f32 v0, v0, v8
	global_store_dword v[4:5], v0, off offset:64

.LBB0_2631:
	s_or_b64 exec, exec, s[0:1]
	ds_read_b32 v0, v222 offset:96
	s_waitcnt lgkmcnt(0)
	v_rcp_f32_e32 v7, v0
	v_lshl_or_b32 v0, v221, 12, v217
	v_lshl_add_u64 v[4:5], v[2:3], 0, v[0:1]
	v_mul_f32_e32 v0, v76, v7
	s_nop 1
	v_mov_b32_dpp v8, v0 quad_perm:[1,0,3,2] row_mask:0xf bank_mask:0xf
	s_and_saveexec_b64 s[0:1], vcc
	s_cbranch_execz .LBB0_2633
	s_waitcnt lgkmcnt(0)
	v_cvt_pk_bf16_f32 v0, v0, v8
	global_store_dword v[4:5], v0, off
.LBB0_2633:
	s_or_b64 exec, exec, s[0:1]
	v_mul_f32_e32 v0, v60, v7
	s_waitcnt lgkmcnt(0)
	s_nop 1
	v_mov_b32_dpp v8, v0 quad_perm:[1,0,3,2] row_mask:0xf bank_mask:0xf
	s_and_saveexec_b64 s[0:1], vcc
	s_cbranch_execz .LBB0_2635
	s_waitcnt lgkmcnt(0)
	v_cvt_pk_bf16_f32 v0, v0, v8
	global_store_dword v[4:5], v0, off offset:64

.LBB0_2639:
	s_or_b64 exec, exec, s[0:1]
	ds_read_b32 v0, v222 offset:100
	s_waitcnt lgkmcnt(0)
	v_rcp_f32_e32 v7, v0
	v_lshl_or_b32 v0, v221, 12, v218
	v_lshl_add_u64 v[4:5], v[2:3], 0, v[0:1]
	v_mul_f32_e32 v0, v77, v7
	s_nop 1
	v_mov_b32_dpp v8, v0 quad_perm:[1,0,3,2] row_mask:0xf bank_mask:0xf
	s_and_saveexec_b64 s[0:1], vcc
	s_cbranch_execz .LBB0_2641
	s_waitcnt lgkmcnt(0)
	v_cvt_pk_bf16_f32 v0, v0, v8
	global_store_dword v[4:5], v0, off
.LBB0_2641:
	s_or_b64 exec, exec, s[0:1]
	v_mul_f32_e32 v0, v61, v7
	s_waitcnt lgkmcnt(0)
	s_nop 1
	v_mov_b32_dpp v8, v0 quad_perm:[1,0,3,2] row_mask:0xf bank_mask:0xf
	s_and_saveexec_b64 s[0:1], vcc
	s_cbranch_execz .LBB0_2643
	s_waitcnt lgkmcnt(0)
	v_cvt_pk_bf16_f32 v0, v0, v8
	global_store_dword v[4:5], v0, off offset:64

.LBB0_2647:
	s_or_b64 exec, exec, s[0:1]
	ds_read_b32 v0, v222 offset:104
	s_waitcnt lgkmcnt(0)
	v_rcp_f32_e32 v7, v0
	v_lshl_or_b32 v0, v221, 12, v219
	v_lshl_add_u64 v[4:5], v[2:3], 0, v[0:1]
	v_mul_f32_e32 v0, v78, v7
	s_nop 1
	v_mov_b32_dpp v8, v0 quad_perm:[1,0,3,2] row_mask:0xf bank_mask:0xf
	s_and_saveexec_b64 s[0:1], vcc
	s_cbranch_execz .LBB0_2649
	s_waitcnt lgkmcnt(0)
	v_cvt_pk_bf16_f32 v0, v0, v8
	global_store_dword v[4:5], v0, off
.LBB0_2649:
	s_or_b64 exec, exec, s[0:1]
	v_mul_f32_e32 v0, v62, v7
	s_waitcnt lgkmcnt(0)
	s_nop 1
	v_mov_b32_dpp v8, v0 quad_perm:[1,0,3,2] row_mask:0xf bank_mask:0xf
	s_and_saveexec_b64 s[0:1], vcc
	s_cbranch_execz .LBB0_2651
	s_waitcnt lgkmcnt(0)
	v_cvt_pk_bf16_f32 v0, v0, v8
	global_store_dword v[4:5], v0, off offset:64

.LBB0_2897:
	s_waitcnt vmcnt(8)
	s_waitcnt vmcnt(9)
	ds_write_b128 v212, v[120:123] offset:32768
	s_waitcnt vmcnt(8)
	ds_write_b128 v212, v[124:127] offset:40960
	v_cmp_gt_u32_e32 vcc, 32, v213
	s_and_saveexec_b64 s[0:1], vcc
	ds_write_b32 v215, v1
	s_or_b64 exec, exec, s[0:1]
	s_waitcnt lgkmcnt(0)
	s_and_b64 vcc, exec, s[36:37]
	s_cbranch_vccnz .LBB0_3029
	ds_read2_b32 v[80:81], v214 offset1:3
	ds_read2_b32 v[82:83], v214 offset0:1 offset1:2
	ds_read_b128 v[10:13], v214 offset:32
	ds_read_b128 v[6:9], v214 offset:64
	ds_read_b128 v[2:5], v214 offset:96
	s_waitcnt lgkmcnt(4)
	v_rcp_f32_e32 v80, v80
	v_and_b32_e32 v14, 64, v204
	v_xor_b32_e32 v1, 1, v204
	v_add_u32_e32 v14, 64, v14
	v_cmp_lt_i32_e32 vcc, v1, v14
	v_mul_f32_e32 v48, v48, v80
	s_ashr_i32 s75, s74, 31
	v_cndmask_b32_e32 v1, v204, v1, vcc
	v_lshlrev_b32_e32 v1, 2, v1
	s_nop 1
	v_mov_b32_dpp v84, v48 quad_perm:[1,0,3,2] row_mask:0xf bank_mask:0xf
	s_lshl_b64 s[0:1], s[74:75], 12
	s_add_u32 s0, s50, s0
	v_and_b32_e32 v14, 1, v210
	s_addc_u32 s1, s51, s1
	v_cmp_eq_u32_e32 vcc, 0, v14
	v_lshlrev_b32_e32 v196, 12, v209
	v_lshlrev_b32_e32 v14, 1, v211
	s_and_saveexec_b64 s[20:21], vcc
	s_cbranch_execz .LBB0_2902
	v_lshl_add_u64 v[86:87], s[0:1], 0, v[196:197]
	v_mov_b32_e32 v15, v197
	v_lshl_add_u64 v[86:87], v[86:87], 0, v[14:15]
	s_waitcnt lgkmcnt(0)
	v_cvt_pk_bf16_f32 v15, v48, v84
	global_store_dword v[86:87], v15, off
.LBB0_2902:
	s_or_b64 exec, exec, s[20:21]
	v_mul_f32_e32 v48, v64, v80
	s_nop 1
	v_mov_b32_dpp v64, v48 quad_perm:[1,0,3,2] row_mask:0xf bank_mask:0xf
	s_and_saveexec_b64 s[20:21], vcc
	s_cbranch_execz .LBB0_2904
	s_waitcnt lgkmcnt(0)
	v_lshl_add_u64 v[84:85], s[0:1], 0, v[196:197]
	v_mov_b32_e32 v15, v197
	v_lshl_add_u64 v[84:85], v[84:85], 0, v[14:15]
	s_waitcnt lgkmcnt(0)
	v_cvt_pk_bf16_f32 v15, v48, v64
	global_store_dword v[84:85], v15, off offset:64
.LBB0_2904:
	s_or_b64 exec, exec, s[20:21]
	v_mul_f32_e32 v32, v32, v80
	s_nop 1
	v_mov_b32_dpp v48, v32 quad_perm:[1,0,3,2] row_mask:0xf bank_mask:0xf
	s_and_saveexec_b64 s[20:21], vcc
	s_cbranch_execz .LBB0_2906
	s_waitcnt lgkmcnt(0)
	v_lshl_add_u64 v[84:85], s[0:1], 0, v[196:197]
	v_mov_b32_e32 v15, v197
	v_lshl_add_u64 v[84:85], v[84:85], 0, v[14:15]
	s_waitcnt lgkmcnt(0)
	v_cvt_pk_bf16_f32 v15, v32, v48
	global_store_dword v[84:85], v15, off offset:128
.LBB0_2906:
	s_or_b64 exec, exec, s[20:21]
	v_mul_f32_e32 v16, v16, v80
	s_nop 1
	v_mov_b32_dpp v32, v16 quad_perm:[1,0,3,2] row_mask:0xf bank_mask:0xf
	s_and_saveexec_b64 s[20:21], vcc
	s_cbranch_execz .LBB0_2908
	s_waitcnt lgkmcnt(0)
	v_lshl_add_u64 v[84:85], s[0:1], 0, v[196:197]
	v_mov_b32_e32 v15, v197
	v_lshl_add_u64 v[84:85], v[84:85], 0, v[14:15]
	s_waitcnt lgkmcnt(0)
	v_cvt_pk_bf16_f32 v15, v16, v32
	global_store_dword v[84:85], v15, off offset:192
.LBB0_2908:
	s_or_b64 exec, exec, s[20:21]
	s_waitcnt lgkmcnt(7)
	v_rcp_f32_e32 v16, v82
	v_or_b32_e32 v15, 1, v209
	v_lshlrev_b32_e32 v196, 12, v15
	s_waitcnt lgkmcnt(0)
	v_mul_f32_e32 v32, v49, v16
	s_nop 1
	v_mov_b32_dpp v48, v32 quad_perm:[1,0,3,2] row_mask:0xf bank_mask:0xf
	s_and_saveexec_b64 s[20:21], vcc
	s_cbranch_execz .LBB0_2910
	v_lshl_add_u64 v[84:85], s[0:1], 0, v[196:197]
	v_mov_b32_e32 v15, v197
	v_lshl_add_u64 v[84:85], v[84:85], 0, v[14:15]
	s_waitcnt lgkmcnt(0)
	v_cvt_pk_bf16_f32 v15, v32, v48
	global_store_dword v[84:85], v15, off
.LBB0_2910:
	s_or_b64 exec, exec, s[20:21]
	v_mul_f32_e32 v32, v65, v16
	s_waitcnt lgkmcnt(0)
	s_nop 1
	v_mov_b32_dpp v48, v32 quad_perm:[1,0,3,2] row_mask:0xf bank_mask:0xf
	s_and_saveexec_b64 s[20:21], vcc
	s_cbranch_execz .LBB0_2912
	v_lshl_add_u64 v[64:65], s[0:1], 0, v[196:197]
	v_mov_b32_e32 v15, v197
	v_lshl_add_u64 v[64:65], v[64:65], 0, v[14:15]
	s_waitcnt lgkmcnt(0)
	v_cvt_pk_bf16_f32 v15, v32, v48
	global_store_dword v[64:65], v15, off offset:64
.LBB0_2912:
	s_or_b64 exec, exec, s[20:21]
	v_mul_f32_e32 v32, v33, v16
	s_nop 1
	v_mov_b32_dpp v33, v32 quad_perm:[1,0,3,2] row_mask:0xf bank_mask:0xf
	s_and_saveexec_b64 s[20:21], vcc
	s_cbranch_execz .LBB0_2914
	s_waitcnt lgkmcnt(0)
	v_lshl_add_u64 v[48:49], s[0:1], 0, v[196:197]
	v_mov_b32_e32 v15, v197
	v_lshl_add_u64 v[48:49], v[48:49], 0, v[14:15]
	s_waitcnt lgkmcnt(0)
	v_cvt_pk_bf16_f32 v15, v32, v33
	global_store_dword v[48:49], v15, off offset:128
.LBB0_2914:
	s_or_b64 exec, exec, s[20:21]
	v_mul_f32_e32 v16, v17, v16
	s_nop 1
	v_mov_b32_dpp v17, v16 quad_perm:[1,0,3,2] row_mask:0xf bank_mask:0xf
	s_and_saveexec_b64 s[20:21], vcc
	s_cbranch_execz .LBB0_2916
	s_waitcnt lgkmcnt(0)
	v_lshl_add_u64 v[32:33], s[0:1], 0, v[196:197]
	v_mov_b32_e32 v15, v197
	v_lshl_add_u64 v[32:33], v[32:33], 0, v[14:15]
	s_waitcnt lgkmcnt(0)
	v_cvt_pk_bf16_f32 v15, v16, v17
	global_store_dword v[32:33], v15, off offset:192
.LBB0_2916:
	s_or_b64 exec, exec, s[20:21]
	v_rcp_f32_e32 v16, v83
	v_or_b32_e32 v15, 2, v209
	v_lshlrev_b32_e32 v196, 12, v15
	s_waitcnt lgkmcnt(0)
	v_mul_f32_e32 v17, v50, v16
	s_nop 1
	v_mov_b32_dpp v32, v17 quad_perm:[1,0,3,2] row_mask:0xf bank_mask:0xf
	s_and_saveexec_b64 s[20:21], vcc
	s_cbranch_execz .LBB0_2918
	v_lshl_add_u64 v[48:49], s[0:1], 0, v[196:197]
	v_mov_b32_e32 v15, v197
	v_lshl_add_u64 v[48:49], v[48:49], 0, v[14:15]
	s_waitcnt lgkmcnt(0)
	v_cvt_pk_bf16_f32 v15, v17, v32
	global_store_dword v[48:49], v15, off
.LBB0_2918:
	s_or_b64 exec, exec, s[20:21]
	v_mul_f32_e32 v17, v66, v16
	s_waitcnt lgkmcnt(0)
	s_nop 1
	v_mov_b32_dpp v32, v17 quad_perm:[1,0,3,2] row_mask:0xf bank_mask:0xf
	s_and_saveexec_b64 s[20:21], vcc
	s_cbranch_execz .LBB0_2920
	v_lshl_add_u64 v[48:49], s[0:1], 0, v[196:197]
	v_mov_b32_e32 v15, v197
	v_lshl_add_u64 v[48:49], v[48:49], 0, v[14:15]
	s_waitcnt lgkmcnt(0)
	v_cvt_pk_bf16_f32 v15, v17, v32
	global_store_dword v[48:49], v15, off offset:64
.LBB0_2920:
	s_or_b64 exec, exec, s[20:21]
	v_mul_f32_e32 v17, v34, v16
	s_waitcnt lgkmcnt(0)
	s_nop 1
	v_mov_b32_dpp v32, v17 quad_perm:[1,0,3,2] row_mask:0xf bank_mask:0xf
	s_and_saveexec_b64 s[20:21], vcc
	s_cbranch_execz .LBB0_2922
	v_lshl_add_u64 v[48:49], s[0:1], 0, v[196:197]
	v_mov_b32_e32 v15, v197
	v_lshl_add_u64 v[48:49], v[48:49], 0, v[14:15]
	s_waitcnt lgkmcnt(0)
	v_cvt_pk_bf16_f32 v15, v17, v32
	global_store_dword v[48:49], v15, off offset:128
.LBB0_2922:
	s_or_b64 exec, exec, s[20:21]
	v_mul_f32_e32 v16, v18, v16
	s_nop 1
	v_mov_b32_dpp v17, v16 quad_perm:[1,0,3,2] row_mask:0xf bank_mask:0xf
	s_and_saveexec_b64 s[20:21], vcc
	s_cbranch_execz .LBB0_2924
	s_waitcnt lgkmcnt(0)
	v_lshl_add_u64 v[32:33], s[0:1], 0, v[196:197]
	v_mov_b32_e32 v15, v197
	v_lshl_add_u64 v[32:33], v[32:33], 0, v[14:15]
	s_waitcnt lgkmcnt(0)
	v_cvt_pk_bf16_f32 v15, v16, v17
	global_store_dword v[32:33], v15, off offset:192
.LBB0_2924:
	s_or_b64 exec, exec, s[20:21]
	v_rcp_f32_e32 v16, v81
	v_or_b32_e32 v15, 3, v209
	v_lshlrev_b32_e32 v196, 12, v15
	s_waitcnt lgkmcnt(0)
	v_mul_f32_e32 v17, v51, v16
	s_nop 1
	v_mov_b32_dpp v18, v17 quad_perm:[1,0,3,2] row_mask:0xf bank_mask:0xf
	s_and_saveexec_b64 s[20:21], vcc
	s_cbranch_execz .LBB0_2926
	v_lshl_add_u64 v[32:33], s[0:1], 0, v[196:197]
	v_mov_b32_e32 v15, v197
	v_lshl_add_u64 v[32:33], v[32:33], 0, v[14:15]
	s_waitcnt lgkmcnt(0)
	v_cvt_pk_bf16_f32 v15, v17, v18
	global_store_dword v[32:33], v15, off
.LBB0_2926:
	s_or_b64 exec, exec, s[20:21]
	v_mul_f32_e32 v17, v67, v16
	s_waitcnt lgkmcnt(0)
	s_nop 1
	v_mov_b32_dpp v18, v17 quad_perm:[1,0,3,2] row_mask:0xf bank_mask:0xf
	s_and_saveexec_b64 s[20:21], vcc
	s_cbranch_execz .LBB0_2928
	v_lshl_add_u64 v[32:33], s[0:1], 0, v[196:197]
	v_mov_b32_e32 v15, v197
	v_lshl_add_u64 v[32:33], v[32:33], 0, v[14:15]
	s_waitcnt lgkmcnt(0)
	v_cvt_pk_bf16_f32 v15, v17, v18
	global_store_dword v[32:33], v15, off offset:64
.LBB0_2928:
	s_or_b64 exec, exec, s[20:21]
	v_mul_f32_e32 v17, v35, v16
	s_waitcnt lgkmcnt(0)
	s_nop 1
	v_mov_b32_dpp v18, v17 quad_perm:[1,0,3,2] row_mask:0xf bank_mask:0xf
	s_and_saveexec_b64 s[20:21], vcc
	s_cbranch_execz .LBB0_2930
	v_lshl_add_u64 v[32:33], s[0:1], 0, v[196:197]
	v_mov_b32_e32 v15, v197
	v_lshl_add_u64 v[32:33], v[32:33], 0, v[14:15]
	s_waitcnt lgkmcnt(0)
	v_cvt_pk_bf16_f32 v15, v17, v18
	global_store_dword v[32:33], v15, off offset:128
.LBB0_2930:
	s_or_b64 exec, exec, s[20:21]
	v_mul_f32_e32 v16, v19, v16
	s_nop 1
	v_mov_b32_dpp v17, v16 quad_perm:[1,0,3,2] row_mask:0xf bank_mask:0xf
	s_and_saveexec_b64 s[20:21], vcc
	s_cbranch_execz .LBB0_2932
	s_waitcnt lgkmcnt(0)
	v_lshl_add_u64 v[18:19], s[0:1], 0, v[196:197]
	v_mov_b32_e32 v15, v197
	v_lshl_add_u64 v[18:19], v[18:19], 0, v[14:15]
	s_waitcnt lgkmcnt(0)
	v_cvt_pk_bf16_f32 v15, v16, v17
	global_store_dword v[18:19], v15, off offset:192
.LBB0_2932:
	s_or_b64 exec, exec, s[20:21]
	v_rcp_f32_e32 v10, v10
	v_or_b32_e32 v15, 8, v209
	v_lshlrev_b32_e32 v196, 12, v15
	v_mul_f32_e32 v16, v52, v10
	s_waitcnt lgkmcnt(0)
	s_nop 1
	v_mov_b32_dpp v17, v16 quad_perm:[1,0,3,2] row_mask:0xf bank_mask:0xf
	s_and_saveexec_b64 s[20:21], vcc
	s_cbranch_execz .LBB0_2934
	v_lshl_add_u64 v[18:19], s[0:1], 0, v[196:197]
	v_mov_b32_e32 v15, v197
	v_lshl_add_u64 v[18:19], v[18:19], 0, v[14:15]
	s_waitcnt lgkmcnt(0)
	v_cvt_pk_bf16_f32 v15, v16, v17
	global_store_dword v[18:19], v15, off
.LBB0_2934:
	s_or_b64 exec, exec, s[20:21]
	v_mul_f32_e32 v16, v68, v10
	s_waitcnt lgkmcnt(0)
	s_nop 1
	v_mov_b32_dpp v17, v16 quad_perm:[1,0,3,2] row_mask:0xf bank_mask:0xf
	s_and_saveexec_b64 s[20:21], vcc
	s_cbranch_execz .LBB0_2936
	v_lshl_add_u64 v[18:19], s[0:1], 0, v[196:197]
	v_mov_b32_e32 v15, v197
	v_lshl_add_u64 v[18:19], v[18:19], 0, v[14:15]
	s_waitcnt lgkmcnt(0)
	v_cvt_pk_bf16_f32 v15, v16, v17
	global_store_dword v[18:19], v15, off offset:64
.LBB0_2936:
	s_or_b64 exec, exec, s[20:21]
	v_mul_f32_e32 v16, v36, v10
	s_waitcnt lgkmcnt(0)
	s_nop 1
	v_mov_b32_dpp v17, v16 quad_perm:[1,0,3,2] row_mask:0xf bank_mask:0xf
	s_and_saveexec_b64 s[20:21], vcc
	s_cbranch_execz .LBB0_2938
	v_lshl_add_u64 v[18:19], s[0:1], 0, v[196:197]
	v_mov_b32_e32 v15, v197
	v_lshl_add_u64 v[18:19], v[18:19], 0, v[14:15]
	s_waitcnt lgkmcnt(0)
	v_cvt_pk_bf16_f32 v15, v16, v17
	global_store_dword v[18:19], v15, off offset:128
.LBB0_2938:
	s_or_b64 exec, exec, s[20:21]
	v_mul_f32_e32 v10, v20, v10
	s_nop 1
	v_mov_b32_dpp v16, v10 quad_perm:[1,0,3,2] row_mask:0xf bank_mask:0xf
	s_and_saveexec_b64 s[20:21], vcc
	s_cbranch_execz .LBB0_2940
	v_lshl_add_u64 v[18:19], s[0:1], 0, v[196:197]
	v_mov_b32_e32 v15, v197
	v_lshl_add_u64 v[18:19], v[18:19], 0, v[14:15]
	s_waitcnt lgkmcnt(0)
	v_cvt_pk_bf16_f32 v10, v10, v16
	global_store_dword v[18:19], v10, off offset:192
.LBB0_2940:
	s_or_b64 exec, exec, s[20:21]
	v_rcp_f32_e32 v10, v11
	v_or_b32_e32 v15, 9, v209
	v_lshlrev_b32_e32 v196, 12, v15
	v_mul_f32_e32 v11, v53, v10
	s_waitcnt lgkmcnt(0)
	s_nop 1
	v_mov_b32_dpp v16, v11 quad_perm:[1,0,3,2] row_mask:0xf bank_mask:0xf
	s_and_saveexec_b64 s[20:21], vcc
	s_cbranch_execz .LBB0_2942
	v_lshl_add_u64 v[18:19], s[0:1], 0, v[196:197]
	v_mov_b32_e32 v15, v197
	v_lshl_add_u64 v[18:19], v[18:19], 0, v[14:15]
	s_waitcnt lgkmcnt(0)
	v_cvt_pk_bf16_f32 v11, v11, v16
	global_store_dword v[18:19], v11, off
.LBB0_2942:
	s_or_b64 exec, exec, s[20:21]
	v_mul_f32_e32 v11, v69, v10
	s_waitcnt lgkmcnt(0)
	s_nop 1
	v_mov_b32_dpp v16, v11 quad_perm:[1,0,3,2] row_mask:0xf bank_mask:0xf
	s_and_saveexec_b64 s[20:21], vcc
	s_cbranch_execz .LBB0_2944
	v_lshl_add_u64 v[18:19], s[0:1], 0, v[196:197]
	v_mov_b32_e32 v15, v197
	v_lshl_add_u64 v[18:19], v[18:19], 0, v[14:15]
	s_waitcnt lgkmcnt(0)
	v_cvt_pk_bf16_f32 v11, v11, v16
	global_store_dword v[18:19], v11, off offset:64
.LBB0_2944:
	s_or_b64 exec, exec, s[20:21]
	v_mul_f32_e32 v11, v37, v10
	s_waitcnt lgkmcnt(0)
	s_nop 1
	v_mov_b32_dpp v16, v11 quad_perm:[1,0,3,2] row_mask:0xf bank_mask:0xf
	s_and_saveexec_b64 s[20:21], vcc
	s_cbranch_execz .LBB0_2946
	v_lshl_add_u64 v[18:19], s[0:1], 0, v[196:197]
	v_mov_b32_e32 v15, v197
	v_lshl_add_u64 v[18:19], v[18:19], 0, v[14:15]
	s_waitcnt lgkmcnt(0)
	v_cvt_pk_bf16_f32 v11, v11, v16
	global_store_dword v[18:19], v11, off offset:128
.LBB0_2946:
	s_or_b64 exec, exec, s[20:21]
	v_mul_f32_e32 v10, v21, v10
	s_nop 1
	v_mov_b32_dpp v11, v10 quad_perm:[1,0,3,2] row_mask:0xf bank_mask:0xf
	s_and_saveexec_b64 s[20:21], vcc
	s_cbranch_execz .LBB0_2948
	s_waitcnt lgkmcnt(0)
	v_lshl_add_u64 v[16:17], s[0:1], 0, v[196:197]
	v_mov_b32_e32 v15, v197
	v_lshl_add_u64 v[16:17], v[16:17], 0, v[14:15]
	s_waitcnt lgkmcnt(0)
	v_cvt_pk_bf16_f32 v10, v10, v11
	global_store_dword v[16:17], v10, off offset:192
.LBB0_2948:
	s_or_b64 exec, exec, s[20:21]
	v_rcp_f32_e32 v10, v12
	v_or_b32_e32 v15, 10, v209
	v_lshlrev_b32_e32 v196, 12, v15
	s_waitcnt lgkmcnt(0)
	v_mul_f32_e32 v11, v54, v10
	s_nop 1
	v_mov_b32_dpp v12, v11 quad_perm:[1,0,3,2] row_mask:0xf bank_mask:0xf
	s_and_saveexec_b64 s[20:21], vcc
	s_cbranch_execz .LBB0_2950
	v_lshl_add_u64 v[16:17], s[0:1], 0, v[196:197]
	v_mov_b32_e32 v15, v197
	v_lshl_add_u64 v[16:17], v[16:17], 0, v[14:15]
	s_waitcnt lgkmcnt(0)
	v_cvt_pk_bf16_f32 v11, v11, v12
	global_store_dword v[16:17], v11, off
.LBB0_2950:
	s_or_b64 exec, exec, s[20:21]
	v_mul_f32_e32 v11, v70, v10
	s_waitcnt lgkmcnt(0)
	s_nop 1
	v_mov_b32_dpp v12, v11 quad_perm:[1,0,3,2] row_mask:0xf bank_mask:0xf
	s_and_saveexec_b64 s[20:21], vcc
	s_cbranch_execz .LBB0_2952
	v_lshl_add_u64 v[16:17], s[0:1], 0, v[196:197]
	v_mov_b32_e32 v15, v197
	v_lshl_add_u64 v[16:17], v[16:17], 0, v[14:15]
	s_waitcnt lgkmcnt(0)
	v_cvt_pk_bf16_f32 v11, v11, v12
	global_store_dword v[16:17], v11, off offset:64
.LBB0_2952:
	s_or_b64 exec, exec, s[20:21]
	v_mul_f32_e32 v11, v38, v10
	s_waitcnt lgkmcnt(0)
	s_nop 1
	v_mov_b32_dpp v12, v11 quad_perm:[1,0,3,2] row_mask:0xf bank_mask:0xf
	s_and_saveexec_b64 s[20:21], vcc
	s_cbranch_execz .LBB0_2954
	v_lshl_add_u64 v[16:17], s[0:1], 0, v[196:197]
	v_mov_b32_e32 v15, v197
	v_lshl_add_u64 v[16:17], v[16:17], 0, v[14:15]
	s_waitcnt lgkmcnt(0)
	v_cvt_pk_bf16_f32 v11, v11, v12
	global_store_dword v[16:17], v11, off offset:128
.LBB0_2954:
	s_or_b64 exec, exec, s[20:21]
	v_mul_f32_e32 v10, v22, v10
	s_nop 1
	v_mov_b32_dpp v11, v10 quad_perm:[1,0,3,2] row_mask:0xf bank_mask:0xf
	s_and_saveexec_b64 s[20:21], vcc
	s_cbranch_execz .LBB0_2956
	v_lshl_add_u64 v[16:17], s[0:1], 0, v[196:197]
	v_mov_b32_e32 v15, v197
	v_lshl_add_u64 v[16:17], v[16:17], 0, v[14:15]
	s_waitcnt lgkmcnt(0)
	v_cvt_pk_bf16_f32 v10, v10, v11
	global_store_dword v[16:17], v10, off offset:192
.LBB0_2956:
	s_or_b64 exec, exec, s[20:21]
	v_rcp_f32_e32 v10, v13
	v_or_b32_e32 v13, 11, v209
	v_lshlrev_b32_e32 v196, 12, v13
	s_waitcnt lgkmcnt(0)
	v_mul_f32_e32 v11, v55, v10
	s_nop 1
	v_mov_b32_dpp v12, v11 quad_perm:[1,0,3,2] row_mask:0xf bank_mask:0xf
	s_and_saveexec_b64 s[20:21], vcc
	s_cbranch_execz .LBB0_2958
	v_lshl_add_u64 v[16:17], s[0:1], 0, v[196:197]
	v_mov_b32_e32 v15, v197
	v_lshl_add_u64 v[16:17], v[16:17], 0, v[14:15]
	s_waitcnt lgkmcnt(0)
	v_cvt_pk_bf16_f32 v11, v11, v12
	global_store_dword v[16:17], v11, off
.LBB0_2958:
	s_or_b64 exec, exec, s[20:21]
	v_mul_f32_e32 v11, v71, v10
	s_waitcnt lgkmcnt(0)
	s_nop 1
	v_mov_b32_dpp v12, v11 quad_perm:[1,0,3,2] row_mask:0xf bank_mask:0xf
	s_and_saveexec_b64 s[20:21], vcc
	s_cbranch_execz .LBB0_2960
	v_lshl_add_u64 v[16:17], s[0:1], 0, v[196:197]
	v_mov_b32_e32 v15, v197
	v_lshl_add_u64 v[16:17], v[16:17], 0, v[14:15]
	s_waitcnt lgkmcnt(0)
	v_cvt_pk_bf16_f32 v11, v11, v12
	global_store_dword v[16:17], v11, off offset:64
.LBB0_2960:
	s_or_b64 exec, exec, s[20:21]
	v_mul_f32_e32 v11, v39, v10
	s_waitcnt lgkmcnt(0)
	s_nop 1
	v_mov_b32_dpp v12, v11 quad_perm:[1,0,3,2] row_mask:0xf bank_mask:0xf
	s_and_saveexec_b64 s[20:21], vcc
	s_cbranch_execz .LBB0_2962
	v_lshl_add_u64 v[16:17], s[0:1], 0, v[196:197]
	v_mov_b32_e32 v15, v197
	v_lshl_add_u64 v[16:17], v[16:17], 0, v[14:15]
	s_waitcnt lgkmcnt(0)
	v_cvt_pk_bf16_f32 v11, v11, v12
	global_store_dword v[16:17], v11, off offset:128
.LBB0_2962:
	s_or_b64 exec, exec, s[20:21]
	v_mul_f32_e32 v10, v23, v10
	s_nop 1
	v_mov_b32_dpp v11, v10 quad_perm:[1,0,3,2] row_mask:0xf bank_mask:0xf
	s_and_saveexec_b64 s[20:21], vcc
	s_cbranch_execz .LBB0_2964
	s_waitcnt lgkmcnt(0)
	v_lshl_add_u64 v[12:13], s[0:1], 0, v[196:197]
	v_mov_b32_e32 v15, v197
	v_lshl_add_u64 v[12:13], v[12:13], 0, v[14:15]
	s_waitcnt lgkmcnt(0)
	v_cvt_pk_bf16_f32 v10, v10, v11
	global_store_dword v[12:13], v10, off offset:192
.LBB0_2964:
	s_or_b64 exec, exec, s[20:21]
	v_rcp_f32_e32 v6, v6
	s_waitcnt lgkmcnt(1)
	v_or_b32_e32 v12, 16, v209
	v_lshlrev_b32_e32 v196, 12, v12
	v_mul_f32_e32 v10, v56, v6
	s_waitcnt lgkmcnt(0)
	s_nop 1
	v_mov_b32_dpp v11, v10 quad_perm:[1,0,3,2] row_mask:0xf bank_mask:0xf
	s_and_saveexec_b64 s[20:21], vcc
	s_cbranch_execz .LBB0_2966
	v_lshl_add_u64 v[12:13], s[0:1], 0, v[196:197]
	v_mov_b32_e32 v15, v197
	v_lshl_add_u64 v[12:13], v[12:13], 0, v[14:15]
	s_waitcnt lgkmcnt(0)
	v_cvt_pk_bf16_f32 v10, v10, v11
	global_store_dword v[12:13], v10, off
.LBB0_2966:
	s_or_b64 exec, exec, s[20:21]
	v_mul_f32_e32 v10, v72, v6
	s_waitcnt lgkmcnt(0)
	s_nop 1
	v_mov_b32_dpp v11, v10 quad_perm:[1,0,3,2] row_mask:0xf bank_mask:0xf
	s_and_saveexec_b64 s[20:21], vcc
	s_cbranch_execz .LBB0_2968
	v_lshl_add_u64 v[12:13], s[0:1], 0, v[196:197]
	v_mov_b32_e32 v15, v197
	v_lshl_add_u64 v[12:13], v[12:13], 0, v[14:15]
	s_waitcnt lgkmcnt(0)
	v_cvt_pk_bf16_f32 v10, v10, v11
	global_store_dword v[12:13], v10, off offset:64
.LBB0_2968:
	s_or_b64 exec, exec, s[20:21]
	v_mul_f32_e32 v10, v40, v6
	s_waitcnt lgkmcnt(0)
	s_nop 1
	v_mov_b32_dpp v11, v10 quad_perm:[1,0,3,2] row_mask:0xf bank_mask:0xf
	s_and_saveexec_b64 s[20:21], vcc
	s_cbranch_execz .LBB0_2970
	v_lshl_add_u64 v[12:13], s[0:1], 0, v[196:197]
	v_mov_b32_e32 v15, v197
	v_lshl_add_u64 v[12:13], v[12:13], 0, v[14:15]
	s_waitcnt lgkmcnt(0)
	v_cvt_pk_bf16_f32 v10, v10, v11
	global_store_dword v[12:13], v10, off offset:128
.LBB0_2970:
	s_or_b64 exec, exec, s[20:21]
	v_mul_f32_e32 v6, v24, v6
	s_nop 1
	v_mov_b32_dpp v10, v6 quad_perm:[1,0,3,2] row_mask:0xf bank_mask:0xf
	s_and_saveexec_b64 s[20:21], vcc
	s_cbranch_execz .LBB0_2972
	v_lshl_add_u64 v[12:13], s[0:1], 0, v[196:197]
	v_mov_b32_e32 v15, v197
	v_lshl_add_u64 v[12:13], v[12:13], 0, v[14:15]
	s_waitcnt lgkmcnt(0)
	v_cvt_pk_bf16_f32 v6, v6, v10
	global_store_dword v[12:13], v6, off offset:192
.LBB0_2972:
	s_or_b64 exec, exec, s[20:21]
	v_rcp_f32_e32 v6, v7
	s_waitcnt lgkmcnt(1)
	v_or_b32_e32 v11, 17, v209
	v_lshlrev_b32_e32 v196, 12, v11
	v_mul_f32_e32 v7, v57, v6
	s_waitcnt lgkmcnt(0)
	s_nop 1
	v_mov_b32_dpp v10, v7 quad_perm:[1,0,3,2] row_mask:0xf bank_mask:0xf
	s_and_saveexec_b64 s[20:21], vcc
	s_cbranch_execz .LBB0_2974
	v_lshl_add_u64 v[12:13], s[0:1], 0, v[196:197]
	v_mov_b32_e32 v15, v197
	v_lshl_add_u64 v[12:13], v[12:13], 0, v[14:15]
	s_waitcnt lgkmcnt(0)
	v_cvt_pk_bf16_f32 v7, v7, v10
	global_store_dword v[12:13], v7, off
.LBB0_2974:
	s_or_b64 exec, exec, s[20:21]
	v_mul_f32_e32 v7, v73, v6
	s_waitcnt lgkmcnt(0)
	s_nop 1
	v_mov_b32_dpp v10, v7 quad_perm:[1,0,3,2] row_mask:0xf bank_mask:0xf
	s_and_saveexec_b64 s[20:21], vcc
	s_cbranch_execz .LBB0_2976
	v_lshl_add_u64 v[12:13], s[0:1], 0, v[196:197]
	v_mov_b32_e32 v15, v197
	v_lshl_add_u64 v[12:13], v[12:13], 0, v[14:15]
	s_waitcnt lgkmcnt(0)
	v_cvt_pk_bf16_f32 v7, v7, v10
	global_store_dword v[12:13], v7, off offset:64
.LBB0_2976:
	s_or_b64 exec, exec, s[20:21]
	v_mul_f32_e32 v7, v41, v6
	s_waitcnt lgkmcnt(0)
	s_nop 1
	v_mov_b32_dpp v10, v7 quad_perm:[1,0,3,2] row_mask:0xf bank_mask:0xf
	s_and_saveexec_b64 s[20:21], vcc
	s_cbranch_execz .LBB0_2978
	v_lshl_add_u64 v[12:13], s[0:1], 0, v[196:197]
	v_mov_b32_e32 v15, v197
	v_lshl_add_u64 v[12:13], v[12:13], 0, v[14:15]
	s_waitcnt lgkmcnt(0)
	v_cvt_pk_bf16_f32 v7, v7, v10
	global_store_dword v[12:13], v7, off offset:128
.LBB0_2978:
	s_or_b64 exec, exec, s[20:21]
	v_mul_f32_e32 v6, v25, v6
	s_nop 1
	v_mov_b32_dpp v7, v6 quad_perm:[1,0,3,2] row_mask:0xf bank_mask:0xf
	s_and_saveexec_b64 s[20:21], vcc
	s_cbranch_execz .LBB0_2980
	s_waitcnt lgkmcnt(0)
	v_lshl_add_u64 v[10:11], s[0:1], 0, v[196:197]
	v_mov_b32_e32 v15, v197
	v_lshl_add_u64 v[10:11], v[10:11], 0, v[14:15]
	s_waitcnt lgkmcnt(0)
	v_cvt_pk_bf16_f32 v6, v6, v7
	global_store_dword v[10:11], v6, off offset:192
.LBB0_2980:
	s_or_b64 exec, exec, s[20:21]
	v_rcp_f32_e32 v6, v8
	s_waitcnt lgkmcnt(1)
	v_or_b32_e32 v10, 18, v209
	v_lshlrev_b32_e32 v196, 12, v10
	s_waitcnt lgkmcnt(0)
	v_mul_f32_e32 v7, v58, v6
	s_nop 1
	v_mov_b32_dpp v8, v7 quad_perm:[1,0,3,2] row_mask:0xf bank_mask:0xf
	s_and_saveexec_b64 s[20:21], vcc
	s_cbranch_execz .LBB0_2982
	v_lshl_add_u64 v[10:11], s[0:1], 0, v[196:197]
	v_mov_b32_e32 v15, v197
	v_lshl_add_u64 v[10:11], v[10:11], 0, v[14:15]
	s_waitcnt lgkmcnt(0)
	v_cvt_pk_bf16_f32 v7, v7, v8
	global_store_dword v[10:11], v7, off
.LBB0_2982:
	s_or_b64 exec, exec, s[20:21]
	v_mul_f32_e32 v7, v74, v6
	s_waitcnt lgkmcnt(0)
	s_nop 1
	v_mov_b32_dpp v8, v7 quad_perm:[1,0,3,2] row_mask:0xf bank_mask:0xf
	s_and_saveexec_b64 s[20:21], vcc
	s_cbranch_execz .LBB0_2984
	v_lshl_add_u64 v[10:11], s[0:1], 0, v[196:197]
	v_mov_b32_e32 v15, v197
	v_lshl_add_u64 v[10:11], v[10:11], 0, v[14:15]
	s_waitcnt lgkmcnt(0)
	v_cvt_pk_bf16_f32 v7, v7, v8
	global_store_dword v[10:11], v7, off offset:64
.LBB0_2984:
	s_or_b64 exec, exec, s[20:21]
	v_mul_f32_e32 v7, v42, v6
	s_waitcnt lgkmcnt(0)
	s_nop 1
	v_mov_b32_dpp v8, v7 quad_perm:[1,0,3,2] row_mask:0xf bank_mask:0xf
	s_and_saveexec_b64 s[20:21], vcc
	s_cbranch_execz .LBB0_2986
	v_lshl_add_u64 v[10:11], s[0:1], 0, v[196:197]
	v_mov_b32_e32 v15, v197
	v_lshl_add_u64 v[10:11], v[10:11], 0, v[14:15]
	s_waitcnt lgkmcnt(0)
	v_cvt_pk_bf16_f32 v7, v7, v8
	global_store_dword v[10:11], v7, off offset:128
.LBB0_2986:
	s_or_b64 exec, exec, s[20:21]
	v_mul_f32_e32 v6, v26, v6
	s_nop 1
	v_mov_b32_dpp v7, v6 quad_perm:[1,0,3,2] row_mask:0xf bank_mask:0xf
	s_and_saveexec_b64 s[20:21], vcc
	s_cbranch_execz .LBB0_2988
	v_lshl_add_u64 v[10:11], s[0:1], 0, v[196:197]
	v_mov_b32_e32 v15, v197
	v_lshl_add_u64 v[10:11], v[10:11], 0, v[14:15]
	s_waitcnt lgkmcnt(0)
	v_cvt_pk_bf16_f32 v6, v6, v7
	global_store_dword v[10:11], v6, off offset:192
.LBB0_2988:
	s_or_b64 exec, exec, s[20:21]
	v_rcp_f32_e32 v6, v9
	v_or_b32_e32 v9, 19, v209
	v_lshlrev_b32_e32 v196, 12, v9
	s_waitcnt lgkmcnt(0)
	v_mul_f32_e32 v7, v59, v6
	s_nop 1
	v_mov_b32_dpp v8, v7 quad_perm:[1,0,3,2] row_mask:0xf bank_mask:0xf
	s_and_saveexec_b64 s[20:21], vcc
	s_cbranch_execz .LBB0_2990
	v_lshl_add_u64 v[10:11], s[0:1], 0, v[196:197]
	v_mov_b32_e32 v15, v197
	v_lshl_add_u64 v[10:11], v[10:11], 0, v[14:15]
	s_waitcnt lgkmcnt(0)
	v_cvt_pk_bf16_f32 v7, v7, v8
	global_store_dword v[10:11], v7, off
.LBB0_2990:
	s_or_b64 exec, exec, s[20:21]
	v_mul_f32_e32 v7, v75, v6
	s_waitcnt lgkmcnt(0)
	s_nop 1
	v_mov_b32_dpp v8, v7 quad_perm:[1,0,3,2] row_mask:0xf bank_mask:0xf
	s_and_saveexec_b64 s[20:21], vcc
	s_cbranch_execz .LBB0_2992
	v_lshl_add_u64 v[10:11], s[0:1], 0, v[196:197]
	v_mov_b32_e32 v15, v197
	v_lshl_add_u64 v[10:11], v[10:11], 0, v[14:15]
	s_waitcnt lgkmcnt(0)
	v_cvt_pk_bf16_f32 v7, v7, v8
	global_store_dword v[10:11], v7, off offset:64
.LBB0_2992:
	s_or_b64 exec, exec, s[20:21]
	v_mul_f32_e32 v7, v43, v6
	s_waitcnt lgkmcnt(0)
	s_nop 1
	v_mov_b32_dpp v8, v7 quad_perm:[1,0,3,2] row_mask:0xf bank_mask:0xf
	s_and_saveexec_b64 s[20:21], vcc
	s_cbranch_execz .LBB0_2994
	v_lshl_add_u64 v[10:11], s[0:1], 0, v[196:197]
	v_mov_b32_e32 v15, v197
	v_lshl_add_u64 v[10:11], v[10:11], 0, v[14:15]
	s_waitcnt lgkmcnt(0)
	v_cvt_pk_bf16_f32 v7, v7, v8
	global_store_dword v[10:11], v7, off offset:128
.LBB0_2994:
	s_or_b64 exec, exec, s[20:21]
	v_mul_f32_e32 v6, v27, v6
	s_nop 1
	v_mov_b32_dpp v7, v6 quad_perm:[1,0,3,2] row_mask:0xf bank_mask:0xf
	s_and_saveexec_b64 s[20:21], vcc
	s_cbranch_execz .LBB0_2996
	s_waitcnt lgkmcnt(0)
	v_lshl_add_u64 v[8:9], s[0:1], 0, v[196:197]
	v_mov_b32_e32 v15, v197
	v_lshl_add_u64 v[8:9], v[8:9], 0, v[14:15]
	s_waitcnt lgkmcnt(0)
	v_cvt_pk_bf16_f32 v6, v6, v7
	global_store_dword v[8:9], v6, off offset:192
.LBB0_2996:
	s_or_b64 exec, exec, s[20:21]
	v_rcp_f32_e32 v2, v2
	s_waitcnt lgkmcnt(1)
	v_or_b32_e32 v8, 24, v209
	v_lshlrev_b32_e32 v196, 12, v8
	v_mul_f32_e32 v6, v60, v2
	s_waitcnt lgkmcnt(0)
	s_nop 1
	v_mov_b32_dpp v7, v6 quad_perm:[1,0,3,2] row_mask:0xf bank_mask:0xf
	s_and_saveexec_b64 s[20:21], vcc
	s_cbranch_execz .LBB0_2998
	v_lshl_add_u64 v[8:9], s[0:1], 0, v[196:197]
	v_mov_b32_e32 v15, v197
	v_lshl_add_u64 v[8:9], v[8:9], 0, v[14:15]
	s_waitcnt lgkmcnt(0)
	v_cvt_pk_bf16_f32 v6, v6, v7
	global_store_dword v[8:9], v6, off
.LBB0_2998:
	s_or_b64 exec, exec, s[20:21]
	v_mul_f32_e32 v6, v76, v2
	s_waitcnt lgkmcnt(0)
	s_nop 1
	v_mov_b32_dpp v7, v6 quad_perm:[1,0,3,2] row_mask:0xf bank_mask:0xf
	s_and_saveexec_b64 s[20:21], vcc
	s_cbranch_execz .LBB0_3000
	v_lshl_add_u64 v[8:9], s[0:1], 0, v[196:197]
	v_mov_b32_e32 v15, v197
	v_lshl_add_u64 v[8:9], v[8:9], 0, v[14:15]
	s_waitcnt lgkmcnt(0)
	v_cvt_pk_bf16_f32 v6, v6, v7
	global_store_dword v[8:9], v6, off offset:64
.LBB0_3000:
	s_or_b64 exec, exec, s[20:21]
	v_mul_f32_e32 v6, v44, v2
	s_waitcnt lgkmcnt(0)
	s_nop 1
	v_mov_b32_dpp v7, v6 quad_perm:[1,0,3,2] row_mask:0xf bank_mask:0xf
	s_and_saveexec_b64 s[20:21], vcc
	s_cbranch_execz .LBB0_3002
	v_lshl_add_u64 v[8:9], s[0:1], 0, v[196:197]
	v_mov_b32_e32 v15, v197
	v_lshl_add_u64 v[8:9], v[8:9], 0, v[14:15]
	s_waitcnt lgkmcnt(0)
	v_cvt_pk_bf16_f32 v6, v6, v7
	global_store_dword v[8:9], v6, off offset:128
.LBB0_3002:
	s_or_b64 exec, exec, s[20:21]
	v_mul_f32_e32 v2, v28, v2
	s_nop 1
	v_mov_b32_dpp v6, v2 quad_perm:[1,0,3,2] row_mask:0xf bank_mask:0xf
	s_and_saveexec_b64 s[20:21], vcc
	s_cbranch_execz .LBB0_3004
	v_lshl_add_u64 v[8:9], s[0:1], 0, v[196:197]
	v_mov_b32_e32 v15, v197
	v_lshl_add_u64 v[8:9], v[8:9], 0, v[14:15]
	s_waitcnt lgkmcnt(0)
	v_cvt_pk_bf16_f32 v2, v2, v6
	global_store_dword v[8:9], v2, off offset:192
.LBB0_3004:
	s_or_b64 exec, exec, s[20:21]
	v_rcp_f32_e32 v2, v3
	s_waitcnt lgkmcnt(1)
	v_or_b32_e32 v7, 25, v209
	v_lshlrev_b32_e32 v196, 12, v7
	v_mul_f32_e32 v3, v61, v2
	s_waitcnt lgkmcnt(0)
	s_nop 1
	v_mov_b32_dpp v6, v3 quad_perm:[1,0,3,2] row_mask:0xf bank_mask:0xf
	s_and_saveexec_b64 s[20:21], vcc
	s_cbranch_execz .LBB0_3006
	v_lshl_add_u64 v[8:9], s[0:1], 0, v[196:197]
	v_mov_b32_e32 v15, v197
	v_lshl_add_u64 v[8:9], v[8:9], 0, v[14:15]
	s_waitcnt lgkmcnt(0)
	v_cvt_pk_bf16_f32 v3, v3, v6
	global_store_dword v[8:9], v3, off
.LBB0_3006:
	s_or_b64 exec, exec, s[20:21]
	v_mul_f32_e32 v3, v77, v2
	s_waitcnt lgkmcnt(0)
	s_nop 1
	v_mov_b32_dpp v6, v3 quad_perm:[1,0,3,2] row_mask:0xf bank_mask:0xf
	s_and_saveexec_b64 s[20:21], vcc
	s_cbranch_execz .LBB0_3008
	v_lshl_add_u64 v[8:9], s[0:1], 0, v[196:197]
	v_mov_b32_e32 v15, v197
	v_lshl_add_u64 v[8:9], v[8:9], 0, v[14:15]
	s_waitcnt lgkmcnt(0)
	v_cvt_pk_bf16_f32 v3, v3, v6
	global_store_dword v[8:9], v3, off offset:64
.LBB0_3008:
	s_or_b64 exec, exec, s[20:21]
	v_mul_f32_e32 v3, v45, v2
	s_waitcnt lgkmcnt(0)
	s_nop 1
	v_mov_b32_dpp v6, v3 quad_perm:[1,0,3,2] row_mask:0xf bank_mask:0xf
	s_and_saveexec_b64 s[20:21], vcc
	s_cbranch_execz .LBB0_3010
	v_lshl_add_u64 v[8:9], s[0:1], 0, v[196:197]
	v_mov_b32_e32 v15, v197
	v_lshl_add_u64 v[8:9], v[8:9], 0, v[14:15]
	s_waitcnt lgkmcnt(0)
	v_cvt_pk_bf16_f32 v3, v3, v6
	global_store_dword v[8:9], v3, off offset:128
.LBB0_3010:
	s_or_b64 exec, exec, s[20:21]
	v_mul_f32_e32 v2, v29, v2
	s_nop 1
	v_mov_b32_dpp v3, v2 quad_perm:[1,0,3,2] row_mask:0xf bank_mask:0xf
	s_and_saveexec_b64 s[20:21], vcc
	s_cbranch_execz .LBB0_3012
	s_waitcnt lgkmcnt(0)
	v_lshl_add_u64 v[6:7], s[0:1], 0, v[196:197]
	v_mov_b32_e32 v15, v197
	v_lshl_add_u64 v[6:7], v[6:7], 0, v[14:15]
	s_waitcnt lgkmcnt(0)
	v_cvt_pk_bf16_f32 v2, v2, v3
	global_store_dword v[6:7], v2, off offset:192
.LBB0_3012:
	s_or_b64 exec, exec, s[20:21]
	v_rcp_f32_e32 v2, v4
	s_waitcnt lgkmcnt(1)
	v_or_b32_e32 v6, 26, v209
	v_lshlrev_b32_e32 v196, 12, v6
	s_waitcnt lgkmcnt(0)
	v_mul_f32_e32 v3, v62, v2
	s_nop 1
	v_mov_b32_dpp v4, v3 quad_perm:[1,0,3,2] row_mask:0xf bank_mask:0xf
	s_and_saveexec_b64 s[20:21], vcc
	s_cbranch_execz .LBB0_3014
	v_lshl_add_u64 v[6:7], s[0:1], 0, v[196:197]
	v_mov_b32_e32 v15, v197
	v_lshl_add_u64 v[6:7], v[6:7], 0, v[14:15]
	s_waitcnt lgkmcnt(0)
	v_cvt_pk_bf16_f32 v3, v3, v4
	global_store_dword v[6:7], v3, off
.LBB0_3014:
	s_or_b64 exec, exec, s[20:21]
	v_mul_f32_e32 v3, v78, v2
	s_waitcnt lgkmcnt(0)
	s_nop 1
	v_mov_b32_dpp v4, v3 quad_perm:[1,0,3,2] row_mask:0xf bank_mask:0xf
	s_and_saveexec_b64 s[20:21], vcc
	s_cbranch_execz .LBB0_3016
	v_lshl_add_u64 v[6:7], s[0:1], 0, v[196:197]
	v_mov_b32_e32 v15, v197
	v_lshl_add_u64 v[6:7], v[6:7], 0, v[14:15]
	s_waitcnt lgkmcnt(0)
	v_cvt_pk_bf16_f32 v3, v3, v4
	global_store_dword v[6:7], v3, off offset:64
.LBB0_3016:
	s_or_b64 exec, exec, s[20:21]
	v_mul_f32_e32 v3, v46, v2
	s_waitcnt lgkmcnt(0)
	s_nop 1
	v_mov_b32_dpp v4, v3 quad_perm:[1,0,3,2] row_mask:0xf bank_mask:0xf
	s_and_saveexec_b64 s[20:21], vcc
	s_cbranch_execz .LBB0_3018
	v_lshl_add_u64 v[6:7], s[0:1], 0, v[196:197]
	v_mov_b32_e32 v15, v197
	v_lshl_add_u64 v[6:7], v[6:7], 0, v[14:15]
	s_waitcnt lgkmcnt(0)
	v_cvt_pk_bf16_f32 v3, v3, v4
	global_store_dword v[6:7], v3, off offset:128
.LBB0_3018:
	s_or_b64 exec, exec, s[20:21]
	v_mul_f32_e32 v2, v30, v2
	s_nop 1
	v_mov_b32_dpp v3, v2 quad_perm:[1,0,3,2] row_mask:0xf bank_mask:0xf
	s_and_saveexec_b64 s[20:21], vcc
	s_cbranch_execz .LBB0_3020
	v_lshl_add_u64 v[6:7], s[0:1], 0, v[196:197]
	v_mov_b32_e32 v15, v197
	v_lshl_add_u64 v[6:7], v[6:7], 0, v[14:15]
	s_waitcnt lgkmcnt(0)
	v_cvt_pk_bf16_f32 v2, v2, v3
	global_store_dword v[6:7], v2, off offset:192
.LBB0_3020:
	s_or_b64 exec, exec, s[20:21]
	v_rcp_f32_e32 v2, v5
	v_or_b32_e32 v5, 27, v209
	v_lshlrev_b32_e32 v196, 12, v5
	s_waitcnt lgkmcnt(0)
	v_mul_f32_e32 v3, v63, v2
	s_nop 1
	v_mov_b32_dpp v4, v3 quad_perm:[1,0,3,2] row_mask:0xf bank_mask:0xf
	s_and_saveexec_b64 s[20:21], vcc
	s_cbranch_execz .LBB0_3022
	v_lshl_add_u64 v[6:7], s[0:1], 0, v[196:197]
	v_mov_b32_e32 v15, v197
	v_lshl_add_u64 v[6:7], v[6:7], 0, v[14:15]
	s_waitcnt lgkmcnt(0)
	v_cvt_pk_bf16_f32 v3, v3, v4
	global_store_dword v[6:7], v3, off
.LBB0_3022:
	s_or_b64 exec, exec, s[20:21]
	v_mul_f32_e32 v3, v79, v2
	s_waitcnt lgkmcnt(0)
	s_nop 1
	v_mov_b32_dpp v4, v3 quad_perm:[1,0,3,2] row_mask:0xf bank_mask:0xf
	s_and_saveexec_b64 s[20:21], vcc
	s_cbranch_execz .LBB0_3024
	v_lshl_add_u64 v[6:7], s[0:1], 0, v[196:197]
	v_mov_b32_e32 v15, v197
	v_lshl_add_u64 v[6:7], v[6:7], 0, v[14:15]
	s_waitcnt lgkmcnt(0)
	v_cvt_pk_bf16_f32 v3, v3, v4
	global_store_dword v[6:7], v3, off offset:64
.LBB0_3024:
	s_or_b64 exec, exec, s[20:21]
	v_mul_f32_e32 v3, v47, v2
	s_waitcnt lgkmcnt(0)
	s_nop 1
	v_mov_b32_dpp v4, v3 quad_perm:[1,0,3,2] row_mask:0xf bank_mask:0xf
	s_and_saveexec_b64 s[20:21], vcc
	s_cbranch_execz .LBB0_3026
	v_lshl_add_u64 v[6:7], s[0:1], 0, v[196:197]
	v_mov_b32_e32 v15, v197
	v_lshl_add_u64 v[6:7], v[6:7], 0, v[14:15]
	s_waitcnt lgkmcnt(0)
	v_cvt_pk_bf16_f32 v3, v3, v4
	global_store_dword v[6:7], v3, off offset:128
.LBB0_3026:
	s_or_b64 exec, exec, s[20:21]
	v_mul_f32_e32 v2, v31, v2
	s_nop 1
	v_mov_b32_dpp v1, v2 quad_perm:[1,0,3,2] row_mask:0xf bank_mask:0xf
	s_and_saveexec_b64 s[20:21], vcc
	s_cbranch_execz .LBB0_3028
	s_waitcnt lgkmcnt(0)
	v_lshl_add_u64 v[4:5], s[0:1], 0, v[196:197]
	v_mov_b32_e32 v15, v197
	v_lshl_add_u64 v[4:5], v[4:5], 0, v[14:15]
	s_waitcnt lgkmcnt(0)
	v_cvt_pk_bf16_f32 v1, v2, v1
	global_store_dword v[4:5], v1, off offset:192

.LBB0_3122:
	v_lshl_add_u64 v[22:23], s[62:63], 0, v[144:145]
	v_mov_b32_e32 v157, v145
	v_lshl_add_u64 v[24:25], s[62:63], 0, v[156:157]
	v_mov_b32_e32 v153, v145
	s_add_i32 m0, s7, 0x18000
	v_lshl_add_u64 v[22:23], v[22:23], 0, s[42:43]
	v_lshl_add_u64 v[26:27], s[60:61], 0, v[152:153]
	v_mov_b32_e32 v155, v145
	s_waitcnt vmcnt(2)
	s_barrier
	global_load_lds_dwordx4 v[22:23], off
	v_lshl_add_u64 v[22:23], v[24:25], 0, s[42:43]
	s_add_i32 m0, s7, 0x1a000
	s_add_i32 s11, s7, 0x8000
	s_add_i32 s12, s7, 0xa000
	v_lshl_add_u64 v[28:29], s[60:61], 0, v[154:155]
	global_load_lds_dwordx4 v[22:23], off
	v_lshl_add_u64 v[22:23], v[26:27], 0, s[42:43]
	s_mov_b32 m0, s11
	s_add_u32 s26, s62, 0x80080
	global_load_lds_dwordx4 v[22:23], off
	v_lshl_add_u64 v[22:23], v[28:29], 0, s[42:43]
	s_mov_b32 m0, s12
	s_addc_u32 s27, s63, 0
	global_load_lds_dwordx4 v[22:23], off
	s_add_i32 m0, s7, 0x1c000
	v_lshl_add_u64 v[22:23], s[26:27], 0, v[144:145]
	global_load_lds_dwordx4 v[22:23], off
	v_lshl_add_u64 v[22:23], s[26:27], 0, v[156:157]
	s_add_i32 m0, s7, 0x1e000
	s_waitcnt vmcnt(0)
	v_pk_add_f32 v[10:11], v[14:15], v[10:11]
	global_load_lds_dwordx4 v[22:23], off
	v_pk_add_f32 v[8:9], v[12:13], v[8:9]
	v_pk_add_f32 v[0:1], v[4:5], v[0:1]
	v_pk_add_f32 v[2:3], v[6:7], v[2:3]
	v_pk_add_f32 v[0:1], v[8:9], v[0:1]
	v_pk_add_f32 v[2:3], v[10:11], v[2:3]
	v_add_f32_e32 v0, v0, v1
	v_add_f32_e32 v1, v2, v3
	v_and_b32_e32 v2, 64, v204
	v_add_f32_e32 v0, v0, v1
	v_xor_b32_e32 v1, 1, v204
	v_add_u32_e32 v2, 64, v2
	v_cmp_lt_i32_e32 vcc, v1, v2
	s_waitcnt vmcnt(6)
	v_cmp_eq_u32_e64 s[34:35], 0, v17
	s_barrier
	v_cndmask_b32_e32 v1, v204, v1, vcc
	v_lshlrev_b32_e32 v167, 2, v1
	s_nop 1
	v_mov_b32_dpp v1, v0 quad_perm:[1,0,3,2] row_mask:0xf bank_mask:0xf
	s_and_saveexec_b64 s[26:27], s[34:35]
	s_cbranch_execz .LBB0_3124
	s_waitcnt lgkmcnt(0)
	v_add_f32_e32 v0, v0, v1
	v_fmamk_f32 v0, v0, 0x3a000000, v164
	v_cmp_gt_f32_e32 vcc, s75, v0
	v_mul_f32_e32 v1, 0x4b800000, v0
	s_nop 0
	v_cndmask_b32_e32 v0, v0, v1, vcc
	v_rsq_f32_e32 v0, v0
	s_nop 0
	v_mul_f32_e32 v1, 0x45800000, v0
	v_cndmask_b32_e32 v0, v0, v1, vcc
	v_lshl_add_u32 v1, v16, 2, 0
	v_add_u32_e32 v1, 0x20000, v1
	ds_write_b32 v1, v0

.LBB0_3731:
	s_mov_b64 s[26:27], 0x80
	s_add_i32 m0, s7, 0x18000
	v_lshl_add_u64 v[26:27], v[26:27], 0, s[26:27]
	s_waitcnt vmcnt(2)
	s_barrier
	global_load_lds_dwordx4 v[26:27], off
	v_lshl_add_u64 v[24:25], v[24:25], 0, s[26:27]
	s_add_i32 m0, s7, 0x1a000
	s_add_i32 s11, s7, 0x8000
	s_add_i32 s12, s7, 0xa000
	global_load_lds_dwordx4 v[24:25], off
	v_lshl_add_u64 v[20:21], v[20:21], 0, s[26:27]
	s_mov_b32 m0, s11
	s_add_u32 s30, s60, 0x80080
	global_load_lds_dwordx4 v[20:21], off
	v_lshl_add_u64 v[20:21], v[22:23], 0, s[26:27]
	s_mov_b32 m0, s12
	s_addc_u32 s31, s61, 0
	global_load_lds_dwordx4 v[20:21], off
	s_add_i32 m0, s7, 0x1c000
	v_lshl_add_u64 v[20:21], s[30:31], 0, v[146:147]
	global_load_lds_dwordx4 v[20:21], off
	v_lshl_add_u64 v[20:21], s[30:31], 0, v[150:151]
	s_add_i32 m0, s7, 0x1e000
	s_waitcnt vmcnt(0)
	v_pk_add_f32 v[10:11], v[14:15], v[10:11]
	global_load_lds_dwordx4 v[20:21], off
	v_pk_add_f32 v[8:9], v[12:13], v[8:9]
	v_pk_add_f32 v[0:1], v[4:5], v[0:1]
	v_pk_add_f32 v[2:3], v[6:7], v[2:3]
	v_pk_add_f32 v[0:1], v[8:9], v[0:1]
	v_pk_add_f32 v[2:3], v[10:11], v[2:3]
	v_add_f32_e32 v0, v0, v1
	v_add_f32_e32 v1, v2, v3
	v_and_b32_e32 v2, 64, v204
	v_add_f32_e32 v0, v0, v1
	v_xor_b32_e32 v1, 1, v204
	v_add_u32_e32 v2, 64, v2
	v_cmp_lt_i32_e32 vcc, v1, v2
	s_waitcnt vmcnt(6)
	s_mov_b32 s41, 0
	v_cmp_eq_u32_e64 s[34:35], 0, v17
	v_cndmask_b32_e32 v1, v204, v1, vcc
	v_lshlrev_b32_e32 v174, 2, v1
	s_nop 1
	v_mov_b32_dpp v1, v0 quad_perm:[1,0,3,2] row_mask:0xf bank_mask:0xf
	s_barrier
	s_and_saveexec_b64 s[38:39], s[34:35]
	s_cbranch_execz .LBB0_3733
	s_waitcnt lgkmcnt(0)
	v_add_f32_e32 v0, v0, v1
	v_mov_b32_e32 v1, 0x358637bd
	v_fmac_f32_e32 v1, 0x3a000000, v0
	s_mov_b32 s30, 0x800000
	v_mul_f32_e32 v0, 0x4b800000, v1
	v_cmp_gt_f32_e32 vcc, s30, v1
	s_nop 1
	v_cndmask_b32_e32 v0, v1, v0, vcc
	v_rsq_f32_e32 v0, v0
	s_nop 0
	v_mul_f32_e32 v1, 0x45800000, v0
	v_cndmask_b32_e32 v0, v0, v1, vcc
	v_lshl_add_u32 v1, v16, 2, 0
	v_add_u32_e32 v1, 0x20000, v1
	ds_write_b32 v1, v0

.LBB0_3856:
	s_or_b64 exec, exec, s[20:21]
	v_mul_lo_u32 v25, v32, s41
	v_lshlrev_b32_e32 v26, 1, v57
	v_add3_u32 v25, s42, v25, v26
	ds_write_b16 v25, v0
	ds_write_b16_d16_hi v25, v0 offset:144
	ds_write_b16 v25, v1 offset:288
	ds_write_b16_d16_hi v25, v1 offset:432
	ds_write_b16 v25, v2 offset:576
	ds_write_b16_d16_hi v25, v2 offset:720
	ds_write_b16 v25, v3 offset:864
	ds_write_b16_d16_hi v25, v3 offset:1008
	v_mul_lo_u32 v0, v28, s41
	v_add3_u32 v0, s42, v0, v26
	ds_write_b16 v0, v12
	ds_write_b16_d16_hi v0, v12 offset:144
	ds_write_b16 v0, v13 offset:288
	ds_write_b16_d16_hi v0, v13 offset:432
	ds_write_b16 v0, v14 offset:576
	ds_write_b16_d16_hi v0, v14 offset:720
	ds_write_b16 v0, v15 offset:864
	ds_write_b16_d16_hi v0, v15 offset:1008
	v_mul_lo_u32 v0, v30, s41
	v_add3_u32 v0, s42, v0, v26
	ds_write_b16 v0, v4
	ds_write_b16_d16_hi v0, v4 offset:144
	ds_write_b16 v0, v5 offset:288
	ds_write_b16_d16_hi v0, v5 offset:432
	ds_write_b16 v0, v6 offset:576
	ds_write_b16_d16_hi v0, v6 offset:720
	ds_write_b16 v0, v7 offset:864
	ds_write_b16_d16_hi v0, v7 offset:1008
	v_mul_lo_u32 v0, v34, s41
	v_add3_u32 v0, s42, v0, v26
	ds_write_b16 v0, v16
	ds_write_b16_d16_hi v0, v16 offset:144
	ds_write_b16 v0, v17 offset:288
	ds_write_b16_d16_hi v0, v17 offset:432
	ds_write_b16 v0, v18 offset:576
	ds_write_b16_d16_hi v0, v18 offset:720
	ds_write_b16 v0, v19 offset:864
	ds_write_b16_d16_hi v0, v19 offset:1008
	v_mul_lo_u32 v0, v36, s41
	v_add3_u32 v0, s42, v0, v26
	v_bfe_u32 v16, v24, 6, 2
	v_bfe_u32 v154, v149, 5, 1
	ds_write_b16 v0, v8
	ds_write_b16_d16_hi v0, v8 offset:144
	ds_write_b16 v0, v9 offset:288
	ds_write_b16_d16_hi v0, v9 offset:432
	ds_write_b16 v0, v10 offset:576
	ds_write_b16_d16_hi v0, v10 offset:720
	ds_write_b16 v0, v11 offset:864
	ds_write_b16_d16_hi v0, v11 offset:1008
	v_mul_lo_u32 v0, v38, s41
	v_and_b32_e32 v146, 31, v149
	v_lshlrev_b32_e32 v1, 4, v154
	v_mul_u32_u24_e32 v176, 0x60, v16
	v_add3_u32 v0, s42, v0, v26
	v_add_u32_e32 v17, s42, v1
	v_add_u32_e32 v4, 0, v1
	v_or_b32_e32 v1, v176, v146
	ds_write_b16 v0, v20
	ds_write_b16_d16_hi v0, v20 offset:144
	ds_write_b16 v0, v21 offset:288
	ds_write_b16_d16_hi v0, v21 offset:432
	ds_write_b16 v0, v22 offset:576
	ds_write_b16_d16_hi v0, v22 offset:720
	ds_write_b16 v0, v23 offset:864
	ds_write_b16_d16_hi v0, v23 offset:1008
	v_lshrrev_b32_e32 v0, 8, v24
	v_mad_u32_u24 v152, v1, s41, v17
	s_waitcnt lgkmcnt(0)
	s_barrier
	v_mul_i32_i24_e32 v148, 0x60, v0
	ds_read_b128 v[0:3], v152
	v_or_b32_e32 v5, v148, v146
	v_mul_lo_u32 v5, v5, s41
	v_add_u32_e32 v172, v4, v5
	ds_read_b128 v[4:7], v172 offset:54272
	ds_read_b128 v[8:11], v172 offset:58880
	ds_read_b128 v[12:15], v172 offset:63488
	v_mad_u32_u24 v155, v16, s43, 32
	v_or_b32_e32 v18, v155, v146
	v_mad_u32_u24 v173, v18, s41, v17
	s_waitcnt lgkmcnt(2)
	v_mfma_f32_32x32x16_bf16 v[128:143], v[0:3], v[4:7], 0
	v_mad_u32_u24 v153, v16, s43, 64
	v_or_b32_e32 v16, v153, v146
	v_mad_u32_u24 v174, v16, s41, v17
	s_mul_hi_i32 s1, s26, 0x24000
	s_mul_i32 s26, s26, 0x24000
	s_add_u32 s0, s2, s26
	s_addc_u32 s1, s3, s1
	s_waitcnt lgkmcnt(1)
	v_mfma_f32_32x32x16_bf16 v[112:127], v[0:3], v[8:11], 0
	v_and_b32_e32 v149, 1, v149
	v_lshlrev_b32_e32 v146, 1, v146
	v_cmp_eq_u32_e64 s[34:35], 0, v149
	v_ashrrev_i32_e32 v149, 31, v148
	v_lshlrev_b32_e32 v154, 2, v154
	s_waitcnt lgkmcnt(0)
	v_mfma_f32_32x32x16_bf16 v[96:111], v[0:3], v[12:15], 0
	ds_read_b128 v[0:3], v173
	s_waitcnt vmcnt(0) lgkmcnt(0)
	v_mfma_f32_32x32x16_bf16 v[80:95], v[0:3], v[4:7], 0
	v_mfma_f32_32x32x16_bf16 v[64:79], v[0:3], v[8:11], 0
	v_mfma_f32_32x32x16_bf16 v[48:63], v[0:3], v[12:15], 0
	ds_read_b128 v[0:3], v174
	ds_read_b128 v[156:159], v152 offset:32
	ds_read_b128 v[160:163], v172 offset:54304
	ds_read_b128 v[164:167], v172 offset:58912
	ds_read_b128 v[168:171], v172 offset:63520
	s_waitcnt lgkmcnt(2)
	v_mfma_f32_32x32x16_bf16 v[128:143], v[156:159], v[160:163], v[128:143]
	s_waitcnt lgkmcnt(1)
	v_mfma_f32_32x32x16_bf16 v[112:127], v[156:159], v[164:167], v[112:127]
	s_waitcnt lgkmcnt(0)
	v_mfma_f32_32x32x16_bf16 v[96:111], v[156:159], v[168:171], v[96:111]
	ds_read_b128 v[156:159], v173 offset:32
	s_waitcnt lgkmcnt(0)
	v_mfma_f32_32x32x16_bf16 v[80:95], v[156:159], v[160:163], v[80:95]
	v_mfma_f32_32x32x16_bf16 v[64:79], v[156:159], v[164:167], v[64:79]
	v_mfma_f32_32x32x16_bf16 v[48:63], v[156:159], v[168:171], v[48:63]
	ds_read_b128 v[156:159], v174 offset:32
	v_mfma_f32_32x32x16_bf16 v[32:47], v[0:3], v[4:7], 0
	v_mfma_f32_32x32x16_bf16 v[16:31], v[0:3], v[8:11], 0
	v_mfma_f32_32x32x16_bf16 v[0:15], v[0:3], v[12:15], 0
	s_waitcnt lgkmcnt(0)
	v_mfma_f32_32x32x16_bf16 v[32:47], v[156:159], v[160:163], v[32:47]
	v_mfma_f32_32x32x16_bf16 v[16:31], v[156:159], v[164:167], v[16:31]
	v_mfma_f32_32x32x16_bf16 v[0:15], v[156:159], v[168:171], v[0:15]
	ds_read_b128 v[156:159], v152 offset:64
	ds_read_b128 v[160:163], v172 offset:54336
	ds_read_b128 v[164:167], v172 offset:58944
	ds_read_b128 v[168:171], v172 offset:63552
	s_waitcnt lgkmcnt(2)
	v_mfma_f32_32x32x16_bf16 v[128:143], v[156:159], v[160:163], v[128:143]
	s_waitcnt lgkmcnt(1)
	v_mfma_f32_32x32x16_bf16 v[112:127], v[156:159], v[164:167], v[112:127]
	s_waitcnt lgkmcnt(0)
	v_mfma_f32_32x32x16_bf16 v[96:111], v[156:159], v[168:171], v[96:111]
	ds_read_b128 v[156:159], v173 offset:64
	s_waitcnt lgkmcnt(0)
	v_mfma_f32_32x32x16_bf16 v[80:95], v[156:159], v[160:163], v[80:95]
	v_mfma_f32_32x32x16_bf16 v[64:79], v[156:159], v[164:167], v[64:79]
	v_mfma_f32_32x32x16_bf16 v[48:63], v[156:159], v[168:171], v[48:63]
	ds_read_b128 v[156:159], v174 offset:64
	s_waitcnt lgkmcnt(0)
	v_mfma_f32_32x32x16_bf16 v[32:47], v[156:159], v[160:163], v[32:47]
	v_mfma_f32_32x32x16_bf16 v[16:31], v[156:159], v[164:167], v[16:31]
	v_mfma_f32_32x32x16_bf16 v[0:15], v[156:159], v[168:171], v[0:15]
	ds_read_b128 v[156:159], v152 offset:96
	ds_read_b128 v[160:163], v172 offset:54368
	ds_read_b128 v[164:167], v172 offset:58976
	ds_read_b128 v[168:171], v172 offset:63584
	v_xor_b32_e32 v152, 1, v204
	s_waitcnt lgkmcnt(2)
	v_mfma_f32_32x32x16_bf16 v[128:143], v[156:159], v[160:163], v[128:143]
	s_waitcnt lgkmcnt(1)
	v_mfma_f32_32x32x16_bf16 v[112:127], v[156:159], v[164:167], v[112:127]
	s_waitcnt lgkmcnt(0)
	v_mfma_f32_32x32x16_bf16 v[96:111], v[156:159], v[168:171], v[96:111]
	ds_read_b128 v[156:159], v173 offset:96
	ds_read_b128 v[172:175], v174 offset:96
	s_waitcnt lgkmcnt(1)
	v_mfma_f32_32x32x16_bf16 v[80:95], v[156:159], v[160:163], v[80:95]
	v_mfma_f32_32x32x16_bf16 v[64:79], v[156:159], v[164:167], v[64:79]
	v_mfma_f32_32x32x16_bf16 v[48:63], v[156:159], v[168:171], v[48:63]
	v_and_b32_e32 v156, 64, v204
	v_add_u32_e32 v156, 64, v156
	v_cmp_lt_i32_e32 vcc, v152, v156
	v_lshl_add_u64 v[156:157], s[0:1], 0, v[146:147]
	v_lshl_add_u64 v[148:149], v[148:149], 1, v[156:157]
	v_cndmask_b32_e32 v152, v204, v152, vcc
	v_lshlrev_b32_e32 v152, 2, v152
	s_waitcnt lgkmcnt(0)
	v_mfma_f32_32x32x16_bf16 v[32:47], v[172:175], v[160:163], v[32:47]
	s_nop 1
	v_mov_b32_dpp v156, v128 quad_perm:[1,0,3,2] row_mask:0xf bank_mask:0xf
	v_or_b32_e32 v146, v176, v154
	v_mul_u32_u24_e32 v146, 0x180, v146
	v_mfma_f32_32x32x16_bf16 v[16:31], v[172:175], v[164:167], v[16:31]
	v_mfma_f32_32x32x16_bf16 v[0:15], v[172:175], v[168:171], v[0:15]
	s_waitcnt lgkmcnt(0)
	v_lshl_add_u64 v[218:219], v[148:149], 0, v[146:147]
	v_mov_b32_dpp v206, v128 quad_perm:[1,0,3,2] row_mask:0xf bank_mask:0xf
	v_mov_b32_dpp v207, v112 quad_perm:[1,0,3,2] row_mask:0xf bank_mask:0xf
	v_mov_b32_dpp v208, v96 quad_perm:[1,0,3,2] row_mask:0xf bank_mask:0xf
	v_mov_b32_dpp v209, v129 quad_perm:[1,0,3,2] row_mask:0xf bank_mask:0xf
	v_mov_b32_dpp v210, v113 quad_perm:[1,0,3,2] row_mask:0xf bank_mask:0xf
	v_mov_b32_dpp v211, v97 quad_perm:[1,0,3,2] row_mask:0xf bank_mask:0xf
	v_mov_b32_dpp v212, v130 quad_perm:[1,0,3,2] row_mask:0xf bank_mask:0xf
	v_mov_b32_dpp v213, v114 quad_perm:[1,0,3,2] row_mask:0xf bank_mask:0xf
	v_mov_b32_dpp v214, v98 quad_perm:[1,0,3,2] row_mask:0xf bank_mask:0xf
	v_mov_b32_dpp v215, v131 quad_perm:[1,0,3,2] row_mask:0xf bank_mask:0xf
	v_mov_b32_dpp v216, v115 quad_perm:[1,0,3,2] row_mask:0xf bank_mask:0xf
	v_mov_b32_dpp v217, v99 quad_perm:[1,0,3,2] row_mask:0xf bank_mask:0xf
	v_cvt_pk_bf16_f32 v206, v128, v206
	v_cvt_pk_bf16_f32 v207, v112, v207
	v_cvt_pk_bf16_f32 v208, v96, v208
	v_cvt_pk_bf16_f32 v209, v129, v209
	v_cvt_pk_bf16_f32 v210, v113, v210
	v_cvt_pk_bf16_f32 v211, v97, v211
	v_cvt_pk_bf16_f32 v212, v130, v212
	v_cvt_pk_bf16_f32 v213, v114, v213
	v_cvt_pk_bf16_f32 v214, v98, v214
	v_cvt_pk_bf16_f32 v215, v131, v215
	v_cvt_pk_bf16_f32 v216, v115, v216
	v_cvt_pk_bf16_f32 v217, v99, v217
	s_mov_b64 exec, s[34:35]
	global_store_dword v[218:219], v206, off
	global_store_dword v[218:219], v207, off offset:64
	global_store_dword v[218:219], v208, off offset:128
	global_store_dword v[218:219], v209, off offset:384
	global_store_dword v[218:219], v210, off offset:448
	global_store_dword v[218:219], v211, off offset:512
	global_store_dword v[218:219], v212, off offset:768
	global_store_dword v[218:219], v213, off offset:832
	global_store_dword v[218:219], v214, off offset:896
	global_store_dword v[218:219], v215, off offset:1152
	global_store_dword v[218:219], v216, off offset:1216
	global_store_dword v[218:219], v217, off offset:1280
	s_mov_b64 exec, -1
	v_add_co_u32_e32 v218, vcc, 0xc00, v218
	s_nop 1
	v_addc_co_u32_e32 v219, vcc, 0, v219, vcc
	v_mov_b32_dpp v206, v132 quad_perm:[1,0,3,2] row_mask:0xf bank_mask:0xf
	v_mov_b32_dpp v207, v116 quad_perm:[1,0,3,2] row_mask:0xf bank_mask:0xf
	v_mov_b32_dpp v208, v100 quad_perm:[1,0,3,2] row_mask:0xf bank_mask:0xf
	v_mov_b32_dpp v209, v133 quad_perm:[1,0,3,2] row_mask:0xf bank_mask:0xf
	v_mov_b32_dpp v210, v117 quad_perm:[1,0,3,2] row_mask:0xf bank_mask:0xf
	v_mov_b32_dpp v211, v101 quad_perm:[1,0,3,2] row_mask:0xf bank_mask:0xf
	v_mov_b32_dpp v212, v134 quad_perm:[1,0,3,2] row_mask:0xf bank_mask:0xf
	v_mov_b32_dpp v213, v118 quad_perm:[1,0,3,2] row_mask:0xf bank_mask:0xf
	v_mov_b32_dpp v214, v102 quad_perm:[1,0,3,2] row_mask:0xf bank_mask:0xf
	v_mov_b32_dpp v215, v135 quad_perm:[1,0,3,2] row_mask:0xf bank_mask:0xf
	v_mov_b32_dpp v216, v119 quad_perm:[1,0,3,2] row_mask:0xf bank_mask:0xf
	v_mov_b32_dpp v217, v103 quad_perm:[1,0,3,2] row_mask:0xf bank_mask:0xf
	v_cvt_pk_bf16_f32 v206, v132, v206
	v_cvt_pk_bf16_f32 v207, v116, v207
	v_cvt_pk_bf16_f32 v208, v100, v208
	v_cvt_pk_bf16_f32 v209, v133, v209
	v_cvt_pk_bf16_f32 v210, v117, v210
	v_cvt_pk_bf16_f32 v211, v101, v211
	v_cvt_pk_bf16_f32 v212, v134, v212
	v_cvt_pk_bf16_f32 v213, v118, v213
	v_cvt_pk_bf16_f32 v214, v102, v214
	v_cvt_pk_bf16_f32 v215, v135, v215
	v_cvt_pk_bf16_f32 v216, v119, v216
	v_cvt_pk_bf16_f32 v217, v103, v217
	s_mov_b64 exec, s[34:35]
	global_store_dword v[218:219], v206, off
	global_store_dword v[218:219], v207, off offset:64
	global_store_dword v[218:219], v208, off offset:128
	global_store_dword v[218:219], v209, off offset:384
	global_store_dword v[218:219], v210, off offset:448
	global_store_dword v[218:219], v211, off offset:512
	global_store_dword v[218:219], v212, off offset:768
	global_store_dword v[218:219], v213, off offset:832
	global_store_dword v[218:219], v214, off offset:896
	global_store_dword v[218:219], v215, off offset:1152
	global_store_dword v[218:219], v216, off offset:1216
	global_store_dword v[218:219], v217, off offset:1280
	s_mov_b64 exec, -1
	v_add_co_u32_e32 v218, vcc, 0xc00, v218
	s_nop 1
	v_addc_co_u32_e32 v219, vcc, 0, v219, vcc
	v_mov_b32_dpp v206, v136 quad_perm:[1,0,3,2] row_mask:0xf bank_mask:0xf
	v_mov_b32_dpp v207, v120 quad_perm:[1,0,3,2] row_mask:0xf bank_mask:0xf
	v_mov_b32_dpp v208, v104 quad_perm:[1,0,3,2] row_mask:0xf bank_mask:0xf
	v_mov_b32_dpp v209, v137 quad_perm:[1,0,3,2] row_mask:0xf bank_mask:0xf
	v_mov_b32_dpp v210, v121 quad_perm:[1,0,3,2] row_mask:0xf bank_mask:0xf
	v_mov_b32_dpp v211, v105 quad_perm:[1,0,3,2] row_mask:0xf bank_mask:0xf
	v_mov_b32_dpp v212, v138 quad_perm:[1,0,3,2] row_mask:0xf bank_mask:0xf
	v_mov_b32_dpp v213, v122 quad_perm:[1,0,3,2] row_mask:0xf bank_mask:0xf
	v_mov_b32_dpp v214, v106 quad_perm:[1,0,3,2] row_mask:0xf bank_mask:0xf
	v_mov_b32_dpp v215, v139 quad_perm:[1,0,3,2] row_mask:0xf bank_mask:0xf
	v_mov_b32_dpp v216, v123 quad_perm:[1,0,3,2] row_mask:0xf bank_mask:0xf
	v_mov_b32_dpp v217, v107 quad_perm:[1,0,3,2] row_mask:0xf bank_mask:0xf
	v_cvt_pk_bf16_f32 v206, v136, v206
	v_cvt_pk_bf16_f32 v207, v120, v207
	v_cvt_pk_bf16_f32 v208, v104, v208
	v_cvt_pk_bf16_f32 v209, v137, v209
	v_cvt_pk_bf16_f32 v210, v121, v210
	v_cvt_pk_bf16_f32 v211, v105, v211
	v_cvt_pk_bf16_f32 v212, v138, v212
	v_cvt_pk_bf16_f32 v213, v122, v213
	v_cvt_pk_bf16_f32 v214, v106, v214
	v_cvt_pk_bf16_f32 v215, v139, v215
	v_cvt_pk_bf16_f32 v216, v123, v216
	v_cvt_pk_bf16_f32 v217, v107, v217
	s_mov_b64 exec, s[34:35]
	global_store_dword v[218:219], v206, off
	global_store_dword v[218:219], v207, off offset:64
	global_store_dword v[218:219], v208, off offset:128
	global_store_dword v[218:219], v209, off offset:384
	global_store_dword v[218:219], v210, off offset:448
	global_store_dword v[218:219], v211, off offset:512
	global_store_dword v[218:219], v212, off offset:768
	global_store_dword v[218:219], v213, off offset:832
	global_store_dword v[218:219], v214, off offset:896
	global_store_dword v[218:219], v215, off offset:1152
	global_store_dword v[218:219], v216, off offset:1216
	global_store_dword v[218:219], v217, off offset:1280
	s_mov_b64 exec, -1
	v_add_co_u32_e32 v218, vcc, 0xc00, v218
	s_nop 1
	v_addc_co_u32_e32 v219, vcc, 0, v219, vcc
	v_mov_b32_dpp v206, v140 quad_perm:[1,0,3,2] row_mask:0xf bank_mask:0xf
	v_mov_b32_dpp v207, v124 quad_perm:[1,0,3,2] row_mask:0xf bank_mask:0xf
	v_mov_b32_dpp v208, v108 quad_perm:[1,0,3,2] row_mask:0xf bank_mask:0xf
	v_mov_b32_dpp v209, v141 quad_perm:[1,0,3,2] row_mask:0xf bank_mask:0xf
	v_mov_b32_dpp v210, v125 quad_perm:[1,0,3,2] row_mask:0xf bank_mask:0xf
	v_mov_b32_dpp v211, v109 quad_perm:[1,0,3,2] row_mask:0xf bank_mask:0xf
	v_mov_b32_dpp v212, v142 quad_perm:[1,0,3,2] row_mask:0xf bank_mask:0xf
	v_mov_b32_dpp v213, v126 quad_perm:[1,0,3,2] row_mask:0xf bank_mask:0xf
	v_mov_b32_dpp v214, v110 quad_perm:[1,0,3,2] row_mask:0xf bank_mask:0xf
	v_mov_b32_dpp v215, v143 quad_perm:[1,0,3,2] row_mask:0xf bank_mask:0xf
	v_mov_b32_dpp v216, v127 quad_perm:[1,0,3,2] row_mask:0xf bank_mask:0xf
	v_mov_b32_dpp v217, v111 quad_perm:[1,0,3,2] row_mask:0xf bank_mask:0xf
	v_cvt_pk_bf16_f32 v206, v140, v206
	v_cvt_pk_bf16_f32 v207, v124, v207
	v_cvt_pk_bf16_f32 v208, v108, v208
	v_cvt_pk_bf16_f32 v209, v141, v209
	v_cvt_pk_bf16_f32 v210, v125, v210
	v_cvt_pk_bf16_f32 v211, v109, v211
	v_cvt_pk_bf16_f32 v212, v142, v212
	v_cvt_pk_bf16_f32 v213, v126, v213
	v_cvt_pk_bf16_f32 v214, v110, v214
	v_cvt_pk_bf16_f32 v215, v143, v215
	v_cvt_pk_bf16_f32 v216, v127, v216
	v_cvt_pk_bf16_f32 v217, v111, v217
	s_mov_b64 exec, s[34:35]
	global_store_dword v[218:219], v206, off
	global_store_dword v[218:219], v207, off offset:64
	global_store_dword v[218:219], v208, off offset:128
	global_store_dword v[218:219], v209, off offset:384
	global_store_dword v[218:219], v210, off offset:448
	global_store_dword v[218:219], v211, off offset:512
	global_store_dword v[218:219], v212, off offset:768
	global_store_dword v[218:219], v213, off offset:832
	global_store_dword v[218:219], v214, off offset:896
	global_store_dword v[218:219], v215, off offset:1152
	global_store_dword v[218:219], v216, off offset:1216
	global_store_dword v[218:219], v217, off offset:1280
	s_mov_b64 exec, -1
	v_add_co_u32_e32 v218, vcc, 0xc00, v218
	s_nop 1
	v_addc_co_u32_e32 v219, vcc, 0, v219, vcc
	v_mov_b32_dpp v206, v80 quad_perm:[1,0,3,2] row_mask:0xf bank_mask:0xf
	v_mov_b32_dpp v207, v64 quad_perm:[1,0,3,2] row_mask:0xf bank_mask:0xf
	v_mov_b32_dpp v208, v48 quad_perm:[1,0,3,2] row_mask:0xf bank_mask:0xf
	v_mov_b32_dpp v209, v81 quad_perm:[1,0,3,2] row_mask:0xf bank_mask:0xf
	v_mov_b32_dpp v210, v65 quad_perm:[1,0,3,2] row_mask:0xf bank_mask:0xf
	v_mov_b32_dpp v211, v49 quad_perm:[1,0,3,2] row_mask:0xf bank_mask:0xf
	v_mov_b32_dpp v212, v82 quad_perm:[1,0,3,2] row_mask:0xf bank_mask:0xf
	v_mov_b32_dpp v213, v66 quad_perm:[1,0,3,2] row_mask:0xf bank_mask:0xf
	v_mov_b32_dpp v214, v50 quad_perm:[1,0,3,2] row_mask:0xf bank_mask:0xf
	v_mov_b32_dpp v215, v83 quad_perm:[1,0,3,2] row_mask:0xf bank_mask:0xf
	v_mov_b32_dpp v216, v67 quad_perm:[1,0,3,2] row_mask:0xf bank_mask:0xf
	v_mov_b32_dpp v217, v51 quad_perm:[1,0,3,2] row_mask:0xf bank_mask:0xf
	v_cvt_pk_bf16_f32 v206, v80, v206
	v_cvt_pk_bf16_f32 v207, v64, v207
	v_cvt_pk_bf16_f32 v208, v48, v208
	v_cvt_pk_bf16_f32 v209, v81, v209
	v_cvt_pk_bf16_f32 v210, v65, v210
	v_cvt_pk_bf16_f32 v211, v49, v211
	v_cvt_pk_bf16_f32 v212, v82, v212
	v_cvt_pk_bf16_f32 v213, v66, v213
	v_cvt_pk_bf16_f32 v214, v50, v214
	v_cvt_pk_bf16_f32 v215, v83, v215
	v_cvt_pk_bf16_f32 v216, v67, v216
	v_cvt_pk_bf16_f32 v217, v51, v217
	s_mov_b64 exec, s[34:35]
	global_store_dword v[218:219], v206, off
	global_store_dword v[218:219], v207, off offset:64
	global_store_dword v[218:219], v208, off offset:128
	global_store_dword v[218:219], v209, off offset:384
	global_store_dword v[218:219], v210, off offset:448
	global_store_dword v[218:219], v211, off offset:512
	global_store_dword v[218:219], v212, off offset:768
	global_store_dword v[218:219], v213, off offset:832
	global_store_dword v[218:219], v214, off offset:896
	global_store_dword v[218:219], v215, off offset:1152
	global_store_dword v[218:219], v216, off offset:1216
	global_store_dword v[218:219], v217, off offset:1280
	s_mov_b64 exec, -1
	v_add_co_u32_e32 v218, vcc, 0xc00, v218
	s_nop 1
	v_addc_co_u32_e32 v219, vcc, 0, v219, vcc
	v_mov_b32_dpp v206, v84 quad_perm:[1,0,3,2] row_mask:0xf bank_mask:0xf
	v_mov_b32_dpp v207, v68 quad_perm:[1,0,3,2] row_mask:0xf bank_mask:0xf
	v_mov_b32_dpp v208, v52 quad_perm:[1,0,3,2] row_mask:0xf bank_mask:0xf
	v_mov_b32_dpp v209, v85 quad_perm:[1,0,3,2] row_mask:0xf bank_mask:0xf
	v_mov_b32_dpp v210, v69 quad_perm:[1,0,3,2] row_mask:0xf bank_mask:0xf
	v_mov_b32_dpp v211, v53 quad_perm:[1,0,3,2] row_mask:0xf bank_mask:0xf
	v_mov_b32_dpp v212, v86 quad_perm:[1,0,3,2] row_mask:0xf bank_mask:0xf
	v_mov_b32_dpp v213, v70 quad_perm:[1,0,3,2] row_mask:0xf bank_mask:0xf
	v_mov_b32_dpp v214, v54 quad_perm:[1,0,3,2] row_mask:0xf bank_mask:0xf
	v_mov_b32_dpp v215, v87 quad_perm:[1,0,3,2] row_mask:0xf bank_mask:0xf
	v_mov_b32_dpp v216, v71 quad_perm:[1,0,3,2] row_mask:0xf bank_mask:0xf
	v_mov_b32_dpp v217, v55 quad_perm:[1,0,3,2] row_mask:0xf bank_mask:0xf
	v_cvt_pk_bf16_f32 v206, v84, v206
	v_cvt_pk_bf16_f32 v207, v68, v207
	v_cvt_pk_bf16_f32 v208, v52, v208
	v_cvt_pk_bf16_f32 v209, v85, v209
	v_cvt_pk_bf16_f32 v210, v69, v210
	v_cvt_pk_bf16_f32 v211, v53, v211
	v_cvt_pk_bf16_f32 v212, v86, v212
	v_cvt_pk_bf16_f32 v213, v70, v213
	v_cvt_pk_bf16_f32 v214, v54, v214
	v_cvt_pk_bf16_f32 v215, v87, v215
	v_cvt_pk_bf16_f32 v216, v71, v216
	v_cvt_pk_bf16_f32 v217, v55, v217
	s_mov_b64 exec, s[34:35]
	global_store_dword v[218:219], v206, off
	global_store_dword v[218:219], v207, off offset:64
	global_store_dword v[218:219], v208, off offset:128
	global_store_dword v[218:219], v209, off offset:384
	global_store_dword v[218:219], v210, off offset:448
	global_store_dword v[218:219], v211, off offset:512
	global_store_dword v[218:219], v212, off offset:768
	global_store_dword v[218:219], v213, off offset:832
	global_store_dword v[218:219], v214, off offset:896
	global_store_dword v[218:219], v215, off offset:1152
	global_store_dword v[218:219], v216, off offset:1216
	global_store_dword v[218:219], v217, off offset:1280
	s_mov_b64 exec, -1
	v_add_co_u32_e32 v218, vcc, 0xc00, v218
	s_nop 1
	v_addc_co_u32_e32 v219, vcc, 0, v219, vcc
	v_mov_b32_dpp v206, v88 quad_perm:[1,0,3,2] row_mask:0xf bank_mask:0xf
	v_mov_b32_dpp v207, v72 quad_perm:[1,0,3,2] row_mask:0xf bank_mask:0xf
	v_mov_b32_dpp v208, v56 quad_perm:[1,0,3,2] row_mask:0xf bank_mask:0xf
	v_mov_b32_dpp v209, v89 quad_perm:[1,0,3,2] row_mask:0xf bank_mask:0xf
	v_mov_b32_dpp v210, v73 quad_perm:[1,0,3,2] row_mask:0xf bank_mask:0xf
	v_mov_b32_dpp v211, v57 quad_perm:[1,0,3,2] row_mask:0xf bank_mask:0xf
	v_mov_b32_dpp v212, v90 quad_perm:[1,0,3,2] row_mask:0xf bank_mask:0xf
	v_mov_b32_dpp v213, v74 quad_perm:[1,0,3,2] row_mask:0xf bank_mask:0xf
	v_mov_b32_dpp v214, v58 quad_perm:[1,0,3,2] row_mask:0xf bank_mask:0xf
	v_mov_b32_dpp v215, v91 quad_perm:[1,0,3,2] row_mask:0xf bank_mask:0xf
	v_mov_b32_dpp v216, v75 quad_perm:[1,0,3,2] row_mask:0xf bank_mask:0xf
	v_mov_b32_dpp v217, v59 quad_perm:[1,0,3,2] row_mask:0xf bank_mask:0xf
	v_cvt_pk_bf16_f32 v206, v88, v206
	v_cvt_pk_bf16_f32 v207, v72, v207
	v_cvt_pk_bf16_f32 v208, v56, v208
	v_cvt_pk_bf16_f32 v209, v89, v209
	v_cvt_pk_bf16_f32 v210, v73, v210
	v_cvt_pk_bf16_f32 v211, v57, v211
	v_cvt_pk_bf16_f32 v212, v90, v212
	v_cvt_pk_bf16_f32 v213, v74, v213
	v_cvt_pk_bf16_f32 v214, v58, v214
	v_cvt_pk_bf16_f32 v215, v91, v215
	v_cvt_pk_bf16_f32 v216, v75, v216
	v_cvt_pk_bf16_f32 v217, v59, v217
	s_mov_b64 exec, s[34:35]
	global_store_dword v[218:219], v206, off
	global_store_dword v[218:219], v207, off offset:64
	global_store_dword v[218:219], v208, off offset:128
	global_store_dword v[218:219], v209, off offset:384
	global_store_dword v[218:219], v210, off offset:448
	global_store_dword v[218:219], v211, off offset:512
	global_store_dword v[218:219], v212, off offset:768
	global_store_dword v[218:219], v213, off offset:832
	global_store_dword v[218:219], v214, off offset:896
	global_store_dword v[218:219], v215, off offset:1152
	global_store_dword v[218:219], v216, off offset:1216
	global_store_dword v[218:219], v217, off offset:1280
	s_mov_b64 exec, -1
	v_add_co_u32_e32 v218, vcc, 0xc00, v218
	s_nop 1
	v_addc_co_u32_e32 v219, vcc, 0, v219, vcc
	v_mov_b32_dpp v206, v92 quad_perm:[1,0,3,2] row_mask:0xf bank_mask:0xf
	v_mov_b32_dpp v207, v76 quad_perm:[1,0,3,2] row_mask:0xf bank_mask:0xf
	v_mov_b32_dpp v208, v60 quad_perm:[1,0,3,2] row_mask:0xf bank_mask:0xf
	v_mov_b32_dpp v209, v93 quad_perm:[1,0,3,2] row_mask:0xf bank_mask:0xf
	v_mov_b32_dpp v210, v77 quad_perm:[1,0,3,2] row_mask:0xf bank_mask:0xf
	v_mov_b32_dpp v211, v61 quad_perm:[1,0,3,2] row_mask:0xf bank_mask:0xf
	v_mov_b32_dpp v212, v94 quad_perm:[1,0,3,2] row_mask:0xf bank_mask:0xf
	v_mov_b32_dpp v213, v78 quad_perm:[1,0,3,2] row_mask:0xf bank_mask:0xf
	v_mov_b32_dpp v214, v62 quad_perm:[1,0,3,2] row_mask:0xf bank_mask:0xf
	v_mov_b32_dpp v215, v95 quad_perm:[1,0,3,2] row_mask:0xf bank_mask:0xf
	v_mov_b32_dpp v216, v79 quad_perm:[1,0,3,2] row_mask:0xf bank_mask:0xf
	v_mov_b32_dpp v217, v63 quad_perm:[1,0,3,2] row_mask:0xf bank_mask:0xf
	v_cvt_pk_bf16_f32 v206, v92, v206
	v_cvt_pk_bf16_f32 v207, v76, v207
	v_cvt_pk_bf16_f32 v208, v60, v208
	v_cvt_pk_bf16_f32 v209, v93, v209
	v_cvt_pk_bf16_f32 v210, v77, v210
	v_cvt_pk_bf16_f32 v211, v61, v211
	v_cvt_pk_bf16_f32 v212, v94, v212
	v_cvt_pk_bf16_f32 v213, v78, v213
	v_cvt_pk_bf16_f32 v214, v62, v214
	v_cvt_pk_bf16_f32 v215, v95, v215
	v_cvt_pk_bf16_f32 v216, v79, v216
	v_cvt_pk_bf16_f32 v217, v63, v217
	s_mov_b64 exec, s[34:35]
	global_store_dword v[218:219], v206, off
	global_store_dword v[218:219], v207, off offset:64
	global_store_dword v[218:219], v208, off offset:128
	global_store_dword v[218:219], v209, off offset:384
	global_store_dword v[218:219], v210, off offset:448
	global_store_dword v[218:219], v211, off offset:512
	global_store_dword v[218:219], v212, off offset:768
	global_store_dword v[218:219], v213, off offset:832
	global_store_dword v[218:219], v214, off offset:896
	global_store_dword v[218:219], v215, off offset:1152
	global_store_dword v[218:219], v216, off offset:1216
	global_store_dword v[218:219], v217, off offset:1280
	s_mov_b64 exec, -1
	v_add_co_u32_e32 v218, vcc, 0xc00, v218
	s_nop 1
	v_addc_co_u32_e32 v219, vcc, 0, v219, vcc
	v_mov_b32_dpp v206, v32 quad_perm:[1,0,3,2] row_mask:0xf bank_mask:0xf
	v_mov_b32_dpp v207, v16 quad_perm:[1,0,3,2] row_mask:0xf bank_mask:0xf
	v_mov_b32_dpp v208, v0 quad_perm:[1,0,3,2] row_mask:0xf bank_mask:0xf
	v_mov_b32_dpp v209, v33 quad_perm:[1,0,3,2] row_mask:0xf bank_mask:0xf
	v_mov_b32_dpp v210, v17 quad_perm:[1,0,3,2] row_mask:0xf bank_mask:0xf
	v_mov_b32_dpp v211, v1 quad_perm:[1,0,3,2] row_mask:0xf bank_mask:0xf
	v_mov_b32_dpp v212, v34 quad_perm:[1,0,3,2] row_mask:0xf bank_mask:0xf
	v_mov_b32_dpp v213, v18 quad_perm:[1,0,3,2] row_mask:0xf bank_mask:0xf
	v_mov_b32_dpp v214, v2 quad_perm:[1,0,3,2] row_mask:0xf bank_mask:0xf
	v_mov_b32_dpp v215, v35 quad_perm:[1,0,3,2] row_mask:0xf bank_mask:0xf
	v_mov_b32_dpp v216, v19 quad_perm:[1,0,3,2] row_mask:0xf bank_mask:0xf
	v_mov_b32_dpp v217, v3 quad_perm:[1,0,3,2] row_mask:0xf bank_mask:0xf
	v_cvt_pk_bf16_f32 v206, v32, v206
	v_cvt_pk_bf16_f32 v207, v16, v207
	v_cvt_pk_bf16_f32 v208, v0, v208
	v_cvt_pk_bf16_f32 v209, v33, v209
	v_cvt_pk_bf16_f32 v210, v17, v210
	v_cvt_pk_bf16_f32 v211, v1, v211
	v_cvt_pk_bf16_f32 v212, v34, v212
	v_cvt_pk_bf16_f32 v213, v18, v213
	v_cvt_pk_bf16_f32 v214, v2, v214
	v_cvt_pk_bf16_f32 v215, v35, v215
	v_cvt_pk_bf16_f32 v216, v19, v216
	v_cvt_pk_bf16_f32 v217, v3, v217
	s_mov_b64 exec, s[34:35]
	global_store_dword v[218:219], v206, off
	global_store_dword v[218:219], v207, off offset:64
	global_store_dword v[218:219], v208, off offset:128
	global_store_dword v[218:219], v209, off offset:384
	global_store_dword v[218:219], v210, off offset:448
	global_store_dword v[218:219], v211, off offset:512
	global_store_dword v[218:219], v212, off offset:768
	global_store_dword v[218:219], v213, off offset:832
	global_store_dword v[218:219], v214, off offset:896
	global_store_dword v[218:219], v215, off offset:1152
	global_store_dword v[218:219], v216, off offset:1216
	global_store_dword v[218:219], v217, off offset:1280
	s_mov_b64 exec, -1
	v_add_co_u32_e32 v218, vcc, 0xc00, v218
	s_nop 1
	v_addc_co_u32_e32 v219, vcc, 0, v219, vcc
	v_mov_b32_dpp v206, v36 quad_perm:[1,0,3,2] row_mask:0xf bank_mask:0xf
	v_mov_b32_dpp v207, v20 quad_perm:[1,0,3,2] row_mask:0xf bank_mask:0xf
	v_mov_b32_dpp v208, v4 quad_perm:[1,0,3,2] row_mask:0xf bank_mask:0xf
	v_mov_b32_dpp v209, v37 quad_perm:[1,0,3,2] row_mask:0xf bank_mask:0xf
	v_mov_b32_dpp v210, v21 quad_perm:[1,0,3,2] row_mask:0xf bank_mask:0xf
	v_mov_b32_dpp v211, v5 quad_perm:[1,0,3,2] row_mask:0xf bank_mask:0xf
	v_mov_b32_dpp v212, v38 quad_perm:[1,0,3,2] row_mask:0xf bank_mask:0xf
	v_mov_b32_dpp v213, v22 quad_perm:[1,0,3,2] row_mask:0xf bank_mask:0xf
	v_mov_b32_dpp v214, v6 quad_perm:[1,0,3,2] row_mask:0xf bank_mask:0xf
	v_mov_b32_dpp v215, v39 quad_perm:[1,0,3,2] row_mask:0xf bank_mask:0xf
	v_mov_b32_dpp v216, v23 quad_perm:[1,0,3,2] row_mask:0xf bank_mask:0xf
	v_mov_b32_dpp v217, v7 quad_perm:[1,0,3,2] row_mask:0xf bank_mask:0xf
	v_cvt_pk_bf16_f32 v206, v36, v206
	v_cvt_pk_bf16_f32 v207, v20, v207
	v_cvt_pk_bf16_f32 v208, v4, v208
	v_cvt_pk_bf16_f32 v209, v37, v209
	v_cvt_pk_bf16_f32 v210, v21, v210
	v_cvt_pk_bf16_f32 v211, v5, v211
	v_cvt_pk_bf16_f32 v212, v38, v212
	v_cvt_pk_bf16_f32 v213, v22, v213
	v_cvt_pk_bf16_f32 v214, v6, v214
	v_cvt_pk_bf16_f32 v215, v39, v215
	v_cvt_pk_bf16_f32 v216, v23, v216
	v_cvt_pk_bf16_f32 v217, v7, v217
	s_mov_b64 exec, s[34:35]
	global_store_dword v[218:219], v206, off
	global_store_dword v[218:219], v207, off offset:64
	global_store_dword v[218:219], v208, off offset:128
	global_store_dword v[218:219], v209, off offset:384
	global_store_dword v[218:219], v210, off offset:448
	global_store_dword v[218:219], v211, off offset:512
	global_store_dword v[218:219], v212, off offset:768
	global_store_dword v[218:219], v213, off offset:832
	global_store_dword v[218:219], v214, off offset:896
	global_store_dword v[218:219], v215, off offset:1152
	global_store_dword v[218:219], v216, off offset:1216
	global_store_dword v[218:219], v217, off offset:1280
	s_mov_b64 exec, -1
	v_add_co_u32_e32 v218, vcc, 0xc00, v218
	s_nop 1
	v_addc_co_u32_e32 v219, vcc, 0, v219, vcc
	v_mov_b32_dpp v206, v40 quad_perm:[1,0,3,2] row_mask:0xf bank_mask:0xf
	v_mov_b32_dpp v207, v24 quad_perm:[1,0,3,2] row_mask:0xf bank_mask:0xf
	v_mov_b32_dpp v208, v8 quad_perm:[1,0,3,2] row_mask:0xf bank_mask:0xf
	v_mov_b32_dpp v209, v41 quad_perm:[1,0,3,2] row_mask:0xf bank_mask:0xf
	v_mov_b32_dpp v210, v25 quad_perm:[1,0,3,2] row_mask:0xf bank_mask:0xf
	v_mov_b32_dpp v211, v9 quad_perm:[1,0,3,2] row_mask:0xf bank_mask:0xf
	v_mov_b32_dpp v212, v42 quad_perm:[1,0,3,2] row_mask:0xf bank_mask:0xf
	v_mov_b32_dpp v213, v26 quad_perm:[1,0,3,2] row_mask:0xf bank_mask:0xf
	v_mov_b32_dpp v214, v10 quad_perm:[1,0,3,2] row_mask:0xf bank_mask:0xf
	v_mov_b32_dpp v215, v43 quad_perm:[1,0,3,2] row_mask:0xf bank_mask:0xf
	v_mov_b32_dpp v216, v27 quad_perm:[1,0,3,2] row_mask:0xf bank_mask:0xf
	v_mov_b32_dpp v217, v11 quad_perm:[1,0,3,2] row_mask:0xf bank_mask:0xf
	v_cvt_pk_bf16_f32 v206, v40, v206
	v_cvt_pk_bf16_f32 v207, v24, v207
	v_cvt_pk_bf16_f32 v208, v8, v208
	v_cvt_pk_bf16_f32 v209, v41, v209
	v_cvt_pk_bf16_f32 v210, v25, v210
	v_cvt_pk_bf16_f32 v211, v9, v211
	v_cvt_pk_bf16_f32 v212, v42, v212
	v_cvt_pk_bf16_f32 v213, v26, v213
	v_cvt_pk_bf16_f32 v214, v10, v214
	v_cvt_pk_bf16_f32 v215, v43, v215
	v_cvt_pk_bf16_f32 v216, v27, v216
	v_cvt_pk_bf16_f32 v217, v11, v217
	s_mov_b64 exec, s[34:35]
	global_store_dword v[218:219], v206, off
	global_store_dword v[218:219], v207, off offset:64
	global_store_dword v[218:219], v208, off offset:128
	global_store_dword v[218:219], v209, off offset:384
	global_store_dword v[218:219], v210, off offset:448
	global_store_dword v[218:219], v211, off offset:512
	global_store_dword v[218:219], v212, off offset:768
	global_store_dword v[218:219], v213, off offset:832
	global_store_dword v[218:219], v214, off offset:896
	global_store_dword v[218:219], v215, off offset:1152
	global_store_dword v[218:219], v216, off offset:1216
	global_store_dword v[218:219], v217, off offset:1280
	s_mov_b64 exec, -1
	v_add_co_u32_e32 v218, vcc, 0xc00, v218
	s_nop 1
	v_addc_co_u32_e32 v219, vcc, 0, v219, vcc
	v_mov_b32_dpp v206, v44 quad_perm:[1,0,3,2] row_mask:0xf bank_mask:0xf
	v_mov_b32_dpp v207, v28 quad_perm:[1,0,3,2] row_mask:0xf bank_mask:0xf
	v_mov_b32_dpp v208, v12 quad_perm:[1,0,3,2] row_mask:0xf bank_mask:0xf
	v_mov_b32_dpp v209, v45 quad_perm:[1,0,3,2] row_mask:0xf bank_mask:0xf
	v_mov_b32_dpp v210, v29 quad_perm:[1,0,3,2] row_mask:0xf bank_mask:0xf
	v_mov_b32_dpp v211, v13 quad_perm:[1,0,3,2] row_mask:0xf bank_mask:0xf
	v_mov_b32_dpp v212, v46 quad_perm:[1,0,3,2] row_mask:0xf bank_mask:0xf
	v_mov_b32_dpp v213, v30 quad_perm:[1,0,3,2] row_mask:0xf bank_mask:0xf
	v_mov_b32_dpp v214, v14 quad_perm:[1,0,3,2] row_mask:0xf bank_mask:0xf
	v_mov_b32_dpp v215, v47 quad_perm:[1,0,3,2] row_mask:0xf bank_mask:0xf
	v_mov_b32_dpp v216, v31 quad_perm:[1,0,3,2] row_mask:0xf bank_mask:0xf
	v_mov_b32_dpp v217, v15 quad_perm:[1,0,3,2] row_mask:0xf bank_mask:0xf
	v_cvt_pk_bf16_f32 v206, v44, v206
	v_cvt_pk_bf16_f32 v207, v28, v207
	v_cvt_pk_bf16_f32 v208, v12, v208
	v_cvt_pk_bf16_f32 v209, v45, v209
	v_cvt_pk_bf16_f32 v210, v29, v210
	v_cvt_pk_bf16_f32 v211, v13, v211
	v_cvt_pk_bf16_f32 v212, v46, v212
	v_cvt_pk_bf16_f32 v213, v30, v213
	v_cvt_pk_bf16_f32 v214, v14, v214
	v_cvt_pk_bf16_f32 v215, v47, v215
	v_cvt_pk_bf16_f32 v216, v31, v216
	v_cvt_pk_bf16_f32 v217, v15, v217
	s_mov_b64 exec, s[34:35]
	global_store_dword v[218:219], v206, off
	global_store_dword v[218:219], v207, off offset:64
	global_store_dword v[218:219], v208, off offset:128
	global_store_dword v[218:219], v209, off offset:384
	global_store_dword v[218:219], v210, off offset:448
	global_store_dword v[218:219], v211, off offset:512
	global_store_dword v[218:219], v212, off offset:768
	global_store_dword v[218:219], v213, off offset:832
	global_store_dword v[218:219], v214, off offset:896
	global_store_dword v[218:219], v215, off offset:1152
	global_store_dword v[218:219], v216, off offset:1216
	global_store_dword v[218:219], v217, off offset:1280
	s_mov_b64 exec, -1
	s_branch .LBB0_3831

.LBB0_4230:
	s_and_b64 vcc, exec, s[38:39]
	s_cbranch_vccz .LBB0_4362
	s_and_saveexec_b64 s[0:1], s[34:35]
	ds_write_b32 v190, v202
	s_or_b64 exec, exec, s[0:1]
	s_mul_i32 s1, s2, 0xffffe600
	s_mul_hi_i32 s0, s2, 0xffffe600
	s_add_u32 s1, s3, s1
	s_addc_u32 s0, s4, s0
	s_lshl_b32 s2, s5, 1
	s_add_u32 s2, s1, s2
	v_and_b32_e32 v65, 64, v204
	s_addc_u32 s3, s0, 0
	s_ashr_i32 s23, s22, 31
	v_xor_b32_e32 v64, 1, v204
	v_add_u32_e32 v65, 64, v65
	s_lshl_b64 s[0:1], s[22:23], 12
	v_cmp_lt_i32_e32 vcc, v64, v65
	s_add_u32 s0, s2, s0
	s_waitcnt lgkmcnt(0)
	s_addc_u32 s1, s3, s1
	v_cndmask_b32_e32 v64, v204, v64, vcc
	v_lshlrev_b32_e32 v68, 2, v64
	v_and_b32_e32 v64, 1, v187
	v_lshlrev_b32_e32 v66, 1, v188
	v_mov_b32_e32 v67, 0
	v_cmp_eq_u32_e32 vcc, 0, v64
	v_lshl_add_u64 v[64:65], s[0:1], 0, v[66:67]
	ds_read_b32 v66, v185
	s_mov_b64 s[0:1], 0x24540c00
	v_lshl_add_u64 v[64:65], v[64:65], 0, s[0:1]
	s_waitcnt lgkmcnt(0)
	v_rcp_f32_e32 v69, v66
	v_lshlrev_b32_e32 v66, 14, v186
	v_lshl_add_u64 v[66:67], v[64:65], 0, v[66:67]
	v_mul_f32_e32 v48, v48, v69
	s_nop 1
	v_mov_b32_dpp v70, v48 quad_perm:[1,0,3,2] row_mask:0xf bank_mask:0xf
	s_and_saveexec_b64 s[0:1], vcc
	s_cbranch_execz .LBB0_4235
	s_waitcnt lgkmcnt(0)
	v_cvt_pk_bf16_f32 v48, v48, v70
	global_store_dword v[66:67], v48, off
.LBB0_4235:
	s_or_b64 exec, exec, s[0:1]
	v_mul_f32_e32 v32, v32, v69
	s_nop 1
	v_mov_b32_dpp v48, v32 quad_perm:[1,0,3,2] row_mask:0xf bank_mask:0xf
	s_and_saveexec_b64 s[0:1], vcc
	s_cbranch_execz .LBB0_4237
	s_waitcnt lgkmcnt(0)
	v_cvt_pk_bf16_f32 v32, v32, v48
	global_store_dword v[66:67], v32, off offset:64
.LBB0_4237:
	s_or_b64 exec, exec, s[0:1]
	v_mul_f32_e32 v16, v16, v69
	s_nop 1
	v_mov_b32_dpp v32, v16 quad_perm:[1,0,3,2] row_mask:0xf bank_mask:0xf
	s_and_saveexec_b64 s[0:1], vcc
	s_cbranch_execz .LBB0_4239
	s_waitcnt lgkmcnt(0)
	v_cvt_pk_bf16_f32 v16, v16, v32
	global_store_dword v[66:67], v16, off offset:128
.LBB0_4239:
	s_or_b64 exec, exec, s[0:1]
	v_mul_f32_e32 v0, v0, v69
	s_nop 1
	v_mov_b32_dpp v16, v0 quad_perm:[1,0,3,2] row_mask:0xf bank_mask:0xf
	s_and_saveexec_b64 s[0:1], vcc
	s_cbranch_execz .LBB0_4241
	s_waitcnt lgkmcnt(0)
	v_cvt_pk_bf16_f32 v0, v0, v16
	global_store_dword v[66:67], v0, off offset:192
.LBB0_4241:
	s_or_b64 exec, exec, s[0:1]
	ds_read_b32 v0, v185 offset:4
	s_waitcnt lgkmcnt(1)
	v_mov_b32_e32 v16, 0x1000
	v_lshl_or_b32 v66, v184, 12, v16
	v_mov_b32_e32 v67, 0
	v_lshl_add_u64 v[66:67], v[64:65], 0, v[66:67]
	s_waitcnt lgkmcnt(0)
	v_rcp_f32_e32 v0, v0
	s_nop 0
	v_mul_f32_e32 v16, v49, v0
	s_nop 1
	v_mov_b32_dpp v32, v16 quad_perm:[1,0,3,2] row_mask:0xf bank_mask:0xf
	s_and_saveexec_b64 s[0:1], vcc
	s_cbranch_execz .LBB0_4243
	s_waitcnt lgkmcnt(0)
	v_cvt_pk_bf16_f32 v16, v16, v32
	global_store_dword v[66:67], v16, off
.LBB0_4243:
	s_or_b64 exec, exec, s[0:1]
	v_mul_f32_e32 v16, v33, v0
	s_waitcnt lgkmcnt(0)
	s_nop 1
	v_mov_b32_dpp v32, v16 quad_perm:[1,0,3,2] row_mask:0xf bank_mask:0xf
	s_and_saveexec_b64 s[0:1], vcc
	s_cbranch_execz .LBB0_4245
	s_waitcnt lgkmcnt(0)
	v_cvt_pk_bf16_f32 v16, v16, v32
	global_store_dword v[66:67], v16, off offset:64
.LBB0_4245:
	s_or_b64 exec, exec, s[0:1]
	v_mul_f32_e32 v16, v17, v0
	s_nop 1
	v_mov_b32_dpp v17, v16 quad_perm:[1,0,3,2] row_mask:0xf bank_mask:0xf
	s_and_saveexec_b64 s[0:1], vcc
	s_cbranch_execz .LBB0_4247
	s_waitcnt lgkmcnt(0)
	v_cvt_pk_bf16_f32 v16, v16, v17
	global_store_dword v[66:67], v16, off offset:128
.LBB0_4247:
	s_or_b64 exec, exec, s[0:1]
	v_mul_f32_e32 v0, v1, v0
	s_nop 1
	v_mov_b32_dpp v1, v0 quad_perm:[1,0,3,2] row_mask:0xf bank_mask:0xf
	s_and_saveexec_b64 s[0:1], vcc
	s_cbranch_execz .LBB0_4249
	s_waitcnt lgkmcnt(0)
	v_cvt_pk_bf16_f32 v0, v0, v1
	global_store_dword v[66:67], v0, off offset:192
.LBB0_4249:
	s_or_b64 exec, exec, s[0:1]
	ds_read_b32 v0, v185 offset:8
	s_waitcnt lgkmcnt(1)
	v_mov_b32_e32 v1, 0
	s_waitcnt lgkmcnt(0)
	v_rcp_f32_e32 v16, v0
	v_mov_b32_e32 v0, 0x2000
	v_lshl_or_b32 v0, v184, 12, v0
	v_lshl_add_u64 v[0:1], v[64:65], 0, v[0:1]
	v_mul_f32_e32 v17, v50, v16
	s_nop 1
	v_mov_b32_dpp v32, v17 quad_perm:[1,0,3,2] row_mask:0xf bank_mask:0xf
	s_and_saveexec_b64 s[0:1], vcc
	s_cbranch_execz .LBB0_4251
	s_waitcnt lgkmcnt(0)
	v_cvt_pk_bf16_f32 v17, v17, v32
	global_store_dword v[0:1], v17, off
.LBB0_4251:
	s_or_b64 exec, exec, s[0:1]
	v_mul_f32_e32 v17, v34, v16
	s_waitcnt lgkmcnt(0)
	s_nop 1
	v_mov_b32_dpp v32, v17 quad_perm:[1,0,3,2] row_mask:0xf bank_mask:0xf
	s_and_saveexec_b64 s[0:1], vcc
	s_cbranch_execz .LBB0_4253
	s_waitcnt lgkmcnt(0)
	v_cvt_pk_bf16_f32 v17, v17, v32
	global_store_dword v[0:1], v17, off offset:64
.LBB0_4253:
	s_or_b64 exec, exec, s[0:1]
	v_mul_f32_e32 v17, v18, v16
	s_nop 1
	v_mov_b32_dpp v18, v17 quad_perm:[1,0,3,2] row_mask:0xf bank_mask:0xf
	s_and_saveexec_b64 s[0:1], vcc
	s_cbranch_execz .LBB0_4255
	s_waitcnt lgkmcnt(0)
	v_cvt_pk_bf16_f32 v17, v17, v18
	global_store_dword v[0:1], v17, off offset:128
.LBB0_4255:
	s_or_b64 exec, exec, s[0:1]
	v_mul_f32_e32 v2, v2, v16
	s_nop 1
	v_mov_b32_dpp v16, v2 quad_perm:[1,0,3,2] row_mask:0xf bank_mask:0xf
	s_and_saveexec_b64 s[0:1], vcc
	s_cbranch_execz .LBB0_4257
	s_waitcnt lgkmcnt(0)
	v_cvt_pk_bf16_f32 v2, v2, v16
	global_store_dword v[0:1], v2, off offset:192
.LBB0_4257:
	s_or_b64 exec, exec, s[0:1]
	ds_read_b32 v0, v185 offset:12
	v_mov_b32_e32 v1, 0
	s_waitcnt lgkmcnt(0)
	v_rcp_f32_e32 v2, v0
	v_mov_b32_e32 v0, 0x3000
	v_lshl_or_b32 v0, v184, 12, v0
	v_lshl_add_u64 v[0:1], v[64:65], 0, v[0:1]
	v_mul_f32_e32 v16, v51, v2
	s_nop 1
	v_mov_b32_dpp v17, v16 quad_perm:[1,0,3,2] row_mask:0xf bank_mask:0xf
	s_and_saveexec_b64 s[0:1], vcc
	s_cbranch_execz .LBB0_4259
	s_waitcnt lgkmcnt(0)
	v_cvt_pk_bf16_f32 v16, v16, v17
	global_store_dword v[0:1], v16, off
.LBB0_4259:
	s_or_b64 exec, exec, s[0:1]
	v_mul_f32_e32 v16, v35, v2
	s_waitcnt lgkmcnt(0)
	s_nop 1
	v_mov_b32_dpp v17, v16 quad_perm:[1,0,3,2] row_mask:0xf bank_mask:0xf
	s_and_saveexec_b64 s[0:1], vcc
	s_cbranch_execz .LBB0_4261
	s_waitcnt lgkmcnt(0)
	v_cvt_pk_bf16_f32 v16, v16, v17
	global_store_dword v[0:1], v16, off offset:64
.LBB0_4261:
	s_or_b64 exec, exec, s[0:1]
	v_mul_f32_e32 v16, v19, v2
	s_waitcnt lgkmcnt(0)
	s_nop 1
	v_mov_b32_dpp v17, v16 quad_perm:[1,0,3,2] row_mask:0xf bank_mask:0xf
	s_and_saveexec_b64 s[0:1], vcc
	s_cbranch_execz .LBB0_4263
	s_waitcnt lgkmcnt(0)
	v_cvt_pk_bf16_f32 v16, v16, v17
	global_store_dword v[0:1], v16, off offset:128
.LBB0_4263:
	s_or_b64 exec, exec, s[0:1]
	v_mul_f32_e32 v2, v3, v2
	s_nop 1
	v_mov_b32_dpp v3, v2 quad_perm:[1,0,3,2] row_mask:0xf bank_mask:0xf
	s_and_saveexec_b64 s[0:1], vcc
	s_cbranch_execz .LBB0_4265
	s_waitcnt lgkmcnt(0)
	v_cvt_pk_bf16_f32 v2, v2, v3
	global_store_dword v[0:1], v2, off offset:192
.LBB0_4265:
	s_or_b64 exec, exec, s[0:1]
	ds_read_b32 v0, v185 offset:32
	v_mov_b32_e32 v1, 0
	s_waitcnt lgkmcnt(0)
	v_rcp_f32_e32 v2, v0
	v_mov_b32_e32 v0, 0x8000
	v_lshl_or_b32 v0, v184, 12, v0
	v_lshl_add_u64 v[0:1], v[64:65], 0, v[0:1]
	v_mul_f32_e32 v3, v52, v2
	s_nop 1
	v_mov_b32_dpp v16, v3 quad_perm:[1,0,3,2] row_mask:0xf bank_mask:0xf
	s_and_saveexec_b64 s[0:1], vcc
	s_cbranch_execz .LBB0_4267
	s_waitcnt lgkmcnt(0)
	v_cvt_pk_bf16_f32 v3, v3, v16
	global_store_dword v[0:1], v3, off
.LBB0_4267:
	s_or_b64 exec, exec, s[0:1]
	v_mul_f32_e32 v3, v36, v2
	s_waitcnt lgkmcnt(0)
	s_nop 1
	v_mov_b32_dpp v16, v3 quad_perm:[1,0,3,2] row_mask:0xf bank_mask:0xf
	s_and_saveexec_b64 s[0:1], vcc
	s_cbranch_execz .LBB0_4269
	s_waitcnt lgkmcnt(0)
	v_cvt_pk_bf16_f32 v3, v3, v16
	global_store_dword v[0:1], v3, off offset:64
.LBB0_4269:
	s_or_b64 exec, exec, s[0:1]
	v_mul_f32_e32 v3, v20, v2
	s_waitcnt lgkmcnt(0)
	s_nop 1
	v_mov_b32_dpp v16, v3 quad_perm:[1,0,3,2] row_mask:0xf bank_mask:0xf
	s_and_saveexec_b64 s[0:1], vcc
	s_cbranch_execz .LBB0_4271
	s_waitcnt lgkmcnt(0)
	v_cvt_pk_bf16_f32 v3, v3, v16
	global_store_dword v[0:1], v3, off offset:128
.LBB0_4271:
	s_or_b64 exec, exec, s[0:1]
	v_mul_f32_e32 v2, v4, v2
	s_nop 1
	v_mov_b32_dpp v3, v2 quad_perm:[1,0,3,2] row_mask:0xf bank_mask:0xf
	s_and_saveexec_b64 s[0:1], vcc
	s_cbranch_execz .LBB0_4273
	s_waitcnt lgkmcnt(0)
	v_cvt_pk_bf16_f32 v2, v2, v3
	global_store_dword v[0:1], v2, off offset:192
.LBB0_4273:
	s_or_b64 exec, exec, s[0:1]
	ds_read_b32 v0, v185 offset:36
	v_mov_b32_e32 v1, 0
	s_waitcnt lgkmcnt(0)
	v_rcp_f32_e32 v2, v0
	v_mov_b32_e32 v0, 0x9000
	v_lshl_or_b32 v0, v184, 12, v0
	v_lshl_add_u64 v[0:1], v[64:65], 0, v[0:1]
	v_mul_f32_e32 v3, v53, v2
	s_nop 1
	v_mov_b32_dpp v4, v3 quad_perm:[1,0,3,2] row_mask:0xf bank_mask:0xf
	s_and_saveexec_b64 s[0:1], vcc
	s_cbranch_execz .LBB0_4275
	s_waitcnt lgkmcnt(0)
	v_cvt_pk_bf16_f32 v3, v3, v4
	global_store_dword v[0:1], v3, off
.LBB0_4275:
	s_or_b64 exec, exec, s[0:1]
	v_mul_f32_e32 v3, v37, v2
	s_waitcnt lgkmcnt(0)
	s_nop 1
	v_mov_b32_dpp v4, v3 quad_perm:[1,0,3,2] row_mask:0xf bank_mask:0xf
	s_and_saveexec_b64 s[0:1], vcc
	s_cbranch_execz .LBB0_4277
	s_waitcnt lgkmcnt(0)
	v_cvt_pk_bf16_f32 v3, v3, v4
	global_store_dword v[0:1], v3, off offset:64
.LBB0_4277:
	s_or_b64 exec, exec, s[0:1]
	v_mul_f32_e32 v3, v21, v2
	s_waitcnt lgkmcnt(0)
	s_nop 1
	v_mov_b32_dpp v4, v3 quad_perm:[1,0,3,2] row_mask:0xf bank_mask:0xf
	s_and_saveexec_b64 s[0:1], vcc
	s_cbranch_execz .LBB0_4279
	s_waitcnt lgkmcnt(0)
	v_cvt_pk_bf16_f32 v3, v3, v4
	global_store_dword v[0:1], v3, off offset:128
.LBB0_4279:
	s_or_b64 exec, exec, s[0:1]
	v_mul_f32_e32 v2, v5, v2
	s_nop 1
	v_mov_b32_dpp v3, v2 quad_perm:[1,0,3,2] row_mask:0xf bank_mask:0xf
	s_and_saveexec_b64 s[0:1], vcc
	s_cbranch_execz .LBB0_4281
	s_waitcnt lgkmcnt(0)
	v_cvt_pk_bf16_f32 v2, v2, v3
	global_store_dword v[0:1], v2, off offset:192
.LBB0_4281:
	s_or_b64 exec, exec, s[0:1]
	ds_read_b32 v0, v185 offset:40
	v_mov_b32_e32 v1, 0
	s_waitcnt lgkmcnt(0)
	v_rcp_f32_e32 v2, v0
	v_mov_b32_e32 v0, 0xa000
	v_lshl_or_b32 v0, v184, 12, v0
	v_lshl_add_u64 v[0:1], v[64:65], 0, v[0:1]
	v_mul_f32_e32 v3, v54, v2
	s_nop 1
	v_mov_b32_dpp v4, v3 quad_perm:[1,0,3,2] row_mask:0xf bank_mask:0xf
	s_and_saveexec_b64 s[0:1], vcc
	s_cbranch_execz .LBB0_4283
	s_waitcnt lgkmcnt(0)
	v_cvt_pk_bf16_f32 v3, v3, v4
	global_store_dword v[0:1], v3, off
.LBB0_4283:
	s_or_b64 exec, exec, s[0:1]
	v_mul_f32_e32 v3, v38, v2
	s_waitcnt lgkmcnt(0)
	s_nop 1
	v_mov_b32_dpp v4, v3 quad_perm:[1,0,3,2] row_mask:0xf bank_mask:0xf
	s_and_saveexec_b64 s[0:1], vcc
	s_cbranch_execz .LBB0_4285
	s_waitcnt lgkmcnt(0)
	v_cvt_pk_bf16_f32 v3, v3, v4
	global_store_dword v[0:1], v3, off offset:64
.LBB0_4285:
	s_or_b64 exec, exec, s[0:1]
	v_mul_f32_e32 v3, v22, v2
	s_waitcnt lgkmcnt(0)
	s_nop 1
	v_mov_b32_dpp v4, v3 quad_perm:[1,0,3,2] row_mask:0xf bank_mask:0xf
	s_and_saveexec_b64 s[0:1], vcc
	s_cbranch_execz .LBB0_4287
	s_waitcnt lgkmcnt(0)
	v_cvt_pk_bf16_f32 v3, v3, v4
	global_store_dword v[0:1], v3, off offset:128
.LBB0_4287:
	s_or_b64 exec, exec, s[0:1]
	v_mul_f32_e32 v2, v6, v2
	s_nop 1
	v_mov_b32_dpp v3, v2 quad_perm:[1,0,3,2] row_mask:0xf bank_mask:0xf
	s_and_saveexec_b64 s[0:1], vcc
	s_cbranch_execz .LBB0_4289
	s_waitcnt lgkmcnt(0)
	v_cvt_pk_bf16_f32 v2, v2, v3
	global_store_dword v[0:1], v2, off offset:192
.LBB0_4289:
	s_or_b64 exec, exec, s[0:1]
	ds_read_b32 v0, v185 offset:44
	v_mov_b32_e32 v1, 0
	s_waitcnt lgkmcnt(0)
	v_rcp_f32_e32 v2, v0
	v_mov_b32_e32 v0, 0xb000
	v_lshl_or_b32 v0, v184, 12, v0
	v_lshl_add_u64 v[0:1], v[64:65], 0, v[0:1]
	v_mul_f32_e32 v3, v55, v2
	s_nop 1
	v_mov_b32_dpp v4, v3 quad_perm:[1,0,3,2] row_mask:0xf bank_mask:0xf
	s_and_saveexec_b64 s[0:1], vcc
	s_cbranch_execz .LBB0_4291
	s_waitcnt lgkmcnt(0)
	v_cvt_pk_bf16_f32 v3, v3, v4
	global_store_dword v[0:1], v3, off
.LBB0_4291:
	s_or_b64 exec, exec, s[0:1]
	v_mul_f32_e32 v3, v39, v2
	s_waitcnt lgkmcnt(0)
	s_nop 1
	v_mov_b32_dpp v4, v3 quad_perm:[1,0,3,2] row_mask:0xf bank_mask:0xf
	s_and_saveexec_b64 s[0:1], vcc
	s_cbranch_execz .LBB0_4293
	s_waitcnt lgkmcnt(0)
	v_cvt_pk_bf16_f32 v3, v3, v4
	global_store_dword v[0:1], v3, off offset:64
.LBB0_4293:
	s_or_b64 exec, exec, s[0:1]
	v_mul_f32_e32 v3, v23, v2
	s_waitcnt lgkmcnt(0)
	s_nop 1
	v_mov_b32_dpp v4, v3 quad_perm:[1,0,3,2] row_mask:0xf bank_mask:0xf
	s_and_saveexec_b64 s[0:1], vcc
	s_cbranch_execz .LBB0_4295
	s_waitcnt lgkmcnt(0)
	v_cvt_pk_bf16_f32 v3, v3, v4
	global_store_dword v[0:1], v3, off offset:128
.LBB0_4295:
	s_or_b64 exec, exec, s[0:1]
	v_mul_f32_e32 v2, v7, v2
	s_nop 1
	v_mov_b32_dpp v3, v2 quad_perm:[1,0,3,2] row_mask:0xf bank_mask:0xf
	s_and_saveexec_b64 s[0:1], vcc
	s_cbranch_execz .LBB0_4297
	s_waitcnt lgkmcnt(0)
	v_cvt_pk_bf16_f32 v2, v2, v3
	global_store_dword v[0:1], v2, off offset:192
.LBB0_4297:
	s_or_b64 exec, exec, s[0:1]
	ds_read_b32 v0, v185 offset:64
	v_mov_b32_e32 v1, 0
	s_waitcnt lgkmcnt(0)
	v_rcp_f32_e32 v2, v0
	v_mov_b32_e32 v0, 0x10000
	v_lshl_or_b32 v0, v184, 12, v0
	v_lshl_add_u64 v[0:1], v[64:65], 0, v[0:1]
	v_mul_f32_e32 v3, v56, v2
	s_nop 1
	v_mov_b32_dpp v4, v3 quad_perm:[1,0,3,2] row_mask:0xf bank_mask:0xf
	s_and_saveexec_b64 s[0:1], vcc
	s_cbranch_execz .LBB0_4299
	s_waitcnt lgkmcnt(0)
	v_cvt_pk_bf16_f32 v3, v3, v4
	global_store_dword v[0:1], v3, off
.LBB0_4299:
	s_or_b64 exec, exec, s[0:1]
	v_mul_f32_e32 v3, v40, v2
	s_waitcnt lgkmcnt(0)
	s_nop 1
	v_mov_b32_dpp v4, v3 quad_perm:[1,0,3,2] row_mask:0xf bank_mask:0xf
	s_and_saveexec_b64 s[0:1], vcc
	s_cbranch_execz .LBB0_4301
	s_waitcnt lgkmcnt(0)
	v_cvt_pk_bf16_f32 v3, v3, v4
	global_store_dword v[0:1], v3, off offset:64
.LBB0_4301:
	s_or_b64 exec, exec, s[0:1]
	v_mul_f32_e32 v3, v24, v2
	s_waitcnt lgkmcnt(0)
	s_nop 1
	v_mov_b32_dpp v4, v3 quad_perm:[1,0,3,2] row_mask:0xf bank_mask:0xf
	s_and_saveexec_b64 s[0:1], vcc
	s_cbranch_execz .LBB0_4303
	s_waitcnt lgkmcnt(0)
	v_cvt_pk_bf16_f32 v3, v3, v4
	global_store_dword v[0:1], v3, off offset:128
.LBB0_4303:
	s_or_b64 exec, exec, s[0:1]
	v_mul_f32_e32 v2, v8, v2
	s_nop 1
	v_mov_b32_dpp v3, v2 quad_perm:[1,0,3,2] row_mask:0xf bank_mask:0xf
	s_and_saveexec_b64 s[0:1], vcc
	s_cbranch_execz .LBB0_4305
	s_waitcnt lgkmcnt(0)
	v_cvt_pk_bf16_f32 v2, v2, v3
	global_store_dword v[0:1], v2, off offset:192
.LBB0_4305:
	s_or_b64 exec, exec, s[0:1]
	ds_read_b32 v0, v185 offset:68
	v_mov_b32_e32 v1, 0
	s_waitcnt lgkmcnt(0)
	v_rcp_f32_e32 v2, v0
	v_mov_b32_e32 v0, 0x11000
	v_lshl_or_b32 v0, v184, 12, v0
	v_lshl_add_u64 v[0:1], v[64:65], 0, v[0:1]
	v_mul_f32_e32 v3, v57, v2
	s_nop 1
	v_mov_b32_dpp v4, v3 quad_perm:[1,0,3,2] row_mask:0xf bank_mask:0xf
	s_and_saveexec_b64 s[0:1], vcc
	s_cbranch_execz .LBB0_4307
	s_waitcnt lgkmcnt(0)
	v_cvt_pk_bf16_f32 v3, v3, v4
	global_store_dword v[0:1], v3, off
.LBB0_4307:
	s_or_b64 exec, exec, s[0:1]
	v_mul_f32_e32 v3, v41, v2
	s_waitcnt lgkmcnt(0)
	s_nop 1
	v_mov_b32_dpp v4, v3 quad_perm:[1,0,3,2] row_mask:0xf bank_mask:0xf
	s_and_saveexec_b64 s[0:1], vcc
	s_cbranch_execz .LBB0_4309
	s_waitcnt lgkmcnt(0)
	v_cvt_pk_bf16_f32 v3, v3, v4
	global_store_dword v[0:1], v3, off offset:64
.LBB0_4309:
	s_or_b64 exec, exec, s[0:1]
	v_mul_f32_e32 v3, v25, v2
	s_waitcnt lgkmcnt(0)
	s_nop 1
	v_mov_b32_dpp v4, v3 quad_perm:[1,0,3,2] row_mask:0xf bank_mask:0xf
	s_and_saveexec_b64 s[0:1], vcc
	s_cbranch_execz .LBB0_4311
	s_waitcnt lgkmcnt(0)
	v_cvt_pk_bf16_f32 v3, v3, v4
	global_store_dword v[0:1], v3, off offset:128
.LBB0_4311:
	s_or_b64 exec, exec, s[0:1]
	v_mul_f32_e32 v2, v9, v2
	s_nop 1
	v_mov_b32_dpp v3, v2 quad_perm:[1,0,3,2] row_mask:0xf bank_mask:0xf
	s_and_saveexec_b64 s[0:1], vcc
	s_cbranch_execz .LBB0_4313
	s_waitcnt lgkmcnt(0)
	v_cvt_pk_bf16_f32 v2, v2, v3
	global_store_dword v[0:1], v2, off offset:192
.LBB0_4313:
	s_or_b64 exec, exec, s[0:1]
	ds_read_b32 v0, v185 offset:72
	v_mov_b32_e32 v1, 0
	s_waitcnt lgkmcnt(0)
	v_rcp_f32_e32 v2, v0
	v_mov_b32_e32 v0, 0x12000
	v_lshl_or_b32 v0, v184, 12, v0
	v_lshl_add_u64 v[0:1], v[64:65], 0, v[0:1]
	v_mul_f32_e32 v3, v58, v2
	s_nop 1
	v_mov_b32_dpp v4, v3 quad_perm:[1,0,3,2] row_mask:0xf bank_mask:0xf
	s_and_saveexec_b64 s[0:1], vcc
	s_cbranch_execz .LBB0_4315
	s_waitcnt lgkmcnt(0)
	v_cvt_pk_bf16_f32 v3, v3, v4
	global_store_dword v[0:1], v3, off
.LBB0_4315:
	s_or_b64 exec, exec, s[0:1]
	v_mul_f32_e32 v3, v42, v2
	s_waitcnt lgkmcnt(0)
	s_nop 1
	v_mov_b32_dpp v4, v3 quad_perm:[1,0,3,2] row_mask:0xf bank_mask:0xf
	s_and_saveexec_b64 s[0:1], vcc
	s_cbranch_execz .LBB0_4317
	s_waitcnt lgkmcnt(0)
	v_cvt_pk_bf16_f32 v3, v3, v4
	global_store_dword v[0:1], v3, off offset:64
.LBB0_4317:
	s_or_b64 exec, exec, s[0:1]
	v_mul_f32_e32 v3, v26, v2
	s_waitcnt lgkmcnt(0)
	s_nop 1
	v_mov_b32_dpp v4, v3 quad_perm:[1,0,3,2] row_mask:0xf bank_mask:0xf
	s_and_saveexec_b64 s[0:1], vcc
	s_cbranch_execz .LBB0_4319
	s_waitcnt lgkmcnt(0)
	v_cvt_pk_bf16_f32 v3, v3, v4
	global_store_dword v[0:1], v3, off offset:128
.LBB0_4319:
	s_or_b64 exec, exec, s[0:1]
	v_mul_f32_e32 v2, v10, v2
	s_nop 1
	v_mov_b32_dpp v3, v2 quad_perm:[1,0,3,2] row_mask:0xf bank_mask:0xf
	s_and_saveexec_b64 s[0:1], vcc
	s_cbranch_execz .LBB0_4321
	s_waitcnt lgkmcnt(0)
	v_cvt_pk_bf16_f32 v2, v2, v3
	global_store_dword v[0:1], v2, off offset:192
.LBB0_4321:
	s_or_b64 exec, exec, s[0:1]
	ds_read_b32 v0, v185 offset:76
	v_mov_b32_e32 v1, 0
	s_waitcnt lgkmcnt(0)
	v_rcp_f32_e32 v2, v0
	v_mov_b32_e32 v0, 0x13000
	v_lshl_or_b32 v0, v184, 12, v0
	v_lshl_add_u64 v[0:1], v[64:65], 0, v[0:1]
	v_mul_f32_e32 v3, v59, v2
	s_nop 1
	v_mov_b32_dpp v4, v3 quad_perm:[1,0,3,2] row_mask:0xf bank_mask:0xf
	s_and_saveexec_b64 s[0:1], vcc
	s_cbranch_execz .LBB0_4323
	s_waitcnt lgkmcnt(0)
	v_cvt_pk_bf16_f32 v3, v3, v4
	global_store_dword v[0:1], v3, off
.LBB0_4323:
	s_or_b64 exec, exec, s[0:1]
	v_mul_f32_e32 v3, v43, v2
	s_waitcnt lgkmcnt(0)
	s_nop 1
	v_mov_b32_dpp v4, v3 quad_perm:[1,0,3,2] row_mask:0xf bank_mask:0xf
	s_and_saveexec_b64 s[0:1], vcc
	s_cbranch_execz .LBB0_4325
	s_waitcnt lgkmcnt(0)
	v_cvt_pk_bf16_f32 v3, v3, v4
	global_store_dword v[0:1], v3, off offset:64
.LBB0_4325:
	s_or_b64 exec, exec, s[0:1]
	v_mul_f32_e32 v3, v27, v2
	s_waitcnt lgkmcnt(0)
	s_nop 1
	v_mov_b32_dpp v4, v3 quad_perm:[1,0,3,2] row_mask:0xf bank_mask:0xf
	s_and_saveexec_b64 s[0:1], vcc
	s_cbranch_execz .LBB0_4327
	s_waitcnt lgkmcnt(0)
	v_cvt_pk_bf16_f32 v3, v3, v4
	global_store_dword v[0:1], v3, off offset:128
.LBB0_4327:
	s_or_b64 exec, exec, s[0:1]
	v_mul_f32_e32 v2, v11, v2
	s_nop 1
	v_mov_b32_dpp v3, v2 quad_perm:[1,0,3,2] row_mask:0xf bank_mask:0xf
	s_and_saveexec_b64 s[0:1], vcc
	s_cbranch_execz .LBB0_4329
	s_waitcnt lgkmcnt(0)
	v_cvt_pk_bf16_f32 v2, v2, v3
	global_store_dword v[0:1], v2, off offset:192
.LBB0_4329:
	s_or_b64 exec, exec, s[0:1]
	ds_read_b32 v0, v185 offset:96
	v_mov_b32_e32 v1, 0
	s_waitcnt lgkmcnt(0)
	v_rcp_f32_e32 v2, v0
	v_mov_b32_e32 v0, 0x18000
	v_lshl_or_b32 v0, v184, 12, v0
	v_lshl_add_u64 v[0:1], v[64:65], 0, v[0:1]
	v_mul_f32_e32 v3, v60, v2
	s_nop 1
	v_mov_b32_dpp v4, v3 quad_perm:[1,0,3,2] row_mask:0xf bank_mask:0xf
	s_and_saveexec_b64 s[0:1], vcc
	s_cbranch_execz .LBB0_4331
	s_waitcnt lgkmcnt(0)
	v_cvt_pk_bf16_f32 v3, v3, v4
	global_store_dword v[0:1], v3, off
.LBB0_4331:
	s_or_b64 exec, exec, s[0:1]
	v_mul_f32_e32 v3, v44, v2
	s_waitcnt lgkmcnt(0)
	s_nop 1
	v_mov_b32_dpp v4, v3 quad_perm:[1,0,3,2] row_mask:0xf bank_mask:0xf
	s_and_saveexec_b64 s[0:1], vcc
	s_cbranch_execz .LBB0_4333
	s_waitcnt lgkmcnt(0)
	v_cvt_pk_bf16_f32 v3, v3, v4
	global_store_dword v[0:1], v3, off offset:64
.LBB0_4333:
	s_or_b64 exec, exec, s[0:1]
	v_mul_f32_e32 v3, v28, v2
	s_waitcnt lgkmcnt(0)
	s_nop 1
	v_mov_b32_dpp v4, v3 quad_perm:[1,0,3,2] row_mask:0xf bank_mask:0xf
	s_and_saveexec_b64 s[0:1], vcc
	s_cbranch_execz .LBB0_4335
	s_waitcnt lgkmcnt(0)
	v_cvt_pk_bf16_f32 v3, v3, v4
	global_store_dword v[0:1], v3, off offset:128
.LBB0_4335:
	s_or_b64 exec, exec, s[0:1]
	v_mul_f32_e32 v2, v12, v2
	s_nop 1
	v_mov_b32_dpp v3, v2 quad_perm:[1,0,3,2] row_mask:0xf bank_mask:0xf
	s_and_saveexec_b64 s[0:1], vcc
	s_cbranch_execz .LBB0_4337
	s_waitcnt lgkmcnt(0)
	v_cvt_pk_bf16_f32 v2, v2, v3
	global_store_dword v[0:1], v2, off offset:192
.LBB0_4337:
	s_or_b64 exec, exec, s[0:1]
	ds_read_b32 v0, v185 offset:100
	v_mov_b32_e32 v1, 0
	s_waitcnt lgkmcnt(0)
	v_rcp_f32_e32 v2, v0
	v_mov_b32_e32 v0, 0x19000
	v_lshl_or_b32 v0, v184, 12, v0
	v_lshl_add_u64 v[0:1], v[64:65], 0, v[0:1]
	v_mul_f32_e32 v3, v61, v2
	s_nop 1
	v_mov_b32_dpp v4, v3 quad_perm:[1,0,3,2] row_mask:0xf bank_mask:0xf
	s_and_saveexec_b64 s[0:1], vcc
	s_cbranch_execz .LBB0_4339
	s_waitcnt lgkmcnt(0)
	v_cvt_pk_bf16_f32 v3, v3, v4
	global_store_dword v[0:1], v3, off
.LBB0_4339:
	s_or_b64 exec, exec, s[0:1]
	v_mul_f32_e32 v3, v45, v2
	s_waitcnt lgkmcnt(0)
	s_nop 1
	v_mov_b32_dpp v4, v3 quad_perm:[1,0,3,2] row_mask:0xf bank_mask:0xf
	s_and_saveexec_b64 s[0:1], vcc
	s_cbranch_execz .LBB0_4341
	s_waitcnt lgkmcnt(0)
	v_cvt_pk_bf16_f32 v3, v3, v4
	global_store_dword v[0:1], v3, off offset:64
.LBB0_4341:
	s_or_b64 exec, exec, s[0:1]
	v_mul_f32_e32 v3, v29, v2
	s_waitcnt lgkmcnt(0)
	s_nop 1
	v_mov_b32_dpp v4, v3 quad_perm:[1,0,3,2] row_mask:0xf bank_mask:0xf
	s_and_saveexec_b64 s[0:1], vcc
	s_cbranch_execz .LBB0_4343
	s_waitcnt lgkmcnt(0)
	v_cvt_pk_bf16_f32 v3, v3, v4
	global_store_dword v[0:1], v3, off offset:128
.LBB0_4343:
	s_or_b64 exec, exec, s[0:1]
	v_mul_f32_e32 v2, v13, v2
	s_nop 1
	v_mov_b32_dpp v3, v2 quad_perm:[1,0,3,2] row_mask:0xf bank_mask:0xf
	s_and_saveexec_b64 s[0:1], vcc
	s_cbranch_execz .LBB0_4345
	s_waitcnt lgkmcnt(0)
	v_cvt_pk_bf16_f32 v2, v2, v3
	global_store_dword v[0:1], v2, off offset:192
.LBB0_4345:
	s_or_b64 exec, exec, s[0:1]
	ds_read_b32 v0, v185 offset:104
	v_mov_b32_e32 v1, 0
	s_waitcnt lgkmcnt(0)
	v_rcp_f32_e32 v2, v0
	v_mov_b32_e32 v0, 0x1a000
	v_lshl_or_b32 v0, v184, 12, v0
	v_lshl_add_u64 v[0:1], v[64:65], 0, v[0:1]
	v_mul_f32_e32 v3, v62, v2
	s_nop 1
	v_mov_b32_dpp v4, v3 quad_perm:[1,0,3,2] row_mask:0xf bank_mask:0xf
	s_and_saveexec_b64 s[0:1], vcc
	s_cbranch_execz .LBB0_4347
	s_waitcnt lgkmcnt(0)
	v_cvt_pk_bf16_f32 v3, v3, v4
	global_store_dword v[0:1], v3, off
.LBB0_4347:
	s_or_b64 exec, exec, s[0:1]
	v_mul_f32_e32 v3, v46, v2
	s_waitcnt lgkmcnt(0)
	s_nop 1
	v_mov_b32_dpp v4, v3 quad_perm:[1,0,3,2] row_mask:0xf bank_mask:0xf
	s_and_saveexec_b64 s[0:1], vcc
	s_cbranch_execz .LBB0_4349
	s_waitcnt lgkmcnt(0)
	v_cvt_pk_bf16_f32 v3, v3, v4
	global_store_dword v[0:1], v3, off offset:64
.LBB0_4349:
	s_or_b64 exec, exec, s[0:1]
	v_mul_f32_e32 v3, v30, v2
	s_waitcnt lgkmcnt(0)
	s_nop 1
	v_mov_b32_dpp v4, v3 quad_perm:[1,0,3,2] row_mask:0xf bank_mask:0xf
	s_and_saveexec_b64 s[0:1], vcc
	s_cbranch_execz .LBB0_4351
	s_waitcnt lgkmcnt(0)
	v_cvt_pk_bf16_f32 v3, v3, v4
	global_store_dword v[0:1], v3, off offset:128
.LBB0_4351:
	s_or_b64 exec, exec, s[0:1]
	v_mul_f32_e32 v2, v14, v2
	s_nop 1
	v_mov_b32_dpp v3, v2 quad_perm:[1,0,3,2] row_mask:0xf bank_mask:0xf
	s_and_saveexec_b64 s[0:1], vcc
	s_cbranch_execz .LBB0_4353
	s_waitcnt lgkmcnt(0)
	v_cvt_pk_bf16_f32 v2, v2, v3
	global_store_dword v[0:1], v2, off offset:192
.LBB0_4353:
	s_or_b64 exec, exec, s[0:1]
	ds_read_b32 v0, v185 offset:108
	v_mov_b32_e32 v1, 0
	s_waitcnt lgkmcnt(0)
	v_rcp_f32_e32 v2, v0
	v_mov_b32_e32 v0, 0x1b000
	v_lshl_or_b32 v0, v184, 12, v0
	v_lshl_add_u64 v[0:1], v[64:65], 0, v[0:1]
	v_mul_f32_e32 v3, v63, v2
	s_nop 1
	v_mov_b32_dpp v4, v3 quad_perm:[1,0,3,2] row_mask:0xf bank_mask:0xf
	s_and_saveexec_b64 s[0:1], vcc
	s_cbranch_execz .LBB0_4355
	s_waitcnt lgkmcnt(0)
	v_cvt_pk_bf16_f32 v3, v3, v4
	global_store_dword v[0:1], v3, off
.LBB0_4355:
	s_or_b64 exec, exec, s[0:1]
	v_mul_f32_e32 v3, v47, v2
	s_waitcnt lgkmcnt(0)
	s_nop 1
	v_mov_b32_dpp v4, v3 quad_perm:[1,0,3,2] row_mask:0xf bank_mask:0xf
	s_and_saveexec_b64 s[0:1], vcc
	s_cbranch_execz .LBB0_4357
	s_waitcnt lgkmcnt(0)
	v_cvt_pk_bf16_f32 v3, v3, v4
	global_store_dword v[0:1], v3, off offset:64
.LBB0_4357:
	s_or_b64 exec, exec, s[0:1]
	v_mul_f32_e32 v3, v31, v2
	s_waitcnt lgkmcnt(0)
	s_nop 1
	v_mov_b32_dpp v4, v3 quad_perm:[1,0,3,2] row_mask:0xf bank_mask:0xf
	s_and_saveexec_b64 s[0:1], vcc
	s_cbranch_execz .LBB0_4359
	s_waitcnt lgkmcnt(0)
	v_cvt_pk_bf16_f32 v3, v3, v4
	global_store_dword v[0:1], v3, off offset:128
.LBB0_4359:
	s_or_b64 exec, exec, s[0:1]
	v_mul_f32_e32 v2, v15, v2
	s_nop 1
	v_mov_b32_dpp v3, v2 quad_perm:[1,0,3,2] row_mask:0xf bank_mask:0xf
	s_and_saveexec_b64 s[0:1], vcc
	s_cbranch_execz .LBB0_4361
	s_waitcnt lgkmcnt(0)
	v_cvt_pk_bf16_f32 v2, v2, v3
	global_store_dword v[0:1], v2, off offset:192

.LBB0_4599:
	s_waitcnt vmcnt(8)
	s_waitcnt vmcnt(9)
	ds_write_b128 v212, v[120:123] offset:32768
	s_waitcnt vmcnt(8)
	ds_write_b128 v212, v[124:127] offset:40960
	v_cmp_gt_u32_e32 vcc, 32, v213
	s_and_saveexec_b64 s[0:1], vcc
	ds_write_b32 v215, v1
	s_or_b64 exec, exec, s[0:1]
	s_waitcnt lgkmcnt(0)
	s_and_b64 vcc, exec, s[36:37]
	s_cbranch_vccnz .LBB0_4731
	ds_read2_b32 v[80:81], v214 offset1:3
	ds_read2_b32 v[82:83], v214 offset0:1 offset1:2
	ds_read_b128 v[10:13], v214 offset:32
	ds_read_b128 v[6:9], v214 offset:64
	ds_read_b128 v[2:5], v214 offset:96
	s_waitcnt lgkmcnt(4)
	v_rcp_f32_e32 v80, v80
	v_and_b32_e32 v14, 64, v204
	v_xor_b32_e32 v1, 1, v204
	v_add_u32_e32 v14, 64, v14
	v_cmp_lt_i32_e32 vcc, v1, v14
	v_mul_f32_e32 v48, v48, v80
	s_ashr_i32 s77, s76, 31
	v_cndmask_b32_e32 v1, v204, v1, vcc
	v_lshlrev_b32_e32 v1, 2, v1
	s_nop 1
	v_mov_b32_dpp v84, v48 quad_perm:[1,0,3,2] row_mask:0xf bank_mask:0xf
	s_lshl_b64 s[0:1], s[76:77], 12
	s_add_u32 s0, s52, s0
	v_and_b32_e32 v14, 1, v210
	s_addc_u32 s1, s53, s1
	v_cmp_eq_u32_e32 vcc, 0, v14
	v_lshlrev_b32_e32 v196, 12, v209
	v_lshlrev_b32_e32 v14, 1, v211
	s_and_saveexec_b64 s[20:21], vcc
	s_cbranch_execz .LBB0_4604
	v_lshl_add_u64 v[86:87], s[0:1], 0, v[196:197]
	v_mov_b32_e32 v15, v197
	v_lshl_add_u64 v[86:87], v[86:87], 0, v[14:15]
	s_waitcnt lgkmcnt(0)
	v_cvt_pk_bf16_f32 v15, v48, v84
	global_store_dword v[86:87], v15, off

.LBB0_4865:
	s_or_b64 exec, exec, s[26:27]
	v_or_b32_e32 v0, v73, v71
	v_mul_i32_i24_e32 v1, 0x190, v0
	v_lshlrev_b32_e32 v88, 4, v83
	v_mul_i32_i24_e32 v0, 0x90, v0
	v_add3_u32 v91, 0, v1, v88
	v_mul_lo_u32 v1, v54, s60
	v_add3_u32 v90, s62, v0, v88
	v_mul_lo_u32 v0, v54, s63
	v_add3_u32 v92, 0, v1, v88
	v_add3_u32 v89, s64, v0, v88
	v_mul_lo_u32 v0, v93, s60
	v_lshlrev_b32_e32 v1, 1, v64
	v_add3_u32 v96, 0, v0, v1
	v_mul_lo_u32 v0, v94, s60
	v_lshlrev_b32_e32 v1, 1, v66
	v_add3_u32 v97, 0, v0, v1
	v_mul_lo_u32 v0, v95, s60
	v_lshlrev_b32_e32 v1, 1, v68
	v_add3_u32 v98, 0, v0, v1
	v_mul_lo_u32 v0, v72, s63
	v_lshlrev_b32_e32 v1, 1, v99
	v_add3_u32 v72, s64, v0, v1
	v_mul_lo_u32 v0, v70, s63
	v_add3_u32 v70, s64, v0, v1
	v_add_u32_e32 v0, 0x80, v95
	v_mov_b64_e32 v[54:55], s[22:23]
	s_waitcnt lgkmcnt(0)
	s_barrier
	s_waitcnt vmcnt(7)
	ds_write_b128 v58, v[16:19]
	s_waitcnt vmcnt(6)
	ds_write_b128 v84, v[20:23]
	s_waitcnt vmcnt(5)
	ds_write_b128 v87, v[28:31]
	s_waitcnt vmcnt(4)
	ds_write_b128 v96, v[24:27]
	s_waitcnt vmcnt(3)
	ds_write_b128 v97, v[36:39]
	s_waitcnt vmcnt(2)
	ds_write_b128 v98, v[32:35]
	s_waitcnt vmcnt(1)
	ds_write_b16 v72, v44
	ds_write_b16_d16_hi v72, v44 offset:144
	ds_write_b16 v72, v45 offset:288
	ds_write_b16_d16_hi v72, v45 offset:432
	ds_write_b16 v72, v46 offset:576
	ds_write_b16_d16_hi v72, v46 offset:720
	ds_write_b16 v72, v47 offset:864
	ds_write_b16_d16_hi v72, v47 offset:1008
	s_waitcnt vmcnt(0)
	ds_write_b16 v70, v40
	ds_write_b16_d16_hi v70, v40 offset:144
	ds_write_b16 v70, v41 offset:288
	ds_write_b16_d16_hi v70, v41 offset:432
	ds_write_b16 v70, v42 offset:576
	ds_write_b16_d16_hi v70, v42 offset:720
	ds_write_b16 v70, v43 offset:864
	ds_write_b16_d16_hi v70, v43 offset:1008
	v_mad_i64_i32 v[0:1], s[2:3], v0, s54, v[54:55]
	v_lshlrev_b64 v[40:41], 1, v[68:69]
	v_lshl_add_u64 v[0:1], v[0:1], 0, v[40:41]
	s_waitcnt lgkmcnt(0)
	s_barrier
	global_load_dwordx4 v[16:19], v[0:1], off
	v_add_u32_e32 v0, 0x80, v94
	v_mad_i64_i32 v[0:1], s[2:3], v0, s54, v[54:55]
	v_lshlrev_b64 v[42:43], 1, v[66:67]
	v_lshl_add_u64 v[0:1], v[0:1], 0, v[42:43]
	global_load_dwordx4 v[20:23], v[0:1], off
	v_add_u32_e32 v0, 0x80, v93
	v_mad_i64_i32 v[0:1], s[2:3], v0, s54, v[54:55]
	v_lshlrev_b64 v[44:45], 1, v[64:65]
	v_lshl_add_u64 v[0:1], v[0:1], 0, v[44:45]
	global_load_dwordx4 v[24:27], v[0:1], off
	v_add_u32_e32 v0, 0x80, v81
	v_mad_i64_i32 v[0:1], s[2:3], v0, s54, v[54:55]
	v_lshlrev_b64 v[46:47], 1, v[52:53]
	v_lshl_add_u64 v[0:1], v[0:1], 0, v[46:47]
	global_load_dwordx4 v[28:31], v[0:1], off
	v_add_u32_e32 v0, 0x80, v80
	v_mad_i64_i32 v[0:1], s[2:3], v0, s54, v[54:55]
	v_lshlrev_b64 v[50:51], 1, v[50:51]
	v_lshl_add_u64 v[0:1], v[0:1], 0, v[50:51]
	global_load_dwordx4 v[32:35], v[0:1], off
	v_add_u32_e32 v0, 0x80, v79
	v_mad_i64_i32 v[0:1], s[2:3], v0, s54, v[54:55]
	v_lshlrev_b64 v[52:53], 1, v[48:49]
	v_lshl_add_u64 v[0:1], v[0:1], 0, v[52:53]
	global_load_dwordx4 v[36:39], v[0:1], off
	ds_read_b128 v[0:3], v91 offset:54272
	ds_read_b128 v[64:67], v91 offset:54304
	ds_read_b128 v[4:7], v92
	ds_read_b128 v[100:103], v92 offset:32
	s_waitcnt lgkmcnt(1)
	v_mfma_f32_32x32x16_bf16 v[0:15], v[0:3], v[4:7], 0
	s_waitcnt lgkmcnt(0)
	v_mfma_f32_32x32x16_bf16 v[0:15], v[64:67], v[100:103], v[0:15]
	ds_read_b128 v[64:67], v91 offset:54336
	ds_read_b128 v[100:103], v92 offset:64
	s_waitcnt lgkmcnt(0)
	v_mfma_f32_32x32x16_bf16 v[0:15], v[64:67], v[100:103], v[0:15]
	ds_read_b128 v[64:67], v91 offset:54368
	ds_read_b128 v[100:103], v92 offset:96
	s_waitcnt lgkmcnt(0)
	v_mfma_f32_32x32x16_bf16 v[0:15], v[64:67], v[100:103], v[0:15]
	ds_read_b128 v[64:67], v91 offset:54400
	ds_read_b128 v[100:103], v92 offset:128
	s_waitcnt lgkmcnt(0)
	v_mfma_f32_32x32x16_bf16 v[0:15], v[64:67], v[100:103], v[0:15]
	ds_read_b128 v[64:67], v91 offset:54432
	ds_read_b128 v[100:103], v92 offset:160
	s_waitcnt lgkmcnt(0)
	v_mfma_f32_32x32x16_bf16 v[0:15], v[64:67], v[100:103], v[0:15]
	ds_read_b128 v[64:67], v91 offset:54464
	ds_read_b128 v[100:103], v92 offset:192
	s_waitcnt lgkmcnt(0)
	v_mfma_f32_32x32x16_bf16 v[0:15], v[64:67], v[100:103], v[0:15]
	ds_read_b128 v[64:67], v91 offset:54496
	ds_read_b128 v[100:103], v92 offset:224
	s_waitcnt lgkmcnt(0)
	v_mfma_f32_32x32x16_bf16 v[0:15], v[64:67], v[100:103], v[0:15]
	ds_read_b128 v[64:67], v91 offset:54528
	ds_read_b128 v[100:103], v92 offset:256
	s_waitcnt lgkmcnt(0)
	v_mfma_f32_32x32x16_bf16 v[0:15], v[64:67], v[100:103], v[0:15]
	ds_read_b128 v[64:67], v91 offset:54560
	ds_read_b128 v[100:103], v92 offset:288
	s_waitcnt lgkmcnt(0)
	v_mfma_f32_32x32x16_bf16 v[0:15], v[64:67], v[100:103], v[0:15]
	ds_read_b128 v[64:67], v91 offset:54592
	ds_read_b128 v[100:103], v92 offset:320
	s_waitcnt lgkmcnt(0)
	v_mfma_f32_32x32x16_bf16 v[0:15], v[64:67], v[100:103], v[0:15]
	ds_read_b128 v[64:67], v91 offset:54624
	ds_read_b128 v[100:103], v92 offset:352
	s_waitcnt lgkmcnt(0)
	v_mfma_f32_32x32x16_bf16 v[0:15], v[64:67], v[100:103], v[0:15]
	ds_read_b128 v[64:67], v90
	ds_read_b128 v[100:103], v90 offset:32
	ds_read_b128 v[104:107], v89
	ds_read_b128 v[108:111], v89 offset:32
	s_waitcnt lgkmcnt(1)
	v_mfma_f32_32x32x16_bf16 v[0:15], v[64:67], v[104:107], v[0:15]
	s_waitcnt lgkmcnt(0)
	v_mfma_f32_32x32x16_bf16 v[0:15], v[100:103], v[108:111], v[0:15]
	ds_read_b128 v[64:67], v90 offset:64
	ds_read_b128 v[100:103], v89 offset:64
	s_waitcnt lgkmcnt(0)
	v_mfma_f32_32x32x16_bf16 v[0:15], v[64:67], v[100:103], v[0:15]
	ds_read_b128 v[64:67], v90 offset:96
	ds_read_b128 v[100:103], v89 offset:96
	s_waitcnt lgkmcnt(0)
	v_mfma_f32_32x32x16_bf16 v[0:15], v[64:67], v[100:103], v[0:15]
	global_load_dwordx4 v[64:67], v[62:63], off offset:3328
	global_load_dwordx4 v[100:103], v[60:61], off offset:3328
	s_barrier
	s_waitcnt vmcnt(2)
	ds_write_b128 v58, v[36:39]
	ds_write_b128 v84, v[32:35]
	ds_write_b128 v87, v[28:31]
	ds_write_b128 v96, v[24:27]
	ds_write_b128 v97, v[20:23]
	ds_write_b128 v98, v[16:19]
	s_waitcnt vmcnt(1)
	ds_write_b16 v72, v64
	ds_write_b16_d16_hi v72, v64 offset:144
	ds_write_b16 v72, v65 offset:288
	ds_write_b16_d16_hi v72, v65 offset:432
	ds_write_b16 v72, v66 offset:576
	ds_write_b16_d16_hi v72, v66 offset:720
	ds_write_b16 v72, v67 offset:864
	ds_write_b16_d16_hi v72, v67 offset:1008
	s_waitcnt vmcnt(0)
	ds_write_b16 v70, v100
	ds_write_b16_d16_hi v70, v100 offset:144
	ds_write_b16 v70, v101 offset:288
	ds_write_b16_d16_hi v70, v101 offset:432
	ds_write_b16 v70, v102 offset:576
	ds_write_b16_d16_hi v70, v102 offset:720
	ds_write_b16 v70, v103 offset:864
	ds_write_b16_d16_hi v70, v103 offset:1008
	v_add_u32_e32 v16, 0x100, v95
	v_mad_i64_i32 v[16:17], s[2:3], v16, s54, v[54:55]
	v_lshl_add_u64 v[16:17], v[16:17], 0, v[40:41]
	s_waitcnt lgkmcnt(0)
	s_barrier
	global_load_dwordx4 v[32:35], v[16:17], off
	v_add_u32_e32 v16, 0x100, v94
	v_mad_i64_i32 v[16:17], s[2:3], v16, s54, v[54:55]
	v_lshl_add_u64 v[16:17], v[16:17], 0, v[42:43]
	global_load_dwordx4 v[36:39], v[16:17], off
	v_add_u32_e32 v16, 0x100, v93
	v_mad_i64_i32 v[16:17], s[2:3], v16, s54, v[54:55]
	v_lshl_add_u64 v[16:17], v[16:17], 0, v[44:45]
	global_load_dwordx4 v[40:43], v[16:17], off
	v_add_u32_e32 v16, 0x100, v81
	v_mad_i64_i32 v[16:17], s[2:3], v16, s54, v[54:55]
	v_lshl_add_u64 v[16:17], v[16:17], 0, v[46:47]
	global_load_dwordx4 v[44:47], v[16:17], off
	v_add_u32_e32 v16, 0x100, v80
	v_mad_i64_i32 v[16:17], s[2:3], v16, s54, v[54:55]
	v_lshl_add_u64 v[16:17], v[16:17], 0, v[50:51]
	global_load_dwordx4 v[48:51], v[16:17], off
	v_add_u32_e32 v16, 0x100, v79
	v_mad_i64_i32 v[16:17], s[2:3], v16, s54, v[54:55]
	v_lshl_add_u64 v[16:17], v[16:17], 0, v[52:53]
	global_load_dwordx4 v[52:55], v[16:17], off
	ds_read_b128 v[16:19], v91 offset:54272
	ds_read_b128 v[64:67], v91 offset:54304
	ds_read_b128 v[20:23], v92
	ds_read_b128 v[100:103], v92 offset:32
	s_waitcnt lgkmcnt(1)
	v_mfma_f32_32x32x16_bf16 v[16:31], v[16:19], v[20:23], 0
	s_waitcnt lgkmcnt(0)
	v_mfma_f32_32x32x16_bf16 v[16:31], v[64:67], v[100:103], v[16:31]
	ds_read_b128 v[64:67], v91 offset:54336
	ds_read_b128 v[100:103], v92 offset:64
	s_waitcnt lgkmcnt(0)
	v_mfma_f32_32x32x16_bf16 v[16:31], v[64:67], v[100:103], v[16:31]
	ds_read_b128 v[64:67], v91 offset:54368
	ds_read_b128 v[100:103], v92 offset:96
	s_waitcnt lgkmcnt(0)
	v_mfma_f32_32x32x16_bf16 v[16:31], v[64:67], v[100:103], v[16:31]
	ds_read_b128 v[64:67], v91 offset:54400
	ds_read_b128 v[100:103], v92 offset:128
	s_waitcnt lgkmcnt(0)
	v_mfma_f32_32x32x16_bf16 v[16:31], v[64:67], v[100:103], v[16:31]
	ds_read_b128 v[64:67], v91 offset:54432
	ds_read_b128 v[100:103], v92 offset:160
	s_waitcnt lgkmcnt(0)
	v_mfma_f32_32x32x16_bf16 v[16:31], v[64:67], v[100:103], v[16:31]
	ds_read_b128 v[64:67], v91 offset:54464
	ds_read_b128 v[100:103], v92 offset:192
	s_waitcnt lgkmcnt(0)
	v_mfma_f32_32x32x16_bf16 v[16:31], v[64:67], v[100:103], v[16:31]
	ds_read_b128 v[64:67], v91 offset:54496
	ds_read_b128 v[100:103], v92 offset:224
	s_waitcnt lgkmcnt(0)
	v_mfma_f32_32x32x16_bf16 v[16:31], v[64:67], v[100:103], v[16:31]
	ds_read_b128 v[64:67], v91 offset:54528
	ds_read_b128 v[100:103], v92 offset:256
	s_waitcnt lgkmcnt(0)
	v_mfma_f32_32x32x16_bf16 v[16:31], v[64:67], v[100:103], v[16:31]
	ds_read_b128 v[64:67], v91 offset:54560
	ds_read_b128 v[100:103], v92 offset:288
	s_waitcnt lgkmcnt(0)
	v_mfma_f32_32x32x16_bf16 v[16:31], v[64:67], v[100:103], v[16:31]
	ds_read_b128 v[64:67], v91 offset:54592
	ds_read_b128 v[100:103], v92 offset:320
	s_waitcnt lgkmcnt(0)
	v_mfma_f32_32x32x16_bf16 v[16:31], v[64:67], v[100:103], v[16:31]
	ds_read_b128 v[64:67], v91 offset:54624
	ds_read_b128 v[100:103], v92 offset:352
	s_waitcnt lgkmcnt(0)
	v_mfma_f32_32x32x16_bf16 v[16:31], v[64:67], v[100:103], v[16:31]
	ds_read_b128 v[64:67], v90
	ds_read_b128 v[100:103], v90 offset:32
	ds_read_b128 v[104:107], v89
	ds_read_b128 v[108:111], v89 offset:32
	s_waitcnt lgkmcnt(1)
	v_mfma_f32_32x32x16_bf16 v[16:31], v[64:67], v[104:107], v[16:31]
	s_waitcnt lgkmcnt(0)
	v_mfma_f32_32x32x16_bf16 v[16:31], v[100:103], v[108:111], v[16:31]
	ds_read_b128 v[64:67], v90 offset:64
	ds_read_b128 v[100:103], v89 offset:64
	s_waitcnt lgkmcnt(0)
	v_mfma_f32_32x32x16_bf16 v[16:31], v[64:67], v[100:103], v[16:31]
	ds_read_b128 v[64:67], v90 offset:96
	ds_read_b128 v[100:103], v89 offset:96
	s_waitcnt lgkmcnt(0)
	v_mfma_f32_32x32x16_bf16 v[16:31], v[64:67], v[100:103], v[16:31]
	global_load_dwordx4 v[62:65], v[62:63], off offset:3584
	s_nop 0
	global_load_dwordx4 v[66:69], v[60:61], off offset:3584
	s_barrier
	s_waitcnt vmcnt(2)
	ds_write_b128 v58, v[52:55]
	ds_write_b128 v84, v[48:51]
	ds_write_b128 v87, v[44:47]
	ds_write_b128 v96, v[40:43]
	ds_write_b128 v97, v[36:39]
	ds_write_b128 v98, v[32:35]
	s_waitcnt vmcnt(1)
	ds_write_b16 v72, v62
	ds_write_b16_d16_hi v72, v62 offset:144
	ds_write_b16 v72, v63 offset:288
	ds_write_b16_d16_hi v72, v63 offset:432
	ds_write_b16 v72, v64 offset:576
	ds_write_b16_d16_hi v72, v64 offset:720
	ds_write_b16 v72, v65 offset:864
	ds_write_b16_d16_hi v72, v65 offset:1008
	s_waitcnt vmcnt(0)
	ds_write_b16 v70, v66
	ds_write_b16_d16_hi v70, v66 offset:144
	ds_write_b16 v70, v67 offset:288
	ds_write_b16_d16_hi v70, v67 offset:432
	ds_write_b16 v70, v68 offset:576
	ds_write_b16_d16_hi v70, v68 offset:720
	ds_write_b16 v70, v69 offset:864
	ds_write_b16_d16_hi v70, v69 offset:1008
	s_waitcnt lgkmcnt(0)
	s_barrier
	ds_read_b128 v[32:35], v91 offset:54272
	ds_read_b128 v[48:51], v91 offset:54304
	ds_read_b128 v[36:39], v92
	ds_read_b128 v[52:55], v92 offset:32
	s_waitcnt lgkmcnt(1)
	v_mfma_f32_32x32x16_bf16 v[32:47], v[32:35], v[36:39], 0
	s_waitcnt lgkmcnt(0)
	v_mfma_f32_32x32x16_bf16 v[32:47], v[48:51], v[52:55], v[32:47]
	ds_read_b128 v[48:51], v91 offset:54336
	ds_read_b128 v[52:55], v92 offset:64
	s_waitcnt lgkmcnt(0)
	v_mfma_f32_32x32x16_bf16 v[32:47], v[48:51], v[52:55], v[32:47]
	ds_read_b128 v[48:51], v91 offset:54368
	ds_read_b128 v[52:55], v92 offset:96
	s_waitcnt lgkmcnt(0)
	v_mfma_f32_32x32x16_bf16 v[32:47], v[48:51], v[52:55], v[32:47]
	ds_read_b128 v[48:51], v91 offset:54400
	ds_read_b128 v[52:55], v92 offset:128
	s_waitcnt lgkmcnt(0)
	v_mfma_f32_32x32x16_bf16 v[32:47], v[48:51], v[52:55], v[32:47]
	ds_read_b128 v[48:51], v91 offset:54432
	ds_read_b128 v[52:55], v92 offset:160
	s_waitcnt lgkmcnt(0)
	v_mfma_f32_32x32x16_bf16 v[32:47], v[48:51], v[52:55], v[32:47]
	ds_read_b128 v[48:51], v91 offset:54464
	ds_read_b128 v[52:55], v92 offset:192
	s_waitcnt lgkmcnt(0)
	v_mfma_f32_32x32x16_bf16 v[32:47], v[48:51], v[52:55], v[32:47]
	ds_read_b128 v[48:51], v91 offset:54496
	ds_read_b128 v[52:55], v92 offset:224
	s_waitcnt lgkmcnt(0)
	v_mfma_f32_32x32x16_bf16 v[32:47], v[48:51], v[52:55], v[32:47]
	ds_read_b128 v[48:51], v91 offset:54528
	ds_read_b128 v[52:55], v92 offset:256
	s_waitcnt lgkmcnt(0)
	v_mfma_f32_32x32x16_bf16 v[32:47], v[48:51], v[52:55], v[32:47]
	ds_read_b128 v[48:51], v91 offset:54560
	ds_read_b128 v[52:55], v92 offset:288
	s_waitcnt lgkmcnt(0)
	v_mfma_f32_32x32x16_bf16 v[32:47], v[48:51], v[52:55], v[32:47]
	ds_read_b128 v[48:51], v91 offset:54592
	ds_read_b128 v[52:55], v92 offset:320
	s_waitcnt lgkmcnt(0)
	v_mfma_f32_32x32x16_bf16 v[32:47], v[48:51], v[52:55], v[32:47]
	ds_read_b128 v[48:51], v91 offset:54624
	ds_read_b128 v[52:55], v92 offset:352
	s_waitcnt lgkmcnt(0)
	v_mfma_f32_32x32x16_bf16 v[32:47], v[48:51], v[52:55], v[32:47]
	ds_read_b128 v[48:51], v90
	ds_read_b128 v[52:55], v90 offset:32
	ds_read_b128 v[60:63], v89
	ds_read_b128 v[64:67], v89 offset:32
	s_waitcnt lgkmcnt(1)
	v_mfma_f32_32x32x16_bf16 v[32:47], v[48:51], v[60:63], v[32:47]
	s_waitcnt lgkmcnt(0)
	v_mfma_f32_32x32x16_bf16 v[32:47], v[52:55], v[64:67], v[32:47]
	ds_read_b128 v[48:51], v90 offset:64
	ds_read_b128 v[52:55], v89 offset:64
	s_waitcnt lgkmcnt(0)
	v_mfma_f32_32x32x16_bf16 v[32:47], v[48:51], v[52:55], v[32:47]
	ds_read_b128 v[48:51], v90 offset:96
	ds_read_b128 v[52:55], v89 offset:96
	s_waitcnt lgkmcnt(0)
	s_barrier
	v_mfma_f32_32x32x16_bf16 v[32:47], v[48:51], v[52:55], v[32:47]
	v_and_b32_e32 v49, 64, v204
	v_xor_b32_e32 v48, 1, v204
	v_add_u32_e32 v49, 64, v49
	v_cmp_lt_i32_e32 vcc, v48, v49
	v_mul_f32_e32 v53, v16, v16
	v_fmac_f32_e32 v53, v0, v0
	v_cndmask_b32_e32 v48, v204, v48, vcc
	v_lshlrev_b32_e32 v58, 2, v48
	s_nop 3
	v_fmac_f32_e32 v53, v32, v32
	s_nop 1
	v_mov_b32_dpp v54, v53 quad_perm:[1,0,3,2] row_mask:0xf bank_mask:0xf
	v_xor_b32_e32 v48, 2, v204
	v_cmp_lt_i32_e32 vcc, v48, v49
	v_xor_b32_e32 v50, 4, v204
	v_xor_b32_e32 v51, 8, v204
	v_cndmask_b32_e32 v48, v204, v48, vcc
	v_lshlrev_b32_e32 v48, 2, v48
	s_waitcnt lgkmcnt(0)
	v_add_f32_e32 v53, v53, v54
	ds_bpermute_b32 v54, v48, v53
	v_cmp_lt_i32_e32 vcc, v50, v49
	v_xor_b32_e32 v52, 16, v204
	s_waitcnt lgkmcnt(0)
	v_add_f32_e32 v53, v53, v54
	v_cndmask_b32_e32 v50, v204, v50, vcc
	v_lshlrev_b32_e32 v50, 2, v50
	ds_bpermute_b32 v54, v50, v53
	v_cmp_lt_i32_e32 vcc, v51, v49
	s_waitcnt lgkmcnt(0)
	v_add_f32_e32 v53, v53, v54
	v_cndmask_b32_e32 v51, v204, v51, vcc
	v_lshlrev_b32_e32 v51, 2, v51
	ds_bpermute_b32 v54, v51, v53
	v_cmp_lt_i32_e32 vcc, v52, v49
	s_waitcnt lgkmcnt(0)
	v_add_f32_e32 v53, v53, v54
	v_cndmask_b32_e32 v49, v204, v52, vcc
	v_lshlrev_b32_e32 v52, 2, v49
	ds_bpermute_b32 v54, v52, v53
	v_lshlrev_b32_e32 v49, 7, v85
	v_cmp_eq_u32_e32 vcc, 0, v71
	v_add3_u32 v49, v88, v86, v49
	s_and_saveexec_b64 s[22:23], vcc
	s_cbranch_execz .LBB0_4867
	s_waitcnt lgkmcnt(0)
	v_add_f32_e32 v53, v53, v54
	v_lshl_add_u32 v54, v49, 2, 0
	v_add_u32_e32 v54, 0x20800, v54
	ds_write_b32 v54, v53
.LBB0_4867:
	s_or_b64 exec, exec, s[22:23]
	v_mul_f32_e32 v53, v17, v17
	v_fmac_f32_e32 v53, v1, v1
	v_fmac_f32_e32 v53, v33, v33
	s_waitcnt lgkmcnt(0)
	s_nop 1
	v_mov_b32_dpp v54, v53 quad_perm:[1,0,3,2] row_mask:0xf bank_mask:0xf
	s_waitcnt lgkmcnt(0)
	v_add_f32_e32 v53, v53, v54
	ds_bpermute_b32 v54, v48, v53
	s_waitcnt lgkmcnt(0)
	v_add_f32_e32 v53, v53, v54
	ds_bpermute_b32 v54, v50, v53
	s_waitcnt lgkmcnt(0)
	v_add_f32_e32 v53, v53, v54
	ds_bpermute_b32 v54, v51, v53
	s_waitcnt lgkmcnt(0)
	v_add_f32_e32 v53, v53, v54
	ds_bpermute_b32 v54, v52, v53
	s_and_saveexec_b64 s[22:23], vcc
	s_cbranch_execz .LBB0_4869
	s_add_i32 s1, 0, 0x20800
	s_waitcnt lgkmcnt(0)
	v_add_f32_e32 v53, v53, v54
	v_lshl_add_u32 v54, v49, 2, s1
	ds_write_b32 v54, v53 offset:16
.LBB0_4869:
	s_or_b64 exec, exec, s[22:23]
	v_mul_f32_e32 v53, v18, v18
	v_fmac_f32_e32 v53, v2, v2
	v_fmac_f32_e32 v53, v34, v34
	s_waitcnt lgkmcnt(0)
	s_nop 1
	v_mov_b32_dpp v54, v53 quad_perm:[1,0,3,2] row_mask:0xf bank_mask:0xf
	s_waitcnt lgkmcnt(0)
	v_add_f32_e32 v53, v53, v54
	ds_bpermute_b32 v54, v48, v53
	s_waitcnt lgkmcnt(0)
	v_add_f32_e32 v53, v53, v54
	ds_bpermute_b32 v54, v50, v53
	s_waitcnt lgkmcnt(0)
	v_add_f32_e32 v53, v53, v54
	ds_bpermute_b32 v54, v51, v53
	s_waitcnt lgkmcnt(0)
	v_add_f32_e32 v53, v53, v54
	ds_bpermute_b32 v54, v52, v53
	s_and_saveexec_b64 s[22:23], vcc
	s_cbranch_execz .LBB0_4871
	s_add_i32 s1, 0, 0x20800
	s_waitcnt lgkmcnt(0)
	v_add_f32_e32 v53, v53, v54
	v_lshl_add_u32 v54, v49, 2, s1
	ds_write_b32 v54, v53 offset:32
.LBB0_4871:
	s_or_b64 exec, exec, s[22:23]
	v_mul_f32_e32 v53, v19, v19
	v_fmac_f32_e32 v53, v3, v3
	v_fmac_f32_e32 v53, v35, v35
	s_waitcnt lgkmcnt(0)
	s_nop 1
	v_mov_b32_dpp v54, v53 quad_perm:[1,0,3,2] row_mask:0xf bank_mask:0xf
	s_waitcnt lgkmcnt(0)
	v_add_f32_e32 v53, v53, v54
	ds_bpermute_b32 v54, v48, v53
	s_waitcnt lgkmcnt(0)
	v_add_f32_e32 v53, v53, v54
	ds_bpermute_b32 v54, v50, v53
	s_waitcnt lgkmcnt(0)
	v_add_f32_e32 v53, v53, v54
	ds_bpermute_b32 v54, v51, v53
	s_waitcnt lgkmcnt(0)
	v_add_f32_e32 v53, v53, v54
	ds_bpermute_b32 v54, v52, v53
	s_and_saveexec_b64 s[22:23], vcc
	s_cbranch_execz .LBB0_4873
	s_add_i32 s1, 0, 0x20800
	s_waitcnt lgkmcnt(0)
	v_add_f32_e32 v53, v53, v54
	v_lshl_add_u32 v54, v49, 2, s1
	ds_write_b32 v54, v53 offset:48
.LBB0_4873:
	s_or_b64 exec, exec, s[22:23]
	v_mul_f32_e32 v53, v20, v20
	v_fmac_f32_e32 v53, v4, v4
	v_fmac_f32_e32 v53, v36, v36
	s_waitcnt lgkmcnt(0)
	s_nop 1
	v_mov_b32_dpp v54, v53 quad_perm:[1,0,3,2] row_mask:0xf bank_mask:0xf
	s_waitcnt lgkmcnt(0)
	v_add_f32_e32 v53, v53, v54
	ds_bpermute_b32 v54, v48, v53
	s_waitcnt lgkmcnt(0)
	v_add_f32_e32 v53, v53, v54
	ds_bpermute_b32 v54, v50, v53
	s_waitcnt lgkmcnt(0)
	v_add_f32_e32 v53, v53, v54
	ds_bpermute_b32 v54, v51, v53
	s_waitcnt lgkmcnt(0)
	v_add_f32_e32 v53, v53, v54
	ds_bpermute_b32 v54, v52, v53
	s_and_saveexec_b64 s[22:23], vcc
	s_cbranch_execz .LBB0_4875
	s_add_i32 s1, 0, 0x20800
	s_waitcnt lgkmcnt(0)
	v_add_f32_e32 v53, v53, v54
	v_lshl_add_u32 v54, v49, 2, s1
	ds_write_b32 v54, v53 offset:128
.LBB0_4875:
	s_or_b64 exec, exec, s[22:23]
	v_mul_f32_e32 v53, v21, v21
	v_fmac_f32_e32 v53, v5, v5
	v_fmac_f32_e32 v53, v37, v37
	s_waitcnt lgkmcnt(0)
	s_nop 1
	v_mov_b32_dpp v54, v53 quad_perm:[1,0,3,2] row_mask:0xf bank_mask:0xf
	s_waitcnt lgkmcnt(0)
	v_add_f32_e32 v53, v53, v54
	ds_bpermute_b32 v54, v48, v53
	s_waitcnt lgkmcnt(0)
	v_add_f32_e32 v53, v53, v54
	ds_bpermute_b32 v54, v50, v53
	s_waitcnt lgkmcnt(0)
	v_add_f32_e32 v53, v53, v54
	ds_bpermute_b32 v54, v51, v53
	s_waitcnt lgkmcnt(0)
	v_add_f32_e32 v53, v53, v54
	ds_bpermute_b32 v54, v52, v53
	s_and_saveexec_b64 s[22:23], vcc
	s_cbranch_execz .LBB0_4877
	s_add_i32 s1, 0, 0x20800
	s_waitcnt lgkmcnt(0)
	v_add_f32_e32 v53, v53, v54
	v_lshl_add_u32 v54, v49, 2, s1
	ds_write_b32 v54, v53 offset:144
.LBB0_4877:
	s_or_b64 exec, exec, s[22:23]
	v_mul_f32_e32 v53, v22, v22
	v_fmac_f32_e32 v53, v6, v6
	v_fmac_f32_e32 v53, v38, v38
	s_waitcnt lgkmcnt(0)
	s_nop 1
	v_mov_b32_dpp v54, v53 quad_perm:[1,0,3,2] row_mask:0xf bank_mask:0xf
	s_waitcnt lgkmcnt(0)
	v_add_f32_e32 v53, v53, v54
	ds_bpermute_b32 v54, v48, v53
	s_waitcnt lgkmcnt(0)
	v_add_f32_e32 v53, v53, v54
	ds_bpermute_b32 v54, v50, v53
	s_waitcnt lgkmcnt(0)
	v_add_f32_e32 v53, v53, v54
	ds_bpermute_b32 v54, v51, v53
	s_waitcnt lgkmcnt(0)
	v_add_f32_e32 v53, v53, v54
	ds_bpermute_b32 v54, v52, v53
	s_and_saveexec_b64 s[22:23], vcc
	s_cbranch_execz .LBB0_4879
	s_add_i32 s1, 0, 0x20800
	s_waitcnt lgkmcnt(0)
	v_add_f32_e32 v53, v53, v54
	v_lshl_add_u32 v54, v49, 2, s1
	ds_write_b32 v54, v53 offset:160
.LBB0_4879:
	s_or_b64 exec, exec, s[22:23]
	v_mul_f32_e32 v53, v23, v23
	v_fmac_f32_e32 v53, v7, v7
	v_fmac_f32_e32 v53, v39, v39
	s_waitcnt lgkmcnt(0)
	s_nop 1
	v_mov_b32_dpp v54, v53 quad_perm:[1,0,3,2] row_mask:0xf bank_mask:0xf
	s_waitcnt lgkmcnt(0)
	v_add_f32_e32 v53, v53, v54
	ds_bpermute_b32 v54, v48, v53
	s_waitcnt lgkmcnt(0)
	v_add_f32_e32 v53, v53, v54
	ds_bpermute_b32 v54, v50, v53
	s_waitcnt lgkmcnt(0)
	v_add_f32_e32 v53, v53, v54
	ds_bpermute_b32 v54, v51, v53
	s_waitcnt lgkmcnt(0)
	v_add_f32_e32 v53, v53, v54
	ds_bpermute_b32 v54, v52, v53
	s_and_saveexec_b64 s[22:23], vcc
	s_cbranch_execz .LBB0_4881
	s_add_i32 s1, 0, 0x20800
	s_waitcnt lgkmcnt(0)
	v_add_f32_e32 v53, v53, v54
	v_lshl_add_u32 v54, v49, 2, s1
	ds_write_b32 v54, v53 offset:176
.LBB0_4881:
	s_or_b64 exec, exec, s[22:23]
	v_mul_f32_e32 v53, v24, v24
	v_fmac_f32_e32 v53, v8, v8
	v_fmac_f32_e32 v53, v40, v40
	s_waitcnt lgkmcnt(0)
	s_nop 1
	v_mov_b32_dpp v54, v53 quad_perm:[1,0,3,2] row_mask:0xf bank_mask:0xf
	s_waitcnt lgkmcnt(0)
	v_add_f32_e32 v53, v53, v54
	ds_bpermute_b32 v54, v48, v53
	s_waitcnt lgkmcnt(0)
	v_add_f32_e32 v53, v53, v54
	ds_bpermute_b32 v54, v50, v53
	s_waitcnt lgkmcnt(0)
	v_add_f32_e32 v53, v53, v54
	ds_bpermute_b32 v54, v51, v53
	s_waitcnt lgkmcnt(0)
	v_add_f32_e32 v53, v53, v54
	ds_bpermute_b32 v54, v52, v53
	s_and_saveexec_b64 s[22:23], vcc
	s_cbranch_execz .LBB0_4883
	s_add_i32 s1, 0, 0x20800
	s_waitcnt lgkmcnt(0)
	v_add_f32_e32 v53, v53, v54
	v_lshl_add_u32 v54, v49, 2, s1
	ds_write_b32 v54, v53 offset:256
.LBB0_4883:
	s_or_b64 exec, exec, s[22:23]
	v_mul_f32_e32 v53, v25, v25
	v_fmac_f32_e32 v53, v9, v9
	v_fmac_f32_e32 v53, v41, v41
	s_waitcnt lgkmcnt(0)
	s_nop 1
	v_mov_b32_dpp v54, v53 quad_perm:[1,0,3,2] row_mask:0xf bank_mask:0xf
	s_waitcnt lgkmcnt(0)
	v_add_f32_e32 v53, v53, v54
	ds_bpermute_b32 v54, v48, v53
	s_waitcnt lgkmcnt(0)
	v_add_f32_e32 v53, v53, v54
	ds_bpermute_b32 v54, v50, v53
	s_waitcnt lgkmcnt(0)
	v_add_f32_e32 v53, v53, v54
	ds_bpermute_b32 v54, v51, v53
	s_waitcnt lgkmcnt(0)
	v_add_f32_e32 v53, v53, v54
	ds_bpermute_b32 v54, v52, v53
	s_and_saveexec_b64 s[22:23], vcc
	s_cbranch_execz .LBB0_4885
	s_add_i32 s1, 0, 0x20800
	s_waitcnt lgkmcnt(0)
	v_add_f32_e32 v53, v53, v54
	v_lshl_add_u32 v54, v49, 2, s1
	ds_write_b32 v54, v53 offset:272
.LBB0_4885:
	s_or_b64 exec, exec, s[22:23]
	v_mul_f32_e32 v53, v26, v26
	v_fmac_f32_e32 v53, v10, v10
	v_fmac_f32_e32 v53, v42, v42
	s_waitcnt lgkmcnt(0)
	s_nop 1
	v_mov_b32_dpp v54, v53 quad_perm:[1,0,3,2] row_mask:0xf bank_mask:0xf
	s_waitcnt lgkmcnt(0)
	v_add_f32_e32 v53, v53, v54
	ds_bpermute_b32 v54, v48, v53
	s_waitcnt lgkmcnt(0)
	v_add_f32_e32 v53, v53, v54
	ds_bpermute_b32 v54, v50, v53
	s_waitcnt lgkmcnt(0)
	v_add_f32_e32 v53, v53, v54
	ds_bpermute_b32 v54, v51, v53
	s_waitcnt lgkmcnt(0)
	v_add_f32_e32 v53, v53, v54
	ds_bpermute_b32 v54, v52, v53
	s_and_saveexec_b64 s[22:23], vcc
	s_cbranch_execz .LBB0_4887
	s_add_i32 s1, 0, 0x20800
	s_waitcnt lgkmcnt(0)
	v_add_f32_e32 v53, v53, v54
	v_lshl_add_u32 v54, v49, 2, s1
	ds_write_b32 v54, v53 offset:288
.LBB0_4887:
	s_or_b64 exec, exec, s[22:23]
	v_mul_f32_e32 v53, v27, v27
	v_fmac_f32_e32 v53, v11, v11
	v_fmac_f32_e32 v53, v43, v43
	s_waitcnt lgkmcnt(0)
	s_nop 1
	v_mov_b32_dpp v54, v53 quad_perm:[1,0,3,2] row_mask:0xf bank_mask:0xf
	s_waitcnt lgkmcnt(0)
	v_add_f32_e32 v53, v53, v54
	ds_bpermute_b32 v54, v48, v53
	s_waitcnt lgkmcnt(0)
	v_add_f32_e32 v53, v53, v54
	ds_bpermute_b32 v54, v50, v53
	s_waitcnt lgkmcnt(0)
	v_add_f32_e32 v53, v53, v54
	ds_bpermute_b32 v54, v51, v53
	s_waitcnt lgkmcnt(0)
	v_add_f32_e32 v53, v53, v54
	ds_bpermute_b32 v54, v52, v53
	s_and_saveexec_b64 s[22:23], vcc
	s_cbranch_execz .LBB0_4889
	s_add_i32 s1, 0, 0x20800
	s_waitcnt lgkmcnt(0)
	v_add_f32_e32 v53, v53, v54
	v_lshl_add_u32 v54, v49, 2, s1
	ds_write_b32 v54, v53 offset:304
.LBB0_4889:
	s_or_b64 exec, exec, s[22:23]
	v_mul_f32_e32 v53, v28, v28
	v_fmac_f32_e32 v53, v12, v12
	v_fmac_f32_e32 v53, v44, v44
	s_waitcnt lgkmcnt(0)
	s_nop 1
	v_mov_b32_dpp v54, v53 quad_perm:[1,0,3,2] row_mask:0xf bank_mask:0xf
	s_waitcnt lgkmcnt(0)
	v_add_f32_e32 v53, v53, v54
	ds_bpermute_b32 v54, v48, v53
	s_waitcnt lgkmcnt(0)
	v_add_f32_e32 v53, v53, v54
	ds_bpermute_b32 v54, v50, v53
	s_waitcnt lgkmcnt(0)
	v_add_f32_e32 v53, v53, v54
	ds_bpermute_b32 v54, v51, v53
	s_waitcnt lgkmcnt(0)
	v_add_f32_e32 v53, v53, v54
	ds_bpermute_b32 v54, v52, v53
	s_and_saveexec_b64 s[22:23], vcc
	s_cbranch_execz .LBB0_4891
	s_add_i32 s1, 0, 0x20800
	s_waitcnt lgkmcnt(0)
	v_add_f32_e32 v53, v53, v54
	v_lshl_add_u32 v54, v49, 2, s1
	ds_write_b32 v54, v53 offset:384
.LBB0_4891:
	s_or_b64 exec, exec, s[22:23]
	v_mul_f32_e32 v53, v29, v29
	v_fmac_f32_e32 v53, v13, v13
	v_fmac_f32_e32 v53, v45, v45
	s_waitcnt lgkmcnt(0)
	s_nop 1
	v_mov_b32_dpp v54, v53 quad_perm:[1,0,3,2] row_mask:0xf bank_mask:0xf
	s_waitcnt lgkmcnt(0)
	v_add_f32_e32 v53, v53, v54
	ds_bpermute_b32 v54, v48, v53
	s_waitcnt lgkmcnt(0)
	v_add_f32_e32 v53, v53, v54
	ds_bpermute_b32 v54, v50, v53
	s_waitcnt lgkmcnt(0)
	v_add_f32_e32 v53, v53, v54
	ds_bpermute_b32 v54, v51, v53
	s_waitcnt lgkmcnt(0)
	v_add_f32_e32 v53, v53, v54
	ds_bpermute_b32 v54, v52, v53
	s_and_saveexec_b64 s[22:23], vcc
	s_cbranch_execz .LBB0_4893
	s_add_i32 s1, 0, 0x20800
	s_waitcnt lgkmcnt(0)
	v_add_f32_e32 v53, v53, v54
	v_lshl_add_u32 v54, v49, 2, s1
	ds_write_b32 v54, v53 offset:400
.LBB0_4893:
	s_or_b64 exec, exec, s[22:23]
	v_mul_f32_e32 v53, v30, v30
	v_fmac_f32_e32 v53, v14, v14
	v_fmac_f32_e32 v53, v46, v46
	s_waitcnt lgkmcnt(0)
	s_nop 1
	v_mov_b32_dpp v54, v53 quad_perm:[1,0,3,2] row_mask:0xf bank_mask:0xf
	s_waitcnt lgkmcnt(0)
	v_add_f32_e32 v53, v53, v54
	ds_bpermute_b32 v54, v48, v53
	s_waitcnt lgkmcnt(0)
	v_add_f32_e32 v53, v53, v54
	ds_bpermute_b32 v54, v50, v53
	s_waitcnt lgkmcnt(0)
	v_add_f32_e32 v53, v53, v54
	ds_bpermute_b32 v54, v51, v53
	s_waitcnt lgkmcnt(0)
	v_add_f32_e32 v53, v53, v54
	ds_bpermute_b32 v54, v52, v53
	s_and_saveexec_b64 s[22:23], vcc
	s_cbranch_execz .LBB0_4895
	s_add_i32 s1, 0, 0x20800
	s_waitcnt lgkmcnt(0)
	v_add_f32_e32 v53, v53, v54
	v_lshl_add_u32 v54, v49, 2, s1
	ds_write_b32 v54, v53 offset:416
.LBB0_4895:
	s_or_b64 exec, exec, s[22:23]
	v_mul_f32_e32 v53, v31, v31
	v_fmac_f32_e32 v53, v15, v15
	v_fmac_f32_e32 v53, v47, v47
	s_waitcnt lgkmcnt(0)
	s_nop 1
	v_mov_b32_dpp v54, v53 quad_perm:[1,0,3,2] row_mask:0xf bank_mask:0xf
	s_waitcnt lgkmcnt(0)
	v_add_f32_e32 v53, v53, v54
	ds_bpermute_b32 v48, v48, v53
	s_waitcnt lgkmcnt(0)
	v_add_f32_e32 v48, v53, v48
	ds_bpermute_b32 v50, v50, v48
	s_waitcnt lgkmcnt(0)
	v_add_f32_e32 v48, v48, v50
	ds_bpermute_b32 v50, v51, v48
	s_waitcnt lgkmcnt(0)
	v_add_f32_e32 v48, v48, v50
	ds_bpermute_b32 v50, v52, v48
	s_and_saveexec_b64 s[22:23], vcc
	s_cbranch_execz .LBB0_4897
	s_add_i32 s1, 0, 0x20800
	s_waitcnt lgkmcnt(0)
	v_add_f32_e32 v48, v48, v50
	v_lshl_add_u32 v49, v49, 2, s1
	ds_write_b32 v49, v48 offset:432

.LBB0_5103:
	s_and_b64 vcc, exec, s[22:23]
	s_cbranch_vccz .LBB0_4997
	v_cmp_gt_u32_e32 vcc, 32, v226
	s_and_saveexec_b64 s[20:21], vcc
	v_lshl_add_u32 v0, v225, 2, s1
	ds_write_b32 v0, v80
	s_or_b64 exec, exec, s[20:21]
	v_and_b32_e32 v2, 64, v204
	v_xor_b32_e32 v0, 1, v204
	v_add_u32_e32 v2, 64, v2
	s_ashr_i32 s1, s0, 31
	v_cmp_lt_i32_e32 vcc, v0, v2
	s_lshl_b64 s[0:1], s[0:1], 12
	s_add_u32 s0, s46, s0
	v_cndmask_b32_e32 v0, v204, v0, vcc
	v_lshlrev_b32_e32 v6, 2, v0
	v_and_b32_e32 v0, 1, v224
	s_waitcnt lgkmcnt(0)
	s_addc_u32 s1, s47, s1
	v_cmp_eq_u32_e32 vcc, 0, v0
	v_lshlrev_b32_e32 v0, 1, v225
	v_lshl_add_u64 v[2:3], s[0:1], 0, v[0:1]
	ds_read_b32 v0, v222
	s_waitcnt lgkmcnt(0)
	v_rcp_f32_e32 v7, v0
	v_lshlrev_b32_e32 v0, 14, v223
	v_lshl_add_u64 v[4:5], v[2:3], 0, v[0:1]
	v_mul_f32_e32 v0, v64, v7
	s_nop 1
	v_mov_b32_dpp v8, v0 quad_perm:[1,0,3,2] row_mask:0xf bank_mask:0xf
	s_and_saveexec_b64 s[0:1], vcc
	s_cbranch_execz .LBB0_5108
	s_waitcnt lgkmcnt(0)
	v_cvt_pk_bf16_f32 v0, v0, v8
	global_store_dword v[4:5], v0, off

.LBB0_6304:
	s_mov_b64 s[60:61], 0x80
	s_add_i32 m0, s5, 0x18000
	v_lshl_add_u64 v[26:27], v[26:27], 0, s[60:61]
	s_waitcnt vmcnt(2)
	s_barrier
	global_load_lds_dwordx4 v[26:27], off
	v_lshl_add_u64 v[24:25], v[24:25], 0, s[60:61]
	s_add_i32 m0, s5, 0x1a000
	s_add_i32 s9, s5, 0x8000
	s_add_i32 s10, s5, 0xa000
	global_load_lds_dwordx4 v[24:25], off
	v_lshl_add_u64 v[20:21], v[20:21], 0, s[60:61]
	s_mov_b32 m0, s9
	s_add_u32 s26, s20, 0x80080
	global_load_lds_dwordx4 v[20:21], off
	v_lshl_add_u64 v[20:21], v[22:23], 0, s[60:61]
	s_mov_b32 m0, s10
	s_addc_u32 s27, s21, 0
	global_load_lds_dwordx4 v[20:21], off
	s_add_i32 m0, s5, 0x1c000
	v_lshl_add_u64 v[20:21], s[26:27], 0, v[150:151]
	global_load_lds_dwordx4 v[20:21], off
	v_lshl_add_u64 v[20:21], s[26:27], 0, v[154:155]
	s_add_i32 m0, s5, 0x1e000
	s_waitcnt vmcnt(0)
	v_pk_add_f32 v[10:11], v[14:15], v[10:11]
	global_load_lds_dwordx4 v[20:21], off
	v_pk_add_f32 v[8:9], v[12:13], v[8:9]
	v_pk_add_f32 v[0:1], v[4:5], v[0:1]
	v_pk_add_f32 v[2:3], v[6:7], v[2:3]
	v_pk_add_f32 v[0:1], v[8:9], v[0:1]
	v_pk_add_f32 v[2:3], v[10:11], v[2:3]
	v_add_f32_e32 v0, v0, v1
	v_add_f32_e32 v1, v2, v3
	v_add_f32_e32 v1, v0, v1
	v_and_b32_e32 v0, 64, v204
	v_xor_b32_e32 v2, 1, v204
	v_add_u32_e32 v0, 64, v0
	v_cmp_lt_i32_e32 vcc, v2, v0
	s_waitcnt vmcnt(6)
	s_mov_b32 s63, 0
	v_cmp_eq_u32_e64 s[34:35], 0, v29
	v_cndmask_b32_e32 v2, v204, v2, vcc
	v_lshlrev_b32_e32 v198, 2, v2
	s_nop 1
	v_mov_b32_dpp v2, v1 quad_perm:[1,0,3,2] row_mask:0xf bank_mask:0xf
	s_barrier
	s_and_saveexec_b64 s[26:27], s[34:35]
	s_cbranch_execz .LBB0_6306
	s_waitcnt lgkmcnt(0)
	v_add_f32_e32 v1, v1, v2
	v_mov_b32_e32 v2, 0x358637bd
	v_fmac_f32_e32 v2, 0x3a000000, v1
	s_mov_b32 s11, 0x800000
	v_mul_f32_e32 v1, 0x4b800000, v2
	v_cmp_gt_f32_e32 vcc, s11, v2
	s_nop 1
	v_cndmask_b32_e32 v1, v2, v1, vcc
	v_rsq_f32_e32 v1, v1
	s_nop 0
	v_mul_f32_e32 v2, 0x45800000, v1
	v_cndmask_b32_e32 v1, v1, v2, vcc
	v_lshl_add_u32 v2, v18, 2, 0
	v_add_u32_e32 v2, 0x20000, v2
	ds_write_b32 v2, v1

.LBB0_6749:
	s_and_b64 vcc, exec, s[20:21]
	s_cbranch_vccz .LBB0_6547
	v_cmp_gt_u32_e32 vcc, 32, v227
	s_and_saveexec_b64 s[20:21], vcc
	v_lshl_add_u32 v0, v226, 2, s1
	ds_write_b32 v0, v80
	s_or_b64 exec, exec, s[20:21]
	v_and_b32_e32 v2, 64, v204
	v_xor_b32_e32 v0, 1, v204
	v_add_u32_e32 v2, 64, v2
	s_ashr_i32 s1, s0, 31
	v_cmp_lt_i32_e32 vcc, v0, v2
	s_lshl_b64 s[0:1], s[0:1], 12
	s_add_u32 s0, s52, s0
	v_cndmask_b32_e32 v0, v204, v0, vcc
	v_lshlrev_b32_e32 v6, 2, v0
	v_and_b32_e32 v0, 1, v225
	s_waitcnt lgkmcnt(0)
	s_addc_u32 s1, s53, s1
	v_cmp_eq_u32_e32 vcc, 0, v0
	v_lshlrev_b32_e32 v0, 1, v226
	v_lshl_add_u64 v[2:3], s[0:1], 0, v[0:1]
	ds_read_b32 v0, v223
	s_waitcnt lgkmcnt(0)
	v_rcp_f32_e32 v7, v0
	v_lshlrev_b32_e32 v0, 14, v224
	v_lshl_add_u64 v[4:5], v[2:3], 0, v[0:1]
	v_mul_f32_e32 v0, v64, v7
	s_nop 1
	v_mov_b32_dpp v8, v0 quad_perm:[1,0,3,2] row_mask:0xf bank_mask:0xf
	s_and_saveexec_b64 s[0:1], vcc
	s_cbranch_execz .LBB0_6754
	s_waitcnt lgkmcnt(0)
	v_cvt_pk_bf16_f32 v0, v0, v8
	global_store_dword v[4:5], v0, off

.LBB0_6760:
	s_or_b64 exec, exec, s[0:1]
	ds_read_b32 v0, v223 offset:4
	s_waitcnt lgkmcnt(0)
	v_rcp_f32_e32 v7, v0
	v_lshl_or_b32 v0, v222, 12, v207
	v_lshl_add_u64 v[4:5], v[2:3], 0, v[0:1]
	v_mul_f32_e32 v0, v65, v7
	s_nop 1
	v_mov_b32_dpp v8, v0 quad_perm:[1,0,3,2] row_mask:0xf bank_mask:0xf
	s_and_saveexec_b64 s[0:1], vcc
	s_cbranch_execz .LBB0_6762
	s_waitcnt lgkmcnt(0)
	v_cvt_pk_bf16_f32 v0, v0, v8
	global_store_dword v[4:5], v0, off

.LBB0_6768:
	s_or_b64 exec, exec, s[0:1]
	ds_read_b32 v0, v223 offset:8
	s_waitcnt lgkmcnt(0)
	v_rcp_f32_e32 v7, v0
	v_lshl_or_b32 v0, v222, 12, v208
	v_lshl_add_u64 v[4:5], v[2:3], 0, v[0:1]
	v_mul_f32_e32 v0, v66, v7
	s_nop 1
	v_mov_b32_dpp v8, v0 quad_perm:[1,0,3,2] row_mask:0xf bank_mask:0xf
	s_and_saveexec_b64 s[0:1], vcc
	s_cbranch_execz .LBB0_6770
	s_waitcnt lgkmcnt(0)
	v_cvt_pk_bf16_f32 v0, v0, v8
	global_store_dword v[4:5], v0, off

.LBB0_6776:
	s_or_b64 exec, exec, s[0:1]
	ds_read_b32 v0, v223 offset:12
	s_waitcnt lgkmcnt(0)
	v_rcp_f32_e32 v7, v0
	v_lshl_or_b32 v0, v222, 12, v209
	v_lshl_add_u64 v[4:5], v[2:3], 0, v[0:1]
	v_mul_f32_e32 v0, v67, v7
	s_nop 1
	v_mov_b32_dpp v8, v0 quad_perm:[1,0,3,2] row_mask:0xf bank_mask:0xf
	s_and_saveexec_b64 s[0:1], vcc
	s_cbranch_execz .LBB0_6778
	s_waitcnt lgkmcnt(0)
	v_cvt_pk_bf16_f32 v0, v0, v8
	global_store_dword v[4:5], v0, off

.LBB0_6784:
	s_or_b64 exec, exec, s[0:1]
	ds_read_b32 v0, v223 offset:32
	s_waitcnt lgkmcnt(0)
	v_rcp_f32_e32 v7, v0
	v_lshl_or_b32 v0, v222, 12, v210
	v_lshl_add_u64 v[4:5], v[2:3], 0, v[0:1]
	v_mul_f32_e32 v0, v68, v7
	s_nop 1
	v_mov_b32_dpp v8, v0 quad_perm:[1,0,3,2] row_mask:0xf bank_mask:0xf
	s_and_saveexec_b64 s[0:1], vcc
	s_cbranch_execz .LBB0_6786
	s_waitcnt lgkmcnt(0)
	v_cvt_pk_bf16_f32 v0, v0, v8
	global_store_dword v[4:5], v0, off

.LBB0_6792:
	s_or_b64 exec, exec, s[0:1]
	ds_read_b32 v0, v223 offset:36
	s_waitcnt lgkmcnt(0)
	v_rcp_f32_e32 v7, v0
	v_lshl_or_b32 v0, v222, 12, v211
	v_lshl_add_u64 v[4:5], v[2:3], 0, v[0:1]
	v_mul_f32_e32 v0, v69, v7
	s_nop 1
	v_mov_b32_dpp v8, v0 quad_perm:[1,0,3,2] row_mask:0xf bank_mask:0xf
	s_and_saveexec_b64 s[0:1], vcc
	s_cbranch_execz .LBB0_6794
	s_waitcnt lgkmcnt(0)
	v_cvt_pk_bf16_f32 v0, v0, v8
	global_store_dword v[4:5], v0, off

.LBB0_6800:
	s_or_b64 exec, exec, s[0:1]
	ds_read_b32 v0, v223 offset:40
	s_waitcnt lgkmcnt(0)
	v_rcp_f32_e32 v7, v0
	v_lshl_or_b32 v0, v222, 12, v212
	v_lshl_add_u64 v[4:5], v[2:3], 0, v[0:1]
	v_mul_f32_e32 v0, v70, v7
	s_nop 1
	v_mov_b32_dpp v8, v0 quad_perm:[1,0,3,2] row_mask:0xf bank_mask:0xf
	s_and_saveexec_b64 s[0:1], vcc
	s_cbranch_execz .LBB0_6802
	s_waitcnt lgkmcnt(0)
	v_cvt_pk_bf16_f32 v0, v0, v8
	global_store_dword v[4:5], v0, off

.LBB0_6808:
	s_or_b64 exec, exec, s[0:1]
	ds_read_b32 v0, v223 offset:44
	s_waitcnt lgkmcnt(0)
	v_rcp_f32_e32 v7, v0
	v_lshl_or_b32 v0, v222, 12, v213
	v_lshl_add_u64 v[4:5], v[2:3], 0, v[0:1]
	v_mul_f32_e32 v0, v71, v7
	s_nop 1
	v_mov_b32_dpp v8, v0 quad_perm:[1,0,3,2] row_mask:0xf bank_mask:0xf
	s_and_saveexec_b64 s[0:1], vcc
	s_cbranch_execz .LBB0_6810
	s_waitcnt lgkmcnt(0)
	v_cvt_pk_bf16_f32 v0, v0, v8
	global_store_dword v[4:5], v0, off

.LBB0_6816:
	s_or_b64 exec, exec, s[0:1]
	ds_read_b32 v0, v223 offset:64
	s_waitcnt lgkmcnt(0)
	v_rcp_f32_e32 v7, v0
	v_lshl_or_b32 v0, v222, 12, v214
	v_lshl_add_u64 v[4:5], v[2:3], 0, v[0:1]
	v_mul_f32_e32 v0, v72, v7
	s_nop 1
	v_mov_b32_dpp v8, v0 quad_perm:[1,0,3,2] row_mask:0xf bank_mask:0xf
	s_and_saveexec_b64 s[0:1], vcc
	s_cbranch_execz .LBB0_6818
	s_waitcnt lgkmcnt(0)
	v_cvt_pk_bf16_f32 v0, v0, v8
	global_store_dword v[4:5], v0, off

.LBB0_6824:
	s_or_b64 exec, exec, s[0:1]
	ds_read_b32 v0, v223 offset:68
	s_waitcnt lgkmcnt(0)
	v_rcp_f32_e32 v7, v0
	v_lshl_or_b32 v0, v222, 12, v215
	v_lshl_add_u64 v[4:5], v[2:3], 0, v[0:1]
	v_mul_f32_e32 v0, v73, v7
	s_nop 1
	v_mov_b32_dpp v8, v0 quad_perm:[1,0,3,2] row_mask:0xf bank_mask:0xf
	s_and_saveexec_b64 s[0:1], vcc
	s_cbranch_execz .LBB0_6826
	s_waitcnt lgkmcnt(0)
	v_cvt_pk_bf16_f32 v0, v0, v8
	global_store_dword v[4:5], v0, off

.LBB0_6832:
	s_or_b64 exec, exec, s[0:1]
	ds_read_b32 v0, v223 offset:72
	s_waitcnt lgkmcnt(0)
	v_rcp_f32_e32 v7, v0
	v_lshl_or_b32 v0, v222, 12, v216
	v_lshl_add_u64 v[4:5], v[2:3], 0, v[0:1]
	v_mul_f32_e32 v0, v74, v7
	s_nop 1
	v_mov_b32_dpp v8, v0 quad_perm:[1,0,3,2] row_mask:0xf bank_mask:0xf
	s_and_saveexec_b64 s[0:1], vcc
	s_cbranch_execz .LBB0_6834
	s_waitcnt lgkmcnt(0)
	v_cvt_pk_bf16_f32 v0, v0, v8
	global_store_dword v[4:5], v0, off

.LBB0_6840:
	s_or_b64 exec, exec, s[0:1]
	ds_read_b32 v0, v223 offset:76
	s_waitcnt lgkmcnt(0)
	v_rcp_f32_e32 v7, v0
	v_lshl_or_b32 v0, v222, 12, v217
	v_lshl_add_u64 v[4:5], v[2:3], 0, v[0:1]
	v_mul_f32_e32 v0, v75, v7
	s_nop 1
	v_mov_b32_dpp v8, v0 quad_perm:[1,0,3,2] row_mask:0xf bank_mask:0xf
	s_and_saveexec_b64 s[0:1], vcc
	s_cbranch_execz .LBB0_6842
	s_waitcnt lgkmcnt(0)
	v_cvt_pk_bf16_f32 v0, v0, v8
	global_store_dword v[4:5], v0, off

.LBB0_6848:
	s_or_b64 exec, exec, s[0:1]
	ds_read_b32 v0, v223 offset:96
	s_waitcnt lgkmcnt(0)
	v_rcp_f32_e32 v7, v0
	v_lshl_or_b32 v0, v222, 12, v218
	v_lshl_add_u64 v[4:5], v[2:3], 0, v[0:1]
	v_mul_f32_e32 v0, v76, v7
	s_nop 1
	v_mov_b32_dpp v8, v0 quad_perm:[1,0,3,2] row_mask:0xf bank_mask:0xf
	s_and_saveexec_b64 s[0:1], vcc
	s_cbranch_execz .LBB0_6850
	s_waitcnt lgkmcnt(0)
	v_cvt_pk_bf16_f32 v0, v0, v8
	global_store_dword v[4:5], v0, off

.LBB0_6856:
	s_or_b64 exec, exec, s[0:1]
	ds_read_b32 v0, v223 offset:100
	s_waitcnt lgkmcnt(0)
	v_rcp_f32_e32 v7, v0
	v_lshl_or_b32 v0, v222, 12, v219
	v_lshl_add_u64 v[4:5], v[2:3], 0, v[0:1]
	v_mul_f32_e32 v0, v77, v7
	s_nop 1
	v_mov_b32_dpp v8, v0 quad_perm:[1,0,3,2] row_mask:0xf bank_mask:0xf
	s_and_saveexec_b64 s[0:1], vcc
	s_cbranch_execz .LBB0_6858
	s_waitcnt lgkmcnt(0)
	v_cvt_pk_bf16_f32 v0, v0, v8
	global_store_dword v[4:5], v0, off

.LBB0_6864:
	s_or_b64 exec, exec, s[0:1]
	ds_read_b32 v0, v223 offset:104
	s_waitcnt lgkmcnt(0)
	v_rcp_f32_e32 v7, v0
	v_lshl_or_b32 v0, v222, 12, v220
	v_lshl_add_u64 v[4:5], v[2:3], 0, v[0:1]
	v_mul_f32_e32 v0, v78, v7
	s_nop 1
	v_mov_b32_dpp v8, v0 quad_perm:[1,0,3,2] row_mask:0xf bank_mask:0xf
	s_and_saveexec_b64 s[0:1], vcc
	s_cbranch_execz .LBB0_6866
	s_waitcnt lgkmcnt(0)
	v_cvt_pk_bf16_f32 v0, v0, v8
	global_store_dword v[4:5], v0, off

.LBB0_6872:
	s_or_b64 exec, exec, s[0:1]
	ds_read_b32 v0, v223 offset:108
	s_waitcnt lgkmcnt(0)
	v_rcp_f32_e32 v4, v0
	v_lshl_or_b32 v0, v222, 12, v221
	v_lshl_add_u64 v[2:3], v[2:3], 0, v[0:1]
	v_mul_f32_e32 v5, v79, v4
	s_nop 1
	v_mov_b32_dpp v7, v5 quad_perm:[1,0,3,2] row_mask:0xf bank_mask:0xf
	s_and_saveexec_b64 s[0:1], vcc
	s_cbranch_execz .LBB0_6874
	s_waitcnt lgkmcnt(0)
	v_cvt_pk_bf16_f32 v0, v5, v7
	global_store_dword v[2:3], v0, off

.LBB0_7298:
	s_waitcnt vmcnt(8)
	s_waitcnt vmcnt(9)
	ds_write_b128 v212, v[120:123] offset:32768
	s_waitcnt vmcnt(8)
	ds_write_b128 v212, v[124:127] offset:40960
	v_cmp_gt_u32_e32 vcc, 32, v213
	s_and_saveexec_b64 s[0:1], vcc
	ds_write_b32 v215, v1
	s_or_b64 exec, exec, s[0:1]
	s_waitcnt lgkmcnt(0)
	s_and_b64 vcc, exec, s[36:37]
	s_cbranch_vccnz .LBB0_7430
	ds_read2_b32 v[80:81], v214 offset1:3
	ds_read2_b32 v[82:83], v214 offset0:1 offset1:2
	ds_read_b128 v[10:13], v214 offset:32
	ds_read_b128 v[6:9], v214 offset:64
	ds_read_b128 v[2:5], v214 offset:96
	s_waitcnt lgkmcnt(4)
	v_rcp_f32_e32 v80, v80
	v_and_b32_e32 v14, 64, v204
	v_xor_b32_e32 v1, 1, v204
	v_add_u32_e32 v14, 64, v14
	v_cmp_lt_i32_e32 vcc, v1, v14
	v_mul_f32_e32 v48, v48, v80
	s_ashr_i32 s77, s76, 31
	v_cndmask_b32_e32 v1, v204, v1, vcc
	v_lshlrev_b32_e32 v1, 2, v1
	s_nop 1
	v_mov_b32_dpp v84, v48 quad_perm:[1,0,3,2] row_mask:0xf bank_mask:0xf
	s_lshl_b64 s[0:1], s[76:77], 12
	s_add_u32 s0, s56, s0
	v_and_b32_e32 v14, 1, v210
	s_addc_u32 s1, s57, s1
	v_cmp_eq_u32_e32 vcc, 0, v14
	v_lshlrev_b32_e32 v196, 12, v209
	v_lshlrev_b32_e32 v14, 1, v211
	s_and_saveexec_b64 s[20:21], vcc
	s_cbranch_execz .LBB0_7303
	v_lshl_add_u64 v[86:87], s[0:1], 0, v[196:197]
	v_mov_b32_e32 v15, v197
	v_lshl_add_u64 v[86:87], v[86:87], 0, v[14:15]
	s_waitcnt lgkmcnt(0)
	v_cvt_pk_bf16_f32 v15, v48, v84
	global_store_dword v[86:87], v15, off

.LBB0_7525:
	v_lshl_add_u64 v[22:23], s[66:67], 0, v[144:145]
	v_mov_b32_e32 v157, v145
	v_lshl_add_u64 v[24:25], s[66:67], 0, v[156:157]
	v_mov_b32_e32 v153, v145
	s_add_i32 m0, s63, 0x18000
	v_lshl_add_u64 v[22:23], v[22:23], 0, s[46:47]
	v_lshl_add_u64 v[26:27], s[64:65], 0, v[152:153]
	v_mov_b32_e32 v155, v145
	s_waitcnt vmcnt(2)
	s_barrier
	global_load_lds_dwordx4 v[22:23], off
	v_lshl_add_u64 v[22:23], v[24:25], 0, s[46:47]
	s_add_i32 m0, s63, 0x1a000
	s_add_i32 s87, s63, 0x8000
	s_add_i32 s88, s63, 0xa000
	v_lshl_add_u64 v[28:29], s[64:65], 0, v[154:155]
	global_load_lds_dwordx4 v[22:23], off
	v_lshl_add_u64 v[22:23], v[26:27], 0, s[46:47]
	s_mov_b32 m0, s87
	s_add_u32 s26, s66, 0x80080
	global_load_lds_dwordx4 v[22:23], off
	v_lshl_add_u64 v[22:23], v[28:29], 0, s[46:47]
	s_mov_b32 m0, s88
	s_addc_u32 s27, s67, 0
	global_load_lds_dwordx4 v[22:23], off
	s_add_i32 m0, s63, 0x1c000
	v_lshl_add_u64 v[22:23], s[26:27], 0, v[144:145]
	global_load_lds_dwordx4 v[22:23], off
	v_lshl_add_u64 v[22:23], s[26:27], 0, v[156:157]
	s_add_i32 m0, s63, 0x1e000
	s_waitcnt vmcnt(0)
	v_pk_add_f32 v[10:11], v[14:15], v[10:11]
	global_load_lds_dwordx4 v[22:23], off
	v_pk_add_f32 v[8:9], v[12:13], v[8:9]
	v_pk_add_f32 v[0:1], v[4:5], v[0:1]
	v_pk_add_f32 v[2:3], v[6:7], v[2:3]
	v_pk_add_f32 v[0:1], v[8:9], v[0:1]
	v_pk_add_f32 v[2:3], v[10:11], v[2:3]
	v_add_f32_e32 v0, v0, v1
	v_add_f32_e32 v1, v2, v3
	v_and_b32_e32 v2, 64, v204
	v_add_f32_e32 v0, v0, v1
	v_xor_b32_e32 v1, 1, v204
	v_add_u32_e32 v2, 64, v2
	v_cmp_lt_i32_e32 vcc, v1, v2
	s_waitcnt vmcnt(6)
	v_cmp_eq_u32_e64 s[34:35], 0, v17
	s_barrier
	v_cndmask_b32_e32 v1, v204, v1, vcc
	v_lshlrev_b32_e32 v166, 2, v1
	s_nop 1
	v_mov_b32_dpp v1, v0 quad_perm:[1,0,3,2] row_mask:0xf bank_mask:0xf
	s_and_saveexec_b64 s[26:27], s[34:35]
	s_cbranch_execz .LBB0_7527
	s_waitcnt lgkmcnt(0)
	v_add_f32_e32 v0, v0, v1
	v_fmamk_f32 v0, v0, 0x3a000000, v164
	v_cmp_gt_f32_e32 vcc, s92, v0
	v_mul_f32_e32 v1, 0x4b800000, v0
	s_nop 0
	v_cndmask_b32_e32 v0, v0, v1, vcc
	v_rsq_f32_e32 v0, v0
	s_nop 0
	v_mul_f32_e32 v1, 0x45800000, v0
	v_cndmask_b32_e32 v0, v0, v1, vcc
	v_lshl_add_u32 v1, v16, 2, 0
	v_add_u32_e32 v1, 0x20000, v1
	ds_write_b32 v1, v0

.LBB0_7721:
	v_readlane_b32 s2, v253, 3
	v_readlane_b32 s3, v253, 4
	s_cmp_lt_i32 s2, 38
	s_cselect_b64 s[0:1], -1, 0
	s_cmp_gt_i32 s3, 37
	s_cselect_b64 s[2:3], -1, 0
	s_and_b64 s[0:1], s[0:1], s[2:3]
	s_andn2_b64 vcc, exec, s[0:1]
	s_cbranch_vccnz .LBB0_7727
	s_add_i32 s0, 0, 0x221e8
	v_mov_b32_e32 v0, s0
	ds_read2_b64 v[2:5], v0 offset1:1
	s_add_i32 s4, 0, 0x22170
	s_waitcnt lgkmcnt(0)
	v_mov_b32_e32 v1, s4
	v_mbcnt_lo_u32_b32 v0, -1, 0
	v_mbcnt_hi_u32_b32 v0, -1, v0
	v_readlane_b32 s4, v253, 7
	v_readfirstlane_b32 s3, v3
	v_readfirstlane_b32 s2, v2
	ds_read_b64 v[2:3], v1
	v_add_u32_e32 v1, s4, v0
	v_readlane_b32 s4, v253, 2
	v_ashrrev_i32_e32 v10, 6, v1
	s_lshl_b32 s6, s4, 3
	v_add_u32_e32 v16, s6, v10
	s_movk_i32 s4, 0x2000
	v_readfirstlane_b32 s1, v5
	v_readfirstlane_b32 s0, v4
	s_waitcnt lgkmcnt(0)
	v_readfirstlane_b32 s9, v3
	v_readfirstlane_b32 s8, v2
	v_cmp_gt_i32_e32 vcc, s4, v16
	s_and_saveexec_b64 s[4:5], vcc
	s_cbranch_execz .LBB0_7727
	v_ashrrev_i32_e32 v11, 31, v10
	s_ashr_i32 s7, s6, 31
	v_and_b32_e32 v17, 63, v0
	v_lshl_add_u64 v[18:19], v[10:11], 0, s[6:7]
	v_lshlrev_b32_e32 v12, 2, v17
	v_mov_b32_e32 v13, 0
	v_lshlrev_b64 v[10:11], 7, v[18:19]
	v_lshlrev_b32_e32 v14, 4, v17
	v_mov_b32_e32 v15, v13
	v_mov_b32_e32 v3, v13
	v_mov_b32_e32 v5, v13
	v_mov_b32_e32 v7, v13
	v_mov_b32_e32 v9, v13
	v_lshl_add_u64 v[10:11], v[10:11], 0, v[12:13]
	v_lshlrev_b64 v[12:13], 13, v[18:19]
	v_lshl_add_u64 v[0:1], s[8:9], 0, v[14:15]
	v_or_b32_e32 v2, 0x1000, v14
	v_or_b32_e32 v4, 0x1400, v14
	v_or_b32_e32 v6, 0x1800, v14
	v_or_b32_e32 v8, 0x1c00, v14
	v_or_b32_e32 v12, v12, v14
	v_lshlrev_b64 v[14:15], 12, v[18:19]
	s_lshl_b32 s4, s24, 3
	v_lshl_or_b32 v14, v17, 3, v14
	v_lshl_add_u64 v[10:11], s[0:1], 0, v[10:11]
	s_mov_b64 s[6:7], 0x437a6000
	s_ashr_i32 s5, s4, 31
	v_lshl_add_u64 v[12:13], s[2:3], 0, v[12:13]
	s_mov_b64 s[2:3], 0x1c00
	v_lshl_add_u64 v[14:15], s[0:1], 0, v[14:15]
	s_mov_b64 s[0:1], 0x1ca00800
	v_cmp_gt_u32_e32 vcc, 32, v17
	v_lshl_add_u64 v[2:3], s[8:9], 0, v[2:3]
	v_lshl_add_u64 v[4:5], s[8:9], 0, v[4:5]
	v_lshl_add_u64 v[6:7], s[8:9], 0, v[6:7]
	v_lshl_add_u64 v[8:9], s[8:9], 0, v[8:9]
	v_lshl_add_u64 v[10:11], v[10:11], 0, s[6:7]
	s_lshl_b64 s[6:7], s[4:5], 7
	v_lshl_add_u64 v[12:13], v[12:13], 0, s[2:3]
	s_lshl_b64 s[8:9], s[4:5], 13
	v_lshl_add_u64 v[14:15], v[14:15], 0, s[0:1]
	s_lshl_b64 s[10:11], s[4:5], 12
	s_mov_b64 s[12:13], 0
	v_mov_b32_e32 v17, 0x358637bd
	s_mov_b32 s5, 0x800000
	s_movk_i32 s14, 0xf000
	s_movk_i32 s15, 0x1fff
	global_load_dwordx4 v[32:35], v[0:1], off
	global_load_dwordx4 v[36:39], v[0:1], off offset:1024
	global_load_dwordx4 v[40:43], v[0:1], off offset:2048
	global_load_dwordx4 v[44:47], v[0:1], off offset:3072
	global_load_dwordx4 v[48:51], v[2:3], off
	global_load_dwordx4 v[52:55], v[4:5], off
	global_load_dwordx4 v[56:59], v[6:7], off
	global_load_dwordx4 v[60:63], v[8:9], off
	s_branch .LBB0_7725
.LBB0_7724:
	s_or_b64 exec, exec, s[0:1]
	global_load_dwordx2 v[64:65], v[14:15], off offset:-2048
	global_load_dwordx2 v[66:67], v[14:15], off offset:-1536
	global_load_dwordx2 v[68:69], v[14:15], off offset:-1024
	global_load_dwordx2 v[70:71], v[14:15], off offset:-512
	global_load_dwordx2 v[72:73], v[14:15], off
	global_load_dwordx2 v[74:75], v[14:15], off offset:512
	global_load_dwordx2 v[76:77], v[14:15], off offset:1024
	global_load_dwordx2 v[78:79], v[14:15], off offset:1536
	v_lshl_add_u64 v[14:15], v[14:15], 0, s[10:11]
	s_waitcnt vmcnt(8)
	ds_swizzle_b32 v19, v18 offset:swizzle(SWAP,1)
	v_add_co_u32_e64 v26, s[2:3], s14, v12
	v_add_u32_e32 v16, s4, v16
	s_nop 0
	v_addc_co_u32_e64 v27, s[2:3], -1, v13, s[2:3]
	s_waitcnt lgkmcnt(0)
	v_add_f32_e32 v18, v18, v19
	ds_swizzle_b32 v19, v18 offset:swizzle(SWAP,2)
	v_lshl_add_u64 v[10:11], v[10:11], 0, s[6:7]
	s_waitcnt lgkmcnt(0)
	v_add_f32_e32 v18, v18, v19
	ds_swizzle_b32 v19, v18 offset:swizzle(SWAP,4)
	s_waitcnt lgkmcnt(0)
	v_add_f32_e32 v18, v18, v19
	ds_swizzle_b32 v19, v18 offset:swizzle(SWAP,8)
	s_waitcnt lgkmcnt(0)
	v_add_f32_e32 v18, v18, v19
	ds_swizzle_b32 v19, v18 offset:swizzle(SWAP,16)
	s_waitcnt lgkmcnt(0)
	v_add_f32_e32 v18, v18, v19
	v_mov_b32_e32 v19, v18
	s_nop 1
	v_permlane32_swap_b32_e32 v18, v19
	v_add_f32_e32 v18, v18, v19
	v_fmamk_f32 v18, v18, 0x3a000000, v17
	v_mul_f32_e32 v19, 0x4b800000, v18
	v_cmp_gt_f32_e64 s[0:1], s5, v18
	s_nop 1
	v_cndmask_b32_e64 v18, v18, v19, s[0:1]
	v_rsq_f32_e32 v18, v18
	s_nop 0
	v_mul_f32_e32 v19, 0x45800000, v18
	v_cndmask_b32_e64 v28, v18, v19, s[0:1]
	v_cmp_lt_i32_e64 s[0:1], s15, v16
	s_or_b64 s[12:13], s[0:1], s[12:13]
	s_waitcnt vmcnt(7)
	v_lshlrev_b32_e32 v24, 16, v64
	v_and_b32_e32 v25, 0xffff0000, v64
	v_lshlrev_b32_e32 v22, 16, v65
	v_and_b32_e32 v23, 0xffff0000, v65
	v_pk_mul_f32 v[24:25], v[28:29], v[24:25] op_sel_hi:[0,1]
	v_pk_mul_f32 v[22:23], v[28:29], v[22:23] op_sel_hi:[0,1]
	v_pk_mul_f32 v[20:21], v[34:35], v[22:23]
	v_pk_mul_f32 v[18:19], v[32:33], v[24:25]
	global_store_dwordx4 v[26:27], v[18:21], off offset:-3072 nt
	s_waitcnt vmcnt(7)
	v_lshlrev_b32_e32 v24, 16, v66
	v_and_b32_e32 v25, 0xffff0000, v66
	v_lshlrev_b32_e32 v22, 16, v67
	v_and_b32_e32 v23, 0xffff0000, v67
	v_pk_mul_f32 v[24:25], v[28:29], v[24:25] op_sel_hi:[0,1]
	v_pk_mul_f32 v[22:23], v[28:29], v[22:23] op_sel_hi:[0,1]
	v_pk_mul_f32 v[86:87], v[38:39], v[22:23]
	v_pk_mul_f32 v[84:85], v[36:37], v[24:25]
	global_store_dwordx4 v[26:27], v[84:87], off offset:-2048 nt
	s_waitcnt vmcnt(7)
	v_lshlrev_b32_e32 v24, 16, v68
	v_and_b32_e32 v25, 0xffff0000, v68
	v_lshlrev_b32_e32 v22, 16, v69
	v_and_b32_e32 v23, 0xffff0000, v69
	v_pk_mul_f32 v[24:25], v[28:29], v[24:25] op_sel_hi:[0,1]
	v_pk_mul_f32 v[22:23], v[28:29], v[22:23] op_sel_hi:[0,1]
	v_pk_mul_f32 v[20:21], v[42:43], v[22:23]
	v_pk_mul_f32 v[18:19], v[40:41], v[24:25]
	global_store_dwordx4 v[26:27], v[18:21], off offset:-1024 nt
	s_waitcnt vmcnt(7)
	v_lshlrev_b32_e32 v24, 16, v70
	v_and_b32_e32 v25, 0xffff0000, v70
	v_lshlrev_b32_e32 v22, 16, v71
	v_and_b32_e32 v23, 0xffff0000, v71
	v_pk_mul_f32 v[24:25], v[28:29], v[24:25] op_sel_hi:[0,1]
	v_pk_mul_f32 v[22:23], v[28:29], v[22:23] op_sel_hi:[0,1]
	v_pk_mul_f32 v[86:87], v[46:47], v[22:23]
	v_pk_mul_f32 v[84:85], v[44:45], v[24:25]
	global_store_dwordx4 v[12:13], v[84:87], off offset:-4096 nt
	s_waitcnt vmcnt(7)
	v_lshlrev_b32_e32 v24, 16, v72
	v_and_b32_e32 v25, 0xffff0000, v72
	v_lshlrev_b32_e32 v22, 16, v73
	v_and_b32_e32 v23, 0xffff0000, v73
	v_pk_mul_f32 v[24:25], v[28:29], v[24:25] op_sel_hi:[0,1]
	v_pk_mul_f32 v[22:23], v[28:29], v[22:23] op_sel_hi:[0,1]
	v_pk_mul_f32 v[20:21], v[50:51], v[22:23]
	v_pk_mul_f32 v[18:19], v[48:49], v[24:25]
	global_store_dwordx4 v[12:13], v[18:21], off offset:-3072 nt
	s_waitcnt vmcnt(7)
	v_lshlrev_b32_e32 v24, 16, v74
	v_and_b32_e32 v25, 0xffff0000, v74
	v_lshlrev_b32_e32 v22, 16, v75
	v_and_b32_e32 v23, 0xffff0000, v75
	v_pk_mul_f32 v[24:25], v[28:29], v[24:25] op_sel_hi:[0,1]
	v_pk_mul_f32 v[22:23], v[28:29], v[22:23] op_sel_hi:[0,1]
	v_pk_mul_f32 v[86:87], v[54:55], v[22:23]
	v_pk_mul_f32 v[84:85], v[52:53], v[24:25]
	global_store_dwordx4 v[12:13], v[84:87], off offset:-2048 nt
	s_waitcnt vmcnt(7)
	v_lshlrev_b32_e32 v24, 16, v76
	v_and_b32_e32 v25, 0xffff0000, v76
	v_lshlrev_b32_e32 v22, 16, v77
	v_and_b32_e32 v23, 0xffff0000, v77
	v_pk_mul_f32 v[24:25], v[28:29], v[24:25] op_sel_hi:[0,1]
	v_pk_mul_f32 v[22:23], v[28:29], v[22:23] op_sel_hi:[0,1]
	v_pk_mul_f32 v[20:21], v[58:59], v[22:23]
	v_pk_mul_f32 v[18:19], v[56:57], v[24:25]
	global_store_dwordx4 v[12:13], v[18:21], off offset:-1024 nt
	s_waitcnt vmcnt(7)
	v_lshlrev_b32_e32 v24, 16, v78
	v_and_b32_e32 v25, 0xffff0000, v78
	v_lshlrev_b32_e32 v22, 16, v79
	v_and_b32_e32 v23, 0xffff0000, v79
	v_pk_mul_f32 v[24:25], v[28:29], v[24:25] op_sel_hi:[0,1]
	v_pk_mul_f32 v[22:23], v[28:29], v[22:23] op_sel_hi:[0,1]
	v_pk_mul_f32 v[86:87], v[62:63], v[22:23]
	v_pk_mul_f32 v[84:85], v[60:61], v[24:25]
	global_store_dwordx4 v[12:13], v[84:87], off nt
	v_lshl_add_u64 v[12:13], v[12:13], 0, s[8:9]
	s_andn2_b64 exec, exec, s[12:13]
	s_cbranch_execz .LBB0_7727
